# baseline (speedup 1.0000x reference)
; #define STAGE_A(P, br, kt) do { const char* _base = (const char*)(((kt) < G.ksplit ? G.A1 : A2m) + (long)(br) * G.lda + (long)(kt) * BK); \
;     __builtin_amdgcn_global_load_lds((const unsigned*)(_base + aoff0), (unsigned*)((char*)(P) + sb0), 16, 0, 0); \
;     __builtin_amdgcn_global_load_lds((const unsigned*)(_base + aoff1), (unsigned*)((char*)(P) + sb1), 16, 0, 0); } while (0)
; #define STAGE_B(P, br, kt) do { const char* _base = (const char*)(G.Bt + (long)(br) * G.ldb + (long)(kt) * BK); \
;     __builtin_amdgcn_global_load_lds((const unsigned*)(_base + boff0), (unsigned*)((char*)(P) + sb0), 16, 0, 0); \
;     __builtin_amdgcn_global_load_lds((const unsigned*)(_base + boff1), (unsigned*)((char*)(P) + sb1), 16, 0, 0); } while (0)
; #define LDA(dst, b, h) for (int m = 0; m < 4; ++m) for (int k = 0; k < 2; ++k) \
;     dst[m][k] = *reinterpret_cast<const bf16x8*>(a_rd + ((b) * 2 + (h)) * (HT * 2) + m * 2048 + k * 1024)
; #define LDB(dst, b, h) for (int n = 0; n < 2; ++n) for (int k = 0; k < 2; ++k) \
;     dst[n][k] = *reinterpret_cast<const bf16x8*>(b_rd + ((b) * 2 + (h)) * (HT * 2) + n * 2048 + k * 1024)
; #define WAIT_V(n) asm volatile("s_waitcnt vmcnt(" #n ")" ::: "memory")
; #define WAIT_L(n) asm volatile("s_waitcnt lgkmcnt(" #n ")" ::: "memory")
; #define BAR __builtin_amdgcn_s_barrier()
; #define SCHED __builtin_amdgcn_sched_barrier(0)
;     ...
;   const int nt = K / BK;
;   if (EPI == EPI_RESID || first) {
;     STAGE_B(SB(0, 0), bcol, 0); STAGE_A(SA(0, 0), brow, 0);
;     STAGE_B(SB(0, 1), bcol + HALF, 0); STAGE_A(SA(0, 1), brow + HALF, 0);
;   }
;   if (wr == 1) BAR;
;   WAIT_V(0); BAR;
;   STAGE_B(SB(1, 0), bcol, 1); STAGE_A(SA(1, 0), brow, 1); STAGE_B(SB(1, 1), bcol + HALF, 1);
;   WAIT_V(6); BAR;
;   for (int t = 0; t < nt - 2; t += 2) {
;     LDB(B0, 0, 0); SCHED; LDA(At, 0, 0); STAGE_A(SA(1, 1), brow + HALF, t + 1);
;     WAIT_L(8); BAR; WAIT_L(0); MMA(0, 0, At, B0); BAR; SCHED;
;     LDB(B1, 0, 1); STAGE_B(SB(0, 0), bcol, t + 2);
;     BAR; WAIT_L(0); MMA(0, 1, At, B1); BAR;
;     LDA(At, 0, 1); STAGE_A(SA(0, 0), brow, t + 2);
;     BAR; WAIT_L(0); MMA(1, 0, At, B0); BAR; SCHED;
;     STAGE_B(SB(0, 1), bcol + HALF, t + 2);
;     WAIT_V(6); BAR; MMA(1, 1, At, B1); BAR;
;     LDB(B0, 1, 0); SCHED; LDA(At, 1, 0); STAGE_A(SA(0, 1), brow + HALF, t + 2);
;     WAIT_L(8); BAR; WAIT_L(0); MMA(0, 0, At, B0); BAR; SCHED;
.LBB0_745:
	s_or_b64 exec, exec, s[10:11]
	v_and_b32_e32 v150, 15, v144
	v_lshlrev_b32_e32 v10, 2, v144
	s_ashr_i32 s9, s8, 31
	v_and_b32_e32 v8, 48, v144
	v_lshlrev_b32_e32 v9, 6, v150
	v_and_b32_e32 v10, 32, v10
	s_add_i32 s10, 32, 0x10000
	s_lshl_b32 s36, s52, 8
	s_lshl_b64 s[44:45], s[8:9], 1
	v_bitop3_b32 v10, v9, v10, v8 bitop3:0x36
	v_lshlrev_b32_e32 v8, 6, v144
	s_add_u32 s46, s49, s44
	v_readlane_b32 s9, v253, 46
	v_and_b32_e32 v8, 0x3000, v8
	s_addc_u32 s47, s50, s45
	v_add_u32_e32 v152, s9, v146
	v_add_u32_e32 v12, s10, v8
	v_lshl_add_u64 v[8:9], s[46:47], 0, v[180:181]
	s_mov_b64 vcc, 0x80
	v_readfirstlane_b32 s9, v152
	v_lshl_add_u64 v[8:9], v[8:9], 0, vcc
	s_mov_b32 m0, s9
	v_mov_b32_e32 v129, v181
	v_add_u32_e32 v153, 0x2000, v152
	s_add_u32 s42, s12, s42
	s_waitcnt vmcnt(0)
	s_barrier
	global_load_lds_dwordx4 v[8:9], off
	v_lshl_add_u64 v[8:9], s[46:47], 0, v[128:129]
	v_readfirstlane_b32 s9, v153
	s_addc_u32 s43, s13, s37
	s_or_b32 s37, s36, 0x80
	v_lshl_add_u64 v[8:9], v[8:9], 0, vcc
	s_mov_b32 m0, s9
	v_add_u32_e32 v154, 0x8000, v149
	s_mul_i32 s46, s37, 0x840
	global_load_lds_dwordx4 v[8:9], off
	v_lshl_add_u64 v[8:9], s[42:43], 0, v[180:181]
	v_readfirstlane_b32 s9, v154
	v_add_u32_e32 v156, 0xa000, v149
	s_ashr_i32 s47, s46, 31
	v_lshl_add_u64 v[8:9], v[8:9], 0, vcc
	s_mov_b32 m0, s9
	v_readfirstlane_b32 s9, v156
	s_lshl_b64 s[46:47], s[46:47], 1
	global_load_lds_dwordx4 v[8:9], off
	v_lshl_add_u64 v[8:9], s[42:43], 0, v[128:129]
	s_mov_b32 m0, s9
	s_add_u32 s46, s49, s46
	v_readlane_b32 s9, v253, 47
	v_lshl_add_u64 v[8:9], v[8:9], 0, vcc
	s_addc_u32 s47, s50, s47
	v_add_u32_e32 v157, s9, v146
	global_load_lds_dwordx4 v[8:9], off
	v_lshl_add_u64 v[8:9], s[46:47], 0, v[180:181]
	v_readfirstlane_b32 s9, v157
	v_lshl_add_u64 v[8:9], v[8:9], 0, vcc
	s_mov_b32 m0, s9
	v_add_u32_e32 v158, 0x2000, v157
	global_load_lds_dwordx4 v[8:9], off
	v_lshl_add_u64 v[8:9], s[46:47], 0, v[128:129]
	v_readfirstlane_b32 s9, v158
	v_lshl_add_u64 v[8:9], v[8:9], 0, vcc
	s_mov_b32 m0, s9
	s_movk_i32 s9, 0x840
	global_load_lds_dwordx4 v[8:9], off
	v_lshrrev_b32_e32 v8, 1, v0
	v_mul_lo_u32 v0, v2, s9
	v_mad_u64_u32 v[8:9], s[46:47], v8, s84, v[0:1]
	s_add_u32 s44, s14, s44
	v_or_b32_e32 v0, v8, v3
	s_addc_u32 s45, s15, s45
	s_add_i32 s8, s8, 0x40000
	v_add_lshl_u32 v2, v0, v4, 1
	v_lshrrev_b32_e32 v1, 1, v1
	v_mul_lo_u32 v0, v5, s9
	s_ashr_i32 s9, s8, 31
	v_mad_u64_u32 v[0:1], s[46:47], v1, s84, v[0:1]
	s_lshl_b64 s[8:9], s[8:9], 1
	v_or_b32_e32 v0, v0, v6
	s_add_u32 s8, s14, s8
	s_waitcnt vmcnt(6)
	v_add_lshl_u32 v0, v0, v7, 1
	v_mov_b32_e32 v1, v181
	s_addc_u32 s9, s15, s9
	v_lshl_add_u32 v11, v148, 13, 32
	v_mov_b32_e32 v3, v181
	v_lshl_add_u64 v[132:133], s[44:45], 0, v[0:1]
	v_lshl_add_u64 v[136:137], s[42:43], 0, v[0:1]
	v_lshl_add_u64 v[140:141], s[8:9], 0, v[0:1]
	v_lshl_add_u64 v[130:131], s[44:45], 0, v[2:3]
	v_lshl_add_u64 v[134:135], s[42:43], 0, v[2:3]
	v_lshl_add_u64 v[138:139], s[8:9], 0, v[2:3]
	s_mov_b32 s11, -2
	s_mov_b64 s[8:9], 0
	v_add_u32_e32 v155, v12, v10
	v_add_u32_e32 v151, v11, v10
	s_waitcnt vmcnt(0)
	s_mov_b64 s[44:45], 0x84080
	s_mov_b64 s[46:47], 0x4360100
	s_mov_b64 vcc, 0x4364100
	s_mov_b64 s[64:65], 0x84100
	s_mov_b64 s[22:23], 0x4360180
	s_mov_b64 s[24:25], 0x4364180
	s_barrier
	ds_read_b128 v[164:167], v155
	ds_read_b128 v[168:171], v155 offset:1024
	ds_read_b128 v[172:175], v155 offset:2048
	ds_read_b128 v[176:179], v155 offset:3072
	v_add_u32_e32 v162, 0xc000, v149
	v_lshl_add_u64 v[222:223], v[134:135], 0, s[8:9]
	v_readfirstlane_b32 s42, v162
	v_add_u32_e32 v163, 0xe000, v149
	v_lshl_add_u64 v[160:161], v[222:223], 0, s[44:45]
	s_mov_b32 m0, s42
	v_lshl_add_u64 v[234:235], v[136:137], 0, s[8:9]
	v_readfirstlane_b32 s42, v163
	ds_read_b128 v[182:185], v151
	ds_read_b128 v[186:189], v151 offset:1024
	ds_read_b128 v[190:193], v151 offset:2048
	ds_read_b128 v[194:197], v151 offset:3072
	ds_read_b128 v[198:201], v151 offset:4096
	ds_read_b128 v[202:205], v151 offset:5120
	ds_read_b128 v[206:209], v151 offset:6144
	ds_read_b128 v[210:213], v151 offset:7168
	global_load_lds_dwordx4 v[160:161], off
	v_lshl_add_u64 v[160:161], v[234:235], 0, s[44:45]
	s_mov_b32 m0, s42
	s_nop 0
	global_load_lds_dwordx4 v[160:161], off
	ds_read_b128 v[214:217], v155 offset:16384
	ds_read_b128 v[218:221], v155 offset:17408
	ds_read_b128 v[230:233], v155 offset:18432
	ds_read_b128 v[238:241], v155 offset:19456
	s_waitcnt lgkmcnt(0)
	s_waitcnt vmcnt(8)
	s_barrier
	s_setprio 1
	v_mfma_f32_16x16x32_bf16 v[124:127], v[164:167], v[182:185], 0
	v_mfma_f32_16x16x32_bf16 v[120:123], v[172:175], v[182:185], 0
	v_mfma_f32_16x16x32_bf16 v[116:119], v[164:167], v[190:193], 0
	v_mfma_f32_16x16x32_bf16 v[112:115], v[172:175], v[190:193], 0
	v_mfma_f32_16x16x32_bf16 v[108:111], v[164:167], v[198:201], 0
	v_mfma_f32_16x16x32_bf16 v[104:107], v[172:175], v[198:201], 0
	v_mfma_f32_16x16x32_bf16 v[100:103], v[164:167], v[206:209], 0
	v_mfma_f32_16x16x32_bf16 v[96:99], v[172:175], v[206:209], 0
	v_mfma_f32_16x16x32_bf16 v[124:127], v[168:171], v[186:189], v[124:127]
	v_mfma_f32_16x16x32_bf16 v[120:123], v[176:179], v[186:189], v[120:123]
	v_mfma_f32_16x16x32_bf16 v[116:119], v[168:171], v[194:197], v[116:119]
	v_mfma_f32_16x16x32_bf16 v[112:115], v[176:179], v[194:197], v[112:115]
	v_mfma_f32_16x16x32_bf16 v[108:111], v[168:171], v[202:205], v[108:111]
	v_mfma_f32_16x16x32_bf16 v[104:107], v[176:179], v[202:205], v[104:107]
	v_mfma_f32_16x16x32_bf16 v[100:103], v[168:171], v[210:213], v[100:103]
	v_mfma_f32_16x16x32_bf16 v[96:99], v[176:179], v[210:213], v[96:99]
	v_mfma_f32_16x16x32_bf16 v[92:95], v[214:217], v[182:185], 0
	v_mfma_f32_16x16x32_bf16 v[88:91], v[230:233], v[182:185], 0
	v_mfma_f32_16x16x32_bf16 v[84:87], v[214:217], v[190:193], 0
	v_mfma_f32_16x16x32_bf16 v[80:83], v[230:233], v[190:193], 0
	v_mfma_f32_16x16x32_bf16 v[76:79], v[214:217], v[198:201], 0
	v_mfma_f32_16x16x32_bf16 v[72:75], v[230:233], v[198:201], 0
	v_mfma_f32_16x16x32_bf16 v[68:71], v[214:217], v[206:209], 0
	v_mfma_f32_16x16x32_bf16 v[64:67], v[230:233], v[206:209], 0
	v_mfma_f32_16x16x32_bf16 v[92:95], v[218:221], v[186:189], v[92:95]
	v_mfma_f32_16x16x32_bf16 v[88:91], v[238:241], v[186:189], v[88:91]
	v_mfma_f32_16x16x32_bf16 v[84:87], v[218:221], v[194:197], v[84:87]
	v_mfma_f32_16x16x32_bf16 v[80:83], v[238:241], v[194:197], v[80:83]
	s_setprio 2
	s_barrier
; #define STAGE_A(P, br, kt) do { const char* _base = (const char*)(((kt) < G.ksplit ? G.A1 : A2m) + (long)(br) * G.lda + (long)(kt) * BK); \
;     __builtin_amdgcn_global_load_lds((const unsigned*)(_base + aoff0), (unsigned*)((char*)(P) + sb0), 16, 0, 0); \
;     __builtin_amdgcn_global_load_lds((const unsigned*)(_base + aoff1), (unsigned*)((char*)(P) + sb1), 16, 0, 0); } while (0)
; #define STAGE_B(P, br, kt) do { const char* _base = (const char*)(G.Bt + (long)(br) * G.ldb + (long)(kt) * BK); \
;     __builtin_amdgcn_global_load_lds((const unsigned*)(_base + boff0), (unsigned*)((char*)(P) + sb0), 16, 0, 0); \
;     __builtin_amdgcn_global_load_lds((const unsigned*)(_base + boff1), (unsigned*)((char*)(P) + sb1), 16, 0, 0); } while (0)
; #define LDA(dst, b, h) for (int m = 0; m < 4; ++m) for (int k = 0; k < 2; ++k) \
;     dst[m][k] = *reinterpret_cast<const bf16x8*>(a_rd + ((b) * 2 + (h)) * (HT * 2) + m * 2048 + k * 1024)
; #define LDB(dst, b, h) for (int n = 0; n < 2; ++n) for (int k = 0; k < 2; ++k) \
;     dst[n][k] = *reinterpret_cast<const bf16x8*>(b_rd + ((b) * 2 + (h)) * (HT * 2) + n * 2048 + k * 1024)
; #define MMA(ai, bj, At_, Bt_) do { __builtin_amdgcn_s_setprio(1); \
;     for (int m = 0; m < 4; ++m) for (int n = 0; n < 2; ++n) for (int k = 0; k < 2; ++k) \
;       acc[ai][bj][m][n] = __builtin_amdgcn_mfma_f32_16x16x32_bf16(Bt_[n][k], At_[m][k], acc[ai][bj][m][n], 0, 0, 0); \
;     __builtin_amdgcn_s_setprio(0); } while (0)
; #define WAIT_V(n) asm volatile("s_waitcnt vmcnt(" #n ")" ::: "memory")
; #define WAIT_L(n) asm volatile("s_waitcnt lgkmcnt(" #n ")" ::: "memory")
; #define BAR __builtin_amdgcn_s_barrier()
; #define SCHED __builtin_amdgcn_sched_barrier(0)
;     ...
;   for (int t = 0; t < nt - 2; t += 2) {
;     LDB(B0, 0, 0); SCHED; LDA(At, 0, 0); STAGE_A(SA(1, 1), brow + HALF, t + 1);
;     WAIT_L(8); BAR; WAIT_L(0); MMA(0, 0, At, B0); BAR; SCHED;
;     LDB(B1, 0, 1); STAGE_B(SB(0, 0), bcol, t + 2);
;     BAR; WAIT_L(0); MMA(0, 1, At, B1); BAR;
;     LDA(At, 0, 1); STAGE_A(SA(0, 0), brow, t + 2);
;     BAR; WAIT_L(0); MMA(1, 0, At, B0); BAR; SCHED;
;     STAGE_B(SB(0, 1), bcol + HALF, t + 2);
;     WAIT_V(6); BAR; MMA(1, 1, At, B1); BAR;
;     LDB(B0, 1, 0); SCHED; LDA(At, 1, 0); STAGE_A(SA(0, 1), brow + HALF, t + 2);
;     WAIT_L(8); BAR; WAIT_L(0); MMA(0, 0, At, B0); BAR; SCHED;
	v_mfma_f32_16x16x32_bf16 v[76:79], v[218:221], v[202:205], v[76:79]
	v_mfma_f32_16x16x32_bf16 v[72:75], v[238:241], v[202:205], v[72:75]
	v_mfma_f32_16x16x32_bf16 v[68:71], v[218:221], v[210:213], v[68:71]
	v_mfma_f32_16x16x32_bf16 v[64:67], v[238:241], v[210:213], v[64:67]
	s_setprio 0
	v_add_u32_e32 v159, s10, v146
	v_lshl_add_u64 v[236:237], v[130:131], 0, s[8:9]
	v_readfirstlane_b32 s42, v159
	v_lshl_add_u64 v[160:161], v[236:237], 0, s[46:47]
	s_mov_b32 m0, s42
	global_load_lds_dwordx4 v[160:161], off
	v_add_u32_e32 v160, 0x2000, v159
	v_lshl_add_u64 v[246:247], v[132:133], 0, s[8:9]
	v_readfirstlane_b32 s42, v160
	v_lshl_add_u64 v[248:249], v[246:247], 0, s[46:47]
	s_mov_b32 m0, s42
	s_nop 0
	global_load_lds_dwordx4 v[248:249], off
	v_readfirstlane_b32 s42, v149
	v_lshl_add_u64 v[248:249], v[222:223], 0, s[90:91]
	s_mov_b32 m0, s42
	v_readfirstlane_b32 s42, v147
	ds_read_b128 v[182:185], v151 offset:16384
	ds_read_b128 v[186:189], v151 offset:17408
	ds_read_b128 v[190:193], v151 offset:18432
	ds_read_b128 v[194:197], v151 offset:19456
	ds_read_b128 v[198:201], v151 offset:20480
	ds_read_b128 v[202:205], v151 offset:21504
	ds_read_b128 v[206:209], v151 offset:22528
	ds_read_b128 v[210:213], v151 offset:23552
	global_load_lds_dwordx4 v[248:249], off
	v_lshl_add_u64 v[248:249], v[234:235], 0, s[90:91]
	s_mov_b32 m0, s42
	s_nop 0
	global_load_lds_dwordx4 v[248:249], off
	v_lshl_add_u64 v[248:249], v[138:139], 0, s[8:9]
	v_readfirstlane_b32 s42, v145
	v_add_u32_e32 v161, 0x2000, v145
	v_lshl_add_u64 v[250:251], v[248:249], 0, vcc
	s_mov_b32 m0, s42
	v_lshl_add_u64 v[226:227], v[140:141], 0, s[8:9]
	v_readfirstlane_b32 s42, v161
	global_load_lds_dwordx4 v[250:251], off
	v_lshl_add_u64 v[250:251], v[226:227], 0, vcc
	s_mov_b32 m0, s42
	s_nop 0
	global_load_lds_dwordx4 v[250:251], off
	s_waitcnt lgkmcnt(0)
	s_waitcnt vmcnt(8)
	s_barrier
	s_setprio 1
	v_mfma_f32_16x16x32_bf16 v[60:63], v[164:167], v[182:185], 0
	v_mfma_f32_16x16x32_bf16 v[56:59], v[172:175], v[182:185], 0
	v_mfma_f32_16x16x32_bf16 v[52:55], v[164:167], v[190:193], 0
	v_mfma_f32_16x16x32_bf16 v[48:51], v[172:175], v[190:193], 0
	v_mfma_f32_16x16x32_bf16 v[44:47], v[164:167], v[198:201], 0
	v_mfma_f32_16x16x32_bf16 v[40:43], v[172:175], v[198:201], 0
	v_mfma_f32_16x16x32_bf16 v[36:39], v[164:167], v[206:209], 0
	v_mfma_f32_16x16x32_bf16 v[32:35], v[172:175], v[206:209], 0
	v_mfma_f32_16x16x32_bf16 v[60:63], v[168:171], v[186:189], v[60:63]
	v_mfma_f32_16x16x32_bf16 v[56:59], v[176:179], v[186:189], v[56:59]
	v_mfma_f32_16x16x32_bf16 v[52:55], v[168:171], v[194:197], v[52:55]
	v_mfma_f32_16x16x32_bf16 v[48:51], v[176:179], v[194:197], v[48:51]
	v_mfma_f32_16x16x32_bf16 v[44:47], v[168:171], v[202:205], v[44:47]
	v_mfma_f32_16x16x32_bf16 v[40:43], v[176:179], v[202:205], v[40:43]
	v_mfma_f32_16x16x32_bf16 v[36:39], v[168:171], v[210:213], v[36:39]
	v_mfma_f32_16x16x32_bf16 v[32:35], v[176:179], v[210:213], v[32:35]
	v_mfma_f32_16x16x32_bf16 v[28:31], v[214:217], v[182:185], 0
	v_mfma_f32_16x16x32_bf16 v[24:27], v[230:233], v[182:185], 0
	v_mfma_f32_16x16x32_bf16 v[20:23], v[214:217], v[190:193], 0
	v_mfma_f32_16x16x32_bf16 v[16:19], v[230:233], v[190:193], 0
	v_mfma_f32_16x16x32_bf16 v[12:15], v[214:217], v[198:201], 0
	v_mfma_f32_16x16x32_bf16 v[8:11], v[230:233], v[198:201], 0
	v_mfma_f32_16x16x32_bf16 v[4:7], v[214:217], v[206:209], 0
	v_mfma_f32_16x16x32_bf16 v[0:3], v[230:233], v[206:209], 0
	v_mfma_f32_16x16x32_bf16 v[28:31], v[218:221], v[186:189], v[28:31]
	v_mfma_f32_16x16x32_bf16 v[24:27], v[238:241], v[186:189], v[24:27]
	v_mfma_f32_16x16x32_bf16 v[20:23], v[218:221], v[194:197], v[20:23]
	v_mfma_f32_16x16x32_bf16 v[16:19], v[238:241], v[194:197], v[16:19]
	s_setprio 2
	s_barrier
	v_mfma_f32_16x16x32_bf16 v[12:15], v[218:221], v[202:205], v[12:15]
	v_mfma_f32_16x16x32_bf16 v[8:11], v[238:241], v[202:205], v[8:11]
	v_mfma_f32_16x16x32_bf16 v[4:7], v[218:221], v[210:213], v[4:7]
	v_mfma_f32_16x16x32_bf16 v[0:3], v[238:241], v[210:213], v[0:3]
	s_setprio 0
	ds_read_b128 v[164:167], v155 offset:32768
	ds_read_b128 v[168:171], v155 offset:33792
	ds_read_b128 v[172:175], v155 offset:34816
	ds_read_b128 v[176:179], v155 offset:35840
	v_readfirstlane_b32 s42, v143
	v_lshl_add_u64 v[214:215], v[222:223], 0, s[64:65]
	s_mov_b32 m0, s42
	v_readfirstlane_b32 s42, v142
	ds_read_b128 v[182:185], v151 offset:32768
	ds_read_b128 v[186:189], v151 offset:33792
	ds_read_b128 v[190:193], v151 offset:34816
	ds_read_b128 v[194:197], v151 offset:35840
	ds_read_b128 v[198:201], v151 offset:36864
	ds_read_b128 v[202:205], v151 offset:37888
	ds_read_b128 v[206:209], v151 offset:38912
	ds_read_b128 v[210:213], v151 offset:39936
	global_load_lds_dwordx4 v[214:215], off
	v_lshl_add_u64 v[214:215], v[234:235], 0, s[64:65]
	s_mov_b32 m0, s42
	s_nop 0
	global_load_lds_dwordx4 v[214:215], off
	ds_read_b128 v[214:217], v155 offset:49152
	ds_read_b128 v[218:221], v155 offset:50176
	ds_read_b128 v[230:233], v155 offset:51200
	ds_read_b128 v[238:241], v155 offset:52224
	s_waitcnt lgkmcnt(0)
	s_waitcnt vmcnt(8)
	s_barrier
; #define STAGE_A(P, br, kt) do { const char* _base = (const char*)(((kt) < G.ksplit ? G.A1 : A2m) + (long)(br) * G.lda + (long)(kt) * BK); \
;     __builtin_amdgcn_global_load_lds((const unsigned*)(_base + aoff0), (unsigned*)((char*)(P) + sb0), 16, 0, 0); \
;     __builtin_amdgcn_global_load_lds((const unsigned*)(_base + aoff1), (unsigned*)((char*)(P) + sb1), 16, 0, 0); } while (0)
; #define STAGE_B(P, br, kt) do { const char* _base = (const char*)(G.Bt + (long)(br) * G.ldb + (long)(kt) * BK); \
;     __builtin_amdgcn_global_load_lds((const unsigned*)(_base + boff0), (unsigned*)((char*)(P) + sb0), 16, 0, 0); \
;     __builtin_amdgcn_global_load_lds((const unsigned*)(_base + boff1), (unsigned*)((char*)(P) + sb1), 16, 0, 0); } while (0)
; #define LDA(dst, b, h) for (int m = 0; m < 4; ++m) for (int k = 0; k < 2; ++k) \
;     dst[m][k] = *reinterpret_cast<const bf16x8*>(a_rd + ((b) * 2 + (h)) * (HT * 2) + m * 2048 + k * 1024)
; #define LDB(dst, b, h) for (int n = 0; n < 2; ++n) for (int k = 0; k < 2; ++k) \
;     dst[n][k] = *reinterpret_cast<const bf16x8*>(b_rd + ((b) * 2 + (h)) * (HT * 2) + n * 2048 + k * 1024)
; #define MMA(ai, bj, At_, Bt_) do { __builtin_amdgcn_s_setprio(1); \
;     for (int m = 0; m < 4; ++m) for (int n = 0; n < 2; ++n) for (int k = 0; k < 2; ++k) \
;       acc[ai][bj][m][n] = __builtin_amdgcn_mfma_f32_16x16x32_bf16(Bt_[n][k], At_[m][k], acc[ai][bj][m][n], 0, 0, 0); \
;     __builtin_amdgcn_s_setprio(0); } while (0)
; #define WAIT_V(n) asm volatile("s_waitcnt vmcnt(" #n ")" ::: "memory")
; #define WAIT_L(n) asm volatile("s_waitcnt lgkmcnt(" #n ")" ::: "memory")
; #define BAR __builtin_amdgcn_s_barrier()
; #define SCHED __builtin_amdgcn_sched_barrier(0)
;     ...
;     LDB(B0, 1, 0); SCHED; LDA(At, 1, 0); STAGE_A(SA(0, 1), brow + HALF, t + 2);
;     WAIT_L(8); BAR; WAIT_L(0); MMA(0, 0, At, B0); BAR; SCHED;
;     LDB(B1, 1, 1); STAGE_B(SB(1, 0), bcol, t + 3);
;     BAR; WAIT_L(0); MMA(0, 1, At, B1); BAR;
;     LDA(At, 1, 1); STAGE_A(SA(1, 0), brow, t + 3);
;     BAR; WAIT_L(0); MMA(1, 0, At, B0); BAR; SCHED;
;     STAGE_B(SB(1, 1), bcol + HALF, t + 3);
;     WAIT_V(6); BAR; MMA(1, 1, At, B1); BAR;
;   }
	s_setprio 1
	v_mfma_f32_16x16x32_bf16 v[124:127], v[164:167], v[182:185], v[124:127]
	v_mfma_f32_16x16x32_bf16 v[120:123], v[172:175], v[182:185], v[120:123]
	v_mfma_f32_16x16x32_bf16 v[116:119], v[164:167], v[190:193], v[116:119]
	v_mfma_f32_16x16x32_bf16 v[112:115], v[172:175], v[190:193], v[112:115]
	v_mfma_f32_16x16x32_bf16 v[108:111], v[164:167], v[198:201], v[108:111]
	v_mfma_f32_16x16x32_bf16 v[104:107], v[172:175], v[198:201], v[104:107]
	v_mfma_f32_16x16x32_bf16 v[100:103], v[164:167], v[206:209], v[100:103]
	v_mfma_f32_16x16x32_bf16 v[96:99], v[172:175], v[206:209], v[96:99]
	v_mfma_f32_16x16x32_bf16 v[124:127], v[168:171], v[186:189], v[124:127]
	v_mfma_f32_16x16x32_bf16 v[120:123], v[176:179], v[186:189], v[120:123]
	v_mfma_f32_16x16x32_bf16 v[116:119], v[168:171], v[194:197], v[116:119]
	v_mfma_f32_16x16x32_bf16 v[112:115], v[176:179], v[194:197], v[112:115]
	v_mfma_f32_16x16x32_bf16 v[108:111], v[168:171], v[202:205], v[108:111]
	v_mfma_f32_16x16x32_bf16 v[104:107], v[176:179], v[202:205], v[104:107]
	v_mfma_f32_16x16x32_bf16 v[100:103], v[168:171], v[210:213], v[100:103]
	v_mfma_f32_16x16x32_bf16 v[96:99], v[176:179], v[210:213], v[96:99]
	v_mfma_f32_16x16x32_bf16 v[92:95], v[214:217], v[182:185], v[92:95]
	v_mfma_f32_16x16x32_bf16 v[88:91], v[230:233], v[182:185], v[88:91]
	v_mfma_f32_16x16x32_bf16 v[84:87], v[214:217], v[190:193], v[84:87]
	v_mfma_f32_16x16x32_bf16 v[80:83], v[230:233], v[190:193], v[80:83]
	v_mfma_f32_16x16x32_bf16 v[76:79], v[214:217], v[198:201], v[76:79]
	v_mfma_f32_16x16x32_bf16 v[72:75], v[230:233], v[198:201], v[72:75]
	v_mfma_f32_16x16x32_bf16 v[68:71], v[214:217], v[206:209], v[68:71]
	v_mfma_f32_16x16x32_bf16 v[64:67], v[230:233], v[206:209], v[64:67]
	v_mfma_f32_16x16x32_bf16 v[92:95], v[218:221], v[186:189], v[92:95]
	v_mfma_f32_16x16x32_bf16 v[88:91], v[238:241], v[186:189], v[88:91]
	v_mfma_f32_16x16x32_bf16 v[84:87], v[218:221], v[194:197], v[84:87]
	v_mfma_f32_16x16x32_bf16 v[80:83], v[238:241], v[194:197], v[80:83]
	s_setprio 2
	s_barrier
	v_mfma_f32_16x16x32_bf16 v[76:79], v[218:221], v[202:205], v[76:79]
	v_mfma_f32_16x16x32_bf16 v[72:75], v[238:241], v[202:205], v[72:75]
	v_mfma_f32_16x16x32_bf16 v[68:71], v[218:221], v[210:213], v[68:71]
	v_mfma_f32_16x16x32_bf16 v[64:67], v[238:241], v[210:213], v[64:67]
	s_setprio 0
	v_readfirstlane_b32 s42, v152
	v_lshl_add_u64 v[236:237], v[236:237], 0, s[22:23]
	s_mov_b32 m0, s42
	v_readfirstlane_b32 s42, v153
	global_load_lds_dwordx4 v[236:237], off
	v_lshl_add_u64 v[236:237], v[246:247], 0, s[22:23]
	s_mov_b32 m0, s42
	s_nop 0
	global_load_lds_dwordx4 v[236:237], off
	v_readfirstlane_b32 s42, v154
	v_lshl_add_u64 v[222:223], v[222:223], 0, s[88:89]
	s_mov_b32 m0, s42
	v_readfirstlane_b32 s42, v156
	ds_read_b128 v[182:185], v151 offset:49152
	ds_read_b128 v[186:189], v151 offset:50176
	ds_read_b128 v[190:193], v151 offset:51200
	ds_read_b128 v[194:197], v151 offset:52224
	ds_read_b128 v[198:201], v151 offset:53248
	ds_read_b128 v[202:205], v151 offset:54272
	ds_read_b128 v[206:209], v151 offset:55296
	ds_read_b128 v[210:213], v151 offset:56320
	global_load_lds_dwordx4 v[222:223], off
	v_lshl_add_u64 v[222:223], v[234:235], 0, s[88:89]
	s_mov_b32 m0, s42
	s_nop 0
	global_load_lds_dwordx4 v[222:223], off
	v_readfirstlane_b32 s42, v157
	v_lshl_add_u64 v[250:251], v[248:249], 0, s[24:25]
	s_mov_b32 m0, s42
	v_readfirstlane_b32 s42, v158
	global_load_lds_dwordx4 v[250:251], off
	v_lshl_add_u64 v[250:251], v[226:227], 0, s[24:25]
	s_mov_b32 m0, s42
	s_nop 0
	global_load_lds_dwordx4 v[250:251], off
	s_waitcnt lgkmcnt(0)
	s_waitcnt vmcnt(8)
	s_barrier
	s_setprio 1
	v_mfma_f32_16x16x32_bf16 v[60:63], v[164:167], v[182:185], v[60:63]
	v_mfma_f32_16x16x32_bf16 v[56:59], v[172:175], v[182:185], v[56:59]
	v_mfma_f32_16x16x32_bf16 v[52:55], v[164:167], v[190:193], v[52:55]
	v_mfma_f32_16x16x32_bf16 v[48:51], v[172:175], v[190:193], v[48:51]
	v_mfma_f32_16x16x32_bf16 v[44:47], v[164:167], v[198:201], v[44:47]
	v_mfma_f32_16x16x32_bf16 v[40:43], v[172:175], v[198:201], v[40:43]
	v_mfma_f32_16x16x32_bf16 v[36:39], v[164:167], v[206:209], v[36:39]
	v_mfma_f32_16x16x32_bf16 v[32:35], v[172:175], v[206:209], v[32:35]
	v_mfma_f32_16x16x32_bf16 v[60:63], v[168:171], v[186:189], v[60:63]
	v_mfma_f32_16x16x32_bf16 v[56:59], v[176:179], v[186:189], v[56:59]
	v_mfma_f32_16x16x32_bf16 v[52:55], v[168:171], v[194:197], v[52:55]
	v_mfma_f32_16x16x32_bf16 v[48:51], v[176:179], v[194:197], v[48:51]
	v_mfma_f32_16x16x32_bf16 v[44:47], v[168:171], v[202:205], v[44:47]
	v_mfma_f32_16x16x32_bf16 v[40:43], v[176:179], v[202:205], v[40:43]
	v_mfma_f32_16x16x32_bf16 v[36:39], v[168:171], v[210:213], v[36:39]
	v_mfma_f32_16x16x32_bf16 v[32:35], v[176:179], v[210:213], v[32:35]
	v_mfma_f32_16x16x32_bf16 v[28:31], v[214:217], v[182:185], v[28:31]
	v_mfma_f32_16x16x32_bf16 v[24:27], v[230:233], v[182:185], v[24:27]
	v_mfma_f32_16x16x32_bf16 v[20:23], v[214:217], v[190:193], v[20:23]
	v_mfma_f32_16x16x32_bf16 v[16:19], v[230:233], v[190:193], v[16:19]
	v_mfma_f32_16x16x32_bf16 v[12:15], v[214:217], v[198:201], v[12:15]
	v_mfma_f32_16x16x32_bf16 v[8:11], v[230:233], v[198:201], v[8:11]
	v_mfma_f32_16x16x32_bf16 v[4:7], v[214:217], v[206:209], v[4:7]
	v_mfma_f32_16x16x32_bf16 v[0:3], v[230:233], v[206:209], v[0:3]
	v_mfma_f32_16x16x32_bf16 v[28:31], v[218:221], v[186:189], v[28:31]
	v_mfma_f32_16x16x32_bf16 v[24:27], v[238:241], v[186:189], v[24:27]
	v_mfma_f32_16x16x32_bf16 v[20:23], v[218:221], v[194:197], v[20:23]
	v_mfma_f32_16x16x32_bf16 v[16:19], v[238:241], v[194:197], v[16:19]
	s_setprio 2
	s_barrier
	v_mfma_f32_16x16x32_bf16 v[12:15], v[218:221], v[202:205], v[12:15]
	v_mfma_f32_16x16x32_bf16 v[8:11], v[238:241], v[202:205], v[8:11]
	v_mfma_f32_16x16x32_bf16 v[4:7], v[218:221], v[210:213], v[4:7]
	v_mfma_f32_16x16x32_bf16 v[0:3], v[238:241], v[210:213], v[0:3]
	s_setprio 0
	s_add_i32 s11, s11, 2
	s_add_u32 s8, s8, 0x100
	s_addc_u32 s9, s9, 0
	s_cmp_lt_u32 s11, 28
	s_cbranch_scc0 .Lmy_kexit_0
; #define STAGE_A(P, br, kt) do { const char* _base = (const char*)(((kt) < G.ksplit ? G.A1 : A2m) + (long)(br) * G.lda + (long)(kt) * BK); \
;     __builtin_amdgcn_global_load_lds((const unsigned*)(_base + aoff0), (unsigned*)((char*)(P) + sb0), 16, 0, 0); \
;     __builtin_amdgcn_global_load_lds((const unsigned*)(_base + aoff1), (unsigned*)((char*)(P) + sb1), 16, 0, 0); } while (0)
; #define STAGE_B(P, br, kt) do { const char* _base = (const char*)(G.Bt + (long)(br) * G.ldb + (long)(kt) * BK); \
;     __builtin_amdgcn_global_load_lds((const unsigned*)(_base + boff0), (unsigned*)((char*)(P) + sb0), 16, 0, 0); \
;     __builtin_amdgcn_global_load_lds((const unsigned*)(_base + boff1), (unsigned*)((char*)(P) + sb1), 16, 0, 0); } while (0)
; #define LDA(dst, b, h) for (int m = 0; m < 4; ++m) for (int k = 0; k < 2; ++k) \
;     dst[m][k] = *reinterpret_cast<const bf16x8*>(a_rd + ((b) * 2 + (h)) * (HT * 2) + m * 2048 + k * 1024)
; #define LDB(dst, b, h) for (int n = 0; n < 2; ++n) for (int k = 0; k < 2; ++k) \
;     dst[n][k] = *reinterpret_cast<const bf16x8*>(b_rd + ((b) * 2 + (h)) * (HT * 2) + n * 2048 + k * 1024)
; #define MMA(ai, bj, At_, Bt_) do { __builtin_amdgcn_s_setprio(1); \
;     for (int m = 0; m < 4; ++m) for (int n = 0; n < 2; ++n) for (int k = 0; k < 2; ++k) \
;       acc[ai][bj][m][n] = __builtin_amdgcn_mfma_f32_16x16x32_bf16(Bt_[n][k], At_[m][k], acc[ai][bj][m][n], 0, 0, 0); \
;     __builtin_amdgcn_s_setprio(0); } while (0)
;     ...
;   for (int t = 0; t < nt - 2; t += 2) {
;     LDB(B0, 0, 0); SCHED; LDA(At, 0, 0); STAGE_A(SA(1, 1), brow + HALF, t + 1);
;     WAIT_L(8); BAR; WAIT_L(0); MMA(0, 0, At, B0); BAR; SCHED;
;     LDB(B1, 0, 1); STAGE_B(SB(0, 0), bcol, t + 2);
;     BAR; WAIT_L(0); MMA(0, 1, At, B1); BAR;
;     LDA(At, 0, 1); STAGE_A(SA(0, 0), brow, t + 2);
;     BAR; WAIT_L(0); MMA(1, 0, At, B0); BAR; SCHED;
;     STAGE_B(SB(0, 1), bcol + HALF, t + 2);
;     WAIT_V(6); BAR; MMA(1, 1, At, B1); BAR;
;     LDB(B0, 1, 0); SCHED; LDA(At, 1, 0); STAGE_A(SA(0, 1), brow + HALF, t + 2);
;     WAIT_L(8); BAR; WAIT_L(0); MMA(0, 0, At, B0); BAR; SCHED;
;     LDB(B1, 1, 1); STAGE_B(SB(1, 0), bcol, t + 3);
;     BAR; WAIT_L(0); MMA(0, 1, At, B1); BAR;
;     LDA(At, 1, 1); STAGE_A(SA(1, 0), brow, t + 3);
;     BAR; WAIT_L(0); MMA(1, 0, At, B0); BAR; SCHED;
;     STAGE_B(SB(1, 1), bcol + HALF, t + 3);
;     WAIT_V(6); BAR; MMA(1, 1, At, B1); BAR;
.LBB0_746:
	ds_read_b128 v[164:167], v155
	ds_read_b128 v[168:171], v155 offset:1024
	ds_read_b128 v[172:175], v155 offset:2048
	ds_read_b128 v[176:179], v155 offset:3072
	v_add_u32_e32 v162, 0xc000, v149
	v_lshl_add_u64 v[222:223], v[134:135], 0, s[8:9]
	v_readfirstlane_b32 s42, v162
	v_add_u32_e32 v163, 0xe000, v149
	v_lshl_add_u64 v[160:161], v[222:223], 0, s[44:45]
	s_mov_b32 m0, s42
	v_lshl_add_u64 v[234:235], v[136:137], 0, s[8:9]
	v_readfirstlane_b32 s42, v163
	ds_read_b128 v[182:185], v151
	ds_read_b128 v[186:189], v151 offset:1024
	ds_read_b128 v[190:193], v151 offset:2048
	ds_read_b128 v[194:197], v151 offset:3072
	ds_read_b128 v[198:201], v151 offset:4096
	ds_read_b128 v[202:205], v151 offset:5120
	ds_read_b128 v[206:209], v151 offset:6144
	ds_read_b128 v[210:213], v151 offset:7168
	global_load_lds_dwordx4 v[160:161], off
	v_lshl_add_u64 v[160:161], v[234:235], 0, s[44:45]
	s_mov_b32 m0, s42
	s_nop 0
	global_load_lds_dwordx4 v[160:161], off
	ds_read_b128 v[214:217], v155 offset:16384
	ds_read_b128 v[218:221], v155 offset:17408
	ds_read_b128 v[230:233], v155 offset:18432
	ds_read_b128 v[238:241], v155 offset:19456
	s_waitcnt lgkmcnt(0)
	s_waitcnt vmcnt(8)
	s_barrier
	s_setprio 1
	v_mfma_f32_16x16x32_bf16 v[124:127], v[164:167], v[182:185], v[124:127]
	v_mfma_f32_16x16x32_bf16 v[120:123], v[172:175], v[182:185], v[120:123]
	v_mfma_f32_16x16x32_bf16 v[116:119], v[164:167], v[190:193], v[116:119]
	v_mfma_f32_16x16x32_bf16 v[112:115], v[172:175], v[190:193], v[112:115]
	v_mfma_f32_16x16x32_bf16 v[108:111], v[164:167], v[198:201], v[108:111]
	v_mfma_f32_16x16x32_bf16 v[104:107], v[172:175], v[198:201], v[104:107]
	v_mfma_f32_16x16x32_bf16 v[100:103], v[164:167], v[206:209], v[100:103]
	v_mfma_f32_16x16x32_bf16 v[96:99], v[172:175], v[206:209], v[96:99]
	v_mfma_f32_16x16x32_bf16 v[124:127], v[168:171], v[186:189], v[124:127]
	v_mfma_f32_16x16x32_bf16 v[120:123], v[176:179], v[186:189], v[120:123]
	v_mfma_f32_16x16x32_bf16 v[116:119], v[168:171], v[194:197], v[116:119]
	v_mfma_f32_16x16x32_bf16 v[112:115], v[176:179], v[194:197], v[112:115]
	v_mfma_f32_16x16x32_bf16 v[108:111], v[168:171], v[202:205], v[108:111]
	v_mfma_f32_16x16x32_bf16 v[104:107], v[176:179], v[202:205], v[104:107]
	v_mfma_f32_16x16x32_bf16 v[100:103], v[168:171], v[210:213], v[100:103]
	v_mfma_f32_16x16x32_bf16 v[96:99], v[176:179], v[210:213], v[96:99]
	v_mfma_f32_16x16x32_bf16 v[92:95], v[214:217], v[182:185], v[92:95]
	v_mfma_f32_16x16x32_bf16 v[88:91], v[230:233], v[182:185], v[88:91]
	v_mfma_f32_16x16x32_bf16 v[84:87], v[214:217], v[190:193], v[84:87]
	v_mfma_f32_16x16x32_bf16 v[80:83], v[230:233], v[190:193], v[80:83]
	v_mfma_f32_16x16x32_bf16 v[76:79], v[214:217], v[198:201], v[76:79]
	v_mfma_f32_16x16x32_bf16 v[72:75], v[230:233], v[198:201], v[72:75]
	v_mfma_f32_16x16x32_bf16 v[68:71], v[214:217], v[206:209], v[68:71]
	v_mfma_f32_16x16x32_bf16 v[64:67], v[230:233], v[206:209], v[64:67]
	v_mfma_f32_16x16x32_bf16 v[92:95], v[218:221], v[186:189], v[92:95]
	v_mfma_f32_16x16x32_bf16 v[88:91], v[238:241], v[186:189], v[88:91]
	v_mfma_f32_16x16x32_bf16 v[84:87], v[218:221], v[194:197], v[84:87]
	v_mfma_f32_16x16x32_bf16 v[80:83], v[238:241], v[194:197], v[80:83]
	s_setprio 2
	s_barrier
	v_mfma_f32_16x16x32_bf16 v[76:79], v[218:221], v[202:205], v[76:79]
	v_mfma_f32_16x16x32_bf16 v[72:75], v[238:241], v[202:205], v[72:75]
	v_mfma_f32_16x16x32_bf16 v[68:71], v[218:221], v[210:213], v[68:71]
	v_mfma_f32_16x16x32_bf16 v[64:67], v[238:241], v[210:213], v[64:67]
	s_setprio 0
	v_add_u32_e32 v159, s10, v146
	v_lshl_add_u64 v[236:237], v[130:131], 0, s[8:9]
	v_readfirstlane_b32 s42, v159
	v_lshl_add_u64 v[160:161], v[236:237], 0, s[46:47]
	s_mov_b32 m0, s42
	global_load_lds_dwordx4 v[160:161], off
	v_add_u32_e32 v160, 0x2000, v159
	v_lshl_add_u64 v[246:247], v[132:133], 0, s[8:9]
	v_readfirstlane_b32 s42, v160
	v_lshl_add_u64 v[248:249], v[246:247], 0, s[46:47]
	s_mov_b32 m0, s42
	s_nop 0
	global_load_lds_dwordx4 v[248:249], off
	v_readfirstlane_b32 s42, v149
	v_lshl_add_u64 v[248:249], v[222:223], 0, s[90:91]
	s_mov_b32 m0, s42
	v_readfirstlane_b32 s42, v147
	ds_read_b128 v[182:185], v151 offset:16384
	ds_read_b128 v[186:189], v151 offset:17408
	ds_read_b128 v[190:193], v151 offset:18432
	ds_read_b128 v[194:197], v151 offset:19456
	ds_read_b128 v[198:201], v151 offset:20480
	ds_read_b128 v[202:205], v151 offset:21504
	ds_read_b128 v[206:209], v151 offset:22528
	ds_read_b128 v[210:213], v151 offset:23552
	global_load_lds_dwordx4 v[248:249], off
	v_lshl_add_u64 v[248:249], v[234:235], 0, s[90:91]
	s_mov_b32 m0, s42
	s_nop 0
	global_load_lds_dwordx4 v[248:249], off
	v_lshl_add_u64 v[248:249], v[138:139], 0, s[8:9]
	v_readfirstlane_b32 s42, v145
	v_add_u32_e32 v161, 0x2000, v145
	v_lshl_add_u64 v[250:251], v[248:249], 0, vcc
	s_mov_b32 m0, s42
	v_lshl_add_u64 v[226:227], v[140:141], 0, s[8:9]
	v_readfirstlane_b32 s42, v161
	global_load_lds_dwordx4 v[250:251], off
	v_lshl_add_u64 v[250:251], v[226:227], 0, vcc
	s_mov_b32 m0, s42
	s_nop 0
	global_load_lds_dwordx4 v[250:251], off
	s_waitcnt lgkmcnt(0)
	s_waitcnt vmcnt(8)
	s_barrier
; #define STAGE_A(P, br, kt) do { const char* _base = (const char*)(((kt) < G.ksplit ? G.A1 : A2m) + (long)(br) * G.lda + (long)(kt) * BK); \
;     __builtin_amdgcn_global_load_lds((const unsigned*)(_base + aoff0), (unsigned*)((char*)(P) + sb0), 16, 0, 0); \
;     __builtin_amdgcn_global_load_lds((const unsigned*)(_base + aoff1), (unsigned*)((char*)(P) + sb1), 16, 0, 0); } while (0)
; #define STAGE_B(P, br, kt) do { const char* _base = (const char*)(G.Bt + (long)(br) * G.ldb + (long)(kt) * BK); \
;     __builtin_amdgcn_global_load_lds((const unsigned*)(_base + boff0), (unsigned*)((char*)(P) + sb0), 16, 0, 0); \
;     __builtin_amdgcn_global_load_lds((const unsigned*)(_base + boff1), (unsigned*)((char*)(P) + sb1), 16, 0, 0); } while (0)
; #define LDA(dst, b, h) for (int m = 0; m < 4; ++m) for (int k = 0; k < 2; ++k) \
;     dst[m][k] = *reinterpret_cast<const bf16x8*>(a_rd + ((b) * 2 + (h)) * (HT * 2) + m * 2048 + k * 1024)
; #define LDB(dst, b, h) for (int n = 0; n < 2; ++n) for (int k = 0; k < 2; ++k) \
;     dst[n][k] = *reinterpret_cast<const bf16x8*>(b_rd + ((b) * 2 + (h)) * (HT * 2) + n * 2048 + k * 1024)
; #define MMA(ai, bj, At_, Bt_) do { __builtin_amdgcn_s_setprio(1); \
;     for (int m = 0; m < 4; ++m) for (int n = 0; n < 2; ++n) for (int k = 0; k < 2; ++k) \
;       acc[ai][bj][m][n] = __builtin_amdgcn_mfma_f32_16x16x32_bf16(Bt_[n][k], At_[m][k], acc[ai][bj][m][n], 0, 0, 0); \
;     __builtin_amdgcn_s_setprio(0); } while (0)
;     ...
;   for (int t = 0; t < nt - 2; t += 2) {
;     LDB(B0, 0, 0); SCHED; LDA(At, 0, 0); STAGE_A(SA(1, 1), brow + HALF, t + 1);
;     WAIT_L(8); BAR; WAIT_L(0); MMA(0, 0, At, B0); BAR; SCHED;
;     LDB(B1, 0, 1); STAGE_B(SB(0, 0), bcol, t + 2);
;     BAR; WAIT_L(0); MMA(0, 1, At, B1); BAR;
;     LDA(At, 0, 1); STAGE_A(SA(0, 0), brow, t + 2);
;     BAR; WAIT_L(0); MMA(1, 0, At, B0); BAR; SCHED;
;     STAGE_B(SB(0, 1), bcol + HALF, t + 2);
;     WAIT_V(6); BAR; MMA(1, 1, At, B1); BAR;
;     LDB(B0, 1, 0); SCHED; LDA(At, 1, 0); STAGE_A(SA(0, 1), brow + HALF, t + 2);
;     WAIT_L(8); BAR; WAIT_L(0); MMA(0, 0, At, B0); BAR; SCHED;
;     LDB(B1, 1, 1); STAGE_B(SB(1, 0), bcol, t + 3);
;     BAR; WAIT_L(0); MMA(0, 1, At, B1); BAR;
;     LDA(At, 1, 1); STAGE_A(SA(1, 0), brow, t + 3);
;     BAR; WAIT_L(0); MMA(1, 0, At, B0); BAR; SCHED;
;     STAGE_B(SB(1, 1), bcol + HALF, t + 3);
;     WAIT_V(6); BAR; MMA(1, 1, At, B1); BAR;
	s_setprio 1
	v_mfma_f32_16x16x32_bf16 v[60:63], v[164:167], v[182:185], v[60:63]
	v_mfma_f32_16x16x32_bf16 v[56:59], v[172:175], v[182:185], v[56:59]
	v_mfma_f32_16x16x32_bf16 v[52:55], v[164:167], v[190:193], v[52:55]
	v_mfma_f32_16x16x32_bf16 v[48:51], v[172:175], v[190:193], v[48:51]
	v_mfma_f32_16x16x32_bf16 v[44:47], v[164:167], v[198:201], v[44:47]
	v_mfma_f32_16x16x32_bf16 v[40:43], v[172:175], v[198:201], v[40:43]
	v_mfma_f32_16x16x32_bf16 v[36:39], v[164:167], v[206:209], v[36:39]
	v_mfma_f32_16x16x32_bf16 v[32:35], v[172:175], v[206:209], v[32:35]
	v_mfma_f32_16x16x32_bf16 v[60:63], v[168:171], v[186:189], v[60:63]
	v_mfma_f32_16x16x32_bf16 v[56:59], v[176:179], v[186:189], v[56:59]
	v_mfma_f32_16x16x32_bf16 v[52:55], v[168:171], v[194:197], v[52:55]
	v_mfma_f32_16x16x32_bf16 v[48:51], v[176:179], v[194:197], v[48:51]
	v_mfma_f32_16x16x32_bf16 v[44:47], v[168:171], v[202:205], v[44:47]
	v_mfma_f32_16x16x32_bf16 v[40:43], v[176:179], v[202:205], v[40:43]
	v_mfma_f32_16x16x32_bf16 v[36:39], v[168:171], v[210:213], v[36:39]
	v_mfma_f32_16x16x32_bf16 v[32:35], v[176:179], v[210:213], v[32:35]
	v_mfma_f32_16x16x32_bf16 v[28:31], v[214:217], v[182:185], v[28:31]
	v_mfma_f32_16x16x32_bf16 v[24:27], v[230:233], v[182:185], v[24:27]
	v_mfma_f32_16x16x32_bf16 v[20:23], v[214:217], v[190:193], v[20:23]
	v_mfma_f32_16x16x32_bf16 v[16:19], v[230:233], v[190:193], v[16:19]
	v_mfma_f32_16x16x32_bf16 v[12:15], v[214:217], v[198:201], v[12:15]
	v_mfma_f32_16x16x32_bf16 v[8:11], v[230:233], v[198:201], v[8:11]
	v_mfma_f32_16x16x32_bf16 v[4:7], v[214:217], v[206:209], v[4:7]
	v_mfma_f32_16x16x32_bf16 v[0:3], v[230:233], v[206:209], v[0:3]
	v_mfma_f32_16x16x32_bf16 v[28:31], v[218:221], v[186:189], v[28:31]
	v_mfma_f32_16x16x32_bf16 v[24:27], v[238:241], v[186:189], v[24:27]
	v_mfma_f32_16x16x32_bf16 v[20:23], v[218:221], v[194:197], v[20:23]
	v_mfma_f32_16x16x32_bf16 v[16:19], v[238:241], v[194:197], v[16:19]
	s_setprio 2
	s_barrier
	v_mfma_f32_16x16x32_bf16 v[12:15], v[218:221], v[202:205], v[12:15]
	v_mfma_f32_16x16x32_bf16 v[8:11], v[238:241], v[202:205], v[8:11]
	v_mfma_f32_16x16x32_bf16 v[4:7], v[218:221], v[210:213], v[4:7]
	v_mfma_f32_16x16x32_bf16 v[0:3], v[238:241], v[210:213], v[0:3]
	s_setprio 0
	ds_read_b128 v[164:167], v155 offset:32768
	ds_read_b128 v[168:171], v155 offset:33792
	ds_read_b128 v[172:175], v155 offset:34816
	ds_read_b128 v[176:179], v155 offset:35840
	v_readfirstlane_b32 s42, v143
	v_lshl_add_u64 v[214:215], v[222:223], 0, s[64:65]
	s_mov_b32 m0, s42
	v_readfirstlane_b32 s42, v142
	ds_read_b128 v[182:185], v151 offset:32768
	ds_read_b128 v[186:189], v151 offset:33792
	ds_read_b128 v[190:193], v151 offset:34816
	ds_read_b128 v[194:197], v151 offset:35840
	ds_read_b128 v[198:201], v151 offset:36864
	ds_read_b128 v[202:205], v151 offset:37888
	ds_read_b128 v[206:209], v151 offset:38912
	ds_read_b128 v[210:213], v151 offset:39936
	global_load_lds_dwordx4 v[214:215], off
	v_lshl_add_u64 v[214:215], v[234:235], 0, s[64:65]
	s_mov_b32 m0, s42
	s_nop 0
	global_load_lds_dwordx4 v[214:215], off
	ds_read_b128 v[214:217], v155 offset:49152
	ds_read_b128 v[218:221], v155 offset:50176
	ds_read_b128 v[230:233], v155 offset:51200
	ds_read_b128 v[238:241], v155 offset:52224
	s_waitcnt lgkmcnt(0)
	s_waitcnt vmcnt(8)
	s_barrier
	s_setprio 1
	v_mfma_f32_16x16x32_bf16 v[124:127], v[164:167], v[182:185], v[124:127]
	v_mfma_f32_16x16x32_bf16 v[120:123], v[172:175], v[182:185], v[120:123]
	v_mfma_f32_16x16x32_bf16 v[116:119], v[164:167], v[190:193], v[116:119]
	v_mfma_f32_16x16x32_bf16 v[112:115], v[172:175], v[190:193], v[112:115]
	v_mfma_f32_16x16x32_bf16 v[108:111], v[164:167], v[198:201], v[108:111]
	v_mfma_f32_16x16x32_bf16 v[104:107], v[172:175], v[198:201], v[104:107]
	v_mfma_f32_16x16x32_bf16 v[100:103], v[164:167], v[206:209], v[100:103]
	v_mfma_f32_16x16x32_bf16 v[96:99], v[172:175], v[206:209], v[96:99]
	v_mfma_f32_16x16x32_bf16 v[124:127], v[168:171], v[186:189], v[124:127]
	v_mfma_f32_16x16x32_bf16 v[120:123], v[176:179], v[186:189], v[120:123]
	v_mfma_f32_16x16x32_bf16 v[116:119], v[168:171], v[194:197], v[116:119]
	v_mfma_f32_16x16x32_bf16 v[112:115], v[176:179], v[194:197], v[112:115]
	v_mfma_f32_16x16x32_bf16 v[108:111], v[168:171], v[202:205], v[108:111]
	v_mfma_f32_16x16x32_bf16 v[104:107], v[176:179], v[202:205], v[104:107]
	v_mfma_f32_16x16x32_bf16 v[100:103], v[168:171], v[210:213], v[100:103]
	v_mfma_f32_16x16x32_bf16 v[96:99], v[176:179], v[210:213], v[96:99]
	v_mfma_f32_16x16x32_bf16 v[92:95], v[214:217], v[182:185], v[92:95]
	v_mfma_f32_16x16x32_bf16 v[88:91], v[230:233], v[182:185], v[88:91]
	v_mfma_f32_16x16x32_bf16 v[84:87], v[214:217], v[190:193], v[84:87]
	v_mfma_f32_16x16x32_bf16 v[80:83], v[230:233], v[190:193], v[80:83]
	v_mfma_f32_16x16x32_bf16 v[76:79], v[214:217], v[198:201], v[76:79]
	v_mfma_f32_16x16x32_bf16 v[72:75], v[230:233], v[198:201], v[72:75]
	v_mfma_f32_16x16x32_bf16 v[68:71], v[214:217], v[206:209], v[68:71]
	v_mfma_f32_16x16x32_bf16 v[64:67], v[230:233], v[206:209], v[64:67]
	v_mfma_f32_16x16x32_bf16 v[92:95], v[218:221], v[186:189], v[92:95]
	v_mfma_f32_16x16x32_bf16 v[88:91], v[238:241], v[186:189], v[88:91]
	v_mfma_f32_16x16x32_bf16 v[84:87], v[218:221], v[194:197], v[84:87]
	v_mfma_f32_16x16x32_bf16 v[80:83], v[238:241], v[194:197], v[80:83]
	s_setprio 2
	s_barrier
; #define STAGE_A(P, br, kt) do { const char* _base = (const char*)(((kt) < G.ksplit ? G.A1 : A2m) + (long)(br) * G.lda + (long)(kt) * BK); \
;     __builtin_amdgcn_global_load_lds((const unsigned*)(_base + aoff0), (unsigned*)((char*)(P) + sb0), 16, 0, 0); \
;     __builtin_amdgcn_global_load_lds((const unsigned*)(_base + aoff1), (unsigned*)((char*)(P) + sb1), 16, 0, 0); } while (0)
; #define STAGE_B(P, br, kt) do { const char* _base = (const char*)(G.Bt + (long)(br) * G.ldb + (long)(kt) * BK); \
;     __builtin_amdgcn_global_load_lds((const unsigned*)(_base + boff0), (unsigned*)((char*)(P) + sb0), 16, 0, 0); \
;     __builtin_amdgcn_global_load_lds((const unsigned*)(_base + boff1), (unsigned*)((char*)(P) + sb1), 16, 0, 0); } while (0)
; #define LDA(dst, b, h) for (int m = 0; m < 4; ++m) for (int k = 0; k < 2; ++k) \
;     dst[m][k] = *reinterpret_cast<const bf16x8*>(a_rd + ((b) * 2 + (h)) * (HT * 2) + m * 2048 + k * 1024)
; #define WAIT_V(n) asm volatile("s_waitcnt vmcnt(" #n ")" ::: "memory")
; #define WAIT_L(n) asm volatile("s_waitcnt lgkmcnt(" #n ")" ::: "memory")
;     ...
;   for (int t = 0; t < nt - 2; t += 2) {
;     LDB(B0, 0, 0); SCHED; LDA(At, 0, 0); STAGE_A(SA(1, 1), brow + HALF, t + 1);
;     WAIT_L(8); BAR; WAIT_L(0); MMA(0, 0, At, B0); BAR; SCHED;
;     LDB(B1, 0, 1); STAGE_B(SB(0, 0), bcol, t + 2);
;     BAR; WAIT_L(0); MMA(0, 1, At, B1); BAR;
;     LDA(At, 0, 1); STAGE_A(SA(0, 0), brow, t + 2);
;     BAR; WAIT_L(0); MMA(1, 0, At, B0); BAR; SCHED;
;     STAGE_B(SB(0, 1), bcol + HALF, t + 2);
;     WAIT_V(6); BAR; MMA(1, 1, At, B1); BAR;
;     LDB(B0, 1, 0); SCHED; LDA(At, 1, 0); STAGE_A(SA(0, 1), brow + HALF, t + 2);
;     WAIT_L(8); BAR; WAIT_L(0); MMA(0, 0, At, B0); BAR; SCHED;
;     LDB(B1, 1, 1); STAGE_B(SB(1, 0), bcol, t + 3);
;     BAR; WAIT_L(0); MMA(0, 1, At, B1); BAR;
;     LDA(At, 1, 1); STAGE_A(SA(1, 0), brow, t + 3);
;     BAR; WAIT_L(0); MMA(1, 0, At, B0); BAR; SCHED;
;     STAGE_B(SB(1, 1), bcol + HALF, t + 3);
;     WAIT_V(6); BAR; MMA(1, 1, At, B1); BAR;
;     ...
;   float ssv[2][4] = {};
;   if constexpr (EPI == EPI_GU || EPI == EPI_EVIN || EPI == EPI_ODIN) {
; #pragma unroll
;     for (int ai = 0; ai < 2; ++ai)
; #pragma unroll
;       for (int m = 0; m < 4; ++m) ssv[ai][m] = G.ssr[brow + ai * HALF + wr * 64 + m * 16 + fr];
;   }
;   { LDB(B0, 0, 0); LDA(At, 0, 0); STAGE_A(SA(1, 1), brow + HALF, nt - 1);
	v_mfma_f32_16x16x32_bf16 v[76:79], v[218:221], v[202:205], v[76:79]
	v_mfma_f32_16x16x32_bf16 v[72:75], v[238:241], v[202:205], v[72:75]
	v_mfma_f32_16x16x32_bf16 v[68:71], v[218:221], v[210:213], v[68:71]
	v_mfma_f32_16x16x32_bf16 v[64:67], v[238:241], v[210:213], v[64:67]
	s_setprio 0
	v_readfirstlane_b32 s42, v152
	v_lshl_add_u64 v[236:237], v[236:237], 0, s[22:23]
	s_mov_b32 m0, s42
	v_readfirstlane_b32 s42, v153
	global_load_lds_dwordx4 v[236:237], off
	v_lshl_add_u64 v[236:237], v[246:247], 0, s[22:23]
	s_mov_b32 m0, s42
	s_nop 0
	global_load_lds_dwordx4 v[236:237], off
	v_readfirstlane_b32 s42, v154
	v_lshl_add_u64 v[222:223], v[222:223], 0, s[88:89]
	s_mov_b32 m0, s42
	v_readfirstlane_b32 s42, v156
	ds_read_b128 v[182:185], v151 offset:49152
	ds_read_b128 v[186:189], v151 offset:50176
	ds_read_b128 v[190:193], v151 offset:51200
	ds_read_b128 v[194:197], v151 offset:52224
	ds_read_b128 v[198:201], v151 offset:53248
	ds_read_b128 v[202:205], v151 offset:54272
	ds_read_b128 v[206:209], v151 offset:55296
	ds_read_b128 v[210:213], v151 offset:56320
	global_load_lds_dwordx4 v[222:223], off
	v_lshl_add_u64 v[222:223], v[234:235], 0, s[88:89]
	s_mov_b32 m0, s42
	s_nop 0
	global_load_lds_dwordx4 v[222:223], off
	v_readfirstlane_b32 s42, v157
	v_lshl_add_u64 v[250:251], v[248:249], 0, s[24:25]
	s_mov_b32 m0, s42
	v_readfirstlane_b32 s42, v158
	global_load_lds_dwordx4 v[250:251], off
	v_lshl_add_u64 v[250:251], v[226:227], 0, s[24:25]
	s_mov_b32 m0, s42
	s_nop 0
	global_load_lds_dwordx4 v[250:251], off
	s_waitcnt lgkmcnt(0)
	s_waitcnt vmcnt(8)
	s_barrier
	s_setprio 1
	v_mfma_f32_16x16x32_bf16 v[60:63], v[164:167], v[182:185], v[60:63]
	v_mfma_f32_16x16x32_bf16 v[56:59], v[172:175], v[182:185], v[56:59]
	v_mfma_f32_16x16x32_bf16 v[52:55], v[164:167], v[190:193], v[52:55]
	v_mfma_f32_16x16x32_bf16 v[48:51], v[172:175], v[190:193], v[48:51]
	v_mfma_f32_16x16x32_bf16 v[44:47], v[164:167], v[198:201], v[44:47]
	v_mfma_f32_16x16x32_bf16 v[40:43], v[172:175], v[198:201], v[40:43]
	v_mfma_f32_16x16x32_bf16 v[36:39], v[164:167], v[206:209], v[36:39]
	v_mfma_f32_16x16x32_bf16 v[32:35], v[172:175], v[206:209], v[32:35]
	v_mfma_f32_16x16x32_bf16 v[60:63], v[168:171], v[186:189], v[60:63]
	v_mfma_f32_16x16x32_bf16 v[56:59], v[176:179], v[186:189], v[56:59]
	v_mfma_f32_16x16x32_bf16 v[52:55], v[168:171], v[194:197], v[52:55]
	v_mfma_f32_16x16x32_bf16 v[48:51], v[176:179], v[194:197], v[48:51]
	v_mfma_f32_16x16x32_bf16 v[44:47], v[168:171], v[202:205], v[44:47]
	v_mfma_f32_16x16x32_bf16 v[40:43], v[176:179], v[202:205], v[40:43]
	v_mfma_f32_16x16x32_bf16 v[36:39], v[168:171], v[210:213], v[36:39]
	v_mfma_f32_16x16x32_bf16 v[32:35], v[176:179], v[210:213], v[32:35]
	v_mfma_f32_16x16x32_bf16 v[28:31], v[214:217], v[182:185], v[28:31]
	v_mfma_f32_16x16x32_bf16 v[24:27], v[230:233], v[182:185], v[24:27]
	v_mfma_f32_16x16x32_bf16 v[20:23], v[214:217], v[190:193], v[20:23]
	v_mfma_f32_16x16x32_bf16 v[16:19], v[230:233], v[190:193], v[16:19]
	v_mfma_f32_16x16x32_bf16 v[12:15], v[214:217], v[198:201], v[12:15]
	v_mfma_f32_16x16x32_bf16 v[8:11], v[230:233], v[198:201], v[8:11]
	v_mfma_f32_16x16x32_bf16 v[4:7], v[214:217], v[206:209], v[4:7]
	v_mfma_f32_16x16x32_bf16 v[0:3], v[230:233], v[206:209], v[0:3]
	v_mfma_f32_16x16x32_bf16 v[28:31], v[218:221], v[186:189], v[28:31]
	v_mfma_f32_16x16x32_bf16 v[24:27], v[238:241], v[186:189], v[24:27]
	v_mfma_f32_16x16x32_bf16 v[20:23], v[218:221], v[194:197], v[20:23]
	v_mfma_f32_16x16x32_bf16 v[16:19], v[238:241], v[194:197], v[16:19]
	s_setprio 2
	s_barrier
	v_mfma_f32_16x16x32_bf16 v[12:15], v[218:221], v[202:205], v[12:15]
	v_mfma_f32_16x16x32_bf16 v[8:11], v[238:241], v[202:205], v[8:11]
	v_mfma_f32_16x16x32_bf16 v[4:7], v[218:221], v[210:213], v[4:7]
	v_mfma_f32_16x16x32_bf16 v[0:3], v[238:241], v[210:213], v[0:3]
	s_setprio 0
	s_add_i32 s11, s11, 2
	s_add_u32 s8, s8, 0x100
	s_addc_u32 s9, s9, 0
	s_cmp_lt_u32 s11, 28
	s_cbranch_scc1 .LBB0_746
.Lmy_kexit_0:
	s_waitcnt vmcnt(6)
	v_not_b32_e32 v250, 63
	v_mov_b32_e32 v251, 0x41b17218
	v_or_b32_e32 v130, s40, v150
	v_lshl_add_u32 v130, v148, 6, v130
	v_ashrrev_i32_e32 v131, 31, v130
	v_lshl_add_u64 v[132:133], v[130:131], 2, s[30:31]
	v_add_u32_e32 v134, 0x80, v130
	v_add_u32_e32 v136, 0x90, v130
	v_add_u32_e32 v138, 0xa0, v130
	v_add_u32_e32 v130, 0xb0, v130
	s_or_b32 s57, s40, 0x80
	v_ashrrev_i32_e32 v135, 31, v134
	v_ashrrev_i32_e32 v137, 31, v136
	v_ashrrev_i32_e32 v139, 31, v138
	v_ashrrev_i32_e32 v131, 31, v130
	s_mul_i32 s8, s57, 0x1080
	v_lshl_add_u64 v[134:135], v[134:135], 2, s[30:31]
	v_lshl_add_u64 v[136:137], v[136:137], 2, s[30:31]
	v_lshl_add_u64 v[138:139], v[138:139], 2, s[30:31]
	v_lshl_add_u64 v[140:141], v[130:131], 2, s[30:31]
	global_load_dword v130, v[132:133], off
	global_load_dword v146, v[132:133], off offset:64
	global_load_dword v148, v[132:133], off offset:128
	global_load_dword v156, v[132:133], off offset:192
	global_load_dword v154, v[134:135], off
	global_load_dword v153, v[136:137], off
	global_load_dword v152, v[138:139], off
	global_load_dword v150, v[140:141], off
	s_mul_hi_i32 s9, s57, 0x1080
	s_add_u32 s8, s12, s8
	s_addc_u32 s9, s13, s9
	v_lshl_add_u64 v[140:141], s[8:9], 0, v[180:181]
	s_mov_b64 s[22:23], 0xf80
	v_readfirstlane_b32 s10, v162
	v_lshl_add_u64 v[140:141], v[140:141], 0, s[22:23]
	s_mov_b32 m0, s10
	ds_read_b128 v[132:135], v155
	ds_read_b128 v[136:139], v155 offset:1024
	ds_read_b128 v[164:167], v155 offset:2048
	ds_read_b128 v[168:171], v155 offset:3072
	ds_read_b128 v[172:175], v151
	ds_read_b128 v[176:179], v151 offset:1024
	ds_read_b128 v[182:185], v151 offset:2048
	ds_read_b128 v[186:189], v151 offset:3072
	ds_read_b128 v[190:193], v151 offset:4096
	ds_read_b128 v[194:197], v151 offset:5120
	ds_read_b128 v[198:201], v151 offset:6144
	ds_read_b128 v[202:205], v151 offset:7168
	global_load_lds_dwordx4 v[140:141], off
	v_lshl_add_u64 v[140:141], s[8:9], 0, v[128:129]
	v_readfirstlane_b32 s8, v163
	v_lshl_add_u64 v[140:141], v[140:141], 0, s[22:23]
	s_mov_b32 m0, s8
	s_nop 0
	global_load_lds_dwordx4 v[140:141], off
	s_barrier
; #define STAGE_A(P, br, kt) do { const char* _base = (const char*)(((kt) < G.ksplit ? G.A1 : A2m) + (long)(br) * G.lda + (long)(kt) * BK); \
;     __builtin_amdgcn_global_load_lds((const unsigned*)(_base + aoff0), (unsigned*)((char*)(P) + sb0), 16, 0, 0); \
;     __builtin_amdgcn_global_load_lds((const unsigned*)(_base + aoff1), (unsigned*)((char*)(P) + sb1), 16, 0, 0); } while (0)
; #define LDA(dst, b, h) for (int m = 0; m < 4; ++m) for (int k = 0; k < 2; ++k) \
;     dst[m][k] = *reinterpret_cast<const bf16x8*>(a_rd + ((b) * 2 + (h)) * (HT * 2) + m * 2048 + k * 1024)
; #define LDB(dst, b, h) for (int n = 0; n < 2; ++n) for (int k = 0; k < 2; ++k) \
;     dst[n][k] = *reinterpret_cast<const bf16x8*>(b_rd + ((b) * 2 + (h)) * (HT * 2) + n * 2048 + k * 1024)
; #define MMA(ai, bj, At_, Bt_) do { __builtin_amdgcn_s_setprio(1); \
;     for (int m = 0; m < 4; ++m) for (int n = 0; n < 2; ++n) for (int k = 0; k < 2; ++k) \
;       acc[ai][bj][m][n] = __builtin_amdgcn_mfma_f32_16x16x32_bf16(Bt_[n][k], At_[m][k], acc[ai][bj][m][n], 0, 0, 0); \
;     __builtin_amdgcn_s_setprio(0); } while (0)
; #define WAIT_V(n) asm volatile("s_waitcnt vmcnt(" #n ")" ::: "memory")
; #define WAIT_L(n) asm volatile("s_waitcnt lgkmcnt(" #n ")" ::: "memory")
; #define BAR __builtin_amdgcn_s_barrier()
;     ...
;   { LDB(B0, 0, 0); LDA(At, 0, 0); STAGE_A(SA(1, 1), brow + HALF, nt - 1);
;     BAR; WAIT_L(0); MMA(0, 0, At, B0); BAR;
;     LDB(B1, 0, 1); BAR; WAIT_L(0); MMA(0, 1, At, B1); BAR;
;     LDA(At, 0, 1); WAIT_V(4); BAR; WAIT_L(0); MMA(1, 0, At, B0); MMA(1, 1, At, B1); BAR; }
;   { LDB(B0, 1, 0); LDA(At, 1, 0); WAIT_V(2); BAR; WAIT_L(0); MMA(0, 0, At, B0); BAR;
	s_waitcnt lgkmcnt(0)
	s_setprio 1
	s_waitcnt lgkmcnt(0)
	v_mfma_f32_16x16x32_bf16 v[124:127], v[132:135], v[172:175], v[124:127]
	v_mfma_f32_16x16x32_bf16 v[120:123], v[164:167], v[172:175], v[120:123]
	v_mfma_f32_16x16x32_bf16 v[116:119], v[132:135], v[182:185], v[116:119]
	v_mfma_f32_16x16x32_bf16 v[112:115], v[164:167], v[182:185], v[112:115]
	v_mfma_f32_16x16x32_bf16 v[108:111], v[132:135], v[190:193], v[108:111]
	v_mfma_f32_16x16x32_bf16 v[104:107], v[164:167], v[190:193], v[104:107]
	v_mfma_f32_16x16x32_bf16 v[100:103], v[132:135], v[198:201], v[100:103]
	v_mfma_f32_16x16x32_bf16 v[96:99], v[164:167], v[198:201], v[96:99]
	v_mfma_f32_16x16x32_bf16 v[124:127], v[136:139], v[176:179], v[124:127]
	v_mfma_f32_16x16x32_bf16 v[120:123], v[168:171], v[176:179], v[120:123]
	v_mfma_f32_16x16x32_bf16 v[116:119], v[136:139], v[186:189], v[116:119]
	v_mfma_f32_16x16x32_bf16 v[112:115], v[168:171], v[186:189], v[112:115]
	s_setprio 2
	s_barrier
	v_mfma_f32_16x16x32_bf16 v[108:111], v[136:139], v[194:197], v[108:111]
	v_mfma_f32_16x16x32_bf16 v[104:107], v[168:171], v[194:197], v[104:107]
	v_mfma_f32_16x16x32_bf16 v[100:103], v[136:139], v[202:205], v[100:103]
	v_mfma_f32_16x16x32_bf16 v[96:99], v[168:171], v[202:205], v[96:99]
	s_setprio 0
	ds_read_b128 v[206:209], v155 offset:16384
	ds_read_b128 v[210:213], v155 offset:17408
	ds_read_b128 v[214:217], v155 offset:18432
	ds_read_b128 v[218:221], v155 offset:19456
	s_barrier
	s_waitcnt lgkmcnt(0)
	s_setprio 1
	s_waitcnt lgkmcnt(0)
	v_mfma_f32_16x16x32_bf16 v[92:95], v[206:209], v[172:175], v[92:95]
	v_mfma_f32_16x16x32_bf16 v[88:91], v[214:217], v[172:175], v[88:91]
	v_mfma_f32_16x16x32_bf16 v[84:87], v[206:209], v[182:185], v[84:87]
	v_mfma_f32_16x16x32_bf16 v[80:83], v[214:217], v[182:185], v[80:83]
	v_mfma_f32_16x16x32_bf16 v[76:79], v[206:209], v[190:193], v[76:79]
	v_mfma_f32_16x16x32_bf16 v[72:75], v[214:217], v[190:193], v[72:75]
	v_mfma_f32_16x16x32_bf16 v[68:71], v[206:209], v[198:201], v[68:71]
	v_mfma_f32_16x16x32_bf16 v[64:67], v[214:217], v[198:201], v[64:67]
	v_mfma_f32_16x16x32_bf16 v[92:95], v[210:213], v[176:179], v[92:95]
	v_mfma_f32_16x16x32_bf16 v[88:91], v[218:221], v[176:179], v[88:91]
	v_mfma_f32_16x16x32_bf16 v[84:87], v[210:213], v[186:189], v[84:87]
	v_mfma_f32_16x16x32_bf16 v[80:83], v[218:221], v[186:189], v[80:83]
	s_setprio 2
	s_barrier
	v_mfma_f32_16x16x32_bf16 v[76:79], v[210:213], v[194:197], v[76:79]
	v_mfma_f32_16x16x32_bf16 v[72:75], v[218:221], v[194:197], v[72:75]
	v_mfma_f32_16x16x32_bf16 v[68:71], v[210:213], v[202:205], v[68:71]
	v_mfma_f32_16x16x32_bf16 v[64:67], v[218:221], v[202:205], v[64:67]
	s_setprio 0
	ds_read_b128 v[172:175], v151 offset:16384
	ds_read_b128 v[176:179], v151 offset:17408
	ds_read_b128 v[182:185], v151 offset:18432
	ds_read_b128 v[186:189], v151 offset:19456
	ds_read_b128 v[190:193], v151 offset:20480
	ds_read_b128 v[194:197], v151 offset:21504
	ds_read_b128 v[198:201], v151 offset:22528
	ds_read_b128 v[202:205], v151 offset:23552
	s_waitcnt vmcnt(4)
	s_barrier
	s_waitcnt lgkmcnt(0)
	s_setprio 1
	s_waitcnt lgkmcnt(0)
	v_mfma_f32_16x16x32_bf16 v[60:63], v[132:135], v[172:175], v[60:63]
	v_mfma_f32_16x16x32_bf16 v[56:59], v[164:167], v[172:175], v[56:59]
	v_mfma_f32_16x16x32_bf16 v[52:55], v[132:135], v[182:185], v[52:55]
	v_mfma_f32_16x16x32_bf16 v[48:51], v[164:167], v[182:185], v[48:51]
	v_mfma_f32_16x16x32_bf16 v[44:47], v[132:135], v[190:193], v[44:47]
	v_mfma_f32_16x16x32_bf16 v[40:43], v[164:167], v[190:193], v[40:43]
	v_mfma_f32_16x16x32_bf16 v[36:39], v[132:135], v[198:201], v[36:39]
	v_mfma_f32_16x16x32_bf16 v[32:35], v[164:167], v[198:201], v[32:35]
	v_mfma_f32_16x16x32_bf16 v[60:63], v[136:139], v[176:179], v[60:63]
	v_mfma_f32_16x16x32_bf16 v[56:59], v[168:171], v[176:179], v[56:59]
	v_mfma_f32_16x16x32_bf16 v[52:55], v[136:139], v[186:189], v[52:55]
	v_mfma_f32_16x16x32_bf16 v[48:51], v[168:171], v[186:189], v[48:51]
	v_mfma_f32_16x16x32_bf16 v[44:47], v[136:139], v[194:197], v[44:47]
	v_mfma_f32_16x16x32_bf16 v[40:43], v[168:171], v[194:197], v[40:43]
	v_mfma_f32_16x16x32_bf16 v[36:39], v[136:139], v[202:205], v[36:39]
	v_mfma_f32_16x16x32_bf16 v[32:35], v[168:171], v[202:205], v[32:35]
	s_setprio 0
	s_setprio 1
	v_mfma_f32_16x16x32_bf16 v[28:31], v[206:209], v[172:175], v[28:31]
	v_mfma_f32_16x16x32_bf16 v[24:27], v[214:217], v[172:175], v[24:27]
	v_mfma_f32_16x16x32_bf16 v[20:23], v[206:209], v[182:185], v[20:23]
	v_mfma_f32_16x16x32_bf16 v[16:19], v[214:217], v[182:185], v[16:19]
	v_mfma_f32_16x16x32_bf16 v[12:15], v[206:209], v[190:193], v[12:15]
	v_mfma_f32_16x16x32_bf16 v[8:11], v[214:217], v[190:193], v[8:11]
	v_mfma_f32_16x16x32_bf16 v[4:7], v[206:209], v[198:201], v[4:7]
	v_mfma_f32_16x16x32_bf16 v[0:3], v[214:217], v[198:201], v[0:3]
	v_mfma_f32_16x16x32_bf16 v[28:31], v[210:213], v[176:179], v[28:31]
	v_mfma_f32_16x16x32_bf16 v[24:27], v[218:221], v[176:179], v[24:27]
	v_mfma_f32_16x16x32_bf16 v[20:23], v[210:213], v[186:189], v[20:23]
	v_mfma_f32_16x16x32_bf16 v[16:19], v[218:221], v[186:189], v[16:19]
	s_setprio 2
	s_barrier
	v_mfma_f32_16x16x32_bf16 v[12:15], v[210:213], v[194:197], v[12:15]
	v_mfma_f32_16x16x32_bf16 v[8:11], v[218:221], v[194:197], v[8:11]
	v_mfma_f32_16x16x32_bf16 v[4:7], v[210:213], v[202:205], v[4:7]
	v_mfma_f32_16x16x32_bf16 v[0:3], v[218:221], v[202:205], v[0:3]
	s_setprio 0
	ds_read_b128 v[132:135], v155 offset:32768
	ds_read_b128 v[136:139], v155 offset:33792
	ds_read_b128 v[162:165], v155 offset:34816
	ds_read_b128 v[166:169], v155 offset:35840
	ds_read_b128 v[170:173], v151 offset:32768
	ds_read_b128 v[174:177], v151 offset:33792
	ds_read_b128 v[182:185], v151 offset:34816
	ds_read_b128 v[186:189], v151 offset:35840
	ds_read_b128 v[190:193], v151 offset:36864
	ds_read_b128 v[194:197], v151 offset:37888
	ds_read_b128 v[198:201], v151 offset:38912
	ds_read_b128 v[202:205], v151 offset:39936
	s_waitcnt vmcnt(2)
	s_barrier
; #define LDA(dst, b, h) for (int m = 0; m < 4; ++m) for (int k = 0; k < 2; ++k) \
;     dst[m][k] = *reinterpret_cast<const bf16x8*>(a_rd + ((b) * 2 + (h)) * (HT * 2) + m * 2048 + k * 1024)
; #define LDB(dst, b, h) for (int n = 0; n < 2; ++n) for (int k = 0; k < 2; ++k) \
;     dst[n][k] = *reinterpret_cast<const bf16x8*>(b_rd + ((b) * 2 + (h)) * (HT * 2) + n * 2048 + k * 1024)
; #define MMA(ai, bj, At_, Bt_) do { __builtin_amdgcn_s_setprio(1); \
;     for (int m = 0; m < 4; ++m) for (int n = 0; n < 2; ++n) for (int k = 0; k < 2; ++k) \
;       acc[ai][bj][m][n] = __builtin_amdgcn_mfma_f32_16x16x32_bf16(Bt_[n][k], At_[m][k], acc[ai][bj][m][n], 0, 0, 0); \
;     __builtin_amdgcn_s_setprio(0); } while (0)
; #define WAIT_V(n) asm volatile("s_waitcnt vmcnt(" #n ")" ::: "memory")
; #define WAIT_L(n) asm volatile("s_waitcnt lgkmcnt(" #n ")" ::: "memory")
; #define BAR __builtin_amdgcn_s_barrier()
;     ...
;   { LDB(B0, 1, 0); LDA(At, 1, 0); WAIT_V(2); BAR; WAIT_L(0); MMA(0, 0, At, B0); BAR;
;     LDB(B1, 1, 1); WAIT_V(0); BAR; WAIT_L(0); MMA(0, 1, At, B1); BAR;
;     LDA(At, 1, 1); BAR; WAIT_L(0); MMA(1, 0, At, B0); MMA(1, 1, At, B1); BAR; }
;   if (wr == 0) BAR;
	s_waitcnt lgkmcnt(0)
	s_setprio 1
	s_waitcnt lgkmcnt(0)
	v_mfma_f32_16x16x32_bf16 v[124:127], v[132:135], v[170:173], v[124:127]
	v_mfma_f32_16x16x32_bf16 v[120:123], v[162:165], v[170:173], v[120:123]
	v_mfma_f32_16x16x32_bf16 v[116:119], v[132:135], v[182:185], v[116:119]
	v_mfma_f32_16x16x32_bf16 v[112:115], v[162:165], v[182:185], v[112:115]
	v_mfma_f32_16x16x32_bf16 v[108:111], v[132:135], v[190:193], v[108:111]
	v_mfma_f32_16x16x32_bf16 v[104:107], v[162:165], v[190:193], v[104:107]
	v_mfma_f32_16x16x32_bf16 v[100:103], v[132:135], v[198:201], v[100:103]
	v_mfma_f32_16x16x32_bf16 v[96:99], v[162:165], v[198:201], v[96:99]
	v_mfma_f32_16x16x32_bf16 v[124:127], v[136:139], v[174:177], v[124:127]
	v_mfma_f32_16x16x32_bf16 v[120:123], v[166:169], v[174:177], v[120:123]
	v_mfma_f32_16x16x32_bf16 v[116:119], v[136:139], v[186:189], v[116:119]
	v_mfma_f32_16x16x32_bf16 v[112:115], v[166:169], v[186:189], v[112:115]
	s_setprio 2
	s_barrier
	v_mfma_f32_16x16x32_bf16 v[108:111], v[136:139], v[194:197], v[108:111]
	v_mfma_f32_16x16x32_bf16 v[104:107], v[166:169], v[194:197], v[104:107]
	v_mfma_f32_16x16x32_bf16 v[100:103], v[136:139], v[202:205], v[100:103]
	v_mfma_f32_16x16x32_bf16 v[96:99], v[166:169], v[202:205], v[96:99]
	s_setprio 0
	ds_read_b128 v[206:209], v155 offset:49152
	ds_read_b128 v[210:213], v155 offset:50176
	ds_read_b128 v[214:217], v155 offset:51200
	ds_read_b128 v[218:221], v155 offset:52224
	s_waitcnt vmcnt(0)
	s_barrier
	s_waitcnt lgkmcnt(0)
	s_setprio 1
	s_waitcnt lgkmcnt(0)
	v_mfma_f32_16x16x32_bf16 v[92:95], v[206:209], v[170:173], v[92:95]
	v_mfma_f32_16x16x32_bf16 v[88:91], v[214:217], v[170:173], v[88:91]
	v_mfma_f32_16x16x32_bf16 v[84:87], v[206:209], v[182:185], v[84:87]
	v_mfma_f32_16x16x32_bf16 v[80:83], v[214:217], v[182:185], v[80:83]
	v_mfma_f32_16x16x32_bf16 v[76:79], v[206:209], v[190:193], v[76:79]
	v_mfma_f32_16x16x32_bf16 v[72:75], v[214:217], v[190:193], v[72:75]
	v_mfma_f32_16x16x32_bf16 v[68:71], v[206:209], v[198:201], v[68:71]
	v_mfma_f32_16x16x32_bf16 v[64:67], v[214:217], v[198:201], v[64:67]
	v_mfma_f32_16x16x32_bf16 v[92:95], v[210:213], v[174:177], v[92:95]
	v_mfma_f32_16x16x32_bf16 v[88:91], v[218:221], v[174:177], v[88:91]
	v_mfma_f32_16x16x32_bf16 v[84:87], v[210:213], v[186:189], v[84:87]
	v_mfma_f32_16x16x32_bf16 v[80:83], v[218:221], v[186:189], v[80:83]
	s_setprio 2
	s_barrier
	v_mfma_f32_16x16x32_bf16 v[76:79], v[210:213], v[194:197], v[76:79]
	v_mfma_f32_16x16x32_bf16 v[72:75], v[218:221], v[194:197], v[72:75]
	v_mfma_f32_16x16x32_bf16 v[68:71], v[210:213], v[202:205], v[68:71]
	v_mfma_f32_16x16x32_bf16 v[64:67], v[218:221], v[202:205], v[64:67]
	s_setprio 0
	ds_read_b128 v[170:173], v151 offset:49152
	ds_read_b128 v[174:177], v151 offset:50176
	ds_read_b128 v[182:185], v151 offset:51200
	ds_read_b128 v[186:189], v151 offset:52224
	ds_read_b128 v[190:193], v151 offset:53248
	ds_read_b128 v[194:197], v151 offset:54272
	ds_read_b128 v[198:201], v151 offset:55296
	ds_read_b128 v[202:205], v151 offset:56320
	s_barrier
	s_waitcnt lgkmcnt(0)
	s_setprio 1
	s_waitcnt lgkmcnt(0)
	v_mfma_f32_16x16x32_bf16 v[60:63], v[132:135], v[170:173], v[60:63]
	v_mfma_f32_16x16x32_bf16 v[56:59], v[162:165], v[170:173], v[56:59]
	v_mfma_f32_16x16x32_bf16 v[52:55], v[132:135], v[182:185], v[52:55]
	v_mfma_f32_16x16x32_bf16 v[48:51], v[162:165], v[182:185], v[48:51]
	v_mfma_f32_16x16x32_bf16 v[44:47], v[132:135], v[190:193], v[44:47]
	v_mfma_f32_16x16x32_bf16 v[40:43], v[162:165], v[190:193], v[40:43]
	v_mfma_f32_16x16x32_bf16 v[36:39], v[132:135], v[198:201], v[36:39]
	v_mfma_f32_16x16x32_bf16 v[32:35], v[162:165], v[198:201], v[32:35]
	v_mfma_f32_16x16x32_bf16 v[60:63], v[136:139], v[174:177], v[60:63]
	v_mfma_f32_16x16x32_bf16 v[56:59], v[166:169], v[174:177], v[56:59]
	v_mfma_f32_16x16x32_bf16 v[52:55], v[136:139], v[186:189], v[52:55]
	v_mfma_f32_16x16x32_bf16 v[48:51], v[166:169], v[186:189], v[48:51]
	v_mfma_f32_16x16x32_bf16 v[44:47], v[136:139], v[194:197], v[44:47]
	v_mfma_f32_16x16x32_bf16 v[40:43], v[166:169], v[194:197], v[40:43]
	v_mfma_f32_16x16x32_bf16 v[36:39], v[136:139], v[202:205], v[36:39]
	v_mfma_f32_16x16x32_bf16 v[32:35], v[166:169], v[202:205], v[32:35]
	s_setprio 0
	s_setprio 1
	v_mfma_f32_16x16x32_bf16 v[28:31], v[206:209], v[170:173], v[28:31]
	v_mfma_f32_16x16x32_bf16 v[24:27], v[214:217], v[170:173], v[24:27]
	v_mfma_f32_16x16x32_bf16 v[20:23], v[206:209], v[182:185], v[20:23]
	v_mfma_f32_16x16x32_bf16 v[16:19], v[214:217], v[182:185], v[16:19]
	v_mfma_f32_16x16x32_bf16 v[12:15], v[206:209], v[190:193], v[12:15]
	v_mfma_f32_16x16x32_bf16 v[8:11], v[214:217], v[190:193], v[8:11]
	v_mfma_f32_16x16x32_bf16 v[4:7], v[206:209], v[198:201], v[4:7]
	v_mfma_f32_16x16x32_bf16 v[0:3], v[214:217], v[198:201], v[0:3]
	v_mfma_f32_16x16x32_bf16 v[28:31], v[210:213], v[174:177], v[28:31]
	v_mfma_f32_16x16x32_bf16 v[24:27], v[218:221], v[174:177], v[24:27]
	v_mfma_f32_16x16x32_bf16 v[20:23], v[210:213], v[186:189], v[20:23]
	v_mfma_f32_16x16x32_bf16 v[16:19], v[218:221], v[186:189], v[16:19]
	s_setprio 2
	s_barrier
	v_mfma_f32_16x16x32_bf16 v[12:15], v[210:213], v[194:197], v[12:15]
	v_mfma_f32_16x16x32_bf16 v[8:11], v[218:221], v[194:197], v[8:11]
	v_mfma_f32_16x16x32_bf16 v[4:7], v[210:213], v[202:205], v[4:7]
	v_mfma_f32_16x16x32_bf16 v[0:3], v[218:221], v[202:205], v[0:3]
	s_setprio 0
	v_cmp_gt_u32_e32 vcc, s60, v144
	s_and_saveexec_b64 s[8:9], vcc
	s_cbranch_execz .LBB0_749
	s_barrier

; #define STAGE_A(P, br, kt) do { const char* _base = (const char*)(((kt) < G.ksplit ? G.A1 : A2m) + (long)(br) * G.lda + (long)(kt) * BK); \
;     __builtin_amdgcn_global_load_lds((const unsigned*)(_base + aoff0), (unsigned*)((char*)(P) + sb0), 16, 0, 0); \
;     __builtin_amdgcn_global_load_lds((const unsigned*)(_base + aoff1), (unsigned*)((char*)(P) + sb1), 16, 0, 0); } while (0)
; #define STAGE_B(P, br, kt) do { const char* _base = (const char*)(G.Bt + (long)(br) * G.ldb + (long)(kt) * BK); \
;     __builtin_amdgcn_global_load_lds((const unsigned*)(_base + boff0), (unsigned*)((char*)(P) + sb0), 16, 0, 0); \
;     __builtin_amdgcn_global_load_lds((const unsigned*)(_base + boff1), (unsigned*)((char*)(P) + sb1), 16, 0, 0); } while (0)
; #define LDA(dst, b, h) for (int m = 0; m < 4; ++m) for (int k = 0; k < 2; ++k) \
;     dst[m][k] = *reinterpret_cast<const bf16x8*>(a_rd + ((b) * 2 + (h)) * (HT * 2) + m * 2048 + k * 1024)
; #define LDB(dst, b, h) for (int n = 0; n < 2; ++n) for (int k = 0; k < 2; ++k) \
;     dst[n][k] = *reinterpret_cast<const bf16x8*>(b_rd + ((b) * 2 + (h)) * (HT * 2) + n * 2048 + k * 1024)
; #define MMA(ai, bj, At_, Bt_) do { __builtin_amdgcn_s_setprio(1); \
;     for (int m = 0; m < 4; ++m) for (int n = 0; n < 2; ++n) for (int k = 0; k < 2; ++k) \
;       acc[ai][bj][m][n] = __builtin_amdgcn_mfma_f32_16x16x32_bf16(Bt_[n][k], At_[m][k], acc[ai][bj][m][n], 0, 0, 0); \
;     __builtin_amdgcn_s_setprio(0); } while (0)
; #define WAIT_V(n) asm volatile("s_waitcnt vmcnt(" #n ")" ::: "memory")
; #define WAIT_L(n) asm volatile("s_waitcnt lgkmcnt(" #n ")" ::: "memory")
;     ...
;   if (wr == 1) BAR;
;   WAIT_V(0); BAR;
;   STAGE_B(SB(1, 0), bcol, 1); STAGE_A(SA(1, 0), brow, 1); STAGE_B(SB(1, 1), bcol + HALF, 1);
;   WAIT_V(6); BAR;
;   for (int t = 0; t < nt - 2; t += 2) {
;     LDB(B0, 0, 0); SCHED; LDA(At, 0, 0); STAGE_A(SA(1, 1), brow + HALF, t + 1);
;     WAIT_L(8); BAR; WAIT_L(0); MMA(0, 0, At, B0); BAR; SCHED;
;     LDB(B1, 0, 1); STAGE_B(SB(0, 0), bcol, t + 2);
;     BAR; WAIT_L(0); MMA(0, 1, At, B1); BAR;
;     LDA(At, 0, 1); STAGE_A(SA(0, 0), brow, t + 2);
;     BAR; WAIT_L(0); MMA(1, 0, At, B0); BAR; SCHED;
;     STAGE_B(SB(0, 1), bcol + HALF, t + 2);
;     WAIT_V(6); BAR; MMA(1, 1, At, B1); BAR;
;     LDB(B0, 1, 0); SCHED; LDA(At, 1, 0); STAGE_A(SA(0, 1), brow + HALF, t + 2);
;     WAIT_L(8); BAR; WAIT_L(0); MMA(0, 0, At, B0); BAR; SCHED;
.LBB0_1800:
	s_or_b64 exec, exec, s[8:9]
	v_and_b32_e32 v20, 15, v144
	v_lshlrev_b32_e32 v22, 2, v144
	v_and_b32_e32 v21, 48, v144
	v_lshlrev_b32_e32 v20, 6, v20
	v_and_b32_e32 v22, 32, v22
	v_bitop3_b32 v20, v20, v22, v21 bitop3:0x36
	v_lshlrev_b32_e32 v21, 6, v144
	v_and_b32_e32 v21, 0x3000, v21
	v_add_u32_e32 v21, s37, v21
	v_readlane_b32 s37, v253, 46
	s_mov_b64 s[40:41], 0x80
	v_lshl_add_u64 v[2:3], v[2:3], 0, s[40:41]
	v_add_u32_e32 v153, s37, v12
	v_add_u32_e32 v154, 0x2000, v153
	v_readfirstlane_b32 s37, v153
	s_mov_b32 m0, s37
	v_readfirstlane_b32 s37, v154
	v_add_u32_e32 v155, 0x8000, v147
	s_waitcnt vmcnt(0)
	s_barrier
	global_load_lds_dwordx4 v[2:3], off
	v_lshl_add_u64 v[2:3], v[4:5], 0, s[40:41]
	s_mov_b32 m0, s37
	v_readfirstlane_b32 s37, v155
	v_add_u32_e32 v156, 0xa000, v147
	global_load_lds_dwordx4 v[2:3], off
	v_lshl_add_u64 v[2:3], v[6:7], 0, s[40:41]
	s_mov_b32 m0, s37
	v_readfirstlane_b32 s37, v156
	s_lshl_b64 s[8:9], s[20:21], 10
	global_load_lds_dwordx4 v[2:3], off
	s_mov_b32 m0, s37
	v_readlane_b32 s37, v253, 47
	s_add_u32 s38, s38, 0x84080
	v_lshl_add_u64 v[2:3], v[8:9], 0, s[40:41]
	v_add_u32_e32 v157, s37, v12
	s_addc_u32 s39, s39, 0
	v_readfirstlane_b32 s37, v157
	v_add_u32_e32 v158, 0x2000, v157
	global_load_lds_dwordx4 v[2:3], off
	v_lshl_add_u64 v[2:3], s[38:39], 0, v[180:181]
	s_mov_b32 m0, s37
	v_readfirstlane_b32 s37, v158
	global_load_lds_dwordx4 v[2:3], off
	v_lshl_add_u64 v[0:1], s[38:39], 0, v[0:1]
	s_mov_b32 m0, s37
	v_lshrrev_b32_e32 v2, 1, v11
	global_load_lds_dwordx4 v[0:1], off
	v_lshrrev_b32_e32 v1, 1, v10
	v_mul_lo_u32 v0, v13, s62
	v_mad_u64_u32 v[0:1], s[38:39], v1, s84, v[0:1]
	v_or_b32_e32 v0, v0, v14
	v_add_lshl_u32 v180, v0, v16, 1
	v_mul_lo_u32 v0, v15, s62
	v_lshlrev_b32_e32 v3, 11, v15
	v_mad_u64_u32 v[0:1], s[38:39], v2, s84, v[0:1]
	v_lshl_add_u32 v2, v2, 15, v3
	v_and_b32_e32 v3, 1, v11
	s_add_u32 s26, s14, s26
	v_lshl_or_b32 v2, v3, 6, v2
	s_addc_u32 s27, s15, s27
	v_lshl_add_u32 v2, v17, 1, v2
	v_mov_b32_e32 v3, v181
	v_or_b32_e32 v0, v0, v18
	v_lshl_add_u64 v[136:137], s[10:11], 0, v[130:131]
	v_lshl_add_u64 v[138:139], s[10:11], 0, v[2:3]
	s_add_u32 s10, s14, s24
	s_waitcnt vmcnt(6)
	v_add_lshl_u32 v0, v0, v17, 1
	v_mov_b32_e32 v1, v181
	s_addc_u32 s11, s15, s25
	v_lshl_add_u32 v19, v19, 13, 32
	v_lshl_add_u64 v[134:135], s[26:27], 0, v[0:1]
	v_lshl_add_u64 v[142:143], s[10:11], 0, v[0:1]
	v_mov_b32_e32 v245, 0x80003fff
	v_lshl_add_u64 v[132:133], s[26:27], 0, v[180:181]
	v_lshl_add_u64 v[140:141], s[10:11], 0, v[180:181]
	s_mov_b32 s24, -2
	s_mov_b64 s[10:11], 0
	v_add_u32_e32 v149, v21, v20
	v_add_u32_e32 v146, v19, v20
	s_waitcnt vmcnt(0)
	s_mov_b64 s[38:39], 0x40080
	s_mov_b64 s[40:41], 0x54e8100
	s_mov_b64 s[42:43], 0x556c100
	s_mov_b64 s[44:45], 0x40100
	s_mov_b64 s[46:47], 0x54e8180
	s_mov_b64 s[48:49], 0x556c180
	s_barrier
	ds_read_b128 v[162:165], v149
	ds_read_b128 v[166:169], v149 offset:1024
	ds_read_b128 v[170:173], v149 offset:2048
	ds_read_b128 v[174:177], v149 offset:3072
	s_add_i32 s24, s24, 2
	s_cmp_lt_u32 s24, 16
	s_cselect_b32 s27, s30, s36
	s_cselect_b32 s26, s29, s35
	v_lshl_add_u64 v[160:161], s[26:27], 0, v[136:137]
	v_add_u32_e32 v159, 0xc000, v147
	v_lshl_add_u64 v[160:161], v[160:161], 0, s[10:11]
	v_readfirstlane_b32 s25, v159
	v_lshl_add_u64 v[160:161], v[160:161], 0, s[38:39]
	s_mov_b32 m0, s25
	ds_read_b128 v[182:185], v146
	ds_read_b128 v[186:189], v146 offset:1024
	ds_read_b128 v[190:193], v146 offset:2048
	ds_read_b128 v[194:197], v146 offset:3072
	ds_read_b128 v[198:201], v146 offset:4096
	ds_read_b128 v[202:205], v146 offset:5120
	ds_read_b128 v[206:209], v146 offset:6144
	ds_read_b128 v[210:213], v146 offset:7168
	global_load_lds_dwordx4 v[160:161], off
	v_lshl_add_u64 v[160:161], s[26:27], 0, v[138:139]
	v_lshl_add_u64 v[160:161], v[160:161], 0, s[10:11]
	v_lshl_add_u64 v[178:179], v[160:161], 0, s[38:39]
	v_add_u32_e32 v160, 0xe000, v147
	s_nop 0
	v_readfirstlane_b32 s25, v160
	s_mov_b32 m0, s25
	s_nop 0
	global_load_lds_dwordx4 v[178:179], off
	ds_read_b128 v[214:217], v149 offset:16384
	ds_read_b128 v[218:221], v149 offset:17408
	ds_read_b128 v[230:233], v149 offset:18432
	ds_read_b128 v[238:241], v149 offset:19456
	s_waitcnt lgkmcnt(0)
	s_waitcnt vmcnt(8)
	s_barrier
	s_setprio 1
	v_mfma_f32_16x16x32_bf16 v[124:127], v[162:165], v[182:185], 0
	v_mfma_f32_16x16x32_bf16 v[120:123], v[170:173], v[182:185], 0
	v_mfma_f32_16x16x32_bf16 v[116:119], v[162:165], v[190:193], 0
	v_mfma_f32_16x16x32_bf16 v[112:115], v[170:173], v[190:193], 0
	v_mfma_f32_16x16x32_bf16 v[108:111], v[162:165], v[198:201], 0
	v_mfma_f32_16x16x32_bf16 v[104:107], v[170:173], v[198:201], 0
	v_mfma_f32_16x16x32_bf16 v[100:103], v[162:165], v[206:209], 0
	v_mfma_f32_16x16x32_bf16 v[96:99], v[170:173], v[206:209], 0
	v_mfma_f32_16x16x32_bf16 v[124:127], v[166:169], v[186:189], v[124:127]
	v_mfma_f32_16x16x32_bf16 v[120:123], v[174:177], v[186:189], v[120:123]
	v_mfma_f32_16x16x32_bf16 v[116:119], v[166:169], v[194:197], v[116:119]
	v_mfma_f32_16x16x32_bf16 v[112:115], v[174:177], v[194:197], v[112:115]
	v_mfma_f32_16x16x32_bf16 v[108:111], v[166:169], v[202:205], v[108:111]
	v_mfma_f32_16x16x32_bf16 v[104:107], v[174:177], v[202:205], v[104:107]
	v_mfma_f32_16x16x32_bf16 v[100:103], v[166:169], v[210:213], v[100:103]
	v_mfma_f32_16x16x32_bf16 v[96:99], v[174:177], v[210:213], v[96:99]
	v_mfma_f32_16x16x32_bf16 v[92:95], v[214:217], v[182:185], 0
	v_mfma_f32_16x16x32_bf16 v[88:91], v[230:233], v[182:185], 0
	v_mfma_f32_16x16x32_bf16 v[84:87], v[214:217], v[190:193], 0
	v_mfma_f32_16x16x32_bf16 v[80:83], v[230:233], v[190:193], 0
	v_mfma_f32_16x16x32_bf16 v[76:79], v[214:217], v[198:201], 0
	v_mfma_f32_16x16x32_bf16 v[72:75], v[230:233], v[198:201], 0
	v_mfma_f32_16x16x32_bf16 v[68:71], v[214:217], v[206:209], 0
	v_mfma_f32_16x16x32_bf16 v[64:67], v[230:233], v[206:209], 0
	v_mfma_f32_16x16x32_bf16 v[92:95], v[218:221], v[186:189], v[92:95]
	v_mfma_f32_16x16x32_bf16 v[88:91], v[238:241], v[186:189], v[88:91]
	v_mfma_f32_16x16x32_bf16 v[84:87], v[218:221], v[194:197], v[84:87]
	v_mfma_f32_16x16x32_bf16 v[80:83], v[238:241], v[194:197], v[80:83]
	s_setprio 2
	s_barrier
; #define STAGE_A(P, br, kt) do { const char* _base = (const char*)(((kt) < G.ksplit ? G.A1 : A2m) + (long)(br) * G.lda + (long)(kt) * BK); \
;     __builtin_amdgcn_global_load_lds((const unsigned*)(_base + aoff0), (unsigned*)((char*)(P) + sb0), 16, 0, 0); \
;     __builtin_amdgcn_global_load_lds((const unsigned*)(_base + aoff1), (unsigned*)((char*)(P) + sb1), 16, 0, 0); } while (0)
; #define STAGE_B(P, br, kt) do { const char* _base = (const char*)(G.Bt + (long)(br) * G.ldb + (long)(kt) * BK); \
;     __builtin_amdgcn_global_load_lds((const unsigned*)(_base + boff0), (unsigned*)((char*)(P) + sb0), 16, 0, 0); \
;     __builtin_amdgcn_global_load_lds((const unsigned*)(_base + boff1), (unsigned*)((char*)(P) + sb1), 16, 0, 0); } while (0)
; #define LDA(dst, b, h) for (int m = 0; m < 4; ++m) for (int k = 0; k < 2; ++k) \
;     dst[m][k] = *reinterpret_cast<const bf16x8*>(a_rd + ((b) * 2 + (h)) * (HT * 2) + m * 2048 + k * 1024)
; #define LDB(dst, b, h) for (int n = 0; n < 2; ++n) for (int k = 0; k < 2; ++k) \
;     dst[n][k] = *reinterpret_cast<const bf16x8*>(b_rd + ((b) * 2 + (h)) * (HT * 2) + n * 2048 + k * 1024)
; #define MMA(ai, bj, At_, Bt_) do { __builtin_amdgcn_s_setprio(1); \
;     for (int m = 0; m < 4; ++m) for (int n = 0; n < 2; ++n) for (int k = 0; k < 2; ++k) \
;       acc[ai][bj][m][n] = __builtin_amdgcn_mfma_f32_16x16x32_bf16(Bt_[n][k], At_[m][k], acc[ai][bj][m][n], 0, 0, 0); \
;     __builtin_amdgcn_s_setprio(0); } while (0)
;     ...
;   for (int t = 0; t < nt - 2; t += 2) {
;     LDB(B0, 0, 0); SCHED; LDA(At, 0, 0); STAGE_A(SA(1, 1), brow + HALF, t + 1);
;     WAIT_L(8); BAR; WAIT_L(0); MMA(0, 0, At, B0); BAR; SCHED;
;     LDB(B1, 0, 1); STAGE_B(SB(0, 0), bcol, t + 2);
;     BAR; WAIT_L(0); MMA(0, 1, At, B1); BAR;
;     LDA(At, 0, 1); STAGE_A(SA(0, 0), brow, t + 2);
;     BAR; WAIT_L(0); MMA(1, 0, At, B0); BAR; SCHED;
;     STAGE_B(SB(0, 1), bcol + HALF, t + 2);
;     WAIT_V(6); BAR; MMA(1, 1, At, B1); BAR;
;     LDB(B0, 1, 0); SCHED; LDA(At, 1, 0); STAGE_A(SA(0, 1), brow + HALF, t + 2);
;     WAIT_L(8); BAR; WAIT_L(0); MMA(0, 0, At, B0); BAR; SCHED;
;     LDB(B1, 1, 1); STAGE_B(SB(1, 0), bcol, t + 3);
;     BAR; WAIT_L(0); MMA(0, 1, At, B1); BAR;
;     LDA(At, 1, 1); STAGE_A(SA(1, 0), brow, t + 3);
;     BAR; WAIT_L(0); MMA(1, 0, At, B0); BAR; SCHED;
;     STAGE_B(SB(1, 1), bcol + HALF, t + 3);
;     WAIT_V(6); BAR; MMA(1, 1, At, B1); BAR;
	v_mfma_f32_16x16x32_bf16 v[76:79], v[218:221], v[202:205], v[76:79]
	v_mfma_f32_16x16x32_bf16 v[72:75], v[238:241], v[202:205], v[72:75]
	v_mfma_f32_16x16x32_bf16 v[68:71], v[218:221], v[210:213], v[68:71]
	v_mfma_f32_16x16x32_bf16 v[64:67], v[238:241], v[210:213], v[64:67]
	s_setprio 0
	v_lshl_add_u64 v[178:179], v[132:133], 0, s[10:11]
	v_readfirstlane_b32 s25, v145
	v_lshl_add_u64 v[222:223], v[178:179], 0, s[40:41]
	s_mov_b32 m0, s25
	v_add_u32_e32 v161, 0x2000, v145
	global_load_lds_dwordx4 v[222:223], off
	v_lshl_add_u64 v[222:223], v[134:135], 0, s[10:11]
	v_readfirstlane_b32 s25, v161
	v_lshl_add_u64 v[226:227], v[222:223], 0, s[40:41]
	s_mov_b32 m0, s25
	s_nop 0
	global_load_lds_dwordx4 v[226:227], off
	s_cmp_lt_u32 s24, 14
	s_cselect_b32 s27, s30, s36
	s_cselect_b32 s26, s29, s35
	v_lshl_add_u64 v[226:227], s[26:27], 0, v[136:137]
	v_lshl_add_u64 v[226:227], v[226:227], 0, s[10:11]
	v_readfirstlane_b32 s25, v147
	v_lshl_add_u64 v[234:235], v[226:227], 0, s[90:91]
	s_mov_b32 m0, s25
	ds_read_b128 v[182:185], v146 offset:16384
	ds_read_b128 v[186:189], v146 offset:17408
	ds_read_b128 v[190:193], v146 offset:18432
	ds_read_b128 v[194:197], v146 offset:19456
	ds_read_b128 v[198:201], v146 offset:20480
	ds_read_b128 v[202:205], v146 offset:21504
	ds_read_b128 v[206:209], v146 offset:22528
	ds_read_b128 v[210:213], v146 offset:23552
	global_load_lds_dwordx4 v[234:235], off
	v_lshl_add_u64 v[234:235], s[26:27], 0, v[138:139]
	v_lshl_add_u64 v[234:235], v[234:235], 0, s[10:11]
	v_readfirstlane_b32 s25, v148
	v_lshl_add_u64 v[236:237], v[234:235], 0, s[90:91]
	s_mov_b32 m0, s25
	s_nop 0
	global_load_lds_dwordx4 v[236:237], off
	v_lshl_add_u64 v[236:237], v[140:141], 0, s[10:11]
	v_readfirstlane_b32 s25, v150
	v_add_u32_e32 v161, 0x2000, v150
	v_lshl_add_u64 v[250:251], v[236:237], 0, s[42:43]
	s_mov_b32 m0, s25
	v_lshl_add_u64 v[246:247], v[142:143], 0, s[10:11]
	v_readfirstlane_b32 s25, v161
	global_load_lds_dwordx4 v[250:251], off
	v_lshl_add_u64 v[250:251], v[246:247], 0, s[42:43]
	s_mov_b32 m0, s25
	s_nop 0
	global_load_lds_dwordx4 v[250:251], off
	s_waitcnt lgkmcnt(0)
	s_waitcnt vmcnt(8)
	s_barrier
	s_setprio 1
	v_mfma_f32_16x16x32_bf16 v[60:63], v[162:165], v[182:185], 0
	v_mfma_f32_16x16x32_bf16 v[56:59], v[170:173], v[182:185], 0
	v_mfma_f32_16x16x32_bf16 v[52:55], v[162:165], v[190:193], 0
	v_mfma_f32_16x16x32_bf16 v[48:51], v[170:173], v[190:193], 0
	v_mfma_f32_16x16x32_bf16 v[44:47], v[162:165], v[198:201], 0
	v_mfma_f32_16x16x32_bf16 v[40:43], v[170:173], v[198:201], 0
	v_mfma_f32_16x16x32_bf16 v[36:39], v[162:165], v[206:209], 0
	v_mfma_f32_16x16x32_bf16 v[32:35], v[170:173], v[206:209], 0
	v_mfma_f32_16x16x32_bf16 v[60:63], v[166:169], v[186:189], v[60:63]
	v_mfma_f32_16x16x32_bf16 v[56:59], v[174:177], v[186:189], v[56:59]
	v_mfma_f32_16x16x32_bf16 v[52:55], v[166:169], v[194:197], v[52:55]
	v_mfma_f32_16x16x32_bf16 v[48:51], v[174:177], v[194:197], v[48:51]
	v_mfma_f32_16x16x32_bf16 v[44:47], v[166:169], v[202:205], v[44:47]
	v_mfma_f32_16x16x32_bf16 v[40:43], v[174:177], v[202:205], v[40:43]
	v_mfma_f32_16x16x32_bf16 v[36:39], v[166:169], v[210:213], v[36:39]
	v_mfma_f32_16x16x32_bf16 v[32:35], v[174:177], v[210:213], v[32:35]
	v_mfma_f32_16x16x32_bf16 v[28:31], v[214:217], v[182:185], 0
	v_mfma_f32_16x16x32_bf16 v[24:27], v[230:233], v[182:185], 0
	v_mfma_f32_16x16x32_bf16 v[20:23], v[214:217], v[190:193], 0
	v_mfma_f32_16x16x32_bf16 v[16:19], v[230:233], v[190:193], 0
	v_mfma_f32_16x16x32_bf16 v[12:15], v[214:217], v[198:201], 0
	v_mfma_f32_16x16x32_bf16 v[8:11], v[230:233], v[198:201], 0
	v_mfma_f32_16x16x32_bf16 v[4:7], v[214:217], v[206:209], 0
	v_mfma_f32_16x16x32_bf16 v[0:3], v[230:233], v[206:209], 0
	v_mfma_f32_16x16x32_bf16 v[28:31], v[218:221], v[186:189], v[28:31]
	v_mfma_f32_16x16x32_bf16 v[24:27], v[238:241], v[186:189], v[24:27]
	v_mfma_f32_16x16x32_bf16 v[20:23], v[218:221], v[194:197], v[20:23]
	v_mfma_f32_16x16x32_bf16 v[16:19], v[238:241], v[194:197], v[16:19]
	s_setprio 2
	s_barrier
	v_mfma_f32_16x16x32_bf16 v[12:15], v[218:221], v[202:205], v[12:15]
	v_mfma_f32_16x16x32_bf16 v[8:11], v[238:241], v[202:205], v[8:11]
	v_mfma_f32_16x16x32_bf16 v[4:7], v[218:221], v[210:213], v[4:7]
	v_mfma_f32_16x16x32_bf16 v[0:3], v[238:241], v[210:213], v[0:3]
	s_setprio 0
	ds_read_b128 v[162:165], v149 offset:32768
	ds_read_b128 v[166:169], v149 offset:33792
	ds_read_b128 v[170:173], v149 offset:34816
	ds_read_b128 v[174:177], v149 offset:35840
	v_readfirstlane_b32 s25, v151
	v_lshl_add_u64 v[214:215], v[226:227], 0, s[44:45]
	s_mov_b32 m0, s25
	v_readfirstlane_b32 s25, v152
	ds_read_b128 v[182:185], v146 offset:32768
	ds_read_b128 v[186:189], v146 offset:33792
	ds_read_b128 v[190:193], v146 offset:34816
	ds_read_b128 v[194:197], v146 offset:35840
	ds_read_b128 v[198:201], v146 offset:36864
	ds_read_b128 v[202:205], v146 offset:37888
	ds_read_b128 v[206:209], v146 offset:38912
	ds_read_b128 v[210:213], v146 offset:39936
	global_load_lds_dwordx4 v[214:215], off
	v_lshl_add_u64 v[214:215], v[234:235], 0, s[44:45]
	s_mov_b32 m0, s25
	s_nop 0
	global_load_lds_dwordx4 v[214:215], off
	ds_read_b128 v[214:217], v149 offset:49152
	ds_read_b128 v[218:221], v149 offset:50176
	ds_read_b128 v[230:233], v149 offset:51200
	ds_read_b128 v[238:241], v149 offset:52224
	s_waitcnt lgkmcnt(0)
	s_waitcnt vmcnt(8)
	s_barrier
; #define STAGE_A(P, br, kt) do { const char* _base = (const char*)(((kt) < G.ksplit ? G.A1 : A2m) + (long)(br) * G.lda + (long)(kt) * BK); \
;     __builtin_amdgcn_global_load_lds((const unsigned*)(_base + aoff0), (unsigned*)((char*)(P) + sb0), 16, 0, 0); \
;     __builtin_amdgcn_global_load_lds((const unsigned*)(_base + aoff1), (unsigned*)((char*)(P) + sb1), 16, 0, 0); } while (0)
; #define STAGE_B(P, br, kt) do { const char* _base = (const char*)(G.Bt + (long)(br) * G.ldb + (long)(kt) * BK); \
;     __builtin_amdgcn_global_load_lds((const unsigned*)(_base + boff0), (unsigned*)((char*)(P) + sb0), 16, 0, 0); \
;     __builtin_amdgcn_global_load_lds((const unsigned*)(_base + boff1), (unsigned*)((char*)(P) + sb1), 16, 0, 0); } while (0)
; #define LDA(dst, b, h) for (int m = 0; m < 4; ++m) for (int k = 0; k < 2; ++k) \
;     dst[m][k] = *reinterpret_cast<const bf16x8*>(a_rd + ((b) * 2 + (h)) * (HT * 2) + m * 2048 + k * 1024)
; #define LDB(dst, b, h) for (int n = 0; n < 2; ++n) for (int k = 0; k < 2; ++k) \
;     dst[n][k] = *reinterpret_cast<const bf16x8*>(b_rd + ((b) * 2 + (h)) * (HT * 2) + n * 2048 + k * 1024)
; #define MMA(ai, bj, At_, Bt_) do { __builtin_amdgcn_s_setprio(1); \
;     for (int m = 0; m < 4; ++m) for (int n = 0; n < 2; ++n) for (int k = 0; k < 2; ++k) \
;       acc[ai][bj][m][n] = __builtin_amdgcn_mfma_f32_16x16x32_bf16(Bt_[n][k], At_[m][k], acc[ai][bj][m][n], 0, 0, 0); \
;     __builtin_amdgcn_s_setprio(0); } while (0)
;     ...
;   for (int t = 0; t < nt - 2; t += 2) {
;     LDB(B0, 0, 0); SCHED; LDA(At, 0, 0); STAGE_A(SA(1, 1), brow + HALF, t + 1);
;     WAIT_L(8); BAR; WAIT_L(0); MMA(0, 0, At, B0); BAR; SCHED;
;     LDB(B1, 0, 1); STAGE_B(SB(0, 0), bcol, t + 2);
;     BAR; WAIT_L(0); MMA(0, 1, At, B1); BAR;
;     LDA(At, 0, 1); STAGE_A(SA(0, 0), brow, t + 2);
;     BAR; WAIT_L(0); MMA(1, 0, At, B0); BAR; SCHED;
;     STAGE_B(SB(0, 1), bcol + HALF, t + 2);
;     WAIT_V(6); BAR; MMA(1, 1, At, B1); BAR;
;     LDB(B0, 1, 0); SCHED; LDA(At, 1, 0); STAGE_A(SA(0, 1), brow + HALF, t + 2);
;     WAIT_L(8); BAR; WAIT_L(0); MMA(0, 0, At, B0); BAR; SCHED;
;     LDB(B1, 1, 1); STAGE_B(SB(1, 0), bcol, t + 3);
;     BAR; WAIT_L(0); MMA(0, 1, At, B1); BAR;
;     LDA(At, 1, 1); STAGE_A(SA(1, 0), brow, t + 3);
;     BAR; WAIT_L(0); MMA(1, 0, At, B0); BAR; SCHED;
;     STAGE_B(SB(1, 1), bcol + HALF, t + 3);
;     WAIT_V(6); BAR; MMA(1, 1, At, B1); BAR;
	s_setprio 1
	v_mfma_f32_16x16x32_bf16 v[124:127], v[162:165], v[182:185], v[124:127]
	v_mfma_f32_16x16x32_bf16 v[120:123], v[170:173], v[182:185], v[120:123]
	v_mfma_f32_16x16x32_bf16 v[116:119], v[162:165], v[190:193], v[116:119]
	v_mfma_f32_16x16x32_bf16 v[112:115], v[170:173], v[190:193], v[112:115]
	v_mfma_f32_16x16x32_bf16 v[108:111], v[162:165], v[198:201], v[108:111]
	v_mfma_f32_16x16x32_bf16 v[104:107], v[170:173], v[198:201], v[104:107]
	v_mfma_f32_16x16x32_bf16 v[100:103], v[162:165], v[206:209], v[100:103]
	v_mfma_f32_16x16x32_bf16 v[96:99], v[170:173], v[206:209], v[96:99]
	v_mfma_f32_16x16x32_bf16 v[124:127], v[166:169], v[186:189], v[124:127]
	v_mfma_f32_16x16x32_bf16 v[120:123], v[174:177], v[186:189], v[120:123]
	v_mfma_f32_16x16x32_bf16 v[116:119], v[166:169], v[194:197], v[116:119]
	v_mfma_f32_16x16x32_bf16 v[112:115], v[174:177], v[194:197], v[112:115]
	v_mfma_f32_16x16x32_bf16 v[108:111], v[166:169], v[202:205], v[108:111]
	v_mfma_f32_16x16x32_bf16 v[104:107], v[174:177], v[202:205], v[104:107]
	v_mfma_f32_16x16x32_bf16 v[100:103], v[166:169], v[210:213], v[100:103]
	v_mfma_f32_16x16x32_bf16 v[96:99], v[174:177], v[210:213], v[96:99]
	v_mfma_f32_16x16x32_bf16 v[92:95], v[214:217], v[182:185], v[92:95]
	v_mfma_f32_16x16x32_bf16 v[88:91], v[230:233], v[182:185], v[88:91]
	v_mfma_f32_16x16x32_bf16 v[84:87], v[214:217], v[190:193], v[84:87]
	v_mfma_f32_16x16x32_bf16 v[80:83], v[230:233], v[190:193], v[80:83]
	v_mfma_f32_16x16x32_bf16 v[76:79], v[214:217], v[198:201], v[76:79]
	v_mfma_f32_16x16x32_bf16 v[72:75], v[230:233], v[198:201], v[72:75]
	v_mfma_f32_16x16x32_bf16 v[68:71], v[214:217], v[206:209], v[68:71]
	v_mfma_f32_16x16x32_bf16 v[64:67], v[230:233], v[206:209], v[64:67]
	v_mfma_f32_16x16x32_bf16 v[92:95], v[218:221], v[186:189], v[92:95]
	v_mfma_f32_16x16x32_bf16 v[88:91], v[238:241], v[186:189], v[88:91]
	v_mfma_f32_16x16x32_bf16 v[84:87], v[218:221], v[194:197], v[84:87]
	v_mfma_f32_16x16x32_bf16 v[80:83], v[238:241], v[194:197], v[80:83]
	s_setprio 2
	s_barrier
	v_mfma_f32_16x16x32_bf16 v[76:79], v[218:221], v[202:205], v[76:79]
	v_mfma_f32_16x16x32_bf16 v[72:75], v[238:241], v[202:205], v[72:75]
	v_mfma_f32_16x16x32_bf16 v[68:71], v[218:221], v[210:213], v[68:71]
	v_mfma_f32_16x16x32_bf16 v[64:67], v[238:241], v[210:213], v[64:67]
	s_setprio 0
	v_readfirstlane_b32 s25, v153
	v_lshl_add_u64 v[178:179], v[178:179], 0, s[46:47]
	s_mov_b32 m0, s25
	v_readfirstlane_b32 s25, v154
	global_load_lds_dwordx4 v[178:179], off
	v_lshl_add_u64 v[178:179], v[222:223], 0, s[46:47]
	s_mov_b32 m0, s25
	s_nop 0
	global_load_lds_dwordx4 v[178:179], off
	s_cmp_lt_u32 s24, 13
	s_cselect_b32 s27, s30, s36
	s_cselect_b32 s26, s29, s35
	v_lshl_add_u64 v[178:179], s[26:27], 0, v[136:137]
	v_lshl_add_u64 v[178:179], v[178:179], 0, s[10:11]
	v_readfirstlane_b32 s25, v155
	v_lshl_add_u64 v[178:179], v[178:179], 0, s[88:89]
	s_mov_b32 m0, s25
	ds_read_b128 v[182:185], v146 offset:49152
	ds_read_b128 v[186:189], v146 offset:50176
	ds_read_b128 v[190:193], v146 offset:51200
	ds_read_b128 v[194:197], v146 offset:52224
	ds_read_b128 v[198:201], v146 offset:53248
	ds_read_b128 v[202:205], v146 offset:54272
	ds_read_b128 v[206:209], v146 offset:55296
	ds_read_b128 v[210:213], v146 offset:56320
	global_load_lds_dwordx4 v[178:179], off
	v_lshl_add_u64 v[178:179], s[26:27], 0, v[138:139]
	v_lshl_add_u64 v[178:179], v[178:179], 0, s[10:11]
	v_readfirstlane_b32 s25, v156
	v_lshl_add_u64 v[178:179], v[178:179], 0, s[88:89]
	s_mov_b32 m0, s25
	s_nop 0
	global_load_lds_dwordx4 v[178:179], off
	v_readfirstlane_b32 s25, v157
	v_lshl_add_u64 v[250:251], v[236:237], 0, s[48:49]
	s_mov_b32 m0, s25
	v_readfirstlane_b32 s25, v158
	global_load_lds_dwordx4 v[250:251], off
	v_lshl_add_u64 v[250:251], v[246:247], 0, s[48:49]
	s_mov_b32 m0, s25
	s_nop 0
	global_load_lds_dwordx4 v[250:251], off
	s_waitcnt lgkmcnt(0)
	s_waitcnt vmcnt(8)
	s_barrier
	s_setprio 1
	v_mfma_f32_16x16x32_bf16 v[60:63], v[162:165], v[182:185], v[60:63]
	v_mfma_f32_16x16x32_bf16 v[56:59], v[170:173], v[182:185], v[56:59]
	v_mfma_f32_16x16x32_bf16 v[52:55], v[162:165], v[190:193], v[52:55]
	v_mfma_f32_16x16x32_bf16 v[48:51], v[170:173], v[190:193], v[48:51]
	v_mfma_f32_16x16x32_bf16 v[44:47], v[162:165], v[198:201], v[44:47]
	v_mfma_f32_16x16x32_bf16 v[40:43], v[170:173], v[198:201], v[40:43]
	v_mfma_f32_16x16x32_bf16 v[36:39], v[162:165], v[206:209], v[36:39]
	v_mfma_f32_16x16x32_bf16 v[32:35], v[170:173], v[206:209], v[32:35]
	v_mfma_f32_16x16x32_bf16 v[60:63], v[166:169], v[186:189], v[60:63]
	v_mfma_f32_16x16x32_bf16 v[56:59], v[174:177], v[186:189], v[56:59]
	v_mfma_f32_16x16x32_bf16 v[52:55], v[166:169], v[194:197], v[52:55]
	v_mfma_f32_16x16x32_bf16 v[48:51], v[174:177], v[194:197], v[48:51]
	v_mfma_f32_16x16x32_bf16 v[44:47], v[166:169], v[202:205], v[44:47]
	v_mfma_f32_16x16x32_bf16 v[40:43], v[174:177], v[202:205], v[40:43]
	v_mfma_f32_16x16x32_bf16 v[36:39], v[166:169], v[210:213], v[36:39]
	v_mfma_f32_16x16x32_bf16 v[32:35], v[174:177], v[210:213], v[32:35]
	v_mfma_f32_16x16x32_bf16 v[28:31], v[214:217], v[182:185], v[28:31]
	v_mfma_f32_16x16x32_bf16 v[24:27], v[230:233], v[182:185], v[24:27]
	v_mfma_f32_16x16x32_bf16 v[20:23], v[214:217], v[190:193], v[20:23]
	v_mfma_f32_16x16x32_bf16 v[16:19], v[230:233], v[190:193], v[16:19]
	v_mfma_f32_16x16x32_bf16 v[12:15], v[214:217], v[198:201], v[12:15]
	v_mfma_f32_16x16x32_bf16 v[8:11], v[230:233], v[198:201], v[8:11]
	v_mfma_f32_16x16x32_bf16 v[4:7], v[214:217], v[206:209], v[4:7]
	v_mfma_f32_16x16x32_bf16 v[0:3], v[230:233], v[206:209], v[0:3]
	v_mfma_f32_16x16x32_bf16 v[28:31], v[218:221], v[186:189], v[28:31]
	v_mfma_f32_16x16x32_bf16 v[24:27], v[238:241], v[186:189], v[24:27]
	v_mfma_f32_16x16x32_bf16 v[20:23], v[218:221], v[194:197], v[20:23]
	v_mfma_f32_16x16x32_bf16 v[16:19], v[238:241], v[194:197], v[16:19]
	s_setprio 2
	s_barrier
	v_mfma_f32_16x16x32_bf16 v[12:15], v[218:221], v[202:205], v[12:15]
	v_mfma_f32_16x16x32_bf16 v[8:11], v[238:241], v[202:205], v[8:11]
	v_mfma_f32_16x16x32_bf16 v[4:7], v[218:221], v[210:213], v[4:7]
	v_mfma_f32_16x16x32_bf16 v[0:3], v[238:241], v[210:213], v[0:3]
	s_setprio 0
	s_add_u32 s10, s10, 0x100
	s_addc_u32 s11, s11, 0
	s_cmp_lt_u32 s24, 28
	s_cbranch_scc0 .Lmy_kexit_1
; #define STAGE_A(P, br, kt) do { const char* _base = (const char*)(((kt) < G.ksplit ? G.A1 : A2m) + (long)(br) * G.lda + (long)(kt) * BK); \
;     __builtin_amdgcn_global_load_lds((const unsigned*)(_base + aoff0), (unsigned*)((char*)(P) + sb0), 16, 0, 0); \
;     __builtin_amdgcn_global_load_lds((const unsigned*)(_base + aoff1), (unsigned*)((char*)(P) + sb1), 16, 0, 0); } while (0)
; #define STAGE_B(P, br, kt) do { const char* _base = (const char*)(G.Bt + (long)(br) * G.ldb + (long)(kt) * BK); \
;     __builtin_amdgcn_global_load_lds((const unsigned*)(_base + boff0), (unsigned*)((char*)(P) + sb0), 16, 0, 0); \
;     __builtin_amdgcn_global_load_lds((const unsigned*)(_base + boff1), (unsigned*)((char*)(P) + sb1), 16, 0, 0); } while (0)
; #define LDA(dst, b, h) for (int m = 0; m < 4; ++m) for (int k = 0; k < 2; ++k) \
;     dst[m][k] = *reinterpret_cast<const bf16x8*>(a_rd + ((b) * 2 + (h)) * (HT * 2) + m * 2048 + k * 1024)
; #define LDB(dst, b, h) for (int n = 0; n < 2; ++n) for (int k = 0; k < 2; ++k) \
;     dst[n][k] = *reinterpret_cast<const bf16x8*>(b_rd + ((b) * 2 + (h)) * (HT * 2) + n * 2048 + k * 1024)
; #define MMA(ai, bj, At_, Bt_) do { __builtin_amdgcn_s_setprio(1); \
;     for (int m = 0; m < 4; ++m) for (int n = 0; n < 2; ++n) for (int k = 0; k < 2; ++k) \
;       acc[ai][bj][m][n] = __builtin_amdgcn_mfma_f32_16x16x32_bf16(Bt_[n][k], At_[m][k], acc[ai][bj][m][n], 0, 0, 0); \
;     __builtin_amdgcn_s_setprio(0); } while (0)
;     ...
;   for (int t = 0; t < nt - 2; t += 2) {
;     LDB(B0, 0, 0); SCHED; LDA(At, 0, 0); STAGE_A(SA(1, 1), brow + HALF, t + 1);
;     WAIT_L(8); BAR; WAIT_L(0); MMA(0, 0, At, B0); BAR; SCHED;
;     LDB(B1, 0, 1); STAGE_B(SB(0, 0), bcol, t + 2);
;     BAR; WAIT_L(0); MMA(0, 1, At, B1); BAR;
;     LDA(At, 0, 1); STAGE_A(SA(0, 0), brow, t + 2);
;     BAR; WAIT_L(0); MMA(1, 0, At, B0); BAR; SCHED;
;     STAGE_B(SB(0, 1), bcol + HALF, t + 2);
;     WAIT_V(6); BAR; MMA(1, 1, At, B1); BAR;
;     LDB(B0, 1, 0); SCHED; LDA(At, 1, 0); STAGE_A(SA(0, 1), brow + HALF, t + 2);
;     WAIT_L(8); BAR; WAIT_L(0); MMA(0, 0, At, B0); BAR; SCHED;
;     LDB(B1, 1, 1); STAGE_B(SB(1, 0), bcol, t + 3);
;     BAR; WAIT_L(0); MMA(0, 1, At, B1); BAR;
;     LDA(At, 1, 1); STAGE_A(SA(1, 0), brow, t + 3);
;     BAR; WAIT_L(0); MMA(1, 0, At, B0); BAR; SCHED;
;     STAGE_B(SB(1, 1), bcol + HALF, t + 3);
;     WAIT_V(6); BAR; MMA(1, 1, At, B1); BAR;
.LBB0_1801:
	ds_read_b128 v[162:165], v149
	ds_read_b128 v[166:169], v149 offset:1024
	ds_read_b128 v[170:173], v149 offset:2048
	ds_read_b128 v[174:177], v149 offset:3072
	s_add_i32 s24, s24, 2
	s_cmp_lt_u32 s24, 16
	s_cselect_b32 s27, s30, s36
	s_cselect_b32 s26, s29, s35
	v_lshl_add_u64 v[160:161], s[26:27], 0, v[136:137]
	v_add_u32_e32 v159, 0xc000, v147
	v_lshl_add_u64 v[160:161], v[160:161], 0, s[10:11]
	v_readfirstlane_b32 s25, v159
	v_lshl_add_u64 v[160:161], v[160:161], 0, s[38:39]
	s_mov_b32 m0, s25
	ds_read_b128 v[182:185], v146
	ds_read_b128 v[186:189], v146 offset:1024
	ds_read_b128 v[190:193], v146 offset:2048
	ds_read_b128 v[194:197], v146 offset:3072
	ds_read_b128 v[198:201], v146 offset:4096
	ds_read_b128 v[202:205], v146 offset:5120
	ds_read_b128 v[206:209], v146 offset:6144
	ds_read_b128 v[210:213], v146 offset:7168
	global_load_lds_dwordx4 v[160:161], off
	v_lshl_add_u64 v[160:161], s[26:27], 0, v[138:139]
	v_lshl_add_u64 v[160:161], v[160:161], 0, s[10:11]
	v_lshl_add_u64 v[178:179], v[160:161], 0, s[38:39]
	v_add_u32_e32 v160, 0xe000, v147
	s_nop 0
	v_readfirstlane_b32 s25, v160
	s_mov_b32 m0, s25
	s_nop 0
	global_load_lds_dwordx4 v[178:179], off
	ds_read_b128 v[214:217], v149 offset:16384
	ds_read_b128 v[218:221], v149 offset:17408
	ds_read_b128 v[230:233], v149 offset:18432
	ds_read_b128 v[238:241], v149 offset:19456
	s_waitcnt lgkmcnt(0)
	s_waitcnt vmcnt(8)
	s_barrier
	s_setprio 1
	v_mfma_f32_16x16x32_bf16 v[124:127], v[162:165], v[182:185], v[124:127]
	v_mfma_f32_16x16x32_bf16 v[120:123], v[170:173], v[182:185], v[120:123]
	v_mfma_f32_16x16x32_bf16 v[116:119], v[162:165], v[190:193], v[116:119]
	v_mfma_f32_16x16x32_bf16 v[112:115], v[170:173], v[190:193], v[112:115]
	v_mfma_f32_16x16x32_bf16 v[108:111], v[162:165], v[198:201], v[108:111]
	v_mfma_f32_16x16x32_bf16 v[104:107], v[170:173], v[198:201], v[104:107]
	v_mfma_f32_16x16x32_bf16 v[100:103], v[162:165], v[206:209], v[100:103]
	v_mfma_f32_16x16x32_bf16 v[96:99], v[170:173], v[206:209], v[96:99]
	v_mfma_f32_16x16x32_bf16 v[124:127], v[166:169], v[186:189], v[124:127]
	v_mfma_f32_16x16x32_bf16 v[120:123], v[174:177], v[186:189], v[120:123]
	v_mfma_f32_16x16x32_bf16 v[116:119], v[166:169], v[194:197], v[116:119]
	v_mfma_f32_16x16x32_bf16 v[112:115], v[174:177], v[194:197], v[112:115]
	v_mfma_f32_16x16x32_bf16 v[108:111], v[166:169], v[202:205], v[108:111]
	v_mfma_f32_16x16x32_bf16 v[104:107], v[174:177], v[202:205], v[104:107]
	v_mfma_f32_16x16x32_bf16 v[100:103], v[166:169], v[210:213], v[100:103]
	v_mfma_f32_16x16x32_bf16 v[96:99], v[174:177], v[210:213], v[96:99]
	v_mfma_f32_16x16x32_bf16 v[92:95], v[214:217], v[182:185], v[92:95]
	v_mfma_f32_16x16x32_bf16 v[88:91], v[230:233], v[182:185], v[88:91]
	v_mfma_f32_16x16x32_bf16 v[84:87], v[214:217], v[190:193], v[84:87]
	v_mfma_f32_16x16x32_bf16 v[80:83], v[230:233], v[190:193], v[80:83]
	v_mfma_f32_16x16x32_bf16 v[76:79], v[214:217], v[198:201], v[76:79]
	v_mfma_f32_16x16x32_bf16 v[72:75], v[230:233], v[198:201], v[72:75]
	v_mfma_f32_16x16x32_bf16 v[68:71], v[214:217], v[206:209], v[68:71]
	v_mfma_f32_16x16x32_bf16 v[64:67], v[230:233], v[206:209], v[64:67]
	v_mfma_f32_16x16x32_bf16 v[92:95], v[218:221], v[186:189], v[92:95]
	v_mfma_f32_16x16x32_bf16 v[88:91], v[238:241], v[186:189], v[88:91]
	v_mfma_f32_16x16x32_bf16 v[84:87], v[218:221], v[194:197], v[84:87]
	v_mfma_f32_16x16x32_bf16 v[80:83], v[238:241], v[194:197], v[80:83]
	s_setprio 2
	s_barrier
	v_mfma_f32_16x16x32_bf16 v[76:79], v[218:221], v[202:205], v[76:79]
	v_mfma_f32_16x16x32_bf16 v[72:75], v[238:241], v[202:205], v[72:75]
	v_mfma_f32_16x16x32_bf16 v[68:71], v[218:221], v[210:213], v[68:71]
	v_mfma_f32_16x16x32_bf16 v[64:67], v[238:241], v[210:213], v[64:67]
	s_setprio 0
	v_lshl_add_u64 v[178:179], v[132:133], 0, s[10:11]
	v_readfirstlane_b32 s25, v145
	v_lshl_add_u64 v[222:223], v[178:179], 0, s[40:41]
	s_mov_b32 m0, s25
	v_add_u32_e32 v161, 0x2000, v145
	global_load_lds_dwordx4 v[222:223], off
	v_lshl_add_u64 v[222:223], v[134:135], 0, s[10:11]
	v_readfirstlane_b32 s25, v161
	v_lshl_add_u64 v[226:227], v[222:223], 0, s[40:41]
	s_mov_b32 m0, s25
	s_nop 0
	global_load_lds_dwordx4 v[226:227], off
	s_cmp_lt_u32 s24, 14
	s_cselect_b32 s27, s30, s36
	s_cselect_b32 s26, s29, s35
	v_lshl_add_u64 v[226:227], s[26:27], 0, v[136:137]
	v_lshl_add_u64 v[226:227], v[226:227], 0, s[10:11]
	v_readfirstlane_b32 s25, v147
	v_lshl_add_u64 v[234:235], v[226:227], 0, s[90:91]
	s_mov_b32 m0, s25
	ds_read_b128 v[182:185], v146 offset:16384
	ds_read_b128 v[186:189], v146 offset:17408
	ds_read_b128 v[190:193], v146 offset:18432
	ds_read_b128 v[194:197], v146 offset:19456
	ds_read_b128 v[198:201], v146 offset:20480
	ds_read_b128 v[202:205], v146 offset:21504
	ds_read_b128 v[206:209], v146 offset:22528
	ds_read_b128 v[210:213], v146 offset:23552
	global_load_lds_dwordx4 v[234:235], off
	v_lshl_add_u64 v[234:235], s[26:27], 0, v[138:139]
	v_lshl_add_u64 v[234:235], v[234:235], 0, s[10:11]
	v_readfirstlane_b32 s25, v148
	v_lshl_add_u64 v[236:237], v[234:235], 0, s[90:91]
	s_mov_b32 m0, s25
	s_nop 0
	global_load_lds_dwordx4 v[236:237], off
	v_lshl_add_u64 v[236:237], v[140:141], 0, s[10:11]
	v_readfirstlane_b32 s25, v150
	v_add_u32_e32 v161, 0x2000, v150
	v_lshl_add_u64 v[250:251], v[236:237], 0, s[42:43]
	s_mov_b32 m0, s25
	v_lshl_add_u64 v[246:247], v[142:143], 0, s[10:11]
	v_readfirstlane_b32 s25, v161
	global_load_lds_dwordx4 v[250:251], off
	v_lshl_add_u64 v[250:251], v[246:247], 0, s[42:43]
	s_mov_b32 m0, s25
	s_nop 0
	global_load_lds_dwordx4 v[250:251], off
	s_waitcnt lgkmcnt(0)
	s_waitcnt vmcnt(8)
	s_barrier
; #define STAGE_A(P, br, kt) do { const char* _base = (const char*)(((kt) < G.ksplit ? G.A1 : A2m) + (long)(br) * G.lda + (long)(kt) * BK); \
;     __builtin_amdgcn_global_load_lds((const unsigned*)(_base + aoff0), (unsigned*)((char*)(P) + sb0), 16, 0, 0); \
;     __builtin_amdgcn_global_load_lds((const unsigned*)(_base + aoff1), (unsigned*)((char*)(P) + sb1), 16, 0, 0); } while (0)
; #define STAGE_B(P, br, kt) do { const char* _base = (const char*)(G.Bt + (long)(br) * G.ldb + (long)(kt) * BK); \
;     __builtin_amdgcn_global_load_lds((const unsigned*)(_base + boff0), (unsigned*)((char*)(P) + sb0), 16, 0, 0); \
;     __builtin_amdgcn_global_load_lds((const unsigned*)(_base + boff1), (unsigned*)((char*)(P) + sb1), 16, 0, 0); } while (0)
; #define LDA(dst, b, h) for (int m = 0; m < 4; ++m) for (int k = 0; k < 2; ++k) \
;     dst[m][k] = *reinterpret_cast<const bf16x8*>(a_rd + ((b) * 2 + (h)) * (HT * 2) + m * 2048 + k * 1024)
; #define LDB(dst, b, h) for (int n = 0; n < 2; ++n) for (int k = 0; k < 2; ++k) \
;     dst[n][k] = *reinterpret_cast<const bf16x8*>(b_rd + ((b) * 2 + (h)) * (HT * 2) + n * 2048 + k * 1024)
; #define MMA(ai, bj, At_, Bt_) do { __builtin_amdgcn_s_setprio(1); \
;     for (int m = 0; m < 4; ++m) for (int n = 0; n < 2; ++n) for (int k = 0; k < 2; ++k) \
;       acc[ai][bj][m][n] = __builtin_amdgcn_mfma_f32_16x16x32_bf16(Bt_[n][k], At_[m][k], acc[ai][bj][m][n], 0, 0, 0); \
;     __builtin_amdgcn_s_setprio(0); } while (0)
;     ...
;   for (int t = 0; t < nt - 2; t += 2) {
;     LDB(B0, 0, 0); SCHED; LDA(At, 0, 0); STAGE_A(SA(1, 1), brow + HALF, t + 1);
;     WAIT_L(8); BAR; WAIT_L(0); MMA(0, 0, At, B0); BAR; SCHED;
;     LDB(B1, 0, 1); STAGE_B(SB(0, 0), bcol, t + 2);
;     BAR; WAIT_L(0); MMA(0, 1, At, B1); BAR;
;     LDA(At, 0, 1); STAGE_A(SA(0, 0), brow, t + 2);
;     BAR; WAIT_L(0); MMA(1, 0, At, B0); BAR; SCHED;
;     STAGE_B(SB(0, 1), bcol + HALF, t + 2);
;     WAIT_V(6); BAR; MMA(1, 1, At, B1); BAR;
;     LDB(B0, 1, 0); SCHED; LDA(At, 1, 0); STAGE_A(SA(0, 1), brow + HALF, t + 2);
;     WAIT_L(8); BAR; WAIT_L(0); MMA(0, 0, At, B0); BAR; SCHED;
;     LDB(B1, 1, 1); STAGE_B(SB(1, 0), bcol, t + 3);
;     BAR; WAIT_L(0); MMA(0, 1, At, B1); BAR;
;     LDA(At, 1, 1); STAGE_A(SA(1, 0), brow, t + 3);
;     BAR; WAIT_L(0); MMA(1, 0, At, B0); BAR; SCHED;
;     STAGE_B(SB(1, 1), bcol + HALF, t + 3);
;     WAIT_V(6); BAR; MMA(1, 1, At, B1); BAR;
	s_setprio 1
	v_mfma_f32_16x16x32_bf16 v[60:63], v[162:165], v[182:185], v[60:63]
	v_mfma_f32_16x16x32_bf16 v[56:59], v[170:173], v[182:185], v[56:59]
	v_mfma_f32_16x16x32_bf16 v[52:55], v[162:165], v[190:193], v[52:55]
	v_mfma_f32_16x16x32_bf16 v[48:51], v[170:173], v[190:193], v[48:51]
	v_mfma_f32_16x16x32_bf16 v[44:47], v[162:165], v[198:201], v[44:47]
	v_mfma_f32_16x16x32_bf16 v[40:43], v[170:173], v[198:201], v[40:43]
	v_mfma_f32_16x16x32_bf16 v[36:39], v[162:165], v[206:209], v[36:39]
	v_mfma_f32_16x16x32_bf16 v[32:35], v[170:173], v[206:209], v[32:35]
	v_mfma_f32_16x16x32_bf16 v[60:63], v[166:169], v[186:189], v[60:63]
	v_mfma_f32_16x16x32_bf16 v[56:59], v[174:177], v[186:189], v[56:59]
	v_mfma_f32_16x16x32_bf16 v[52:55], v[166:169], v[194:197], v[52:55]
	v_mfma_f32_16x16x32_bf16 v[48:51], v[174:177], v[194:197], v[48:51]
	v_mfma_f32_16x16x32_bf16 v[44:47], v[166:169], v[202:205], v[44:47]
	v_mfma_f32_16x16x32_bf16 v[40:43], v[174:177], v[202:205], v[40:43]
	v_mfma_f32_16x16x32_bf16 v[36:39], v[166:169], v[210:213], v[36:39]
	v_mfma_f32_16x16x32_bf16 v[32:35], v[174:177], v[210:213], v[32:35]
	v_mfma_f32_16x16x32_bf16 v[28:31], v[214:217], v[182:185], v[28:31]
	v_mfma_f32_16x16x32_bf16 v[24:27], v[230:233], v[182:185], v[24:27]
	v_mfma_f32_16x16x32_bf16 v[20:23], v[214:217], v[190:193], v[20:23]
	v_mfma_f32_16x16x32_bf16 v[16:19], v[230:233], v[190:193], v[16:19]
	v_mfma_f32_16x16x32_bf16 v[12:15], v[214:217], v[198:201], v[12:15]
	v_mfma_f32_16x16x32_bf16 v[8:11], v[230:233], v[198:201], v[8:11]
	v_mfma_f32_16x16x32_bf16 v[4:7], v[214:217], v[206:209], v[4:7]
	v_mfma_f32_16x16x32_bf16 v[0:3], v[230:233], v[206:209], v[0:3]
	v_mfma_f32_16x16x32_bf16 v[28:31], v[218:221], v[186:189], v[28:31]
	v_mfma_f32_16x16x32_bf16 v[24:27], v[238:241], v[186:189], v[24:27]
	v_mfma_f32_16x16x32_bf16 v[20:23], v[218:221], v[194:197], v[20:23]
	v_mfma_f32_16x16x32_bf16 v[16:19], v[238:241], v[194:197], v[16:19]
	s_setprio 2
	s_barrier
	v_mfma_f32_16x16x32_bf16 v[12:15], v[218:221], v[202:205], v[12:15]
	v_mfma_f32_16x16x32_bf16 v[8:11], v[238:241], v[202:205], v[8:11]
	v_mfma_f32_16x16x32_bf16 v[4:7], v[218:221], v[210:213], v[4:7]
	v_mfma_f32_16x16x32_bf16 v[0:3], v[238:241], v[210:213], v[0:3]
	s_setprio 0
	ds_read_b128 v[162:165], v149 offset:32768
	ds_read_b128 v[166:169], v149 offset:33792
	ds_read_b128 v[170:173], v149 offset:34816
	ds_read_b128 v[174:177], v149 offset:35840
	v_readfirstlane_b32 s25, v151
	v_lshl_add_u64 v[214:215], v[226:227], 0, s[44:45]
	s_mov_b32 m0, s25
	v_readfirstlane_b32 s25, v152
	ds_read_b128 v[182:185], v146 offset:32768
	ds_read_b128 v[186:189], v146 offset:33792
	ds_read_b128 v[190:193], v146 offset:34816
	ds_read_b128 v[194:197], v146 offset:35840
	ds_read_b128 v[198:201], v146 offset:36864
	ds_read_b128 v[202:205], v146 offset:37888
	ds_read_b128 v[206:209], v146 offset:38912
	ds_read_b128 v[210:213], v146 offset:39936
	global_load_lds_dwordx4 v[214:215], off
	v_lshl_add_u64 v[214:215], v[234:235], 0, s[44:45]
	s_mov_b32 m0, s25
	s_nop 0
	global_load_lds_dwordx4 v[214:215], off
	ds_read_b128 v[214:217], v149 offset:49152
	ds_read_b128 v[218:221], v149 offset:50176
	ds_read_b128 v[230:233], v149 offset:51200
	ds_read_b128 v[238:241], v149 offset:52224
	s_waitcnt lgkmcnt(0)
	s_waitcnt vmcnt(8)
	s_barrier
	s_setprio 1
	v_mfma_f32_16x16x32_bf16 v[124:127], v[162:165], v[182:185], v[124:127]
	v_mfma_f32_16x16x32_bf16 v[120:123], v[170:173], v[182:185], v[120:123]
	v_mfma_f32_16x16x32_bf16 v[116:119], v[162:165], v[190:193], v[116:119]
	v_mfma_f32_16x16x32_bf16 v[112:115], v[170:173], v[190:193], v[112:115]
	v_mfma_f32_16x16x32_bf16 v[108:111], v[162:165], v[198:201], v[108:111]
	v_mfma_f32_16x16x32_bf16 v[104:107], v[170:173], v[198:201], v[104:107]
	v_mfma_f32_16x16x32_bf16 v[100:103], v[162:165], v[206:209], v[100:103]
	v_mfma_f32_16x16x32_bf16 v[96:99], v[170:173], v[206:209], v[96:99]
	v_mfma_f32_16x16x32_bf16 v[124:127], v[166:169], v[186:189], v[124:127]
	v_mfma_f32_16x16x32_bf16 v[120:123], v[174:177], v[186:189], v[120:123]
	v_mfma_f32_16x16x32_bf16 v[116:119], v[166:169], v[194:197], v[116:119]
	v_mfma_f32_16x16x32_bf16 v[112:115], v[174:177], v[194:197], v[112:115]
	v_mfma_f32_16x16x32_bf16 v[108:111], v[166:169], v[202:205], v[108:111]
	v_mfma_f32_16x16x32_bf16 v[104:107], v[174:177], v[202:205], v[104:107]
	v_mfma_f32_16x16x32_bf16 v[100:103], v[166:169], v[210:213], v[100:103]
	v_mfma_f32_16x16x32_bf16 v[96:99], v[174:177], v[210:213], v[96:99]
	v_mfma_f32_16x16x32_bf16 v[92:95], v[214:217], v[182:185], v[92:95]
	v_mfma_f32_16x16x32_bf16 v[88:91], v[230:233], v[182:185], v[88:91]
	v_mfma_f32_16x16x32_bf16 v[84:87], v[214:217], v[190:193], v[84:87]
	v_mfma_f32_16x16x32_bf16 v[80:83], v[230:233], v[190:193], v[80:83]
	v_mfma_f32_16x16x32_bf16 v[76:79], v[214:217], v[198:201], v[76:79]
	v_mfma_f32_16x16x32_bf16 v[72:75], v[230:233], v[198:201], v[72:75]
	v_mfma_f32_16x16x32_bf16 v[68:71], v[214:217], v[206:209], v[68:71]
	v_mfma_f32_16x16x32_bf16 v[64:67], v[230:233], v[206:209], v[64:67]
	v_mfma_f32_16x16x32_bf16 v[92:95], v[218:221], v[186:189], v[92:95]
	v_mfma_f32_16x16x32_bf16 v[88:91], v[238:241], v[186:189], v[88:91]
	v_mfma_f32_16x16x32_bf16 v[84:87], v[218:221], v[194:197], v[84:87]
	v_mfma_f32_16x16x32_bf16 v[80:83], v[238:241], v[194:197], v[80:83]
	s_setprio 2
	s_barrier
; #define STAGE_A(P, br, kt) do { const char* _base = (const char*)(((kt) < G.ksplit ? G.A1 : A2m) + (long)(br) * G.lda + (long)(kt) * BK); \
;     __builtin_amdgcn_global_load_lds((const unsigned*)(_base + aoff0), (unsigned*)((char*)(P) + sb0), 16, 0, 0); \
;     __builtin_amdgcn_global_load_lds((const unsigned*)(_base + aoff1), (unsigned*)((char*)(P) + sb1), 16, 0, 0); } while (0)
; #define STAGE_B(P, br, kt) do { const char* _base = (const char*)(G.Bt + (long)(br) * G.ldb + (long)(kt) * BK); \
;     __builtin_amdgcn_global_load_lds((const unsigned*)(_base + boff0), (unsigned*)((char*)(P) + sb0), 16, 0, 0); \
;     __builtin_amdgcn_global_load_lds((const unsigned*)(_base + boff1), (unsigned*)((char*)(P) + sb1), 16, 0, 0); } while (0)
; #define LDA(dst, b, h) for (int m = 0; m < 4; ++m) for (int k = 0; k < 2; ++k) \
;     dst[m][k] = *reinterpret_cast<const bf16x8*>(a_rd + ((b) * 2 + (h)) * (HT * 2) + m * 2048 + k * 1024)
; #define LDB(dst, b, h) for (int n = 0; n < 2; ++n) for (int k = 0; k < 2; ++k) \
;     dst[n][k] = *reinterpret_cast<const bf16x8*>(b_rd + ((b) * 2 + (h)) * (HT * 2) + n * 2048 + k * 1024)
; #define WAIT_V(n) asm volatile("s_waitcnt vmcnt(" #n ")" ::: "memory")
; #define WAIT_L(n) asm volatile("s_waitcnt lgkmcnt(" #n ")" ::: "memory")
; #define BAR __builtin_amdgcn_s_barrier()
; #define SCHED __builtin_amdgcn_sched_barrier(0)
;     ...
;   for (int t = 0; t < nt - 2; t += 2) {
;     LDB(B0, 0, 0); SCHED; LDA(At, 0, 0); STAGE_A(SA(1, 1), brow + HALF, t + 1);
;     WAIT_L(8); BAR; WAIT_L(0); MMA(0, 0, At, B0); BAR; SCHED;
;     LDB(B1, 0, 1); STAGE_B(SB(0, 0), bcol, t + 2);
;     BAR; WAIT_L(0); MMA(0, 1, At, B1); BAR;
;     LDA(At, 0, 1); STAGE_A(SA(0, 0), brow, t + 2);
;     BAR; WAIT_L(0); MMA(1, 0, At, B0); BAR; SCHED;
;     STAGE_B(SB(0, 1), bcol + HALF, t + 2);
;     WAIT_V(6); BAR; MMA(1, 1, At, B1); BAR;
;     LDB(B0, 1, 0); SCHED; LDA(At, 1, 0); STAGE_A(SA(0, 1), brow + HALF, t + 2);
;     WAIT_L(8); BAR; WAIT_L(0); MMA(0, 0, At, B0); BAR; SCHED;
;     LDB(B1, 1, 1); STAGE_B(SB(1, 0), bcol, t + 3);
;     BAR; WAIT_L(0); MMA(0, 1, At, B1); BAR;
;     LDA(At, 1, 1); STAGE_A(SA(1, 0), brow, t + 3);
;     BAR; WAIT_L(0); MMA(1, 0, At, B0); BAR; SCHED;
;     STAGE_B(SB(1, 1), bcol + HALF, t + 3);
;     WAIT_V(6); BAR; MMA(1, 1, At, B1); BAR;
;     ...
;   { LDB(B0, 0, 0); LDA(At, 0, 0); STAGE_A(SA(1, 1), brow + HALF, nt - 1);
	v_mfma_f32_16x16x32_bf16 v[76:79], v[218:221], v[202:205], v[76:79]
	v_mfma_f32_16x16x32_bf16 v[72:75], v[238:241], v[202:205], v[72:75]
	v_mfma_f32_16x16x32_bf16 v[68:71], v[218:221], v[210:213], v[68:71]
	v_mfma_f32_16x16x32_bf16 v[64:67], v[238:241], v[210:213], v[64:67]
	s_setprio 0
	v_readfirstlane_b32 s25, v153
	v_lshl_add_u64 v[178:179], v[178:179], 0, s[46:47]
	s_mov_b32 m0, s25
	v_readfirstlane_b32 s25, v154
	global_load_lds_dwordx4 v[178:179], off
	v_lshl_add_u64 v[178:179], v[222:223], 0, s[46:47]
	s_mov_b32 m0, s25
	s_nop 0
	global_load_lds_dwordx4 v[178:179], off
	s_cmp_lt_u32 s24, 13
	s_cselect_b32 s27, s30, s36
	s_cselect_b32 s26, s29, s35
	v_lshl_add_u64 v[178:179], s[26:27], 0, v[136:137]
	v_lshl_add_u64 v[178:179], v[178:179], 0, s[10:11]
	v_readfirstlane_b32 s25, v155
	v_lshl_add_u64 v[178:179], v[178:179], 0, s[88:89]
	s_mov_b32 m0, s25
	ds_read_b128 v[182:185], v146 offset:49152
	ds_read_b128 v[186:189], v146 offset:50176
	ds_read_b128 v[190:193], v146 offset:51200
	ds_read_b128 v[194:197], v146 offset:52224
	ds_read_b128 v[198:201], v146 offset:53248
	ds_read_b128 v[202:205], v146 offset:54272
	ds_read_b128 v[206:209], v146 offset:55296
	ds_read_b128 v[210:213], v146 offset:56320
	global_load_lds_dwordx4 v[178:179], off
	v_lshl_add_u64 v[178:179], s[26:27], 0, v[138:139]
	v_lshl_add_u64 v[178:179], v[178:179], 0, s[10:11]
	v_readfirstlane_b32 s25, v156
	v_lshl_add_u64 v[178:179], v[178:179], 0, s[88:89]
	s_mov_b32 m0, s25
	s_nop 0
	global_load_lds_dwordx4 v[178:179], off
	v_readfirstlane_b32 s25, v157
	v_lshl_add_u64 v[250:251], v[236:237], 0, s[48:49]
	s_mov_b32 m0, s25
	v_readfirstlane_b32 s25, v158
	global_load_lds_dwordx4 v[250:251], off
	v_lshl_add_u64 v[250:251], v[246:247], 0, s[48:49]
	s_mov_b32 m0, s25
	s_nop 0
	global_load_lds_dwordx4 v[250:251], off
	s_waitcnt lgkmcnt(0)
	s_waitcnt vmcnt(8)
	s_barrier
	s_setprio 1
	v_mfma_f32_16x16x32_bf16 v[60:63], v[162:165], v[182:185], v[60:63]
	v_mfma_f32_16x16x32_bf16 v[56:59], v[170:173], v[182:185], v[56:59]
	v_mfma_f32_16x16x32_bf16 v[52:55], v[162:165], v[190:193], v[52:55]
	v_mfma_f32_16x16x32_bf16 v[48:51], v[170:173], v[190:193], v[48:51]
	v_mfma_f32_16x16x32_bf16 v[44:47], v[162:165], v[198:201], v[44:47]
	v_mfma_f32_16x16x32_bf16 v[40:43], v[170:173], v[198:201], v[40:43]
	v_mfma_f32_16x16x32_bf16 v[36:39], v[162:165], v[206:209], v[36:39]
	v_mfma_f32_16x16x32_bf16 v[32:35], v[170:173], v[206:209], v[32:35]
	v_mfma_f32_16x16x32_bf16 v[60:63], v[166:169], v[186:189], v[60:63]
	v_mfma_f32_16x16x32_bf16 v[56:59], v[174:177], v[186:189], v[56:59]
	v_mfma_f32_16x16x32_bf16 v[52:55], v[166:169], v[194:197], v[52:55]
	v_mfma_f32_16x16x32_bf16 v[48:51], v[174:177], v[194:197], v[48:51]
	v_mfma_f32_16x16x32_bf16 v[44:47], v[166:169], v[202:205], v[44:47]
	v_mfma_f32_16x16x32_bf16 v[40:43], v[174:177], v[202:205], v[40:43]
	v_mfma_f32_16x16x32_bf16 v[36:39], v[166:169], v[210:213], v[36:39]
	v_mfma_f32_16x16x32_bf16 v[32:35], v[174:177], v[210:213], v[32:35]
	v_mfma_f32_16x16x32_bf16 v[28:31], v[214:217], v[182:185], v[28:31]
	v_mfma_f32_16x16x32_bf16 v[24:27], v[230:233], v[182:185], v[24:27]
	v_mfma_f32_16x16x32_bf16 v[20:23], v[214:217], v[190:193], v[20:23]
	v_mfma_f32_16x16x32_bf16 v[16:19], v[230:233], v[190:193], v[16:19]
	v_mfma_f32_16x16x32_bf16 v[12:15], v[214:217], v[198:201], v[12:15]
	v_mfma_f32_16x16x32_bf16 v[8:11], v[230:233], v[198:201], v[8:11]
	v_mfma_f32_16x16x32_bf16 v[4:7], v[214:217], v[206:209], v[4:7]
	v_mfma_f32_16x16x32_bf16 v[0:3], v[230:233], v[206:209], v[0:3]
	v_mfma_f32_16x16x32_bf16 v[28:31], v[218:221], v[186:189], v[28:31]
	v_mfma_f32_16x16x32_bf16 v[24:27], v[238:241], v[186:189], v[24:27]
	v_mfma_f32_16x16x32_bf16 v[20:23], v[218:221], v[194:197], v[20:23]
	v_mfma_f32_16x16x32_bf16 v[16:19], v[238:241], v[194:197], v[16:19]
	s_setprio 2
	s_barrier
	v_mfma_f32_16x16x32_bf16 v[12:15], v[218:221], v[202:205], v[12:15]
	v_mfma_f32_16x16x32_bf16 v[8:11], v[238:241], v[202:205], v[8:11]
	v_mfma_f32_16x16x32_bf16 v[4:7], v[218:221], v[210:213], v[4:7]
	v_mfma_f32_16x16x32_bf16 v[0:3], v[238:241], v[210:213], v[0:3]
	s_setprio 0
	s_add_u32 s10, s10, 0x100
	s_addc_u32 s11, s11, 0
	s_cmp_lt_u32 s24, 28
	s_cbranch_scc1 .LBB0_1801
.Lmy_kexit_1:
	s_waitcnt vmcnt(6)
	v_not_b32_e32 v250, 63
	v_mov_b32_e32 v251, 0x41b17218
	s_lshl_b64 s[8:9], s[8:9], 1
	s_add_u32 s8, s35, s8
	s_addc_u32 s9, s36, s9
	v_lshl_add_u64 v[130:131], s[8:9], 0, v[130:131]
	s_mov_b64 s[24:25], 0xf80
	v_readfirstlane_b32 s10, v159
	v_lshl_add_u64 v[130:131], v[130:131], 0, s[24:25]
	s_mov_b32 m0, s10
	v_lshl_add_u64 v[128:129], s[8:9], 0, v[128:129]
	v_readfirstlane_b32 s8, v160
	ds_read_b128 v[132:135], v149
	ds_read_b128 v[136:139], v149 offset:1024
	ds_read_b128 v[140:143], v149 offset:2048
	ds_read_b128 v[150:153], v149 offset:3072
	ds_read_b128 v[154:157], v146
	ds_read_b128 v[162:165], v146 offset:1024
	ds_read_b128 v[166:169], v146 offset:2048
	ds_read_b128 v[170:173], v146 offset:3072
	ds_read_b128 v[174:177], v146 offset:4096
	ds_read_b128 v[182:185], v146 offset:5120
	ds_read_b128 v[186:189], v146 offset:6144
	ds_read_b128 v[190:193], v146 offset:7168
	global_load_lds_dwordx4 v[130:131], off
	v_lshl_add_u64 v[128:129], v[128:129], 0, s[24:25]
	s_mov_b32 m0, s8
	s_nop 0
	global_load_lds_dwordx4 v[128:129], off
	s_barrier
; #define STAGE_A(P, br, kt) do { const char* _base = (const char*)(((kt) < G.ksplit ? G.A1 : A2m) + (long)(br) * G.lda + (long)(kt) * BK); \
;     __builtin_amdgcn_global_load_lds((const unsigned*)(_base + aoff0), (unsigned*)((char*)(P) + sb0), 16, 0, 0); \
;     __builtin_amdgcn_global_load_lds((const unsigned*)(_base + aoff1), (unsigned*)((char*)(P) + sb1), 16, 0, 0); } while (0)
; #define LDA(dst, b, h) for (int m = 0; m < 4; ++m) for (int k = 0; k < 2; ++k) \
;     dst[m][k] = *reinterpret_cast<const bf16x8*>(a_rd + ((b) * 2 + (h)) * (HT * 2) + m * 2048 + k * 1024)
; #define LDB(dst, b, h) for (int n = 0; n < 2; ++n) for (int k = 0; k < 2; ++k) \
;     dst[n][k] = *reinterpret_cast<const bf16x8*>(b_rd + ((b) * 2 + (h)) * (HT * 2) + n * 2048 + k * 1024)
; #define MMA(ai, bj, At_, Bt_) do { __builtin_amdgcn_s_setprio(1); \
;     for (int m = 0; m < 4; ++m) for (int n = 0; n < 2; ++n) for (int k = 0; k < 2; ++k) \
;       acc[ai][bj][m][n] = __builtin_amdgcn_mfma_f32_16x16x32_bf16(Bt_[n][k], At_[m][k], acc[ai][bj][m][n], 0, 0, 0); \
;     __builtin_amdgcn_s_setprio(0); } while (0)
; #define WAIT_V(n) asm volatile("s_waitcnt vmcnt(" #n ")" ::: "memory")
; #define WAIT_L(n) asm volatile("s_waitcnt lgkmcnt(" #n ")" ::: "memory")
; #define BAR __builtin_amdgcn_s_barrier()
;     ...
;   { LDB(B0, 0, 0); LDA(At, 0, 0); STAGE_A(SA(1, 1), brow + HALF, nt - 1);
;     BAR; WAIT_L(0); MMA(0, 0, At, B0); BAR;
;     LDB(B1, 0, 1); BAR; WAIT_L(0); MMA(0, 1, At, B1); BAR;
;     LDA(At, 0, 1); WAIT_V(4); BAR; WAIT_L(0); MMA(1, 0, At, B0); MMA(1, 1, At, B1); BAR; }
;   { LDB(B0, 1, 0); LDA(At, 1, 0); WAIT_V(2); BAR; WAIT_L(0); MMA(0, 0, At, B0); BAR;
	s_waitcnt lgkmcnt(0)
	s_setprio 1
	s_waitcnt lgkmcnt(0)
	v_mfma_f32_16x16x32_bf16 v[124:127], v[132:135], v[154:157], v[124:127]
	v_mfma_f32_16x16x32_bf16 v[120:123], v[140:143], v[154:157], v[120:123]
	v_mfma_f32_16x16x32_bf16 v[116:119], v[132:135], v[166:169], v[116:119]
	v_mfma_f32_16x16x32_bf16 v[112:115], v[140:143], v[166:169], v[112:115]
	v_mfma_f32_16x16x32_bf16 v[108:111], v[132:135], v[174:177], v[108:111]
	v_mfma_f32_16x16x32_bf16 v[104:107], v[140:143], v[174:177], v[104:107]
	v_mfma_f32_16x16x32_bf16 v[100:103], v[132:135], v[186:189], v[100:103]
	v_mfma_f32_16x16x32_bf16 v[96:99], v[140:143], v[186:189], v[96:99]
	v_mfma_f32_16x16x32_bf16 v[124:127], v[136:139], v[162:165], v[124:127]
	v_mfma_f32_16x16x32_bf16 v[120:123], v[150:153], v[162:165], v[120:123]
	v_mfma_f32_16x16x32_bf16 v[116:119], v[136:139], v[170:173], v[116:119]
	v_mfma_f32_16x16x32_bf16 v[112:115], v[150:153], v[170:173], v[112:115]
	s_setprio 2
	s_barrier
	v_mfma_f32_16x16x32_bf16 v[108:111], v[136:139], v[182:185], v[108:111]
	v_mfma_f32_16x16x32_bf16 v[104:107], v[150:153], v[182:185], v[104:107]
	v_mfma_f32_16x16x32_bf16 v[100:103], v[136:139], v[190:193], v[100:103]
	v_mfma_f32_16x16x32_bf16 v[96:99], v[150:153], v[190:193], v[96:99]
	s_setprio 0
	ds_read_b128 v[128:131], v149 offset:16384
	ds_read_b128 v[158:161], v149 offset:17408
	ds_read_b128 v[194:197], v149 offset:18432
	ds_read_b128 v[198:201], v149 offset:19456
	s_barrier
	s_waitcnt lgkmcnt(0)
	s_setprio 1
	s_waitcnt lgkmcnt(0)
	v_mfma_f32_16x16x32_bf16 v[92:95], v[128:131], v[154:157], v[92:95]
	v_mfma_f32_16x16x32_bf16 v[88:91], v[194:197], v[154:157], v[88:91]
	v_mfma_f32_16x16x32_bf16 v[84:87], v[128:131], v[166:169], v[84:87]
	v_mfma_f32_16x16x32_bf16 v[80:83], v[194:197], v[166:169], v[80:83]
	v_mfma_f32_16x16x32_bf16 v[76:79], v[128:131], v[174:177], v[76:79]
	v_mfma_f32_16x16x32_bf16 v[72:75], v[194:197], v[174:177], v[72:75]
	v_mfma_f32_16x16x32_bf16 v[68:71], v[128:131], v[186:189], v[68:71]
	v_mfma_f32_16x16x32_bf16 v[64:67], v[194:197], v[186:189], v[64:67]
	v_mfma_f32_16x16x32_bf16 v[202:205], v[158:161], v[162:165], v[92:95]
	v_mfma_f32_16x16x32_bf16 v[154:157], v[198:201], v[162:165], v[88:91]
	v_mfma_f32_16x16x32_bf16 v[162:165], v[158:161], v[170:173], v[84:87]
	v_mfma_f32_16x16x32_bf16 v[166:169], v[198:201], v[170:173], v[80:83]
	s_setprio 2
	s_barrier
	v_mfma_f32_16x16x32_bf16 v[170:173], v[158:161], v[182:185], v[76:79]
	v_mfma_f32_16x16x32_bf16 v[174:177], v[198:201], v[182:185], v[72:75]
	v_mfma_f32_16x16x32_bf16 v[182:185], v[158:161], v[190:193], v[68:71]
	v_mfma_f32_16x16x32_bf16 v[186:189], v[198:201], v[190:193], v[64:67]
	s_setprio 0
	s_nop 0
	ds_read_b128 v[64:67], v146 offset:16384
	ds_read_b128 v[68:71], v146 offset:17408
	ds_read_b128 v[72:75], v146 offset:18432
	ds_read_b128 v[76:79], v146 offset:19456
	ds_read_b128 v[80:83], v146 offset:20480
	ds_read_b128 v[84:87], v146 offset:21504
	ds_read_b128 v[88:91], v146 offset:22528
	ds_read_b128 v[92:95], v146 offset:23552
	s_waitcnt vmcnt(4)
	s_barrier
	s_waitcnt lgkmcnt(0)
	s_setprio 1
	s_waitcnt lgkmcnt(0)
	v_mfma_f32_16x16x32_bf16 v[60:63], v[132:135], v[64:67], v[60:63]
	v_mfma_f32_16x16x32_bf16 v[56:59], v[140:143], v[64:67], v[56:59]
	v_mfma_f32_16x16x32_bf16 v[52:55], v[132:135], v[72:75], v[52:55]
	v_mfma_f32_16x16x32_bf16 v[48:51], v[140:143], v[72:75], v[48:51]
	v_mfma_f32_16x16x32_bf16 v[44:47], v[132:135], v[80:83], v[44:47]
	v_mfma_f32_16x16x32_bf16 v[40:43], v[140:143], v[80:83], v[40:43]
	v_mfma_f32_16x16x32_bf16 v[36:39], v[132:135], v[88:91], v[36:39]
	v_mfma_f32_16x16x32_bf16 v[32:35], v[140:143], v[88:91], v[32:35]
	v_mfma_f32_16x16x32_bf16 v[60:63], v[136:139], v[68:71], v[60:63]
	v_mfma_f32_16x16x32_bf16 v[56:59], v[150:153], v[68:71], v[56:59]
	v_mfma_f32_16x16x32_bf16 v[52:55], v[136:139], v[76:79], v[52:55]
	v_mfma_f32_16x16x32_bf16 v[48:51], v[150:153], v[76:79], v[48:51]
	v_mfma_f32_16x16x32_bf16 v[44:47], v[136:139], v[84:87], v[44:47]
	v_mfma_f32_16x16x32_bf16 v[40:43], v[150:153], v[84:87], v[40:43]
	v_mfma_f32_16x16x32_bf16 v[36:39], v[136:139], v[92:95], v[36:39]
	v_mfma_f32_16x16x32_bf16 v[32:35], v[150:153], v[92:95], v[32:35]
	s_setprio 0
	s_setprio 1
	v_mfma_f32_16x16x32_bf16 v[28:31], v[128:131], v[64:67], v[28:31]
	v_mfma_f32_16x16x32_bf16 v[24:27], v[194:197], v[64:67], v[24:27]
	v_mfma_f32_16x16x32_bf16 v[20:23], v[128:131], v[72:75], v[20:23]
	v_mfma_f32_16x16x32_bf16 v[16:19], v[194:197], v[72:75], v[16:19]
	v_mfma_f32_16x16x32_bf16 v[12:15], v[128:131], v[80:83], v[12:15]
	v_mfma_f32_16x16x32_bf16 v[8:11], v[194:197], v[80:83], v[8:11]
	v_mfma_f32_16x16x32_bf16 v[4:7], v[128:131], v[88:91], v[4:7]
	v_mfma_f32_16x16x32_bf16 v[0:3], v[194:197], v[88:91], v[0:3]
	v_mfma_f32_16x16x32_bf16 v[132:135], v[158:161], v[68:71], v[28:31]
	v_mfma_f32_16x16x32_bf16 v[136:139], v[198:201], v[68:71], v[24:27]
	v_mfma_f32_16x16x32_bf16 v[140:143], v[158:161], v[76:79], v[20:23]
	v_mfma_f32_16x16x32_bf16 v[150:153], v[198:201], v[76:79], v[16:19]
	s_setprio 2
	s_barrier
	v_mfma_f32_16x16x32_bf16 v[190:193], v[158:161], v[84:87], v[12:15]
	v_mfma_f32_16x16x32_bf16 v[206:209], v[198:201], v[84:87], v[8:11]
	v_mfma_f32_16x16x32_bf16 v[128:131], v[158:161], v[92:95], v[4:7]
	v_mfma_f32_16x16x32_bf16 v[158:161], v[198:201], v[92:95], v[0:3]
	s_setprio 0
	ds_read_b128 v[24:27], v149 offset:32768
	ds_read_b128 v[28:31], v149 offset:33792
	ds_read_b128 v[194:197], v149 offset:34816
	ds_read_b128 v[198:201], v149 offset:35840
	ds_read_b128 v[0:3], v146 offset:32768
	ds_read_b128 v[4:7], v146 offset:33792
	ds_read_b128 v[8:11], v146 offset:34816
	ds_read_b128 v[12:15], v146 offset:35840
	ds_read_b128 v[16:19], v146 offset:36864
	ds_read_b128 v[20:23], v146 offset:37888
	ds_read_b128 v[210:213], v146 offset:38912
	ds_read_b128 v[214:217], v146 offset:39936
	s_waitcnt vmcnt(2)
	s_barrier
; #define LDA(dst, b, h) for (int m = 0; m < 4; ++m) for (int k = 0; k < 2; ++k) \
;     dst[m][k] = *reinterpret_cast<const bf16x8*>(a_rd + ((b) * 2 + (h)) * (HT * 2) + m * 2048 + k * 1024)
; #define LDB(dst, b, h) for (int n = 0; n < 2; ++n) for (int k = 0; k < 2; ++k) \
;     dst[n][k] = *reinterpret_cast<const bf16x8*>(b_rd + ((b) * 2 + (h)) * (HT * 2) + n * 2048 + k * 1024)
; #define MMA(ai, bj, At_, Bt_) do { __builtin_amdgcn_s_setprio(1); \
;     for (int m = 0; m < 4; ++m) for (int n = 0; n < 2; ++n) for (int k = 0; k < 2; ++k) \
;       acc[ai][bj][m][n] = __builtin_amdgcn_mfma_f32_16x16x32_bf16(Bt_[n][k], At_[m][k], acc[ai][bj][m][n], 0, 0, 0); \
;     __builtin_amdgcn_s_setprio(0); } while (0)
; #define WAIT_V(n) asm volatile("s_waitcnt vmcnt(" #n ")" ::: "memory")
; #define WAIT_L(n) asm volatile("s_waitcnt lgkmcnt(" #n ")" ::: "memory")
; #define BAR __builtin_amdgcn_s_barrier()
;     ...
;   { LDB(B0, 1, 0); LDA(At, 1, 0); WAIT_V(2); BAR; WAIT_L(0); MMA(0, 0, At, B0); BAR;
;     LDB(B1, 1, 1); WAIT_V(0); BAR; WAIT_L(0); MMA(0, 1, At, B1); BAR;
;     LDA(At, 1, 1); BAR; WAIT_L(0); MMA(1, 0, At, B0); MMA(1, 1, At, B1); BAR; }
;   if (wr == 0) BAR;
	s_waitcnt lgkmcnt(0)
	s_setprio 1
	s_waitcnt lgkmcnt(0)
	v_mfma_f32_16x16x32_bf16 v[64:67], v[24:27], v[0:3], v[124:127]
	v_mfma_f32_16x16x32_bf16 v[68:71], v[194:197], v[0:3], v[120:123]
	v_mfma_f32_16x16x32_bf16 v[72:75], v[24:27], v[8:11], v[116:119]
	v_mfma_f32_16x16x32_bf16 v[76:79], v[194:197], v[8:11], v[112:115]
	v_mfma_f32_16x16x32_bf16 v[80:83], v[24:27], v[16:19], v[108:111]
	v_mfma_f32_16x16x32_bf16 v[84:87], v[194:197], v[16:19], v[104:107]
	v_mfma_f32_16x16x32_bf16 v[88:91], v[24:27], v[210:213], v[100:103]
	v_mfma_f32_16x16x32_bf16 v[92:95], v[194:197], v[210:213], v[96:99]
	v_mfma_f32_16x16x32_bf16 v[64:67], v[28:31], v[4:7], v[64:67]
	v_mfma_f32_16x16x32_bf16 v[68:71], v[198:201], v[4:7], v[68:71]
	v_mfma_f32_16x16x32_bf16 v[72:75], v[28:31], v[12:15], v[72:75]
	v_mfma_f32_16x16x32_bf16 v[76:79], v[198:201], v[12:15], v[76:79]
	s_setprio 2
	s_barrier
	v_mfma_f32_16x16x32_bf16 v[80:83], v[28:31], v[20:23], v[80:83]
	v_mfma_f32_16x16x32_bf16 v[84:87], v[198:201], v[20:23], v[84:87]
	v_mfma_f32_16x16x32_bf16 v[88:91], v[28:31], v[214:217], v[88:91]
	v_mfma_f32_16x16x32_bf16 v[92:95], v[198:201], v[214:217], v[92:95]
	s_setprio 0
	ds_read_b128 v[218:221], v149 offset:49152
	ds_read_b128 v[230:233], v149 offset:50176
	ds_read_b128 v[238:241], v149 offset:51200
	ds_read_b128 v[246:249], v149 offset:52224
	s_waitcnt vmcnt(0)
	s_barrier
	s_waitcnt lgkmcnt(0)
	s_setprio 1
	s_waitcnt lgkmcnt(0)
	v_mfma_f32_16x16x32_bf16 v[96:99], v[218:221], v[0:3], v[202:205]
	v_mfma_f32_16x16x32_bf16 v[0:3], v[238:241], v[0:3], v[154:157]
	v_mfma_f32_16x16x32_bf16 v[100:103], v[246:249], v[4:7], v[0:3]
	v_mfma_f32_16x16x32_bf16 v[0:3], v[218:221], v[8:11], v[162:165]
	v_mfma_f32_16x16x32_bf16 v[104:107], v[230:233], v[12:15], v[0:3]
	v_mfma_f32_16x16x32_bf16 v[0:3], v[238:241], v[8:11], v[166:169]
	v_mfma_f32_16x16x32_bf16 v[108:111], v[246:249], v[12:15], v[0:3]
	v_mfma_f32_16x16x32_bf16 v[0:3], v[218:221], v[16:19], v[170:173]
	v_mfma_f32_16x16x32_bf16 v[112:115], v[230:233], v[20:23], v[0:3]
	v_mfma_f32_16x16x32_bf16 v[0:3], v[238:241], v[16:19], v[174:177]
	v_mfma_f32_16x16x32_bf16 v[116:119], v[246:249], v[20:23], v[0:3]
	v_mfma_f32_16x16x32_bf16 v[0:3], v[218:221], v[210:213], v[182:185]
	s_setprio 2
	s_barrier
	v_mfma_f32_16x16x32_bf16 v[120:123], v[230:233], v[214:217], v[0:3]
	v_mfma_f32_16x16x32_bf16 v[0:3], v[238:241], v[210:213], v[186:189]
	v_mfma_f32_16x16x32_bf16 v[96:99], v[230:233], v[4:7], v[96:99]
	v_mfma_f32_16x16x32_bf16 v[124:127], v[246:249], v[214:217], v[0:3]
	s_setprio 0
	ds_read_b128 v[154:157], v146 offset:49152
	ds_read_b128 v[162:165], v146 offset:50176
	ds_read_b128 v[166:169], v146 offset:51200
	ds_read_b128 v[170:173], v146 offset:52224
	ds_read_b128 v[174:177], v146 offset:53248
	ds_read_b128 v[182:185], v146 offset:54272
	ds_read_b128 v[186:189], v146 offset:55296
	ds_read_b128 v[146:149], v146 offset:56320
	s_barrier
	s_waitcnt lgkmcnt(0)
	s_setprio 1
	s_waitcnt lgkmcnt(0)
	v_mfma_f32_16x16x32_bf16 v[0:3], v[24:27], v[154:157], v[60:63]
	v_mfma_f32_16x16x32_bf16 v[8:11], v[24:27], v[166:169], v[52:55]
	v_mfma_f32_16x16x32_bf16 v[16:19], v[24:27], v[174:177], v[44:47]
	v_mfma_f32_16x16x32_bf16 v[24:27], v[24:27], v[186:189], v[36:39]
	v_mfma_f32_16x16x32_bf16 v[0:3], v[28:31], v[162:165], v[0:3]
	v_mfma_f32_16x16x32_bf16 v[4:7], v[194:197], v[154:157], v[56:59]
	v_mfma_f32_16x16x32_bf16 v[8:11], v[28:31], v[170:173], v[8:11]
	v_mfma_f32_16x16x32_bf16 v[12:15], v[194:197], v[166:169], v[48:51]
	v_mfma_f32_16x16x32_bf16 v[16:19], v[28:31], v[182:185], v[16:19]
	v_mfma_f32_16x16x32_bf16 v[20:23], v[194:197], v[174:177], v[40:43]
	v_mfma_f32_16x16x32_bf16 v[24:27], v[28:31], v[146:149], v[24:27]
	v_mfma_f32_16x16x32_bf16 v[28:31], v[194:197], v[186:189], v[32:35]
	v_mfma_f32_16x16x32_bf16 v[4:7], v[198:201], v[162:165], v[4:7]
	v_mfma_f32_16x16x32_bf16 v[12:15], v[198:201], v[170:173], v[12:15]
	v_mfma_f32_16x16x32_bf16 v[20:23], v[198:201], v[182:185], v[20:23]
	v_mfma_f32_16x16x32_bf16 v[28:31], v[198:201], v[146:149], v[28:31]
	s_setprio 0
	s_setprio 1
	v_mfma_f32_16x16x32_bf16 v[32:35], v[218:221], v[154:157], v[132:135]
	v_mfma_f32_16x16x32_bf16 v[36:39], v[238:241], v[154:157], v[136:139]
	v_mfma_f32_16x16x32_bf16 v[40:43], v[218:221], v[166:169], v[140:143]
	v_mfma_f32_16x16x32_bf16 v[44:47], v[238:241], v[166:169], v[150:153]
	v_mfma_f32_16x16x32_bf16 v[48:51], v[218:221], v[174:177], v[190:193]
	v_mfma_f32_16x16x32_bf16 v[52:55], v[238:241], v[174:177], v[206:209]
	v_mfma_f32_16x16x32_bf16 v[56:59], v[218:221], v[186:189], v[128:131]
	v_mfma_f32_16x16x32_bf16 v[60:63], v[238:241], v[186:189], v[158:161]
	v_mfma_f32_16x16x32_bf16 v[32:35], v[230:233], v[162:165], v[32:35]
	v_mfma_f32_16x16x32_bf16 v[36:39], v[246:249], v[162:165], v[36:39]
	v_mfma_f32_16x16x32_bf16 v[40:43], v[230:233], v[170:173], v[40:43]
	v_mfma_f32_16x16x32_bf16 v[44:47], v[246:249], v[170:173], v[44:47]
	s_setprio 2
	s_barrier
	v_mfma_f32_16x16x32_bf16 v[48:51], v[230:233], v[182:185], v[48:51]
	v_mfma_f32_16x16x32_bf16 v[52:55], v[246:249], v[182:185], v[52:55]
	v_mfma_f32_16x16x32_bf16 v[56:59], v[230:233], v[146:149], v[56:59]
	v_mfma_f32_16x16x32_bf16 v[60:63], v[246:249], v[146:149], v[60:63]
	s_setprio 0
	v_cmp_gt_u32_e32 vcc, s60, v144
	s_and_saveexec_b64 s[8:9], vcc
	s_cbranch_execz .LBB0_1804
	s_barrier

; #define STAGE_A(P, br, kt) do { const char* _base = (const char*)(((kt) < G.ksplit ? G.A1 : A2m) + (long)(br) * G.lda + (long)(kt) * BK); \
;     __builtin_amdgcn_global_load_lds((const unsigned*)(_base + aoff0), (unsigned*)((char*)(P) + sb0), 16, 0, 0); \
;     __builtin_amdgcn_global_load_lds((const unsigned*)(_base + aoff1), (unsigned*)((char*)(P) + sb1), 16, 0, 0); } while (0)
; #define STAGE_B(P, br, kt) do { const char* _base = (const char*)(G.Bt + (long)(br) * G.ldb + (long)(kt) * BK); \
;     __builtin_amdgcn_global_load_lds((const unsigned*)(_base + boff0), (unsigned*)((char*)(P) + sb0), 16, 0, 0); \
;     __builtin_amdgcn_global_load_lds((const unsigned*)(_base + boff1), (unsigned*)((char*)(P) + sb1), 16, 0, 0); } while (0)
; #define LDA(dst, b, h) for (int m = 0; m < 4; ++m) for (int k = 0; k < 2; ++k) \
;     dst[m][k] = *reinterpret_cast<const bf16x8*>(a_rd + ((b) * 2 + (h)) * (HT * 2) + m * 2048 + k * 1024)
; #define LDB(dst, b, h) for (int n = 0; n < 2; ++n) for (int k = 0; k < 2; ++k) \
;     dst[n][k] = *reinterpret_cast<const bf16x8*>(b_rd + ((b) * 2 + (h)) * (HT * 2) + n * 2048 + k * 1024)
; #define MMA(ai, bj, At_, Bt_) do { __builtin_amdgcn_s_setprio(1); \
;     for (int m = 0; m < 4; ++m) for (int n = 0; n < 2; ++n) for (int k = 0; k < 2; ++k) \
;       acc[ai][bj][m][n] = __builtin_amdgcn_mfma_f32_16x16x32_bf16(Bt_[n][k], At_[m][k], acc[ai][bj][m][n], 0, 0, 0); \
;     __builtin_amdgcn_s_setprio(0); } while (0)
; #define WAIT_V(n) asm volatile("s_waitcnt vmcnt(" #n ")" ::: "memory")
; #define WAIT_L(n) asm volatile("s_waitcnt lgkmcnt(" #n ")" ::: "memory")
;     ...
;   if (wr == 1) BAR;
;   WAIT_V(0); BAR;
;   STAGE_B(SB(1, 0), bcol, 1); STAGE_A(SA(1, 0), brow, 1); STAGE_B(SB(1, 1), bcol + HALF, 1);
;   WAIT_V(6); BAR;
;   for (int t = 0; t < nt - 2; t += 2) {
;     LDB(B0, 0, 0); SCHED; LDA(At, 0, 0); STAGE_A(SA(1, 1), brow + HALF, t + 1);
;     WAIT_L(8); BAR; WAIT_L(0); MMA(0, 0, At, B0); BAR; SCHED;
;     LDB(B1, 0, 1); STAGE_B(SB(0, 0), bcol, t + 2);
;     BAR; WAIT_L(0); MMA(0, 1, At, B1); BAR;
;     LDA(At, 0, 1); STAGE_A(SA(0, 0), brow, t + 2);
;     BAR; WAIT_L(0); MMA(1, 0, At, B0); BAR; SCHED;
;     STAGE_B(SB(0, 1), bcol + HALF, t + 2);
;     WAIT_V(6); BAR; MMA(1, 1, At, B1); BAR;
;     LDB(B0, 1, 0); SCHED; LDA(At, 1, 0); STAGE_A(SA(0, 1), brow + HALF, t + 2);
;     WAIT_L(8); BAR; WAIT_L(0); MMA(0, 0, At, B0); BAR; SCHED;
.LBB0_1864:
	s_or_b64 exec, exec, s[24:25]
	v_and_b32_e32 v144, 15, v139
	v_lshlrev_b32_e32 v10, 2, v139
	s_ashr_i32 s27, s26, 31
	s_lshr_b32 s25, s30, 3
	v_and_b32_e32 v8, 48, v139
	v_lshlrev_b32_e32 v9, 6, v144
	v_and_b32_e32 v10, 32, v10
	s_add_i32 s30, 32, 0x10000
	s_lshl_b32 s24, s31, 8
	s_lshl_b64 s[26:27], s[26:27], 1
	v_bitop3_b32 v10, v9, v10, v8 bitop3:0x36
	v_lshlrev_b32_e32 v8, 6, v139
	s_add_u32 s44, s39, s26
	v_readlane_b32 s31, v253, 46
	v_and_b32_e32 v8, 0x3000, v8
	s_addc_u32 s45, s40, s27
	v_add_u32_e32 v145, s31, v142
	s_waitcnt vmcnt(0)
	v_add_u32_e32 v12, s30, v8
	v_lshl_add_u64 v[8:9], s[44:45], 0, v[180:181]
	s_mov_b64 s[46:47], 0x80
	v_readfirstlane_b32 s31, v145
	v_lshl_add_u64 v[8:9], v[8:9], 0, s[46:47]
	s_mov_b32 m0, s31
	v_mov_b32_e32 v129, v181
	v_add_u32_e32 v150, 0x2000, v145
	s_waitcnt vmcnt(0)
	s_barrier
	global_load_lds_dwordx4 v[8:9], off
	v_lshl_add_u64 v[8:9], s[44:45], 0, v[128:129]
	v_readfirstlane_b32 s31, v150
	s_add_u32 s42, s37, s42
	v_lshl_add_u64 v[8:9], v[8:9], 0, s[46:47]
	s_mov_b32 m0, s31
	s_addc_u32 s43, s38, s35
	v_add_u32_e32 v151, 0x8000, v147
	global_load_lds_dwordx4 v[8:9], off
	v_lshl_add_u64 v[8:9], s[42:43], 0, v[180:181]
	v_readfirstlane_b32 s31, v151
	v_add_u32_e32 v152, 0xa000, v147
	v_lshl_add_u64 v[8:9], v[8:9], 0, s[46:47]
	s_mov_b32 m0, s31
	v_readfirstlane_b32 s31, v152
	global_load_lds_dwordx4 v[8:9], off
	s_mov_b32 m0, s31
	s_or_b32 s31, s24, 0x80
	v_lshl_add_u64 v[8:9], s[42:43], 0, v[128:129]
	s_mul_i32 s42, s31, 0x840
	s_ashr_i32 s43, s42, 31
	s_lshl_b64 s[42:43], s[42:43], 1
	s_add_u32 s42, s39, s42
	v_readlane_b32 s31, v253, 47
	v_lshl_add_u64 v[8:9], v[8:9], 0, s[46:47]
	s_addc_u32 s43, s40, s43
	v_add_u32_e32 v153, s31, v142
	global_load_lds_dwordx4 v[8:9], off
	v_lshl_add_u64 v[8:9], s[42:43], 0, v[180:181]
	v_readfirstlane_b32 s31, v153
	v_lshl_add_u64 v[8:9], v[8:9], 0, s[46:47]
	s_mov_b32 m0, s31
	v_add_u32_e32 v154, 0x2000, v153
	global_load_lds_dwordx4 v[8:9], off
	v_lshl_add_u64 v[8:9], s[42:43], 0, v[128:129]
	v_readfirstlane_b32 s31, v154
	v_lshl_add_u64 v[8:9], v[8:9], 0, s[46:47]
	s_mov_b32 m0, s31
	v_lshl_add_u32 v11, v143, 13, 32
	global_load_lds_dwordx4 v[8:9], off
	v_lshrrev_b32_e32 v8, 1, v0
	v_mul_lo_u32 v0, v1, s62
	v_mad_u64_u32 v[0:1], s[42:43], v8, s84, v[0:1]
	v_or_b32_e32 v0, v0, v2
	v_add_lshl_u32 v0, v0, v3, 1
	v_lshrrev_b32_e32 v3, 1, v4
	v_mul_lo_u32 v2, v5, s62
	v_mad_u64_u32 v[2:3], s[42:43], v3, s84, v[2:3]
	v_or_b32_e32 v2, v2, v6
	s_waitcnt vmcnt(6)
	v_mov_b32_e32 v1, v181
	v_add_lshl_u32 v2, v2, v7, 1
	v_mov_b32_e32 v3, v181
	v_lshl_add_u64 v[130:131], s[26:27], 0, v[0:1]
	v_lshl_add_u64 v[132:133], s[26:27], 0, v[2:3]
	v_mad_i64_i32 v[134:135], s[26:27], s29, v243, v[0:1]
	v_mad_i64_i32 v[136:137], s[26:27], s29, v243, v[2:3]
	s_mov_b32 s31, -2
	v_add_u32_e32 v149, v12, v10
	v_add_u32_e32 v148, v11, v10
	s_mov_b64 s[26:27], s[10:11]
	s_mov_b64 s[42:43], 0x4360100
	s_mov_b64 s[44:45], 0x4360180
	s_mov_b64 s[46:47], 0x43e4100
	s_mov_b64 s[48:49], 0x43e4180
	s_barrier
	ds_read_b128 v[160:163], v149
	ds_read_b128 v[164:167], v149 offset:1024
	ds_read_b128 v[168:171], v149 offset:2048
	ds_read_b128 v[172:175], v149 offset:3072
	v_add_u32_e32 v158, 0xc000, v147
	v_lshl_add_u64 v[222:223], s[26:27], 0, v[134:135]
	v_readfirstlane_b32 s35, v158
	v_add_u32_e32 v159, 0xe000, v147
	v_lshl_add_u64 v[156:157], v[222:223], 0, s[94:95]
	s_mov_b32 m0, s35
	v_lshl_add_u64 v[230:231], s[26:27], 0, v[136:137]
	v_readfirstlane_b32 s35, v159
	ds_read_b128 v[176:179], v148
	ds_read_b128 v[182:185], v148 offset:1024
	ds_read_b128 v[186:189], v148 offset:2048
	ds_read_b128 v[190:193], v148 offset:3072
	ds_read_b128 v[194:197], v148 offset:4096
	ds_read_b128 v[198:201], v148 offset:5120
	ds_read_b128 v[202:205], v148 offset:6144
	ds_read_b128 v[206:209], v148 offset:7168
	global_load_lds_dwordx4 v[156:157], off
	v_lshl_add_u64 v[156:157], v[230:231], 0, s[94:95]
	s_mov_b32 m0, s35
	s_nop 0
	global_load_lds_dwordx4 v[156:157], off
	ds_read_b128 v[210:213], v149 offset:16384
	ds_read_b128 v[214:217], v149 offset:17408
	ds_read_b128 v[218:221], v149 offset:18432
	ds_read_b128 v[246:249], v149 offset:19456
	s_waitcnt lgkmcnt(0)
	s_waitcnt vmcnt(8)
	s_barrier
	s_setprio 1
	v_mfma_f32_16x16x32_bf16 v[124:127], v[160:163], v[176:179], 0
	v_mfma_f32_16x16x32_bf16 v[120:123], v[168:171], v[176:179], 0
	v_mfma_f32_16x16x32_bf16 v[116:119], v[160:163], v[186:189], 0
	v_mfma_f32_16x16x32_bf16 v[112:115], v[168:171], v[186:189], 0
	v_mfma_f32_16x16x32_bf16 v[108:111], v[160:163], v[194:197], 0
	v_mfma_f32_16x16x32_bf16 v[104:107], v[168:171], v[194:197], 0
	v_mfma_f32_16x16x32_bf16 v[100:103], v[160:163], v[202:205], 0
	v_mfma_f32_16x16x32_bf16 v[96:99], v[168:171], v[202:205], 0
	v_mfma_f32_16x16x32_bf16 v[124:127], v[164:167], v[182:185], v[124:127]
	v_mfma_f32_16x16x32_bf16 v[120:123], v[172:175], v[182:185], v[120:123]
	v_mfma_f32_16x16x32_bf16 v[116:119], v[164:167], v[190:193], v[116:119]
	v_mfma_f32_16x16x32_bf16 v[112:115], v[172:175], v[190:193], v[112:115]
	v_mfma_f32_16x16x32_bf16 v[108:111], v[164:167], v[198:201], v[108:111]
	v_mfma_f32_16x16x32_bf16 v[104:107], v[172:175], v[198:201], v[104:107]
	v_mfma_f32_16x16x32_bf16 v[100:103], v[164:167], v[206:209], v[100:103]
	v_mfma_f32_16x16x32_bf16 v[96:99], v[172:175], v[206:209], v[96:99]
	v_mfma_f32_16x16x32_bf16 v[92:95], v[210:213], v[176:179], 0
	v_mfma_f32_16x16x32_bf16 v[88:91], v[218:221], v[176:179], 0
	v_mfma_f32_16x16x32_bf16 v[84:87], v[210:213], v[186:189], 0
	v_mfma_f32_16x16x32_bf16 v[80:83], v[218:221], v[186:189], 0
	v_mfma_f32_16x16x32_bf16 v[76:79], v[210:213], v[194:197], 0
	v_mfma_f32_16x16x32_bf16 v[72:75], v[218:221], v[194:197], 0
	v_mfma_f32_16x16x32_bf16 v[68:71], v[210:213], v[202:205], 0
	v_mfma_f32_16x16x32_bf16 v[64:67], v[218:221], v[202:205], 0
	v_mfma_f32_16x16x32_bf16 v[92:95], v[214:217], v[182:185], v[92:95]
	v_mfma_f32_16x16x32_bf16 v[88:91], v[246:249], v[182:185], v[88:91]
	v_mfma_f32_16x16x32_bf16 v[84:87], v[214:217], v[190:193], v[84:87]
	v_mfma_f32_16x16x32_bf16 v[80:83], v[246:249], v[190:193], v[80:83]
	s_setprio 2
	s_barrier
; #define STAGE_A(P, br, kt) do { const char* _base = (const char*)(((kt) < G.ksplit ? G.A1 : A2m) + (long)(br) * G.lda + (long)(kt) * BK); \
;     __builtin_amdgcn_global_load_lds((const unsigned*)(_base + aoff0), (unsigned*)((char*)(P) + sb0), 16, 0, 0); \
;     __builtin_amdgcn_global_load_lds((const unsigned*)(_base + aoff1), (unsigned*)((char*)(P) + sb1), 16, 0, 0); } while (0)
; #define STAGE_B(P, br, kt) do { const char* _base = (const char*)(G.Bt + (long)(br) * G.ldb + (long)(kt) * BK); \
;     __builtin_amdgcn_global_load_lds((const unsigned*)(_base + boff0), (unsigned*)((char*)(P) + sb0), 16, 0, 0); \
;     __builtin_amdgcn_global_load_lds((const unsigned*)(_base + boff1), (unsigned*)((char*)(P) + sb1), 16, 0, 0); } while (0)
; #define LDA(dst, b, h) for (int m = 0; m < 4; ++m) for (int k = 0; k < 2; ++k) \
;     dst[m][k] = *reinterpret_cast<const bf16x8*>(a_rd + ((b) * 2 + (h)) * (HT * 2) + m * 2048 + k * 1024)
; #define LDB(dst, b, h) for (int n = 0; n < 2; ++n) for (int k = 0; k < 2; ++k) \
;     dst[n][k] = *reinterpret_cast<const bf16x8*>(b_rd + ((b) * 2 + (h)) * (HT * 2) + n * 2048 + k * 1024)
; #define MMA(ai, bj, At_, Bt_) do { __builtin_amdgcn_s_setprio(1); \
;     for (int m = 0; m < 4; ++m) for (int n = 0; n < 2; ++n) for (int k = 0; k < 2; ++k) \
;       acc[ai][bj][m][n] = __builtin_amdgcn_mfma_f32_16x16x32_bf16(Bt_[n][k], At_[m][k], acc[ai][bj][m][n], 0, 0, 0); \
;     __builtin_amdgcn_s_setprio(0); } while (0)
;     ...
;   for (int t = 0; t < nt - 2; t += 2) {
;     LDB(B0, 0, 0); SCHED; LDA(At, 0, 0); STAGE_A(SA(1, 1), brow + HALF, t + 1);
;     WAIT_L(8); BAR; WAIT_L(0); MMA(0, 0, At, B0); BAR; SCHED;
;     LDB(B1, 0, 1); STAGE_B(SB(0, 0), bcol, t + 2);
;     BAR; WAIT_L(0); MMA(0, 1, At, B1); BAR;
;     LDA(At, 0, 1); STAGE_A(SA(0, 0), brow, t + 2);
;     BAR; WAIT_L(0); MMA(1, 0, At, B0); BAR; SCHED;
;     STAGE_B(SB(0, 1), bcol + HALF, t + 2);
;     WAIT_V(6); BAR; MMA(1, 1, At, B1); BAR;
;     LDB(B0, 1, 0); SCHED; LDA(At, 1, 0); STAGE_A(SA(0, 1), brow + HALF, t + 2);
;     WAIT_L(8); BAR; WAIT_L(0); MMA(0, 0, At, B0); BAR; SCHED;
;     LDB(B1, 1, 1); STAGE_B(SB(1, 0), bcol, t + 3);
;     BAR; WAIT_L(0); MMA(0, 1, At, B1); BAR;
;     LDA(At, 1, 1); STAGE_A(SA(1, 0), brow, t + 3);
;     BAR; WAIT_L(0); MMA(1, 0, At, B0); BAR; SCHED;
;     STAGE_B(SB(1, 1), bcol + HALF, t + 3);
;     WAIT_V(6); BAR; MMA(1, 1, At, B1); BAR;
	v_mfma_f32_16x16x32_bf16 v[76:79], v[214:217], v[198:201], v[76:79]
	v_mfma_f32_16x16x32_bf16 v[72:75], v[246:249], v[198:201], v[72:75]
	v_mfma_f32_16x16x32_bf16 v[68:71], v[214:217], v[206:209], v[68:71]
	v_mfma_f32_16x16x32_bf16 v[64:67], v[246:249], v[206:209], v[64:67]
	s_setprio 0
	v_add_u32_e32 v155, s30, v142
	v_lshl_add_u64 v[232:233], s[26:27], 0, v[130:131]
	v_readfirstlane_b32 s35, v155
	v_lshl_add_u64 v[156:157], v[232:233], 0, s[42:43]
	s_mov_b32 m0, s35
	global_load_lds_dwordx4 v[156:157], off
	v_add_u32_e32 v156, 0x2000, v155
	v_lshl_add_u64 v[234:235], s[26:27], 0, v[132:133]
	v_readfirstlane_b32 s35, v156
	v_lshl_add_u64 v[236:237], v[234:235], 0, s[42:43]
	s_mov_b32 m0, s35
	s_nop 0
	global_load_lds_dwordx4 v[236:237], off
	v_readfirstlane_b32 s35, v147
	v_lshl_add_u64 v[236:237], v[222:223], 0, s[4:5]
	s_mov_b32 m0, s35
	v_readfirstlane_b32 s35, v146
	ds_read_b128 v[176:179], v148 offset:16384
	ds_read_b128 v[182:185], v148 offset:17408
	ds_read_b128 v[186:189], v148 offset:18432
	ds_read_b128 v[190:193], v148 offset:19456
	ds_read_b128 v[194:197], v148 offset:20480
	ds_read_b128 v[198:201], v148 offset:21504
	ds_read_b128 v[202:205], v148 offset:22528
	ds_read_b128 v[206:209], v148 offset:23552
	global_load_lds_dwordx4 v[236:237], off
	v_lshl_add_u64 v[236:237], v[230:231], 0, s[4:5]
	s_mov_b32 m0, s35
	s_nop 0
	global_load_lds_dwordx4 v[236:237], off
	v_readfirstlane_b32 s35, v141
	v_add_u32_e32 v157, 0x2000, v141
	v_lshl_add_u64 v[250:251], v[232:233], 0, s[46:47]
	s_mov_b32 m0, s35
	v_readfirstlane_b32 s35, v157
	global_load_lds_dwordx4 v[250:251], off
	v_lshl_add_u64 v[250:251], v[234:235], 0, s[46:47]
	s_mov_b32 m0, s35
	s_nop 0
	global_load_lds_dwordx4 v[250:251], off
	s_waitcnt lgkmcnt(0)
	s_waitcnt vmcnt(8)
	s_barrier
	s_setprio 1
	v_mfma_f32_16x16x32_bf16 v[60:63], v[160:163], v[176:179], 0
	v_mfma_f32_16x16x32_bf16 v[56:59], v[168:171], v[176:179], 0
	v_mfma_f32_16x16x32_bf16 v[52:55], v[160:163], v[186:189], 0
	v_mfma_f32_16x16x32_bf16 v[48:51], v[168:171], v[186:189], 0
	v_mfma_f32_16x16x32_bf16 v[44:47], v[160:163], v[194:197], 0
	v_mfma_f32_16x16x32_bf16 v[40:43], v[168:171], v[194:197], 0
	v_mfma_f32_16x16x32_bf16 v[36:39], v[160:163], v[202:205], 0
	v_mfma_f32_16x16x32_bf16 v[32:35], v[168:171], v[202:205], 0
	v_mfma_f32_16x16x32_bf16 v[60:63], v[164:167], v[182:185], v[60:63]
	v_mfma_f32_16x16x32_bf16 v[56:59], v[172:175], v[182:185], v[56:59]
	v_mfma_f32_16x16x32_bf16 v[52:55], v[164:167], v[190:193], v[52:55]
	v_mfma_f32_16x16x32_bf16 v[48:51], v[172:175], v[190:193], v[48:51]
	v_mfma_f32_16x16x32_bf16 v[44:47], v[164:167], v[198:201], v[44:47]
	v_mfma_f32_16x16x32_bf16 v[40:43], v[172:175], v[198:201], v[40:43]
	v_mfma_f32_16x16x32_bf16 v[36:39], v[164:167], v[206:209], v[36:39]
	v_mfma_f32_16x16x32_bf16 v[32:35], v[172:175], v[206:209], v[32:35]
	v_mfma_f32_16x16x32_bf16 v[28:31], v[210:213], v[176:179], 0
	v_mfma_f32_16x16x32_bf16 v[24:27], v[218:221], v[176:179], 0
	v_mfma_f32_16x16x32_bf16 v[20:23], v[210:213], v[186:189], 0
	v_mfma_f32_16x16x32_bf16 v[16:19], v[218:221], v[186:189], 0
	v_mfma_f32_16x16x32_bf16 v[12:15], v[210:213], v[194:197], 0
	v_mfma_f32_16x16x32_bf16 v[8:11], v[218:221], v[194:197], 0
	v_mfma_f32_16x16x32_bf16 v[4:7], v[210:213], v[202:205], 0
	v_mfma_f32_16x16x32_bf16 v[0:3], v[218:221], v[202:205], 0
	v_mfma_f32_16x16x32_bf16 v[28:31], v[214:217], v[182:185], v[28:31]
	v_mfma_f32_16x16x32_bf16 v[24:27], v[246:249], v[182:185], v[24:27]
	v_mfma_f32_16x16x32_bf16 v[20:23], v[214:217], v[190:193], v[20:23]
	v_mfma_f32_16x16x32_bf16 v[16:19], v[246:249], v[190:193], v[16:19]
	s_setprio 2
	s_barrier
	v_mfma_f32_16x16x32_bf16 v[12:15], v[214:217], v[198:201], v[12:15]
	v_mfma_f32_16x16x32_bf16 v[8:11], v[246:249], v[198:201], v[8:11]
	v_mfma_f32_16x16x32_bf16 v[4:7], v[214:217], v[206:209], v[4:7]
	v_mfma_f32_16x16x32_bf16 v[0:3], v[246:249], v[206:209], v[0:3]
	s_setprio 0
	ds_read_b128 v[160:163], v149 offset:32768
	ds_read_b128 v[164:167], v149 offset:33792
	ds_read_b128 v[168:171], v149 offset:34816
	ds_read_b128 v[172:175], v149 offset:35840
	v_readfirstlane_b32 s35, v140
	v_lshl_add_u64 v[210:211], v[222:223], 0, s[96:97]
	s_mov_b32 m0, s35
	v_readfirstlane_b32 s35, v138
	ds_read_b128 v[176:179], v148 offset:32768
	ds_read_b128 v[182:185], v148 offset:33792
	ds_read_b128 v[186:189], v148 offset:34816
	ds_read_b128 v[190:193], v148 offset:35840
	ds_read_b128 v[194:197], v148 offset:36864
	ds_read_b128 v[198:201], v148 offset:37888
	ds_read_b128 v[202:205], v148 offset:38912
	ds_read_b128 v[206:209], v148 offset:39936
	global_load_lds_dwordx4 v[210:211], off
	v_lshl_add_u64 v[210:211], v[230:231], 0, s[96:97]
	s_mov_b32 m0, s35
	s_nop 0
	global_load_lds_dwordx4 v[210:211], off
	ds_read_b128 v[210:213], v149 offset:49152
	ds_read_b128 v[214:217], v149 offset:50176
	ds_read_b128 v[218:221], v149 offset:51200
	ds_read_b128 v[246:249], v149 offset:52224
	s_waitcnt lgkmcnt(0)
	s_waitcnt vmcnt(8)
	s_barrier
; #define STAGE_A(P, br, kt) do { const char* _base = (const char*)(((kt) < G.ksplit ? G.A1 : A2m) + (long)(br) * G.lda + (long)(kt) * BK); \
;     __builtin_amdgcn_global_load_lds((const unsigned*)(_base + aoff0), (unsigned*)((char*)(P) + sb0), 16, 0, 0); \
;     __builtin_amdgcn_global_load_lds((const unsigned*)(_base + aoff1), (unsigned*)((char*)(P) + sb1), 16, 0, 0); } while (0)
; #define STAGE_B(P, br, kt) do { const char* _base = (const char*)(G.Bt + (long)(br) * G.ldb + (long)(kt) * BK); \
;     __builtin_amdgcn_global_load_lds((const unsigned*)(_base + boff0), (unsigned*)((char*)(P) + sb0), 16, 0, 0); \
;     __builtin_amdgcn_global_load_lds((const unsigned*)(_base + boff1), (unsigned*)((char*)(P) + sb1), 16, 0, 0); } while (0)
; #define LDA(dst, b, h) for (int m = 0; m < 4; ++m) for (int k = 0; k < 2; ++k) \
;     dst[m][k] = *reinterpret_cast<const bf16x8*>(a_rd + ((b) * 2 + (h)) * (HT * 2) + m * 2048 + k * 1024)
; #define LDB(dst, b, h) for (int n = 0; n < 2; ++n) for (int k = 0; k < 2; ++k) \
;     dst[n][k] = *reinterpret_cast<const bf16x8*>(b_rd + ((b) * 2 + (h)) * (HT * 2) + n * 2048 + k * 1024)
; #define MMA(ai, bj, At_, Bt_) do { __builtin_amdgcn_s_setprio(1); \
;     for (int m = 0; m < 4; ++m) for (int n = 0; n < 2; ++n) for (int k = 0; k < 2; ++k) \
;       acc[ai][bj][m][n] = __builtin_amdgcn_mfma_f32_16x16x32_bf16(Bt_[n][k], At_[m][k], acc[ai][bj][m][n], 0, 0, 0); \
;     __builtin_amdgcn_s_setprio(0); } while (0)
;     ...
;   for (int t = 0; t < nt - 2; t += 2) {
;     LDB(B0, 0, 0); SCHED; LDA(At, 0, 0); STAGE_A(SA(1, 1), brow + HALF, t + 1);
;     WAIT_L(8); BAR; WAIT_L(0); MMA(0, 0, At, B0); BAR; SCHED;
;     LDB(B1, 0, 1); STAGE_B(SB(0, 0), bcol, t + 2);
;     BAR; WAIT_L(0); MMA(0, 1, At, B1); BAR;
;     LDA(At, 0, 1); STAGE_A(SA(0, 0), brow, t + 2);
;     BAR; WAIT_L(0); MMA(1, 0, At, B0); BAR; SCHED;
;     STAGE_B(SB(0, 1), bcol + HALF, t + 2);
;     WAIT_V(6); BAR; MMA(1, 1, At, B1); BAR;
;     LDB(B0, 1, 0); SCHED; LDA(At, 1, 0); STAGE_A(SA(0, 1), brow + HALF, t + 2);
;     WAIT_L(8); BAR; WAIT_L(0); MMA(0, 0, At, B0); BAR; SCHED;
;     LDB(B1, 1, 1); STAGE_B(SB(1, 0), bcol, t + 3);
;     BAR; WAIT_L(0); MMA(0, 1, At, B1); BAR;
;     LDA(At, 1, 1); STAGE_A(SA(1, 0), brow, t + 3);
;     BAR; WAIT_L(0); MMA(1, 0, At, B0); BAR; SCHED;
;     STAGE_B(SB(1, 1), bcol + HALF, t + 3);
;     WAIT_V(6); BAR; MMA(1, 1, At, B1); BAR;
	s_setprio 1
	v_mfma_f32_16x16x32_bf16 v[124:127], v[160:163], v[176:179], v[124:127]
	v_mfma_f32_16x16x32_bf16 v[120:123], v[168:171], v[176:179], v[120:123]
	v_mfma_f32_16x16x32_bf16 v[116:119], v[160:163], v[186:189], v[116:119]
	v_mfma_f32_16x16x32_bf16 v[112:115], v[168:171], v[186:189], v[112:115]
	v_mfma_f32_16x16x32_bf16 v[108:111], v[160:163], v[194:197], v[108:111]
	v_mfma_f32_16x16x32_bf16 v[104:107], v[168:171], v[194:197], v[104:107]
	v_mfma_f32_16x16x32_bf16 v[100:103], v[160:163], v[202:205], v[100:103]
	v_mfma_f32_16x16x32_bf16 v[96:99], v[168:171], v[202:205], v[96:99]
	v_mfma_f32_16x16x32_bf16 v[124:127], v[164:167], v[182:185], v[124:127]
	v_mfma_f32_16x16x32_bf16 v[120:123], v[172:175], v[182:185], v[120:123]
	v_mfma_f32_16x16x32_bf16 v[116:119], v[164:167], v[190:193], v[116:119]
	v_mfma_f32_16x16x32_bf16 v[112:115], v[172:175], v[190:193], v[112:115]
	v_mfma_f32_16x16x32_bf16 v[108:111], v[164:167], v[198:201], v[108:111]
	v_mfma_f32_16x16x32_bf16 v[104:107], v[172:175], v[198:201], v[104:107]
	v_mfma_f32_16x16x32_bf16 v[100:103], v[164:167], v[206:209], v[100:103]
	v_mfma_f32_16x16x32_bf16 v[96:99], v[172:175], v[206:209], v[96:99]
	v_mfma_f32_16x16x32_bf16 v[92:95], v[210:213], v[176:179], v[92:95]
	v_mfma_f32_16x16x32_bf16 v[88:91], v[218:221], v[176:179], v[88:91]
	v_mfma_f32_16x16x32_bf16 v[84:87], v[210:213], v[186:189], v[84:87]
	v_mfma_f32_16x16x32_bf16 v[80:83], v[218:221], v[186:189], v[80:83]
	v_mfma_f32_16x16x32_bf16 v[76:79], v[210:213], v[194:197], v[76:79]
	v_mfma_f32_16x16x32_bf16 v[72:75], v[218:221], v[194:197], v[72:75]
	v_mfma_f32_16x16x32_bf16 v[68:71], v[210:213], v[202:205], v[68:71]
	v_mfma_f32_16x16x32_bf16 v[64:67], v[218:221], v[202:205], v[64:67]
	v_mfma_f32_16x16x32_bf16 v[92:95], v[214:217], v[182:185], v[92:95]
	v_mfma_f32_16x16x32_bf16 v[88:91], v[246:249], v[182:185], v[88:91]
	v_mfma_f32_16x16x32_bf16 v[84:87], v[214:217], v[190:193], v[84:87]
	v_mfma_f32_16x16x32_bf16 v[80:83], v[246:249], v[190:193], v[80:83]
	s_setprio 2
	s_barrier
	v_mfma_f32_16x16x32_bf16 v[76:79], v[214:217], v[198:201], v[76:79]
	v_mfma_f32_16x16x32_bf16 v[72:75], v[246:249], v[198:201], v[72:75]
	v_mfma_f32_16x16x32_bf16 v[68:71], v[214:217], v[206:209], v[68:71]
	v_mfma_f32_16x16x32_bf16 v[64:67], v[246:249], v[206:209], v[64:67]
	s_setprio 0
	v_readfirstlane_b32 s35, v145
	v_lshl_add_u64 v[236:237], v[232:233], 0, s[44:45]
	s_mov_b32 m0, s35
	v_readfirstlane_b32 s35, v150
	global_load_lds_dwordx4 v[236:237], off
	v_lshl_add_u64 v[236:237], v[234:235], 0, s[44:45]
	s_mov_b32 m0, s35
	s_nop 0
	global_load_lds_dwordx4 v[236:237], off
	v_readfirstlane_b32 s35, v151
	v_lshl_add_u64 v[222:223], v[222:223], 0, s[2:3]
	s_mov_b32 m0, s35
	v_readfirstlane_b32 s35, v152
	ds_read_b128 v[176:179], v148 offset:49152
	ds_read_b128 v[182:185], v148 offset:50176
	ds_read_b128 v[186:189], v148 offset:51200
	ds_read_b128 v[190:193], v148 offset:52224
	ds_read_b128 v[194:197], v148 offset:53248
	ds_read_b128 v[198:201], v148 offset:54272
	ds_read_b128 v[202:205], v148 offset:55296
	ds_read_b128 v[206:209], v148 offset:56320
	global_load_lds_dwordx4 v[222:223], off
	v_lshl_add_u64 v[222:223], v[230:231], 0, s[2:3]
	s_mov_b32 m0, s35
	s_nop 0
	global_load_lds_dwordx4 v[222:223], off
	v_readfirstlane_b32 s35, v153
	v_lshl_add_u64 v[250:251], v[232:233], 0, s[48:49]
	s_mov_b32 m0, s35
	v_readfirstlane_b32 s35, v154
	global_load_lds_dwordx4 v[250:251], off
	v_lshl_add_u64 v[250:251], v[234:235], 0, s[48:49]
	s_mov_b32 m0, s35
	s_nop 0
	global_load_lds_dwordx4 v[250:251], off
	s_waitcnt lgkmcnt(0)
	s_waitcnt vmcnt(8)
	s_barrier
	s_setprio 1
	v_mfma_f32_16x16x32_bf16 v[60:63], v[160:163], v[176:179], v[60:63]
	v_mfma_f32_16x16x32_bf16 v[56:59], v[168:171], v[176:179], v[56:59]
	v_mfma_f32_16x16x32_bf16 v[52:55], v[160:163], v[186:189], v[52:55]
	v_mfma_f32_16x16x32_bf16 v[48:51], v[168:171], v[186:189], v[48:51]
	v_mfma_f32_16x16x32_bf16 v[44:47], v[160:163], v[194:197], v[44:47]
	v_mfma_f32_16x16x32_bf16 v[40:43], v[168:171], v[194:197], v[40:43]
	v_mfma_f32_16x16x32_bf16 v[36:39], v[160:163], v[202:205], v[36:39]
	v_mfma_f32_16x16x32_bf16 v[32:35], v[168:171], v[202:205], v[32:35]
	v_mfma_f32_16x16x32_bf16 v[60:63], v[164:167], v[182:185], v[60:63]
	v_mfma_f32_16x16x32_bf16 v[56:59], v[172:175], v[182:185], v[56:59]
	v_mfma_f32_16x16x32_bf16 v[52:55], v[164:167], v[190:193], v[52:55]
	v_mfma_f32_16x16x32_bf16 v[48:51], v[172:175], v[190:193], v[48:51]
	v_mfma_f32_16x16x32_bf16 v[44:47], v[164:167], v[198:201], v[44:47]
	v_mfma_f32_16x16x32_bf16 v[40:43], v[172:175], v[198:201], v[40:43]
	v_mfma_f32_16x16x32_bf16 v[36:39], v[164:167], v[206:209], v[36:39]
	v_mfma_f32_16x16x32_bf16 v[32:35], v[172:175], v[206:209], v[32:35]
	v_mfma_f32_16x16x32_bf16 v[28:31], v[210:213], v[176:179], v[28:31]
	v_mfma_f32_16x16x32_bf16 v[24:27], v[218:221], v[176:179], v[24:27]
	v_mfma_f32_16x16x32_bf16 v[20:23], v[210:213], v[186:189], v[20:23]
	v_mfma_f32_16x16x32_bf16 v[16:19], v[218:221], v[186:189], v[16:19]
	v_mfma_f32_16x16x32_bf16 v[12:15], v[210:213], v[194:197], v[12:15]
	v_mfma_f32_16x16x32_bf16 v[8:11], v[218:221], v[194:197], v[8:11]
	v_mfma_f32_16x16x32_bf16 v[4:7], v[210:213], v[202:205], v[4:7]
	v_mfma_f32_16x16x32_bf16 v[0:3], v[218:221], v[202:205], v[0:3]
	v_mfma_f32_16x16x32_bf16 v[28:31], v[214:217], v[182:185], v[28:31]
	v_mfma_f32_16x16x32_bf16 v[24:27], v[246:249], v[182:185], v[24:27]
	v_mfma_f32_16x16x32_bf16 v[20:23], v[214:217], v[190:193], v[20:23]
	v_mfma_f32_16x16x32_bf16 v[16:19], v[246:249], v[190:193], v[16:19]
	s_setprio 2
	s_barrier
	v_mfma_f32_16x16x32_bf16 v[12:15], v[214:217], v[198:201], v[12:15]
	v_mfma_f32_16x16x32_bf16 v[8:11], v[246:249], v[198:201], v[8:11]
	v_mfma_f32_16x16x32_bf16 v[4:7], v[214:217], v[206:209], v[4:7]
	v_mfma_f32_16x16x32_bf16 v[0:3], v[246:249], v[206:209], v[0:3]
	s_setprio 0
	s_add_i32 s31, s31, 2
	s_add_u32 s26, s26, 0x100
	s_addc_u32 s27, s27, 0
	s_cmp_lt_u32 s31, 28
	s_cbranch_scc0 .Lmy_kexit_2
; #define STAGE_A(P, br, kt) do { const char* _base = (const char*)(((kt) < G.ksplit ? G.A1 : A2m) + (long)(br) * G.lda + (long)(kt) * BK); \
;     __builtin_amdgcn_global_load_lds((const unsigned*)(_base + aoff0), (unsigned*)((char*)(P) + sb0), 16, 0, 0); \
;     __builtin_amdgcn_global_load_lds((const unsigned*)(_base + aoff1), (unsigned*)((char*)(P) + sb1), 16, 0, 0); } while (0)
; #define STAGE_B(P, br, kt) do { const char* _base = (const char*)(G.Bt + (long)(br) * G.ldb + (long)(kt) * BK); \
;     __builtin_amdgcn_global_load_lds((const unsigned*)(_base + boff0), (unsigned*)((char*)(P) + sb0), 16, 0, 0); \
;     __builtin_amdgcn_global_load_lds((const unsigned*)(_base + boff1), (unsigned*)((char*)(P) + sb1), 16, 0, 0); } while (0)
; #define LDA(dst, b, h) for (int m = 0; m < 4; ++m) for (int k = 0; k < 2; ++k) \
;     dst[m][k] = *reinterpret_cast<const bf16x8*>(a_rd + ((b) * 2 + (h)) * (HT * 2) + m * 2048 + k * 1024)
; #define LDB(dst, b, h) for (int n = 0; n < 2; ++n) for (int k = 0; k < 2; ++k) \
;     dst[n][k] = *reinterpret_cast<const bf16x8*>(b_rd + ((b) * 2 + (h)) * (HT * 2) + n * 2048 + k * 1024)
; #define MMA(ai, bj, At_, Bt_) do { __builtin_amdgcn_s_setprio(1); \
;     for (int m = 0; m < 4; ++m) for (int n = 0; n < 2; ++n) for (int k = 0; k < 2; ++k) \
;       acc[ai][bj][m][n] = __builtin_amdgcn_mfma_f32_16x16x32_bf16(Bt_[n][k], At_[m][k], acc[ai][bj][m][n], 0, 0, 0); \
;     __builtin_amdgcn_s_setprio(0); } while (0)
;     ...
;   for (int t = 0; t < nt - 2; t += 2) {
;     LDB(B0, 0, 0); SCHED; LDA(At, 0, 0); STAGE_A(SA(1, 1), brow + HALF, t + 1);
;     WAIT_L(8); BAR; WAIT_L(0); MMA(0, 0, At, B0); BAR; SCHED;
;     LDB(B1, 0, 1); STAGE_B(SB(0, 0), bcol, t + 2);
;     BAR; WAIT_L(0); MMA(0, 1, At, B1); BAR;
;     LDA(At, 0, 1); STAGE_A(SA(0, 0), brow, t + 2);
;     BAR; WAIT_L(0); MMA(1, 0, At, B0); BAR; SCHED;
;     STAGE_B(SB(0, 1), bcol + HALF, t + 2);
;     WAIT_V(6); BAR; MMA(1, 1, At, B1); BAR;
;     LDB(B0, 1, 0); SCHED; LDA(At, 1, 0); STAGE_A(SA(0, 1), brow + HALF, t + 2);
;     WAIT_L(8); BAR; WAIT_L(0); MMA(0, 0, At, B0); BAR; SCHED;
;     LDB(B1, 1, 1); STAGE_B(SB(1, 0), bcol, t + 3);
;     BAR; WAIT_L(0); MMA(0, 1, At, B1); BAR;
;     LDA(At, 1, 1); STAGE_A(SA(1, 0), brow, t + 3);
;     BAR; WAIT_L(0); MMA(1, 0, At, B0); BAR; SCHED;
;     STAGE_B(SB(1, 1), bcol + HALF, t + 3);
;     WAIT_V(6); BAR; MMA(1, 1, At, B1); BAR;
.LBB0_1865:
	ds_read_b128 v[160:163], v149
	ds_read_b128 v[164:167], v149 offset:1024
	ds_read_b128 v[168:171], v149 offset:2048
	ds_read_b128 v[172:175], v149 offset:3072
	v_add_u32_e32 v158, 0xc000, v147
	v_lshl_add_u64 v[222:223], s[26:27], 0, v[134:135]
	v_readfirstlane_b32 s35, v158
	v_add_u32_e32 v159, 0xe000, v147
	v_lshl_add_u64 v[156:157], v[222:223], 0, s[94:95]
	s_mov_b32 m0, s35
	v_lshl_add_u64 v[230:231], s[26:27], 0, v[136:137]
	v_readfirstlane_b32 s35, v159
	ds_read_b128 v[176:179], v148
	ds_read_b128 v[182:185], v148 offset:1024
	ds_read_b128 v[186:189], v148 offset:2048
	ds_read_b128 v[190:193], v148 offset:3072
	ds_read_b128 v[194:197], v148 offset:4096
	ds_read_b128 v[198:201], v148 offset:5120
	ds_read_b128 v[202:205], v148 offset:6144
	ds_read_b128 v[206:209], v148 offset:7168
	global_load_lds_dwordx4 v[156:157], off
	v_lshl_add_u64 v[156:157], v[230:231], 0, s[94:95]
	s_mov_b32 m0, s35
	s_nop 0
	global_load_lds_dwordx4 v[156:157], off
	ds_read_b128 v[210:213], v149 offset:16384
	ds_read_b128 v[214:217], v149 offset:17408
	ds_read_b128 v[218:221], v149 offset:18432
	ds_read_b128 v[246:249], v149 offset:19456
	s_waitcnt lgkmcnt(0)
	s_waitcnt vmcnt(8)
	s_barrier
	s_setprio 1
	v_mfma_f32_16x16x32_bf16 v[124:127], v[160:163], v[176:179], v[124:127]
	v_mfma_f32_16x16x32_bf16 v[120:123], v[168:171], v[176:179], v[120:123]
	v_mfma_f32_16x16x32_bf16 v[116:119], v[160:163], v[186:189], v[116:119]
	v_mfma_f32_16x16x32_bf16 v[112:115], v[168:171], v[186:189], v[112:115]
	v_mfma_f32_16x16x32_bf16 v[108:111], v[160:163], v[194:197], v[108:111]
	v_mfma_f32_16x16x32_bf16 v[104:107], v[168:171], v[194:197], v[104:107]
	v_mfma_f32_16x16x32_bf16 v[100:103], v[160:163], v[202:205], v[100:103]
	v_mfma_f32_16x16x32_bf16 v[96:99], v[168:171], v[202:205], v[96:99]
	v_mfma_f32_16x16x32_bf16 v[124:127], v[164:167], v[182:185], v[124:127]
	v_mfma_f32_16x16x32_bf16 v[120:123], v[172:175], v[182:185], v[120:123]
	v_mfma_f32_16x16x32_bf16 v[116:119], v[164:167], v[190:193], v[116:119]
	v_mfma_f32_16x16x32_bf16 v[112:115], v[172:175], v[190:193], v[112:115]
	v_mfma_f32_16x16x32_bf16 v[108:111], v[164:167], v[198:201], v[108:111]
	v_mfma_f32_16x16x32_bf16 v[104:107], v[172:175], v[198:201], v[104:107]
	v_mfma_f32_16x16x32_bf16 v[100:103], v[164:167], v[206:209], v[100:103]
	v_mfma_f32_16x16x32_bf16 v[96:99], v[172:175], v[206:209], v[96:99]
	v_mfma_f32_16x16x32_bf16 v[92:95], v[210:213], v[176:179], v[92:95]
	v_mfma_f32_16x16x32_bf16 v[88:91], v[218:221], v[176:179], v[88:91]
	v_mfma_f32_16x16x32_bf16 v[84:87], v[210:213], v[186:189], v[84:87]
	v_mfma_f32_16x16x32_bf16 v[80:83], v[218:221], v[186:189], v[80:83]
	v_mfma_f32_16x16x32_bf16 v[76:79], v[210:213], v[194:197], v[76:79]
	v_mfma_f32_16x16x32_bf16 v[72:75], v[218:221], v[194:197], v[72:75]
	v_mfma_f32_16x16x32_bf16 v[68:71], v[210:213], v[202:205], v[68:71]
	v_mfma_f32_16x16x32_bf16 v[64:67], v[218:221], v[202:205], v[64:67]
	v_mfma_f32_16x16x32_bf16 v[92:95], v[214:217], v[182:185], v[92:95]
	v_mfma_f32_16x16x32_bf16 v[88:91], v[246:249], v[182:185], v[88:91]
	v_mfma_f32_16x16x32_bf16 v[84:87], v[214:217], v[190:193], v[84:87]
	v_mfma_f32_16x16x32_bf16 v[80:83], v[246:249], v[190:193], v[80:83]
	s_setprio 2
	s_barrier
	v_mfma_f32_16x16x32_bf16 v[76:79], v[214:217], v[198:201], v[76:79]
	v_mfma_f32_16x16x32_bf16 v[72:75], v[246:249], v[198:201], v[72:75]
	v_mfma_f32_16x16x32_bf16 v[68:71], v[214:217], v[206:209], v[68:71]
	v_mfma_f32_16x16x32_bf16 v[64:67], v[246:249], v[206:209], v[64:67]
	s_setprio 0
	v_add_u32_e32 v155, s30, v142
	v_lshl_add_u64 v[232:233], s[26:27], 0, v[130:131]
	v_readfirstlane_b32 s35, v155
	v_lshl_add_u64 v[156:157], v[232:233], 0, s[42:43]
	s_mov_b32 m0, s35
	global_load_lds_dwordx4 v[156:157], off
	v_add_u32_e32 v156, 0x2000, v155
	v_lshl_add_u64 v[234:235], s[26:27], 0, v[132:133]
	v_readfirstlane_b32 s35, v156
	v_lshl_add_u64 v[236:237], v[234:235], 0, s[42:43]
	s_mov_b32 m0, s35
	s_nop 0
	global_load_lds_dwordx4 v[236:237], off
	v_readfirstlane_b32 s35, v147
	v_lshl_add_u64 v[236:237], v[222:223], 0, s[4:5]
	s_mov_b32 m0, s35
	v_readfirstlane_b32 s35, v146
	ds_read_b128 v[176:179], v148 offset:16384
	ds_read_b128 v[182:185], v148 offset:17408
	ds_read_b128 v[186:189], v148 offset:18432
	ds_read_b128 v[190:193], v148 offset:19456
	ds_read_b128 v[194:197], v148 offset:20480
	ds_read_b128 v[198:201], v148 offset:21504
	ds_read_b128 v[202:205], v148 offset:22528
	ds_read_b128 v[206:209], v148 offset:23552
	global_load_lds_dwordx4 v[236:237], off
	v_lshl_add_u64 v[236:237], v[230:231], 0, s[4:5]
	s_mov_b32 m0, s35
	s_nop 0
	global_load_lds_dwordx4 v[236:237], off
	v_readfirstlane_b32 s35, v141
	v_add_u32_e32 v157, 0x2000, v141
	v_lshl_add_u64 v[250:251], v[232:233], 0, s[46:47]
	s_mov_b32 m0, s35
	v_readfirstlane_b32 s35, v157
	global_load_lds_dwordx4 v[250:251], off
	v_lshl_add_u64 v[250:251], v[234:235], 0, s[46:47]
	s_mov_b32 m0, s35
	s_nop 0
	global_load_lds_dwordx4 v[250:251], off
	s_waitcnt lgkmcnt(0)
	s_waitcnt vmcnt(8)
	s_barrier
; #define STAGE_A(P, br, kt) do { const char* _base = (const char*)(((kt) < G.ksplit ? G.A1 : A2m) + (long)(br) * G.lda + (long)(kt) * BK); \
;     __builtin_amdgcn_global_load_lds((const unsigned*)(_base + aoff0), (unsigned*)((char*)(P) + sb0), 16, 0, 0); \
;     __builtin_amdgcn_global_load_lds((const unsigned*)(_base + aoff1), (unsigned*)((char*)(P) + sb1), 16, 0, 0); } while (0)
; #define STAGE_B(P, br, kt) do { const char* _base = (const char*)(G.Bt + (long)(br) * G.ldb + (long)(kt) * BK); \
;     __builtin_amdgcn_global_load_lds((const unsigned*)(_base + boff0), (unsigned*)((char*)(P) + sb0), 16, 0, 0); \
;     __builtin_amdgcn_global_load_lds((const unsigned*)(_base + boff1), (unsigned*)((char*)(P) + sb1), 16, 0, 0); } while (0)
; #define LDA(dst, b, h) for (int m = 0; m < 4; ++m) for (int k = 0; k < 2; ++k) \
;     dst[m][k] = *reinterpret_cast<const bf16x8*>(a_rd + ((b) * 2 + (h)) * (HT * 2) + m * 2048 + k * 1024)
; #define LDB(dst, b, h) for (int n = 0; n < 2; ++n) for (int k = 0; k < 2; ++k) \
;     dst[n][k] = *reinterpret_cast<const bf16x8*>(b_rd + ((b) * 2 + (h)) * (HT * 2) + n * 2048 + k * 1024)
; #define MMA(ai, bj, At_, Bt_) do { __builtin_amdgcn_s_setprio(1); \
;     for (int m = 0; m < 4; ++m) for (int n = 0; n < 2; ++n) for (int k = 0; k < 2; ++k) \
;       acc[ai][bj][m][n] = __builtin_amdgcn_mfma_f32_16x16x32_bf16(Bt_[n][k], At_[m][k], acc[ai][bj][m][n], 0, 0, 0); \
;     __builtin_amdgcn_s_setprio(0); } while (0)
;     ...
;   for (int t = 0; t < nt - 2; t += 2) {
;     LDB(B0, 0, 0); SCHED; LDA(At, 0, 0); STAGE_A(SA(1, 1), brow + HALF, t + 1);
;     WAIT_L(8); BAR; WAIT_L(0); MMA(0, 0, At, B0); BAR; SCHED;
;     LDB(B1, 0, 1); STAGE_B(SB(0, 0), bcol, t + 2);
;     BAR; WAIT_L(0); MMA(0, 1, At, B1); BAR;
;     LDA(At, 0, 1); STAGE_A(SA(0, 0), brow, t + 2);
;     BAR; WAIT_L(0); MMA(1, 0, At, B0); BAR; SCHED;
;     STAGE_B(SB(0, 1), bcol + HALF, t + 2);
;     WAIT_V(6); BAR; MMA(1, 1, At, B1); BAR;
;     LDB(B0, 1, 0); SCHED; LDA(At, 1, 0); STAGE_A(SA(0, 1), brow + HALF, t + 2);
;     WAIT_L(8); BAR; WAIT_L(0); MMA(0, 0, At, B0); BAR; SCHED;
;     LDB(B1, 1, 1); STAGE_B(SB(1, 0), bcol, t + 3);
;     BAR; WAIT_L(0); MMA(0, 1, At, B1); BAR;
;     LDA(At, 1, 1); STAGE_A(SA(1, 0), brow, t + 3);
;     BAR; WAIT_L(0); MMA(1, 0, At, B0); BAR; SCHED;
;     STAGE_B(SB(1, 1), bcol + HALF, t + 3);
;     WAIT_V(6); BAR; MMA(1, 1, At, B1); BAR;
	s_setprio 1
	v_mfma_f32_16x16x32_bf16 v[60:63], v[160:163], v[176:179], v[60:63]
	v_mfma_f32_16x16x32_bf16 v[56:59], v[168:171], v[176:179], v[56:59]
	v_mfma_f32_16x16x32_bf16 v[52:55], v[160:163], v[186:189], v[52:55]
	v_mfma_f32_16x16x32_bf16 v[48:51], v[168:171], v[186:189], v[48:51]
	v_mfma_f32_16x16x32_bf16 v[44:47], v[160:163], v[194:197], v[44:47]
	v_mfma_f32_16x16x32_bf16 v[40:43], v[168:171], v[194:197], v[40:43]
	v_mfma_f32_16x16x32_bf16 v[36:39], v[160:163], v[202:205], v[36:39]
	v_mfma_f32_16x16x32_bf16 v[32:35], v[168:171], v[202:205], v[32:35]
	v_mfma_f32_16x16x32_bf16 v[60:63], v[164:167], v[182:185], v[60:63]
	v_mfma_f32_16x16x32_bf16 v[56:59], v[172:175], v[182:185], v[56:59]
	v_mfma_f32_16x16x32_bf16 v[52:55], v[164:167], v[190:193], v[52:55]
	v_mfma_f32_16x16x32_bf16 v[48:51], v[172:175], v[190:193], v[48:51]
	v_mfma_f32_16x16x32_bf16 v[44:47], v[164:167], v[198:201], v[44:47]
	v_mfma_f32_16x16x32_bf16 v[40:43], v[172:175], v[198:201], v[40:43]
	v_mfma_f32_16x16x32_bf16 v[36:39], v[164:167], v[206:209], v[36:39]
	v_mfma_f32_16x16x32_bf16 v[32:35], v[172:175], v[206:209], v[32:35]
	v_mfma_f32_16x16x32_bf16 v[28:31], v[210:213], v[176:179], v[28:31]
	v_mfma_f32_16x16x32_bf16 v[24:27], v[218:221], v[176:179], v[24:27]
	v_mfma_f32_16x16x32_bf16 v[20:23], v[210:213], v[186:189], v[20:23]
	v_mfma_f32_16x16x32_bf16 v[16:19], v[218:221], v[186:189], v[16:19]
	v_mfma_f32_16x16x32_bf16 v[12:15], v[210:213], v[194:197], v[12:15]
	v_mfma_f32_16x16x32_bf16 v[8:11], v[218:221], v[194:197], v[8:11]
	v_mfma_f32_16x16x32_bf16 v[4:7], v[210:213], v[202:205], v[4:7]
	v_mfma_f32_16x16x32_bf16 v[0:3], v[218:221], v[202:205], v[0:3]
	v_mfma_f32_16x16x32_bf16 v[28:31], v[214:217], v[182:185], v[28:31]
	v_mfma_f32_16x16x32_bf16 v[24:27], v[246:249], v[182:185], v[24:27]
	v_mfma_f32_16x16x32_bf16 v[20:23], v[214:217], v[190:193], v[20:23]
	v_mfma_f32_16x16x32_bf16 v[16:19], v[246:249], v[190:193], v[16:19]
	s_setprio 2
	s_barrier
	v_mfma_f32_16x16x32_bf16 v[12:15], v[214:217], v[198:201], v[12:15]
	v_mfma_f32_16x16x32_bf16 v[8:11], v[246:249], v[198:201], v[8:11]
	v_mfma_f32_16x16x32_bf16 v[4:7], v[214:217], v[206:209], v[4:7]
	v_mfma_f32_16x16x32_bf16 v[0:3], v[246:249], v[206:209], v[0:3]
	s_setprio 0
	ds_read_b128 v[160:163], v149 offset:32768
	ds_read_b128 v[164:167], v149 offset:33792
	ds_read_b128 v[168:171], v149 offset:34816
	ds_read_b128 v[172:175], v149 offset:35840
	v_readfirstlane_b32 s35, v140
	v_lshl_add_u64 v[210:211], v[222:223], 0, s[96:97]
	s_mov_b32 m0, s35
	v_readfirstlane_b32 s35, v138
	ds_read_b128 v[176:179], v148 offset:32768
	ds_read_b128 v[182:185], v148 offset:33792
	ds_read_b128 v[186:189], v148 offset:34816
	ds_read_b128 v[190:193], v148 offset:35840
	ds_read_b128 v[194:197], v148 offset:36864
	ds_read_b128 v[198:201], v148 offset:37888
	ds_read_b128 v[202:205], v148 offset:38912
	ds_read_b128 v[206:209], v148 offset:39936
	global_load_lds_dwordx4 v[210:211], off
	v_lshl_add_u64 v[210:211], v[230:231], 0, s[96:97]
	s_mov_b32 m0, s35
	s_nop 0
	global_load_lds_dwordx4 v[210:211], off
	ds_read_b128 v[210:213], v149 offset:49152
	ds_read_b128 v[214:217], v149 offset:50176
	ds_read_b128 v[218:221], v149 offset:51200
	ds_read_b128 v[246:249], v149 offset:52224
	s_waitcnt lgkmcnt(0)
	s_waitcnt vmcnt(8)
	s_barrier
	s_setprio 1
	v_mfma_f32_16x16x32_bf16 v[124:127], v[160:163], v[176:179], v[124:127]
	v_mfma_f32_16x16x32_bf16 v[120:123], v[168:171], v[176:179], v[120:123]
	v_mfma_f32_16x16x32_bf16 v[116:119], v[160:163], v[186:189], v[116:119]
	v_mfma_f32_16x16x32_bf16 v[112:115], v[168:171], v[186:189], v[112:115]
	v_mfma_f32_16x16x32_bf16 v[108:111], v[160:163], v[194:197], v[108:111]
	v_mfma_f32_16x16x32_bf16 v[104:107], v[168:171], v[194:197], v[104:107]
	v_mfma_f32_16x16x32_bf16 v[100:103], v[160:163], v[202:205], v[100:103]
	v_mfma_f32_16x16x32_bf16 v[96:99], v[168:171], v[202:205], v[96:99]
	v_mfma_f32_16x16x32_bf16 v[124:127], v[164:167], v[182:185], v[124:127]
	v_mfma_f32_16x16x32_bf16 v[120:123], v[172:175], v[182:185], v[120:123]
	v_mfma_f32_16x16x32_bf16 v[116:119], v[164:167], v[190:193], v[116:119]
	v_mfma_f32_16x16x32_bf16 v[112:115], v[172:175], v[190:193], v[112:115]
	v_mfma_f32_16x16x32_bf16 v[108:111], v[164:167], v[198:201], v[108:111]
	v_mfma_f32_16x16x32_bf16 v[104:107], v[172:175], v[198:201], v[104:107]
	v_mfma_f32_16x16x32_bf16 v[100:103], v[164:167], v[206:209], v[100:103]
	v_mfma_f32_16x16x32_bf16 v[96:99], v[172:175], v[206:209], v[96:99]
	v_mfma_f32_16x16x32_bf16 v[92:95], v[210:213], v[176:179], v[92:95]
	v_mfma_f32_16x16x32_bf16 v[88:91], v[218:221], v[176:179], v[88:91]
	v_mfma_f32_16x16x32_bf16 v[84:87], v[210:213], v[186:189], v[84:87]
	v_mfma_f32_16x16x32_bf16 v[80:83], v[218:221], v[186:189], v[80:83]
	v_mfma_f32_16x16x32_bf16 v[76:79], v[210:213], v[194:197], v[76:79]
	v_mfma_f32_16x16x32_bf16 v[72:75], v[218:221], v[194:197], v[72:75]
	v_mfma_f32_16x16x32_bf16 v[68:71], v[210:213], v[202:205], v[68:71]
	v_mfma_f32_16x16x32_bf16 v[64:67], v[218:221], v[202:205], v[64:67]
	v_mfma_f32_16x16x32_bf16 v[92:95], v[214:217], v[182:185], v[92:95]
	v_mfma_f32_16x16x32_bf16 v[88:91], v[246:249], v[182:185], v[88:91]
	v_mfma_f32_16x16x32_bf16 v[84:87], v[214:217], v[190:193], v[84:87]
	v_mfma_f32_16x16x32_bf16 v[80:83], v[246:249], v[190:193], v[80:83]
	s_setprio 2
	s_barrier
; #define STAGE_A(P, br, kt) do { const char* _base = (const char*)(((kt) < G.ksplit ? G.A1 : A2m) + (long)(br) * G.lda + (long)(kt) * BK); \
;     __builtin_amdgcn_global_load_lds((const unsigned*)(_base + aoff0), (unsigned*)((char*)(P) + sb0), 16, 0, 0); \
;     __builtin_amdgcn_global_load_lds((const unsigned*)(_base + aoff1), (unsigned*)((char*)(P) + sb1), 16, 0, 0); } while (0)
; #define STAGE_B(P, br, kt) do { const char* _base = (const char*)(G.Bt + (long)(br) * G.ldb + (long)(kt) * BK); \
;     __builtin_amdgcn_global_load_lds((const unsigned*)(_base + boff0), (unsigned*)((char*)(P) + sb0), 16, 0, 0); \
;     __builtin_amdgcn_global_load_lds((const unsigned*)(_base + boff1), (unsigned*)((char*)(P) + sb1), 16, 0, 0); } while (0)
; #define LDA(dst, b, h) for (int m = 0; m < 4; ++m) for (int k = 0; k < 2; ++k) \
;     dst[m][k] = *reinterpret_cast<const bf16x8*>(a_rd + ((b) * 2 + (h)) * (HT * 2) + m * 2048 + k * 1024)
; #define WAIT_V(n) asm volatile("s_waitcnt vmcnt(" #n ")" ::: "memory")
; #define WAIT_L(n) asm volatile("s_waitcnt lgkmcnt(" #n ")" ::: "memory")
;     ...
;   for (int t = 0; t < nt - 2; t += 2) {
;     LDB(B0, 0, 0); SCHED; LDA(At, 0, 0); STAGE_A(SA(1, 1), brow + HALF, t + 1);
;     WAIT_L(8); BAR; WAIT_L(0); MMA(0, 0, At, B0); BAR; SCHED;
;     LDB(B1, 0, 1); STAGE_B(SB(0, 0), bcol, t + 2);
;     BAR; WAIT_L(0); MMA(0, 1, At, B1); BAR;
;     LDA(At, 0, 1); STAGE_A(SA(0, 0), brow, t + 2);
;     BAR; WAIT_L(0); MMA(1, 0, At, B0); BAR; SCHED;
;     STAGE_B(SB(0, 1), bcol + HALF, t + 2);
;     WAIT_V(6); BAR; MMA(1, 1, At, B1); BAR;
;     LDB(B0, 1, 0); SCHED; LDA(At, 1, 0); STAGE_A(SA(0, 1), brow + HALF, t + 2);
;     WAIT_L(8); BAR; WAIT_L(0); MMA(0, 0, At, B0); BAR; SCHED;
;     LDB(B1, 1, 1); STAGE_B(SB(1, 0), bcol, t + 3);
;     BAR; WAIT_L(0); MMA(0, 1, At, B1); BAR;
;     LDA(At, 1, 1); STAGE_A(SA(1, 0), brow, t + 3);
;     BAR; WAIT_L(0); MMA(1, 0, At, B0); BAR; SCHED;
;     STAGE_B(SB(1, 1), bcol + HALF, t + 3);
;     WAIT_V(6); BAR; MMA(1, 1, At, B1); BAR;
;     ...
;   float ssv[2][4] = {};
;   if constexpr (EPI == EPI_GU || EPI == EPI_EVIN || EPI == EPI_ODIN) {
; #pragma unroll
;     for (int ai = 0; ai < 2; ++ai)
; #pragma unroll
;       for (int m = 0; m < 4; ++m) ssv[ai][m] = G.ssr[brow + ai * HALF + wr * 64 + m * 16 + fr];
;   }
;   { LDB(B0, 0, 0); LDA(At, 0, 0); STAGE_A(SA(1, 1), brow + HALF, nt - 1);
	v_mfma_f32_16x16x32_bf16 v[76:79], v[214:217], v[198:201], v[76:79]
	v_mfma_f32_16x16x32_bf16 v[72:75], v[246:249], v[198:201], v[72:75]
	v_mfma_f32_16x16x32_bf16 v[68:71], v[214:217], v[206:209], v[68:71]
	v_mfma_f32_16x16x32_bf16 v[64:67], v[246:249], v[206:209], v[64:67]
	s_setprio 0
	v_readfirstlane_b32 s35, v145
	v_lshl_add_u64 v[236:237], v[232:233], 0, s[44:45]
	s_mov_b32 m0, s35
	v_readfirstlane_b32 s35, v150
	global_load_lds_dwordx4 v[236:237], off
	v_lshl_add_u64 v[236:237], v[234:235], 0, s[44:45]
	s_mov_b32 m0, s35
	s_nop 0
	global_load_lds_dwordx4 v[236:237], off
	v_readfirstlane_b32 s35, v151
	v_lshl_add_u64 v[222:223], v[222:223], 0, s[2:3]
	s_mov_b32 m0, s35
	v_readfirstlane_b32 s35, v152
	ds_read_b128 v[176:179], v148 offset:49152
	ds_read_b128 v[182:185], v148 offset:50176
	ds_read_b128 v[186:189], v148 offset:51200
	ds_read_b128 v[190:193], v148 offset:52224
	ds_read_b128 v[194:197], v148 offset:53248
	ds_read_b128 v[198:201], v148 offset:54272
	ds_read_b128 v[202:205], v148 offset:55296
	ds_read_b128 v[206:209], v148 offset:56320
	global_load_lds_dwordx4 v[222:223], off
	v_lshl_add_u64 v[222:223], v[230:231], 0, s[2:3]
	s_mov_b32 m0, s35
	s_nop 0
	global_load_lds_dwordx4 v[222:223], off
	v_readfirstlane_b32 s35, v153
	v_lshl_add_u64 v[250:251], v[232:233], 0, s[48:49]
	s_mov_b32 m0, s35
	v_readfirstlane_b32 s35, v154
	global_load_lds_dwordx4 v[250:251], off
	v_lshl_add_u64 v[250:251], v[234:235], 0, s[48:49]
	s_mov_b32 m0, s35
	s_nop 0
	global_load_lds_dwordx4 v[250:251], off
	s_waitcnt lgkmcnt(0)
	s_waitcnt vmcnt(8)
	s_barrier
	s_setprio 1
	v_mfma_f32_16x16x32_bf16 v[60:63], v[160:163], v[176:179], v[60:63]
	v_mfma_f32_16x16x32_bf16 v[56:59], v[168:171], v[176:179], v[56:59]
	v_mfma_f32_16x16x32_bf16 v[52:55], v[160:163], v[186:189], v[52:55]
	v_mfma_f32_16x16x32_bf16 v[48:51], v[168:171], v[186:189], v[48:51]
	v_mfma_f32_16x16x32_bf16 v[44:47], v[160:163], v[194:197], v[44:47]
	v_mfma_f32_16x16x32_bf16 v[40:43], v[168:171], v[194:197], v[40:43]
	v_mfma_f32_16x16x32_bf16 v[36:39], v[160:163], v[202:205], v[36:39]
	v_mfma_f32_16x16x32_bf16 v[32:35], v[168:171], v[202:205], v[32:35]
	v_mfma_f32_16x16x32_bf16 v[60:63], v[164:167], v[182:185], v[60:63]
	v_mfma_f32_16x16x32_bf16 v[56:59], v[172:175], v[182:185], v[56:59]
	v_mfma_f32_16x16x32_bf16 v[52:55], v[164:167], v[190:193], v[52:55]
	v_mfma_f32_16x16x32_bf16 v[48:51], v[172:175], v[190:193], v[48:51]
	v_mfma_f32_16x16x32_bf16 v[44:47], v[164:167], v[198:201], v[44:47]
	v_mfma_f32_16x16x32_bf16 v[40:43], v[172:175], v[198:201], v[40:43]
	v_mfma_f32_16x16x32_bf16 v[36:39], v[164:167], v[206:209], v[36:39]
	v_mfma_f32_16x16x32_bf16 v[32:35], v[172:175], v[206:209], v[32:35]
	v_mfma_f32_16x16x32_bf16 v[28:31], v[210:213], v[176:179], v[28:31]
	v_mfma_f32_16x16x32_bf16 v[24:27], v[218:221], v[176:179], v[24:27]
	v_mfma_f32_16x16x32_bf16 v[20:23], v[210:213], v[186:189], v[20:23]
	v_mfma_f32_16x16x32_bf16 v[16:19], v[218:221], v[186:189], v[16:19]
	v_mfma_f32_16x16x32_bf16 v[12:15], v[210:213], v[194:197], v[12:15]
	v_mfma_f32_16x16x32_bf16 v[8:11], v[218:221], v[194:197], v[8:11]
	v_mfma_f32_16x16x32_bf16 v[4:7], v[210:213], v[202:205], v[4:7]
	v_mfma_f32_16x16x32_bf16 v[0:3], v[218:221], v[202:205], v[0:3]
	v_mfma_f32_16x16x32_bf16 v[28:31], v[214:217], v[182:185], v[28:31]
	v_mfma_f32_16x16x32_bf16 v[24:27], v[246:249], v[182:185], v[24:27]
	v_mfma_f32_16x16x32_bf16 v[20:23], v[214:217], v[190:193], v[20:23]
	v_mfma_f32_16x16x32_bf16 v[16:19], v[246:249], v[190:193], v[16:19]
	s_setprio 2
	s_barrier
	v_mfma_f32_16x16x32_bf16 v[12:15], v[214:217], v[198:201], v[12:15]
	v_mfma_f32_16x16x32_bf16 v[8:11], v[246:249], v[198:201], v[8:11]
	v_mfma_f32_16x16x32_bf16 v[4:7], v[214:217], v[206:209], v[4:7]
	v_mfma_f32_16x16x32_bf16 v[0:3], v[246:249], v[206:209], v[0:3]
	s_setprio 0
	s_add_i32 s31, s31, 2
	s_add_u32 s26, s26, 0x100
	s_addc_u32 s27, s27, 0
	s_cmp_lt_u32 s31, 28
	s_cbranch_scc1 .LBB0_1865
.Lmy_kexit_2:
	s_waitcnt vmcnt(6)
	v_not_b32_e32 v250, 63
	v_mov_b32_e32 v251, 0x41b17218
	v_or_b32_e32 v130, s29, v144
	v_lshl_add_u32 v130, v143, 6, v130
	v_ashrrev_i32_e32 v131, 31, v130
	v_add_u32_e32 v142, 0xa0, v130
	v_lshl_add_u64 v[132:133], v[130:131], 2, s[20:21]
	v_add_u32_e32 v134, 0x80, v130
	v_add_u32_e32 v136, 0x90, v130
	v_ashrrev_i32_e32 v143, 31, v142
	v_add_u32_e32 v130, 0xb0, v130
	s_or_b32 s42, s29, 0x80
	v_ashrrev_i32_e32 v135, 31, v134
	v_ashrrev_i32_e32 v137, 31, v136
	v_lshl_add_u64 v[142:143], v[142:143], 2, s[20:21]
	v_ashrrev_i32_e32 v131, 31, v130
	s_mul_i32 s26, s42, 0x1080
	v_lshl_add_u64 v[134:135], v[134:135], 2, s[20:21]
	v_lshl_add_u64 v[136:137], v[136:137], 2, s[20:21]
	v_lshl_add_u64 v[160:161], v[130:131], 2, s[20:21]
	global_load_dword v130, v[132:133], off
	global_load_dword v152, v[132:133], off offset:64
	global_load_dword v151, v[132:133], off offset:128
	global_load_dword v150, v[132:133], off offset:192
	global_load_dword v145, v[134:135], off
	global_load_dword v144, v[136:137], off
	s_nop 0
	global_load_dword v143, v[142:143], off
	s_nop 0
	global_load_dword v142, v[160:161], off
	s_mul_hi_i32 s27, s42, 0x1080
	s_add_u32 s26, s37, s26
	s_addc_u32 s27, s38, s27
	v_lshl_add_u64 v[136:137], s[26:27], 0, v[180:181]
	s_mov_b64 s[44:45], 0xf80
	v_readfirstlane_b32 s30, v158
	v_lshl_add_u64 v[136:137], v[136:137], 0, s[44:45]
	s_mov_b32 m0, s30
	ds_read_b128 v[132:135], v149
	ds_read_b128 v[160:163], v149 offset:1024
	ds_read_b128 v[164:167], v149 offset:2048
	ds_read_b128 v[168:171], v149 offset:3072
	ds_read_b128 v[172:175], v148
	ds_read_b128 v[176:179], v148 offset:1024
	ds_read_b128 v[182:185], v148 offset:2048
	ds_read_b128 v[186:189], v148 offset:3072
	ds_read_b128 v[190:193], v148 offset:4096
	ds_read_b128 v[194:197], v148 offset:5120
	ds_read_b128 v[198:201], v148 offset:6144
	ds_read_b128 v[202:205], v148 offset:7168
	global_load_lds_dwordx4 v[136:137], off
	v_lshl_add_u64 v[136:137], s[26:27], 0, v[128:129]
	v_readfirstlane_b32 s26, v159
	v_lshl_add_u64 v[136:137], v[136:137], 0, s[44:45]
	s_mov_b32 m0, s26
	s_nop 0
	global_load_lds_dwordx4 v[136:137], off
	s_barrier
; #define STAGE_A(P, br, kt) do { const char* _base = (const char*)(((kt) < G.ksplit ? G.A1 : A2m) + (long)(br) * G.lda + (long)(kt) * BK); \
;     __builtin_amdgcn_global_load_lds((const unsigned*)(_base + aoff0), (unsigned*)((char*)(P) + sb0), 16, 0, 0); \
;     __builtin_amdgcn_global_load_lds((const unsigned*)(_base + aoff1), (unsigned*)((char*)(P) + sb1), 16, 0, 0); } while (0)
; #define LDA(dst, b, h) for (int m = 0; m < 4; ++m) for (int k = 0; k < 2; ++k) \
;     dst[m][k] = *reinterpret_cast<const bf16x8*>(a_rd + ((b) * 2 + (h)) * (HT * 2) + m * 2048 + k * 1024)
; #define LDB(dst, b, h) for (int n = 0; n < 2; ++n) for (int k = 0; k < 2; ++k) \
;     dst[n][k] = *reinterpret_cast<const bf16x8*>(b_rd + ((b) * 2 + (h)) * (HT * 2) + n * 2048 + k * 1024)
; #define MMA(ai, bj, At_, Bt_) do { __builtin_amdgcn_s_setprio(1); \
;     for (int m = 0; m < 4; ++m) for (int n = 0; n < 2; ++n) for (int k = 0; k < 2; ++k) \
;       acc[ai][bj][m][n] = __builtin_amdgcn_mfma_f32_16x16x32_bf16(Bt_[n][k], At_[m][k], acc[ai][bj][m][n], 0, 0, 0); \
;     __builtin_amdgcn_s_setprio(0); } while (0)
; #define WAIT_V(n) asm volatile("s_waitcnt vmcnt(" #n ")" ::: "memory")
; #define WAIT_L(n) asm volatile("s_waitcnt lgkmcnt(" #n ")" ::: "memory")
; #define BAR __builtin_amdgcn_s_barrier()
;     ...
;   { LDB(B0, 0, 0); LDA(At, 0, 0); STAGE_A(SA(1, 1), brow + HALF, nt - 1);
;     BAR; WAIT_L(0); MMA(0, 0, At, B0); BAR;
;     LDB(B1, 0, 1); BAR; WAIT_L(0); MMA(0, 1, At, B1); BAR;
;     LDA(At, 0, 1); WAIT_V(4); BAR; WAIT_L(0); MMA(1, 0, At, B0); MMA(1, 1, At, B1); BAR; }
;   { LDB(B0, 1, 0); LDA(At, 1, 0); WAIT_V(2); BAR; WAIT_L(0); MMA(0, 0, At, B0); BAR;
	s_waitcnt lgkmcnt(0)
	s_setprio 1
	s_waitcnt lgkmcnt(0)
	v_mfma_f32_16x16x32_bf16 v[124:127], v[132:135], v[172:175], v[124:127]
	v_mfma_f32_16x16x32_bf16 v[120:123], v[164:167], v[172:175], v[120:123]
	v_mfma_f32_16x16x32_bf16 v[116:119], v[132:135], v[182:185], v[116:119]
	v_mfma_f32_16x16x32_bf16 v[112:115], v[164:167], v[182:185], v[112:115]
	v_mfma_f32_16x16x32_bf16 v[108:111], v[132:135], v[190:193], v[108:111]
	v_mfma_f32_16x16x32_bf16 v[104:107], v[164:167], v[190:193], v[104:107]
	v_mfma_f32_16x16x32_bf16 v[100:103], v[132:135], v[198:201], v[100:103]
	v_mfma_f32_16x16x32_bf16 v[96:99], v[164:167], v[198:201], v[96:99]
	v_mfma_f32_16x16x32_bf16 v[124:127], v[160:163], v[176:179], v[124:127]
	v_mfma_f32_16x16x32_bf16 v[120:123], v[168:171], v[176:179], v[120:123]
	v_mfma_f32_16x16x32_bf16 v[116:119], v[160:163], v[186:189], v[116:119]
	v_mfma_f32_16x16x32_bf16 v[112:115], v[168:171], v[186:189], v[112:115]
	s_setprio 2
	s_barrier
	v_mfma_f32_16x16x32_bf16 v[108:111], v[160:163], v[194:197], v[108:111]
	v_mfma_f32_16x16x32_bf16 v[104:107], v[168:171], v[194:197], v[104:107]
	v_mfma_f32_16x16x32_bf16 v[100:103], v[160:163], v[202:205], v[100:103]
	v_mfma_f32_16x16x32_bf16 v[96:99], v[168:171], v[202:205], v[96:99]
	s_setprio 0
	ds_read_b128 v[206:209], v149 offset:16384
	ds_read_b128 v[210:213], v149 offset:17408
	ds_read_b128 v[214:217], v149 offset:18432
	ds_read_b128 v[218:221], v149 offset:19456
	s_barrier
	s_waitcnt lgkmcnt(0)
	s_setprio 1
	s_waitcnt lgkmcnt(0)
	v_mfma_f32_16x16x32_bf16 v[92:95], v[206:209], v[172:175], v[92:95]
	v_mfma_f32_16x16x32_bf16 v[88:91], v[214:217], v[172:175], v[88:91]
	v_mfma_f32_16x16x32_bf16 v[84:87], v[206:209], v[182:185], v[84:87]
	v_mfma_f32_16x16x32_bf16 v[80:83], v[214:217], v[182:185], v[80:83]
	v_mfma_f32_16x16x32_bf16 v[76:79], v[206:209], v[190:193], v[76:79]
	v_mfma_f32_16x16x32_bf16 v[72:75], v[214:217], v[190:193], v[72:75]
	v_mfma_f32_16x16x32_bf16 v[68:71], v[206:209], v[198:201], v[68:71]
	v_mfma_f32_16x16x32_bf16 v[64:67], v[214:217], v[198:201], v[64:67]
	v_mfma_f32_16x16x32_bf16 v[92:95], v[210:213], v[176:179], v[92:95]
	v_mfma_f32_16x16x32_bf16 v[88:91], v[218:221], v[176:179], v[88:91]
	v_mfma_f32_16x16x32_bf16 v[84:87], v[210:213], v[186:189], v[84:87]
	v_mfma_f32_16x16x32_bf16 v[80:83], v[218:221], v[186:189], v[80:83]
	s_setprio 2
	s_barrier
	v_mfma_f32_16x16x32_bf16 v[76:79], v[210:213], v[194:197], v[76:79]
	v_mfma_f32_16x16x32_bf16 v[72:75], v[218:221], v[194:197], v[72:75]
	v_mfma_f32_16x16x32_bf16 v[68:71], v[210:213], v[202:205], v[68:71]
	v_mfma_f32_16x16x32_bf16 v[64:67], v[218:221], v[202:205], v[64:67]
	s_setprio 0
	ds_read_b128 v[172:175], v148 offset:16384
	ds_read_b128 v[176:179], v148 offset:17408
	ds_read_b128 v[182:185], v148 offset:18432
	ds_read_b128 v[186:189], v148 offset:19456
	ds_read_b128 v[190:193], v148 offset:20480
	ds_read_b128 v[194:197], v148 offset:21504
	ds_read_b128 v[198:201], v148 offset:22528
	ds_read_b128 v[202:205], v148 offset:23552
	s_waitcnt vmcnt(4)
	s_barrier
	s_waitcnt lgkmcnt(0)
	s_setprio 1
	s_waitcnt lgkmcnt(0)
	v_mfma_f32_16x16x32_bf16 v[60:63], v[132:135], v[172:175], v[60:63]
	v_mfma_f32_16x16x32_bf16 v[56:59], v[164:167], v[172:175], v[56:59]
	v_mfma_f32_16x16x32_bf16 v[52:55], v[132:135], v[182:185], v[52:55]
	v_mfma_f32_16x16x32_bf16 v[48:51], v[164:167], v[182:185], v[48:51]
	v_mfma_f32_16x16x32_bf16 v[44:47], v[132:135], v[190:193], v[44:47]
	v_mfma_f32_16x16x32_bf16 v[40:43], v[164:167], v[190:193], v[40:43]
	v_mfma_f32_16x16x32_bf16 v[36:39], v[132:135], v[198:201], v[36:39]
	v_mfma_f32_16x16x32_bf16 v[32:35], v[164:167], v[198:201], v[32:35]
	v_mfma_f32_16x16x32_bf16 v[60:63], v[160:163], v[176:179], v[60:63]
	v_mfma_f32_16x16x32_bf16 v[56:59], v[168:171], v[176:179], v[56:59]
	v_mfma_f32_16x16x32_bf16 v[52:55], v[160:163], v[186:189], v[52:55]
	v_mfma_f32_16x16x32_bf16 v[48:51], v[168:171], v[186:189], v[48:51]
	v_mfma_f32_16x16x32_bf16 v[44:47], v[160:163], v[194:197], v[44:47]
	v_mfma_f32_16x16x32_bf16 v[40:43], v[168:171], v[194:197], v[40:43]
	v_mfma_f32_16x16x32_bf16 v[36:39], v[160:163], v[202:205], v[36:39]
	v_mfma_f32_16x16x32_bf16 v[32:35], v[168:171], v[202:205], v[32:35]
	s_setprio 0
	s_setprio 1
	v_mfma_f32_16x16x32_bf16 v[28:31], v[206:209], v[172:175], v[28:31]
	v_mfma_f32_16x16x32_bf16 v[24:27], v[214:217], v[172:175], v[24:27]
	v_mfma_f32_16x16x32_bf16 v[20:23], v[206:209], v[182:185], v[20:23]
	v_mfma_f32_16x16x32_bf16 v[16:19], v[214:217], v[182:185], v[16:19]
	v_mfma_f32_16x16x32_bf16 v[12:15], v[206:209], v[190:193], v[12:15]
	v_mfma_f32_16x16x32_bf16 v[8:11], v[214:217], v[190:193], v[8:11]
	v_mfma_f32_16x16x32_bf16 v[4:7], v[206:209], v[198:201], v[4:7]
	v_mfma_f32_16x16x32_bf16 v[0:3], v[214:217], v[198:201], v[0:3]
	v_mfma_f32_16x16x32_bf16 v[28:31], v[210:213], v[176:179], v[28:31]
	v_mfma_f32_16x16x32_bf16 v[24:27], v[218:221], v[176:179], v[24:27]
	v_mfma_f32_16x16x32_bf16 v[20:23], v[210:213], v[186:189], v[20:23]
	v_mfma_f32_16x16x32_bf16 v[16:19], v[218:221], v[186:189], v[16:19]
	s_setprio 2
	s_barrier
	v_mfma_f32_16x16x32_bf16 v[12:15], v[210:213], v[194:197], v[12:15]
	v_mfma_f32_16x16x32_bf16 v[8:11], v[218:221], v[194:197], v[8:11]
	v_mfma_f32_16x16x32_bf16 v[4:7], v[210:213], v[202:205], v[4:7]
	v_mfma_f32_16x16x32_bf16 v[0:3], v[218:221], v[202:205], v[0:3]
	s_setprio 0
	ds_read_b128 v[132:135], v149 offset:32768
	ds_read_b128 v[158:161], v149 offset:33792
	ds_read_b128 v[162:165], v149 offset:34816
	ds_read_b128 v[166:169], v149 offset:35840
	ds_read_b128 v[170:173], v148 offset:32768
	ds_read_b128 v[174:177], v148 offset:33792
	ds_read_b128 v[182:185], v148 offset:34816
	ds_read_b128 v[186:189], v148 offset:35840
	ds_read_b128 v[190:193], v148 offset:36864
	ds_read_b128 v[194:197], v148 offset:37888
	ds_read_b128 v[198:201], v148 offset:38912
	ds_read_b128 v[202:205], v148 offset:39936
	s_waitcnt vmcnt(2)
	s_barrier
; #define LDA(dst, b, h) for (int m = 0; m < 4; ++m) for (int k = 0; k < 2; ++k) \
;     dst[m][k] = *reinterpret_cast<const bf16x8*>(a_rd + ((b) * 2 + (h)) * (HT * 2) + m * 2048 + k * 1024)
; #define LDB(dst, b, h) for (int n = 0; n < 2; ++n) for (int k = 0; k < 2; ++k) \
;     dst[n][k] = *reinterpret_cast<const bf16x8*>(b_rd + ((b) * 2 + (h)) * (HT * 2) + n * 2048 + k * 1024)
; #define MMA(ai, bj, At_, Bt_) do { __builtin_amdgcn_s_setprio(1); \
;     for (int m = 0; m < 4; ++m) for (int n = 0; n < 2; ++n) for (int k = 0; k < 2; ++k) \
;       acc[ai][bj][m][n] = __builtin_amdgcn_mfma_f32_16x16x32_bf16(Bt_[n][k], At_[m][k], acc[ai][bj][m][n], 0, 0, 0); \
;     __builtin_amdgcn_s_setprio(0); } while (0)
; #define WAIT_V(n) asm volatile("s_waitcnt vmcnt(" #n ")" ::: "memory")
; #define WAIT_L(n) asm volatile("s_waitcnt lgkmcnt(" #n ")" ::: "memory")
; #define BAR __builtin_amdgcn_s_barrier()
;     ...
;   { LDB(B0, 1, 0); LDA(At, 1, 0); WAIT_V(2); BAR; WAIT_L(0); MMA(0, 0, At, B0); BAR;
;     LDB(B1, 1, 1); WAIT_V(0); BAR; WAIT_L(0); MMA(0, 1, At, B1); BAR;
;     LDA(At, 1, 1); BAR; WAIT_L(0); MMA(1, 0, At, B0); MMA(1, 1, At, B1); BAR; }
;   if (wr == 0) BAR;
	s_waitcnt lgkmcnt(0)
	s_setprio 1
	s_waitcnt lgkmcnt(0)
	v_mfma_f32_16x16x32_bf16 v[124:127], v[132:135], v[170:173], v[124:127]
	v_mfma_f32_16x16x32_bf16 v[120:123], v[162:165], v[170:173], v[120:123]
	v_mfma_f32_16x16x32_bf16 v[116:119], v[132:135], v[182:185], v[116:119]
	v_mfma_f32_16x16x32_bf16 v[112:115], v[162:165], v[182:185], v[112:115]
	v_mfma_f32_16x16x32_bf16 v[108:111], v[132:135], v[190:193], v[108:111]
	v_mfma_f32_16x16x32_bf16 v[104:107], v[162:165], v[190:193], v[104:107]
	v_mfma_f32_16x16x32_bf16 v[100:103], v[132:135], v[198:201], v[100:103]
	v_mfma_f32_16x16x32_bf16 v[96:99], v[162:165], v[198:201], v[96:99]
	v_mfma_f32_16x16x32_bf16 v[124:127], v[158:161], v[174:177], v[124:127]
	v_mfma_f32_16x16x32_bf16 v[120:123], v[166:169], v[174:177], v[120:123]
	v_mfma_f32_16x16x32_bf16 v[116:119], v[158:161], v[186:189], v[116:119]
	v_mfma_f32_16x16x32_bf16 v[112:115], v[166:169], v[186:189], v[112:115]
	s_setprio 2
	s_barrier
	v_mfma_f32_16x16x32_bf16 v[108:111], v[158:161], v[194:197], v[108:111]
	v_mfma_f32_16x16x32_bf16 v[104:107], v[166:169], v[194:197], v[104:107]
	v_mfma_f32_16x16x32_bf16 v[100:103], v[158:161], v[202:205], v[100:103]
	v_mfma_f32_16x16x32_bf16 v[96:99], v[166:169], v[202:205], v[96:99]
	s_setprio 0
	ds_read_b128 v[206:209], v149 offset:49152
	ds_read_b128 v[210:213], v149 offset:50176
	ds_read_b128 v[214:217], v149 offset:51200
	ds_read_b128 v[218:221], v149 offset:52224
	s_waitcnt vmcnt(0)
	s_barrier
	s_waitcnt lgkmcnt(0)
	s_setprio 1
	s_waitcnt lgkmcnt(0)
	v_mfma_f32_16x16x32_bf16 v[92:95], v[206:209], v[170:173], v[92:95]
	v_mfma_f32_16x16x32_bf16 v[88:91], v[214:217], v[170:173], v[88:91]
	v_mfma_f32_16x16x32_bf16 v[84:87], v[206:209], v[182:185], v[84:87]
	v_mfma_f32_16x16x32_bf16 v[80:83], v[214:217], v[182:185], v[80:83]
	v_mfma_f32_16x16x32_bf16 v[76:79], v[206:209], v[190:193], v[76:79]
	v_mfma_f32_16x16x32_bf16 v[72:75], v[214:217], v[190:193], v[72:75]
	v_mfma_f32_16x16x32_bf16 v[68:71], v[206:209], v[198:201], v[68:71]
	v_mfma_f32_16x16x32_bf16 v[64:67], v[214:217], v[198:201], v[64:67]
	v_mfma_f32_16x16x32_bf16 v[92:95], v[210:213], v[174:177], v[92:95]
	v_mfma_f32_16x16x32_bf16 v[88:91], v[218:221], v[174:177], v[88:91]
	v_mfma_f32_16x16x32_bf16 v[84:87], v[210:213], v[186:189], v[84:87]
	v_mfma_f32_16x16x32_bf16 v[80:83], v[218:221], v[186:189], v[80:83]
	s_setprio 2
	s_barrier
	v_mfma_f32_16x16x32_bf16 v[76:79], v[210:213], v[194:197], v[76:79]
	v_mfma_f32_16x16x32_bf16 v[72:75], v[218:221], v[194:197], v[72:75]
	v_mfma_f32_16x16x32_bf16 v[68:71], v[210:213], v[202:205], v[68:71]
	v_mfma_f32_16x16x32_bf16 v[64:67], v[218:221], v[202:205], v[64:67]
	s_setprio 0
	ds_read_b128 v[170:173], v148 offset:49152
	ds_read_b128 v[174:177], v148 offset:50176
	ds_read_b128 v[182:185], v148 offset:51200
	ds_read_b128 v[186:189], v148 offset:52224
	ds_read_b128 v[190:193], v148 offset:53248
	ds_read_b128 v[194:197], v148 offset:54272
	ds_read_b128 v[198:201], v148 offset:55296
	ds_read_b128 v[202:205], v148 offset:56320
	s_barrier
	s_waitcnt lgkmcnt(0)
	s_setprio 1
	s_waitcnt lgkmcnt(0)
	v_mfma_f32_16x16x32_bf16 v[60:63], v[132:135], v[170:173], v[60:63]
	v_mfma_f32_16x16x32_bf16 v[56:59], v[162:165], v[170:173], v[56:59]
	v_mfma_f32_16x16x32_bf16 v[52:55], v[132:135], v[182:185], v[52:55]
	v_mfma_f32_16x16x32_bf16 v[48:51], v[162:165], v[182:185], v[48:51]
	v_mfma_f32_16x16x32_bf16 v[44:47], v[132:135], v[190:193], v[44:47]
	v_mfma_f32_16x16x32_bf16 v[40:43], v[162:165], v[190:193], v[40:43]
	v_mfma_f32_16x16x32_bf16 v[36:39], v[132:135], v[198:201], v[36:39]
	v_mfma_f32_16x16x32_bf16 v[32:35], v[162:165], v[198:201], v[32:35]
	v_mfma_f32_16x16x32_bf16 v[60:63], v[158:161], v[174:177], v[60:63]
	v_mfma_f32_16x16x32_bf16 v[56:59], v[166:169], v[174:177], v[56:59]
	v_mfma_f32_16x16x32_bf16 v[52:55], v[158:161], v[186:189], v[52:55]
	v_mfma_f32_16x16x32_bf16 v[48:51], v[166:169], v[186:189], v[48:51]
	v_mfma_f32_16x16x32_bf16 v[44:47], v[158:161], v[194:197], v[44:47]
	v_mfma_f32_16x16x32_bf16 v[40:43], v[166:169], v[194:197], v[40:43]
	v_mfma_f32_16x16x32_bf16 v[36:39], v[158:161], v[202:205], v[36:39]
	v_mfma_f32_16x16x32_bf16 v[32:35], v[166:169], v[202:205], v[32:35]
	s_setprio 0
	s_setprio 1
	v_mfma_f32_16x16x32_bf16 v[28:31], v[206:209], v[170:173], v[28:31]
	v_mfma_f32_16x16x32_bf16 v[24:27], v[214:217], v[170:173], v[24:27]
	v_mfma_f32_16x16x32_bf16 v[20:23], v[206:209], v[182:185], v[20:23]
	v_mfma_f32_16x16x32_bf16 v[16:19], v[214:217], v[182:185], v[16:19]
	v_mfma_f32_16x16x32_bf16 v[12:15], v[206:209], v[190:193], v[12:15]
	v_mfma_f32_16x16x32_bf16 v[8:11], v[214:217], v[190:193], v[8:11]
	v_mfma_f32_16x16x32_bf16 v[4:7], v[206:209], v[198:201], v[4:7]
	v_mfma_f32_16x16x32_bf16 v[0:3], v[214:217], v[198:201], v[0:3]
	v_mfma_f32_16x16x32_bf16 v[28:31], v[210:213], v[174:177], v[28:31]
	v_mfma_f32_16x16x32_bf16 v[24:27], v[218:221], v[174:177], v[24:27]
	v_mfma_f32_16x16x32_bf16 v[20:23], v[210:213], v[186:189], v[20:23]
	v_mfma_f32_16x16x32_bf16 v[16:19], v[218:221], v[186:189], v[16:19]
	s_setprio 2
	s_barrier
	v_mfma_f32_16x16x32_bf16 v[12:15], v[210:213], v[194:197], v[12:15]
	v_mfma_f32_16x16x32_bf16 v[8:11], v[218:221], v[194:197], v[8:11]
	v_mfma_f32_16x16x32_bf16 v[4:7], v[210:213], v[202:205], v[4:7]
	v_mfma_f32_16x16x32_bf16 v[0:3], v[218:221], v[202:205], v[0:3]
	s_setprio 0
	v_cmp_gt_u32_e32 vcc, s60, v139
	s_and_saveexec_b64 s[26:27], vcc
	s_cbranch_execz .LBB0_1868
	s_barrier

; #define STAGE_A(P, br, kt) do { const char* _base = (const char*)(((kt) < G.ksplit ? G.A1 : A2m) + (long)(br) * G.lda + (long)(kt) * BK); \
;     __builtin_amdgcn_global_load_lds((const unsigned*)(_base + aoff0), (unsigned*)((char*)(P) + sb0), 16, 0, 0); \
;     __builtin_amdgcn_global_load_lds((const unsigned*)(_base + aoff1), (unsigned*)((char*)(P) + sb1), 16, 0, 0); } while (0)
; #define STAGE_B(P, br, kt) do { const char* _base = (const char*)(G.Bt + (long)(br) * G.ldb + (long)(kt) * BK); \
;     __builtin_amdgcn_global_load_lds((const unsigned*)(_base + boff0), (unsigned*)((char*)(P) + sb0), 16, 0, 0); \
;     __builtin_amdgcn_global_load_lds((const unsigned*)(_base + boff1), (unsigned*)((char*)(P) + sb1), 16, 0, 0); } while (0)
; #define LDA(dst, b, h) for (int m = 0; m < 4; ++m) for (int k = 0; k < 2; ++k) \
;     dst[m][k] = *reinterpret_cast<const bf16x8*>(a_rd + ((b) * 2 + (h)) * (HT * 2) + m * 2048 + k * 1024)
; #define LDB(dst, b, h) for (int n = 0; n < 2; ++n) for (int k = 0; k < 2; ++k) \
;     dst[n][k] = *reinterpret_cast<const bf16x8*>(b_rd + ((b) * 2 + (h)) * (HT * 2) + n * 2048 + k * 1024)
; #define MMA(ai, bj, At_, Bt_) do { __builtin_amdgcn_s_setprio(1); \
;     for (int m = 0; m < 4; ++m) for (int n = 0; n < 2; ++n) for (int k = 0; k < 2; ++k) \
;       acc[ai][bj][m][n] = __builtin_amdgcn_mfma_f32_16x16x32_bf16(Bt_[n][k], At_[m][k], acc[ai][bj][m][n], 0, 0, 0); \
;     __builtin_amdgcn_s_setprio(0); } while (0)
; #define WAIT_V(n) asm volatile("s_waitcnt vmcnt(" #n ")" ::: "memory")
; #define WAIT_L(n) asm volatile("s_waitcnt lgkmcnt(" #n ")" ::: "memory")
;     ...
;   if (wr == 1) BAR;
;   WAIT_V(0); BAR;
;   STAGE_B(SB(1, 0), bcol, 1); STAGE_A(SA(1, 0), brow, 1); STAGE_B(SB(1, 1), bcol + HALF, 1);
;   WAIT_V(6); BAR;
;   for (int t = 0; t < nt - 2; t += 2) {
;     LDB(B0, 0, 0); SCHED; LDA(At, 0, 0); STAGE_A(SA(1, 1), brow + HALF, t + 1);
;     WAIT_L(8); BAR; WAIT_L(0); MMA(0, 0, At, B0); BAR; SCHED;
;     LDB(B1, 0, 1); STAGE_B(SB(0, 0), bcol, t + 2);
;     BAR; WAIT_L(0); MMA(0, 1, At, B1); BAR;
;     LDA(At, 0, 1); STAGE_A(SA(0, 0), brow, t + 2);
;     BAR; WAIT_L(0); MMA(1, 0, At, B0); BAR; SCHED;
;     STAGE_B(SB(0, 1), bcol + HALF, t + 2);
;     WAIT_V(6); BAR; MMA(1, 1, At, B1); BAR;
;     LDB(B0, 1, 0); SCHED; LDA(At, 1, 0); STAGE_A(SA(0, 1), brow + HALF, t + 2);
;     WAIT_L(8); BAR; WAIT_L(0); MMA(0, 0, At, B0); BAR; SCHED;
.LBB0_2453:
	s_or_b64 exec, exec, s[20:21]
	v_mov_b32_e32 v3, v181
	v_mov_b32_e32 v5, v181
	v_lshl_add_u64 v[12:13], s[6:7], 0, v[2:3]
	v_lshl_add_u64 v[14:15], s[6:7], 0, v[4:5]
	s_waitcnt vmcnt(0)
	v_lshlrev_b32_e32 v27, 13, v23
	v_lshlrev_b32_e32 v23, 6, v128
	v_readlane_b32 s6, v253, 46
	v_mov_b32_e32 v1, v181
	v_and_b32_e32 v24, 15, v128
	v_lshlrev_b32_e32 v26, 2, v128
	v_and_b32_e32 v28, 0x3000, v23
	v_add_u32_e32 v23, s6, v22
	v_lshl_add_u64 v[10:11], s[14:15], 0, v[0:1]
	v_lshl_add_u64 v[6:7], s[16:17], 0, v[2:3]
	v_lshl_add_u64 v[2:3], s[18:19], 0, v[180:181]
	v_lshl_add_u64 v[0:1], s[18:19], 0, v[0:1]
	v_and_b32_e32 v25, 48, v128
	v_lshlrev_b32_e32 v24, 6, v24
	v_and_b32_e32 v26, 32, v26
	s_mov_b64 s[20:21], 0x80
	v_readfirstlane_b32 s18, v23
	v_add_u32_e32 v23, 0x2000, v23
	v_lshl_add_u64 v[4:5], s[16:17], 0, v[4:5]
	v_bitop3_b32 v26, v24, v26, v25 bitop3:0x36
	v_lshl_add_u64 v[24:25], v[12:13], 0, s[20:21]
	s_mov_b32 m0, s18
	v_readfirstlane_b32 s17, v23
	v_add_u32_e32 v23, 0x8000, v19
	v_lshl_add_u64 v[8:9], s[14:15], 0, v[180:181]
	s_waitcnt vmcnt(0)
	s_barrier
	global_load_lds_dwordx4 v[24:25], off
	v_lshl_add_u64 v[24:25], v[14:15], 0, s[20:21]
	s_mov_b32 m0, s17
	v_readfirstlane_b32 s15, v23
	v_add_u32_e32 v23, 0xa000, v19
	v_readlane_b32 s6, v253, 47
	global_load_lds_dwordx4 v[24:25], off
	v_lshl_add_u64 v[24:25], v[8:9], 0, s[20:21]
	s_mov_b32 m0, s15
	v_readfirstlane_b32 s14, v23
	v_add_u32_e32 v29, s6, v22
	global_load_lds_dwordx4 v[24:25], off
	v_lshl_add_u64 v[24:25], v[10:11], 0, s[20:21]
	s_mov_b32 m0, s14
	v_readfirstlane_b32 s7, v29
	global_load_lds_dwordx4 v[24:25], off
	v_lshl_add_u64 v[24:25], v[6:7], 0, s[20:21]
	s_mov_b32 m0, s7
	v_lshl_add_u64 v[22:23], v[4:5], 0, s[20:21]
	global_load_lds_dwordx4 v[24:25], off
	v_add_u32_e32 v24, 0x2000, v29
	v_add3_u32 v129, s28, v28, v26
	v_readfirstlane_b32 s6, v24
	s_mov_b32 m0, s6
	v_add3_u32 v178, 32, v27, v26
	global_load_lds_dwordx4 v[22:23], off
	s_waitcnt vmcnt(6)
	s_barrier
	ds_read_b128 v[22:25], v129
	ds_read_b128 v[26:29], v129 offset:1024
	ds_read_b128 v[30:33], v129 offset:2048
	ds_read_b128 v[34:37], v129 offset:3072
	v_add_u32_e32 v72, 0xc000, v19
	v_lshl_add_u64 v[70:71], v[2:3], 0, s[20:21]
	v_readfirstlane_b32 s19, v72
	v_add_u32_e32 v72, 0xe000, v19
	s_mov_b32 m0, s19
	v_readfirstlane_b32 s16, v72
	ds_read_b128 v[38:41], v178
	ds_read_b128 v[42:45], v178 offset:1024
	ds_read_b128 v[46:49], v178 offset:2048
	ds_read_b128 v[50:53], v178 offset:3072
	ds_read_b128 v[54:57], v178 offset:4096
	ds_read_b128 v[58:61], v178 offset:5120
	ds_read_b128 v[62:65], v178 offset:6144
	ds_read_b128 v[66:69], v178 offset:7168
	global_load_lds_dwordx4 v[70:71], off
	v_lshl_add_u64 v[70:71], v[0:1], 0, s[20:21]
	s_mov_b32 m0, s16
	s_nop 0
	global_load_lds_dwordx4 v[70:71], off
	s_waitcnt lgkmcnt(8)
	s_barrier
	s_waitcnt lgkmcnt(0)
	s_setprio 1
	s_waitcnt lgkmcnt(0)
	v_mfma_f32_16x16x32_bf16 v[70:73], v[22:25], v[38:41], 0
	v_mfma_f32_16x16x32_bf16 v[74:77], v[30:33], v[38:41], 0
	v_mfma_f32_16x16x32_bf16 v[78:81], v[22:25], v[46:49], 0
	v_mfma_f32_16x16x32_bf16 v[82:85], v[30:33], v[46:49], 0
	v_mfma_f32_16x16x32_bf16 v[86:89], v[22:25], v[54:57], 0
	v_mfma_f32_16x16x32_bf16 v[90:93], v[30:33], v[54:57], 0
	v_mfma_f32_16x16x32_bf16 v[94:97], v[22:25], v[62:65], 0
	v_mfma_f32_16x16x32_bf16 v[98:101], v[30:33], v[62:65], 0
	v_mfma_f32_16x16x32_bf16 v[70:73], v[26:29], v[42:45], v[70:73]
	v_mfma_f32_16x16x32_bf16 v[74:77], v[34:37], v[42:45], v[74:77]
	v_mfma_f32_16x16x32_bf16 v[78:81], v[26:29], v[50:53], v[78:81]
	v_mfma_f32_16x16x32_bf16 v[82:85], v[34:37], v[50:53], v[82:85]
	s_setprio 2
	s_barrier
	v_mfma_f32_16x16x32_bf16 v[86:89], v[26:29], v[58:61], v[86:89]
	v_mfma_f32_16x16x32_bf16 v[90:93], v[34:37], v[58:61], v[90:93]
	v_mfma_f32_16x16x32_bf16 v[94:97], v[26:29], v[66:69], v[94:97]
	v_mfma_f32_16x16x32_bf16 v[98:101], v[34:37], v[66:69], v[98:101]
	s_setprio 0
	v_readfirstlane_b32 s20, v21
	v_add_u32_e32 v21, 0x2000, v21
	v_lshl_add_u64 v[118:119], v[12:13], 0, s[90:91]
	s_mov_b32 m0, s20
	v_readfirstlane_b32 s20, v21
	ds_read_b128 v[102:105], v129 offset:16384
	ds_read_b128 v[106:109], v129 offset:17408
	ds_read_b128 v[110:113], v129 offset:18432
	ds_read_b128 v[114:117], v129 offset:19456
	global_load_lds_dwordx4 v[118:119], off
	v_lshl_add_u64 v[118:119], v[14:15], 0, s[90:91]
	s_mov_b32 m0, s20
	s_nop 0
	global_load_lds_dwordx4 v[118:119], off
	s_barrier
	s_waitcnt lgkmcnt(0)
	s_setprio 1
	s_waitcnt lgkmcnt(0)
	v_mfma_f32_16x16x32_bf16 v[118:121], v[102:105], v[38:41], 0
	v_mfma_f32_16x16x32_bf16 v[38:41], v[110:113], v[38:41], 0
	v_mfma_f32_16x16x32_bf16 v[118:121], v[106:109], v[42:45], v[118:121]
	v_mfma_f32_16x16x32_bf16 v[38:41], v[114:117], v[42:45], v[38:41]
	v_mfma_f32_16x16x32_bf16 v[42:45], v[102:105], v[46:49], 0
	v_mfma_f32_16x16x32_bf16 v[46:49], v[110:113], v[46:49], 0
	v_mfma_f32_16x16x32_bf16 v[42:45], v[106:109], v[50:53], v[42:45]
	v_mfma_f32_16x16x32_bf16 v[46:49], v[114:117], v[50:53], v[46:49]
	v_mfma_f32_16x16x32_bf16 v[50:53], v[102:105], v[54:57], 0
	v_mfma_f32_16x16x32_bf16 v[54:57], v[110:113], v[54:57], 0
	v_mfma_f32_16x16x32_bf16 v[50:53], v[106:109], v[58:61], v[50:53]
	v_mfma_f32_16x16x32_bf16 v[54:57], v[114:117], v[58:61], v[54:57]
	s_setprio 2
	s_barrier
; #define STAGE_A(P, br, kt) do { const char* _base = (const char*)(((kt) < G.ksplit ? G.A1 : A2m) + (long)(br) * G.lda + (long)(kt) * BK); \
;     __builtin_amdgcn_global_load_lds((const unsigned*)(_base + aoff0), (unsigned*)((char*)(P) + sb0), 16, 0, 0); \
;     __builtin_amdgcn_global_load_lds((const unsigned*)(_base + aoff1), (unsigned*)((char*)(P) + sb1), 16, 0, 0); } while (0)
; #define STAGE_B(P, br, kt) do { const char* _base = (const char*)(G.Bt + (long)(br) * G.ldb + (long)(kt) * BK); \
;     __builtin_amdgcn_global_load_lds((const unsigned*)(_base + boff0), (unsigned*)((char*)(P) + sb0), 16, 0, 0); \
;     __builtin_amdgcn_global_load_lds((const unsigned*)(_base + boff1), (unsigned*)((char*)(P) + sb1), 16, 0, 0); } while (0)
; #define LDA(dst, b, h) for (int m = 0; m < 4; ++m) for (int k = 0; k < 2; ++k) \
;     dst[m][k] = *reinterpret_cast<const bf16x8*>(a_rd + ((b) * 2 + (h)) * (HT * 2) + m * 2048 + k * 1024)
; #define LDB(dst, b, h) for (int n = 0; n < 2; ++n) for (int k = 0; k < 2; ++k) \
;     dst[n][k] = *reinterpret_cast<const bf16x8*>(b_rd + ((b) * 2 + (h)) * (HT * 2) + n * 2048 + k * 1024)
; #define MMA(ai, bj, At_, Bt_) do { __builtin_amdgcn_s_setprio(1); \
;     for (int m = 0; m < 4; ++m) for (int n = 0; n < 2; ++n) for (int k = 0; k < 2; ++k) \
;       acc[ai][bj][m][n] = __builtin_amdgcn_mfma_f32_16x16x32_bf16(Bt_[n][k], At_[m][k], acc[ai][bj][m][n], 0, 0, 0); \
;     __builtin_amdgcn_s_setprio(0); } while (0)
;     ...
;   for (int t = 0; t < nt - 2; t += 2) {
;     LDB(B0, 0, 0); SCHED; LDA(At, 0, 0); STAGE_A(SA(1, 1), brow + HALF, t + 1);
;     WAIT_L(8); BAR; WAIT_L(0); MMA(0, 0, At, B0); BAR; SCHED;
;     LDB(B1, 0, 1); STAGE_B(SB(0, 0), bcol, t + 2);
;     BAR; WAIT_L(0); MMA(0, 1, At, B1); BAR;
;     LDA(At, 0, 1); STAGE_A(SA(0, 0), brow, t + 2);
;     BAR; WAIT_L(0); MMA(1, 0, At, B0); BAR; SCHED;
;     STAGE_B(SB(0, 1), bcol + HALF, t + 2);
;     WAIT_V(6); BAR; MMA(1, 1, At, B1); BAR;
;     LDB(B0, 1, 0); SCHED; LDA(At, 1, 0); STAGE_A(SA(0, 1), brow + HALF, t + 2);
;     WAIT_L(8); BAR; WAIT_L(0); MMA(0, 0, At, B0); BAR; SCHED;
;     LDB(B1, 1, 1); STAGE_B(SB(1, 0), bcol, t + 3);
;     BAR; WAIT_L(0); MMA(0, 1, At, B1); BAR;
;     LDA(At, 1, 1); STAGE_A(SA(1, 0), brow, t + 3);
;     BAR; WAIT_L(0); MMA(1, 0, At, B0); BAR; SCHED;
;     STAGE_B(SB(1, 1), bcol + HALF, t + 3);
;     WAIT_V(6); BAR; MMA(1, 1, At, B1); BAR;
;   }
	v_mfma_f32_16x16x32_bf16 v[58:61], v[102:105], v[62:65], 0
	v_mfma_f32_16x16x32_bf16 v[62:65], v[110:113], v[62:65], 0
	v_mfma_f32_16x16x32_bf16 v[58:61], v[106:109], v[66:69], v[58:61]
	v_mfma_f32_16x16x32_bf16 v[62:65], v[114:117], v[66:69], v[62:65]
	s_setprio 0
	v_readfirstlane_b32 s20, v19
	v_lshl_add_u64 v[126:127], v[8:9], 0, s[90:91]
	s_mov_b32 m0, s20
	v_readfirstlane_b32 s20, v20
	ds_read_b128 v[66:69], v178 offset:16384
	ds_read_b128 v[122:125], v178 offset:17408
	ds_read_b128 v[130:133], v178 offset:18432
	ds_read_b128 v[134:137], v178 offset:19456
	ds_read_b128 v[138:141], v178 offset:20480
	ds_read_b128 v[142:145], v178 offset:21504
	ds_read_b128 v[146:149], v178 offset:22528
	ds_read_b128 v[150:153], v178 offset:23552
	global_load_lds_dwordx4 v[126:127], off
	v_lshl_add_u64 v[126:127], v[10:11], 0, s[90:91]
	s_mov_b32 m0, s20
	s_nop 0
	global_load_lds_dwordx4 v[126:127], off
	s_barrier
	s_waitcnt lgkmcnt(0)
	s_setprio 1
	s_waitcnt lgkmcnt(0)
	v_mfma_f32_16x16x32_bf16 v[154:157], v[22:25], v[66:69], 0
	v_mfma_f32_16x16x32_bf16 v[162:165], v[22:25], v[130:133], 0
	v_mfma_f32_16x16x32_bf16 v[170:173], v[22:25], v[138:141], 0
	v_mfma_f32_16x16x32_bf16 v[20:23], v[22:25], v[146:149], 0
	v_mfma_f32_16x16x32_bf16 v[154:157], v[26:29], v[122:125], v[154:157]
	v_mfma_f32_16x16x32_bf16 v[162:165], v[26:29], v[134:137], v[162:165]
	v_mfma_f32_16x16x32_bf16 v[170:173], v[26:29], v[142:145], v[170:173]
	v_mfma_f32_16x16x32_bf16 v[20:23], v[26:29], v[150:153], v[20:23]
	v_mfma_f32_16x16x32_bf16 v[24:27], v[30:33], v[146:149], 0
	v_mfma_f32_16x16x32_bf16 v[158:161], v[30:33], v[66:69], 0
	v_mfma_f32_16x16x32_bf16 v[166:169], v[30:33], v[130:133], 0
	v_mfma_f32_16x16x32_bf16 v[174:177], v[30:33], v[138:141], 0
	s_setprio 2
	s_barrier
	v_mfma_f32_16x16x32_bf16 v[24:27], v[34:37], v[150:153], v[24:27]
	v_mfma_f32_16x16x32_bf16 v[158:161], v[34:37], v[122:125], v[158:161]
	v_mfma_f32_16x16x32_bf16 v[166:169], v[34:37], v[134:137], v[166:169]
	v_mfma_f32_16x16x32_bf16 v[174:177], v[34:37], v[142:145], v[174:177]
	s_setprio 0
	v_readfirstlane_b32 s20, v18
	v_add_u32_e32 v18, 0x2000, v18
	v_lshl_add_u64 v[28:29], v[6:7], 0, s[90:91]
	s_mov_b32 m0, s20
	v_readfirstlane_b32 s20, v18
	global_load_lds_dwordx4 v[28:29], off
	v_lshl_add_u64 v[28:29], v[4:5], 0, s[90:91]
	s_mov_b32 m0, s20
	s_nop 0
	global_load_lds_dwordx4 v[28:29], off
	s_waitcnt vmcnt(6)
	s_barrier
	s_setprio 1
	v_mfma_f32_16x16x32_bf16 v[28:31], v[102:105], v[66:69], 0
	v_mfma_f32_16x16x32_bf16 v[32:35], v[110:113], v[66:69], 0
	v_mfma_f32_16x16x32_bf16 v[28:31], v[106:109], v[122:125], v[28:31]
	v_mfma_f32_16x16x32_bf16 v[32:35], v[114:117], v[122:125], v[32:35]
	v_mfma_f32_16x16x32_bf16 v[66:69], v[102:105], v[130:133], 0
	v_mfma_f32_16x16x32_bf16 v[122:125], v[110:113], v[130:133], 0
	v_mfma_f32_16x16x32_bf16 v[130:133], v[102:105], v[138:141], 0
	v_mfma_f32_16x16x32_bf16 v[102:105], v[102:105], v[146:149], 0
	v_mfma_f32_16x16x32_bf16 v[66:69], v[106:109], v[134:137], v[66:69]
	v_mfma_f32_16x16x32_bf16 v[130:133], v[106:109], v[142:145], v[130:133]
	v_mfma_f32_16x16x32_bf16 v[102:105], v[106:109], v[150:153], v[102:105]
	v_mfma_f32_16x16x32_bf16 v[106:109], v[110:113], v[146:149], 0
	s_setprio 2
	s_barrier
	v_mfma_f32_16x16x32_bf16 v[122:125], v[114:117], v[134:137], v[122:125]
	v_mfma_f32_16x16x32_bf16 v[134:137], v[110:113], v[138:141], 0
	v_mfma_f32_16x16x32_bf16 v[106:109], v[114:117], v[150:153], v[106:109]
	v_mfma_f32_16x16x32_bf16 v[134:137], v[114:117], v[142:145], v[134:137]
	s_setprio 0
	ds_read_b128 v[110:113], v129 offset:32768
	ds_read_b128 v[114:117], v129 offset:33792
	ds_read_b128 v[138:141], v129 offset:34816
	ds_read_b128 v[142:145], v129 offset:35840
	v_readfirstlane_b32 s20, v16
	v_lshl_add_u64 v[18:19], v[2:3], 0, s[90:91]
	s_mov_b32 m0, s20
	v_readfirstlane_b32 s20, v17
	ds_read_b128 v[146:149], v178 offset:32768
	ds_read_b128 v[150:153], v178 offset:33792
	ds_read_b128 v[182:185], v178 offset:34816
	ds_read_b128 v[186:189], v178 offset:35840
	ds_read_b128 v[190:193], v178 offset:36864
	ds_read_b128 v[194:197], v178 offset:37888
	ds_read_b128 v[198:201], v178 offset:38912
	ds_read_b128 v[202:205], v178 offset:39936
	global_load_lds_dwordx4 v[18:19], off
	v_lshl_add_u64 v[18:19], v[0:1], 0, s[90:91]
	s_mov_b32 m0, s20
	s_nop 0
	global_load_lds_dwordx4 v[18:19], off
	s_waitcnt lgkmcnt(8)
	s_barrier
	s_waitcnt lgkmcnt(0)
	s_setprio 1
	s_waitcnt lgkmcnt(0)
	v_mfma_f32_16x16x32_bf16 v[16:19], v[110:113], v[146:149], v[70:73]
	v_mfma_f32_16x16x32_bf16 v[70:73], v[138:141], v[146:149], v[74:77]
	v_mfma_f32_16x16x32_bf16 v[74:77], v[110:113], v[182:185], v[78:81]
	v_mfma_f32_16x16x32_bf16 v[78:81], v[138:141], v[182:185], v[82:85]
	v_mfma_f32_16x16x32_bf16 v[82:85], v[110:113], v[190:193], v[86:89]
	v_mfma_f32_16x16x32_bf16 v[86:89], v[138:141], v[190:193], v[90:93]
	v_mfma_f32_16x16x32_bf16 v[90:93], v[110:113], v[198:201], v[94:97]
	v_mfma_f32_16x16x32_bf16 v[94:97], v[138:141], v[198:201], v[98:101]
	v_mfma_f32_16x16x32_bf16 v[16:19], v[114:117], v[150:153], v[16:19]
	v_mfma_f32_16x16x32_bf16 v[70:73], v[142:145], v[150:153], v[70:73]
	v_mfma_f32_16x16x32_bf16 v[74:77], v[114:117], v[186:189], v[74:77]
	v_mfma_f32_16x16x32_bf16 v[78:81], v[142:145], v[186:189], v[78:81]
	s_setprio 2
	s_barrier
	v_mfma_f32_16x16x32_bf16 v[82:85], v[114:117], v[194:197], v[82:85]
	v_mfma_f32_16x16x32_bf16 v[86:89], v[142:145], v[194:197], v[86:89]
	v_mfma_f32_16x16x32_bf16 v[90:93], v[114:117], v[202:205], v[90:93]
	v_mfma_f32_16x16x32_bf16 v[94:97], v[142:145], v[202:205], v[94:97]
	s_setprio 0
	s_mov_b32 m0, s18
	v_lshl_add_u64 v[12:13], v[12:13], 0, s[88:89]
	ds_read_b128 v[98:101], v129 offset:49152
	ds_read_b128 v[206:209], v129 offset:50176
	ds_read_b128 v[210:213], v129 offset:51200
	ds_read_b128 v[214:217], v129 offset:52224
	global_load_lds_dwordx4 v[12:13], off
	v_lshl_add_u64 v[12:13], v[14:15], 0, s[88:89]
	s_mov_b32 m0, s17
	s_nop 0
	global_load_lds_dwordx4 v[12:13], off
	s_barrier
; #define STAGE_A(P, br, kt) do { const char* _base = (const char*)(((kt) < G.ksplit ? G.A1 : A2m) + (long)(br) * G.lda + (long)(kt) * BK); \
;     __builtin_amdgcn_global_load_lds((const unsigned*)(_base + aoff0), (unsigned*)((char*)(P) + sb0), 16, 0, 0); \
;     __builtin_amdgcn_global_load_lds((const unsigned*)(_base + aoff1), (unsigned*)((char*)(P) + sb1), 16, 0, 0); } while (0)
; #define STAGE_B(P, br, kt) do { const char* _base = (const char*)(G.Bt + (long)(br) * G.ldb + (long)(kt) * BK); \
;     __builtin_amdgcn_global_load_lds((const unsigned*)(_base + boff0), (unsigned*)((char*)(P) + sb0), 16, 0, 0); \
;     __builtin_amdgcn_global_load_lds((const unsigned*)(_base + boff1), (unsigned*)((char*)(P) + sb1), 16, 0, 0); } while (0)
; #define LDA(dst, b, h) for (int m = 0; m < 4; ++m) for (int k = 0; k < 2; ++k) \
;     dst[m][k] = *reinterpret_cast<const bf16x8*>(a_rd + ((b) * 2 + (h)) * (HT * 2) + m * 2048 + k * 1024)
; #define LDB(dst, b, h) for (int n = 0; n < 2; ++n) for (int k = 0; k < 2; ++k) \
;     dst[n][k] = *reinterpret_cast<const bf16x8*>(b_rd + ((b) * 2 + (h)) * (HT * 2) + n * 2048 + k * 1024)
; #define MMA(ai, bj, At_, Bt_) do { __builtin_amdgcn_s_setprio(1); \
;     for (int m = 0; m < 4; ++m) for (int n = 0; n < 2; ++n) for (int k = 0; k < 2; ++k) \
;       acc[ai][bj][m][n] = __builtin_amdgcn_mfma_f32_16x16x32_bf16(Bt_[n][k], At_[m][k], acc[ai][bj][m][n], 0, 0, 0); \
;     __builtin_amdgcn_s_setprio(0); } while (0)
;     ...
;   for (int t = 0; t < nt - 2; t += 2) {
;     LDB(B0, 0, 0); SCHED; LDA(At, 0, 0); STAGE_A(SA(1, 1), brow + HALF, t + 1);
;     WAIT_L(8); BAR; WAIT_L(0); MMA(0, 0, At, B0); BAR; SCHED;
;     LDB(B1, 0, 1); STAGE_B(SB(0, 0), bcol, t + 2);
;     BAR; WAIT_L(0); MMA(0, 1, At, B1); BAR;
;     LDA(At, 0, 1); STAGE_A(SA(0, 0), brow, t + 2);
;     BAR; WAIT_L(0); MMA(1, 0, At, B0); BAR; SCHED;
;     STAGE_B(SB(0, 1), bcol + HALF, t + 2);
;     WAIT_V(6); BAR; MMA(1, 1, At, B1); BAR;
;     LDB(B0, 1, 0); SCHED; LDA(At, 1, 0); STAGE_A(SA(0, 1), brow + HALF, t + 2);
;     WAIT_L(8); BAR; WAIT_L(0); MMA(0, 0, At, B0); BAR; SCHED;
;     LDB(B1, 1, 1); STAGE_B(SB(1, 0), bcol, t + 3);
;     BAR; WAIT_L(0); MMA(0, 1, At, B1); BAR;
;     LDA(At, 1, 1); STAGE_A(SA(1, 0), brow, t + 3);
;     BAR; WAIT_L(0); MMA(1, 0, At, B0); BAR; SCHED;
;     STAGE_B(SB(1, 1), bcol + HALF, t + 3);
;     WAIT_V(6); BAR; MMA(1, 1, At, B1); BAR;
;   }
	s_waitcnt lgkmcnt(0)
	s_setprio 1
	s_waitcnt lgkmcnt(0)
	v_mfma_f32_16x16x32_bf16 v[12:15], v[98:101], v[146:149], v[118:121]
	v_mfma_f32_16x16x32_bf16 v[36:39], v[210:213], v[146:149], v[38:41]
	v_mfma_f32_16x16x32_bf16 v[40:43], v[98:101], v[182:185], v[42:45]
	v_mfma_f32_16x16x32_bf16 v[44:47], v[210:213], v[182:185], v[46:49]
	v_mfma_f32_16x16x32_bf16 v[48:51], v[98:101], v[190:193], v[50:53]
	v_mfma_f32_16x16x32_bf16 v[52:55], v[210:213], v[190:193], v[54:57]
	v_mfma_f32_16x16x32_bf16 v[56:59], v[98:101], v[198:201], v[58:61]
	v_mfma_f32_16x16x32_bf16 v[60:63], v[210:213], v[198:201], v[62:65]
	v_mfma_f32_16x16x32_bf16 v[12:15], v[206:209], v[150:153], v[12:15]
	v_mfma_f32_16x16x32_bf16 v[36:39], v[214:217], v[150:153], v[36:39]
	v_mfma_f32_16x16x32_bf16 v[40:43], v[206:209], v[186:189], v[40:43]
	v_mfma_f32_16x16x32_bf16 v[44:47], v[214:217], v[186:189], v[44:47]
	s_setprio 2
	s_barrier
	v_mfma_f32_16x16x32_bf16 v[48:51], v[206:209], v[194:197], v[48:51]
	v_mfma_f32_16x16x32_bf16 v[52:55], v[214:217], v[194:197], v[52:55]
	v_mfma_f32_16x16x32_bf16 v[56:59], v[206:209], v[202:205], v[56:59]
	v_mfma_f32_16x16x32_bf16 v[60:63], v[214:217], v[202:205], v[60:63]
	s_setprio 0
	s_mov_b32 m0, s15
	v_lshl_add_u64 v[8:9], v[8:9], 0, s[88:89]
	ds_read_b128 v[118:121], v178 offset:49152
	ds_read_b128 v[146:149], v178 offset:50176
	ds_read_b128 v[150:153], v178 offset:51200
	ds_read_b128 v[182:185], v178 offset:52224
	ds_read_b128 v[186:189], v178 offset:53248
	ds_read_b128 v[190:193], v178 offset:54272
	ds_read_b128 v[194:197], v178 offset:55296
	ds_read_b128 v[198:201], v178 offset:56320
	global_load_lds_dwordx4 v[8:9], off
	v_lshl_add_u64 v[8:9], v[10:11], 0, s[88:89]
	s_mov_b32 m0, s14
	s_nop 0
	global_load_lds_dwordx4 v[8:9], off
	s_barrier
	s_waitcnt lgkmcnt(0)
	s_setprio 1
	s_waitcnt lgkmcnt(0)
	v_mfma_f32_16x16x32_bf16 v[8:11], v[110:113], v[118:121], v[154:157]
	v_mfma_f32_16x16x32_bf16 v[20:23], v[110:113], v[194:197], v[20:23]
	v_mfma_f32_16x16x32_bf16 v[24:27], v[138:141], v[194:197], v[24:27]
	v_mfma_f32_16x16x32_bf16 v[8:11], v[114:117], v[146:149], v[8:11]
	v_mfma_f32_16x16x32_bf16 v[154:157], v[138:141], v[118:121], v[158:161]
	v_mfma_f32_16x16x32_bf16 v[158:161], v[110:113], v[150:153], v[162:165]
	v_mfma_f32_16x16x32_bf16 v[162:165], v[138:141], v[150:153], v[166:169]
	v_mfma_f32_16x16x32_bf16 v[166:169], v[110:113], v[186:189], v[170:173]
	v_mfma_f32_16x16x32_bf16 v[170:173], v[138:141], v[186:189], v[174:177]
	v_mfma_f32_16x16x32_bf16 v[20:23], v[114:117], v[198:201], v[20:23]
	v_mfma_f32_16x16x32_bf16 v[24:27], v[142:145], v[198:201], v[24:27]
	v_mfma_f32_16x16x32_bf16 v[154:157], v[142:145], v[146:149], v[154:157]
	s_setprio 2
	s_barrier
	v_mfma_f32_16x16x32_bf16 v[158:161], v[114:117], v[182:185], v[158:161]
	v_mfma_f32_16x16x32_bf16 v[162:165], v[142:145], v[182:185], v[162:165]
	v_mfma_f32_16x16x32_bf16 v[166:169], v[114:117], v[190:193], v[166:169]
	v_mfma_f32_16x16x32_bf16 v[170:173], v[142:145], v[190:193], v[170:173]
	s_setprio 0
	s_mov_b32 m0, s7
	v_lshl_add_u64 v[6:7], v[6:7], 0, s[88:89]
	global_load_lds_dwordx4 v[6:7], off
	v_lshl_add_u64 v[4:5], v[4:5], 0, s[88:89]
	s_mov_b32 m0, s6
	s_nop 0
	global_load_lds_dwordx4 v[4:5], off
	s_waitcnt vmcnt(6)
	s_barrier
	s_setprio 1
	v_mfma_f32_16x16x32_bf16 v[4:7], v[98:101], v[118:121], v[28:31]
	v_mfma_f32_16x16x32_bf16 v[28:31], v[210:213], v[118:121], v[32:35]
	v_mfma_f32_16x16x32_bf16 v[32:35], v[98:101], v[150:153], v[66:69]
	v_mfma_f32_16x16x32_bf16 v[64:67], v[210:213], v[150:153], v[122:125]
	v_mfma_f32_16x16x32_bf16 v[110:113], v[98:101], v[186:189], v[130:133]
	v_mfma_f32_16x16x32_bf16 v[114:117], v[210:213], v[186:189], v[134:137]
	v_mfma_f32_16x16x32_bf16 v[98:101], v[98:101], v[194:197], v[102:105]
	v_mfma_f32_16x16x32_bf16 v[102:105], v[210:213], v[194:197], v[106:109]
	v_mfma_f32_16x16x32_bf16 v[4:7], v[206:209], v[146:149], v[4:7]
	v_mfma_f32_16x16x32_bf16 v[28:31], v[214:217], v[146:149], v[28:31]
	v_mfma_f32_16x16x32_bf16 v[32:35], v[206:209], v[182:185], v[32:35]
	v_mfma_f32_16x16x32_bf16 v[64:67], v[214:217], v[182:185], v[64:67]
	s_setprio 2
	s_barrier
	v_mfma_f32_16x16x32_bf16 v[110:113], v[206:209], v[190:193], v[110:113]
	v_mfma_f32_16x16x32_bf16 v[114:117], v[214:217], v[190:193], v[114:117]
	v_mfma_f32_16x16x32_bf16 v[98:101], v[206:209], v[198:201], v[98:101]
	v_mfma_f32_16x16x32_bf16 v[102:105], v[214:217], v[198:201], v[102:105]
	s_setprio 0
	s_mov_b32 m0, s19
	v_lshl_add_u64 v[2:3], v[2:3], 0, s[88:89]
	ds_read_b128 v[106:109], v129
	ds_read_b128 v[118:121], v129 offset:1024
	ds_read_b128 v[122:125], v129 offset:2048
	ds_read_b128 v[130:133], v129 offset:3072
	ds_read_b128 v[134:137], v178
	ds_read_b128 v[138:141], v178 offset:1024
	ds_read_b128 v[142:145], v178 offset:2048
	ds_read_b128 v[146:149], v178 offset:3072
	ds_read_b128 v[150:153], v178 offset:4096
	ds_read_b128 v[174:177], v178 offset:5120
	ds_read_b128 v[182:185], v178 offset:6144
	ds_read_b128 v[186:189], v178 offset:7168
	global_load_lds_dwordx4 v[2:3], off
	v_lshl_add_u64 v[0:1], v[0:1], 0, s[88:89]
	s_mov_b32 m0, s16
	s_nop 0
	global_load_lds_dwordx4 v[0:1], off
	s_barrier
	s_waitcnt lgkmcnt(0)
	s_setprio 1
	s_waitcnt lgkmcnt(0)
	v_mfma_f32_16x16x32_bf16 v[0:3], v[106:109], v[134:137], v[16:19]
	v_mfma_f32_16x16x32_bf16 v[16:19], v[122:125], v[134:137], v[70:73]
	v_mfma_f32_16x16x32_bf16 v[68:71], v[106:109], v[142:145], v[74:77]
	v_mfma_f32_16x16x32_bf16 v[72:75], v[122:125], v[142:145], v[78:81]
	v_mfma_f32_16x16x32_bf16 v[76:79], v[106:109], v[150:153], v[82:85]
	v_mfma_f32_16x16x32_bf16 v[80:83], v[122:125], v[150:153], v[86:89]
	v_mfma_f32_16x16x32_bf16 v[84:87], v[106:109], v[182:185], v[90:93]
	v_mfma_f32_16x16x32_bf16 v[88:91], v[122:125], v[182:185], v[94:97]
	v_mfma_f32_16x16x32_bf16 v[0:3], v[118:121], v[138:141], v[0:3]
	v_mfma_f32_16x16x32_bf16 v[16:19], v[130:133], v[138:141], v[16:19]
	v_mfma_f32_16x16x32_bf16 v[68:71], v[118:121], v[146:149], v[68:71]
	v_mfma_f32_16x16x32_bf16 v[72:75], v[130:133], v[146:149], v[72:75]
	s_setprio 2
	s_barrier
; #define STAGE_A(P, br, kt) do { const char* _base = (const char*)(((kt) < G.ksplit ? G.A1 : A2m) + (long)(br) * G.lda + (long)(kt) * BK); \
;     __builtin_amdgcn_global_load_lds((const unsigned*)(_base + aoff0), (unsigned*)((char*)(P) + sb0), 16, 0, 0); \
;     __builtin_amdgcn_global_load_lds((const unsigned*)(_base + aoff1), (unsigned*)((char*)(P) + sb1), 16, 0, 0); } while (0)
; #define LDA(dst, b, h) for (int m = 0; m < 4; ++m) for (int k = 0; k < 2; ++k) \
;     dst[m][k] = *reinterpret_cast<const bf16x8*>(a_rd + ((b) * 2 + (h)) * (HT * 2) + m * 2048 + k * 1024)
; #define LDB(dst, b, h) for (int n = 0; n < 2; ++n) for (int k = 0; k < 2; ++k) \
;     dst[n][k] = *reinterpret_cast<const bf16x8*>(b_rd + ((b) * 2 + (h)) * (HT * 2) + n * 2048 + k * 1024)
; #define MMA(ai, bj, At_, Bt_) do { __builtin_amdgcn_s_setprio(1); \
;     for (int m = 0; m < 4; ++m) for (int n = 0; n < 2; ++n) for (int k = 0; k < 2; ++k) \
;       acc[ai][bj][m][n] = __builtin_amdgcn_mfma_f32_16x16x32_bf16(Bt_[n][k], At_[m][k], acc[ai][bj][m][n], 0, 0, 0); \
;     __builtin_amdgcn_s_setprio(0); } while (0)
; #define WAIT_V(n) asm volatile("s_waitcnt vmcnt(" #n ")" ::: "memory")
; #define WAIT_L(n) asm volatile("s_waitcnt lgkmcnt(" #n ")" ::: "memory")
; #define BAR __builtin_amdgcn_s_barrier()
;     ...
;   { LDB(B0, 0, 0); LDA(At, 0, 0); STAGE_A(SA(1, 1), brow + HALF, nt - 1);
;     BAR; WAIT_L(0); MMA(0, 0, At, B0); BAR;
;     LDB(B1, 0, 1); BAR; WAIT_L(0); MMA(0, 1, At, B1); BAR;
;     LDA(At, 0, 1); WAIT_V(4); BAR; WAIT_L(0); MMA(1, 0, At, B0); MMA(1, 1, At, B1); BAR; }
;   { LDB(B0, 1, 0); LDA(At, 1, 0); WAIT_V(2); BAR; WAIT_L(0); MMA(0, 0, At, B0); BAR;
;     LDB(B1, 1, 1); WAIT_V(0); BAR; WAIT_L(0); MMA(0, 1, At, B1); BAR;
;     LDA(At, 1, 1); BAR; WAIT_L(0); MMA(1, 0, At, B0); MMA(1, 1, At, B1); BAR; }
	v_mfma_f32_16x16x32_bf16 v[76:79], v[118:121], v[174:177], v[76:79]
	v_mfma_f32_16x16x32_bf16 v[80:83], v[130:133], v[174:177], v[80:83]
	v_mfma_f32_16x16x32_bf16 v[84:87], v[118:121], v[186:189], v[84:87]
	v_mfma_f32_16x16x32_bf16 v[88:91], v[130:133], v[186:189], v[88:91]
	s_setprio 0
	ds_read_b128 v[92:95], v129 offset:16384
	ds_read_b128 v[190:193], v129 offset:17408
	ds_read_b128 v[194:197], v129 offset:18432
	ds_read_b128 v[198:201], v129 offset:19456
	s_barrier
	s_waitcnt lgkmcnt(0)
	s_setprio 1
	s_waitcnt lgkmcnt(0)
	v_mfma_f32_16x16x32_bf16 v[12:15], v[92:95], v[134:137], v[12:15]
	v_mfma_f32_16x16x32_bf16 v[36:39], v[194:197], v[134:137], v[36:39]
	v_mfma_f32_16x16x32_bf16 v[40:43], v[92:95], v[142:145], v[40:43]
	v_mfma_f32_16x16x32_bf16 v[44:47], v[194:197], v[142:145], v[44:47]
	v_mfma_f32_16x16x32_bf16 v[48:51], v[92:95], v[150:153], v[48:51]
	v_mfma_f32_16x16x32_bf16 v[52:55], v[194:197], v[150:153], v[52:55]
	v_mfma_f32_16x16x32_bf16 v[56:59], v[92:95], v[182:185], v[56:59]
	v_mfma_f32_16x16x32_bf16 v[60:63], v[194:197], v[182:185], v[60:63]
	v_mfma_f32_16x16x32_bf16 v[12:15], v[190:193], v[138:141], v[12:15]
	v_mfma_f32_16x16x32_bf16 v[36:39], v[198:201], v[138:141], v[36:39]
	v_mfma_f32_16x16x32_bf16 v[40:43], v[190:193], v[146:149], v[40:43]
	v_mfma_f32_16x16x32_bf16 v[44:47], v[198:201], v[146:149], v[44:47]
	s_setprio 2
	s_barrier
	v_mfma_f32_16x16x32_bf16 v[48:51], v[190:193], v[174:177], v[48:51]
	v_mfma_f32_16x16x32_bf16 v[52:55], v[198:201], v[174:177], v[52:55]
	v_mfma_f32_16x16x32_bf16 v[56:59], v[190:193], v[186:189], v[56:59]
	v_mfma_f32_16x16x32_bf16 v[60:63], v[198:201], v[186:189], v[60:63]
	s_setprio 0
	ds_read_b128 v[134:137], v178 offset:16384
	ds_read_b128 v[138:141], v178 offset:17408
	ds_read_b128 v[142:145], v178 offset:18432
	ds_read_b128 v[146:149], v178 offset:19456
	ds_read_b128 v[150:153], v178 offset:20480
	ds_read_b128 v[174:177], v178 offset:21504
	ds_read_b128 v[182:185], v178 offset:22528
	ds_read_b128 v[186:189], v178 offset:23552
	s_waitcnt vmcnt(4)
	s_barrier
	s_waitcnt lgkmcnt(0)
	s_setprio 1
	s_waitcnt lgkmcnt(0)
	v_mfma_f32_16x16x32_bf16 v[8:11], v[106:109], v[134:137], v[8:11]
	v_mfma_f32_16x16x32_bf16 v[20:23], v[106:109], v[182:185], v[20:23]
	v_mfma_f32_16x16x32_bf16 v[24:27], v[122:125], v[182:185], v[24:27]
	v_mfma_f32_16x16x32_bf16 v[8:11], v[118:121], v[138:141], v[8:11]
	v_mfma_f32_16x16x32_bf16 v[154:157], v[122:125], v[134:137], v[154:157]
	v_mfma_f32_16x16x32_bf16 v[158:161], v[106:109], v[142:145], v[158:161]
	v_mfma_f32_16x16x32_bf16 v[162:165], v[122:125], v[142:145], v[162:165]
	v_mfma_f32_16x16x32_bf16 v[166:169], v[106:109], v[150:153], v[166:169]
	v_mfma_f32_16x16x32_bf16 v[170:173], v[122:125], v[150:153], v[170:173]
	v_mfma_f32_16x16x32_bf16 v[20:23], v[118:121], v[186:189], v[20:23]
	v_mfma_f32_16x16x32_bf16 v[24:27], v[130:133], v[186:189], v[24:27]
	v_mfma_f32_16x16x32_bf16 v[154:157], v[130:133], v[138:141], v[154:157]
	v_mfma_f32_16x16x32_bf16 v[158:161], v[118:121], v[146:149], v[158:161]
	v_mfma_f32_16x16x32_bf16 v[162:165], v[130:133], v[146:149], v[162:165]
	v_mfma_f32_16x16x32_bf16 v[166:169], v[118:121], v[174:177], v[166:169]
	v_mfma_f32_16x16x32_bf16 v[170:173], v[130:133], v[174:177], v[170:173]
	s_setprio 0
	s_setprio 1
	v_mfma_f32_16x16x32_bf16 v[28:31], v[194:197], v[134:137], v[28:31]
	v_mfma_f32_16x16x32_bf16 v[130:133], v[198:201], v[138:141], v[28:31]
	v_mfma_f32_16x16x32_bf16 v[28:31], v[92:95], v[142:145], v[32:35]
	v_mfma_f32_16x16x32_bf16 v[4:7], v[92:95], v[134:137], v[4:7]
	v_mfma_f32_16x16x32_bf16 v[134:137], v[190:193], v[146:149], v[28:31]
	v_mfma_f32_16x16x32_bf16 v[28:31], v[194:197], v[142:145], v[64:67]
	v_mfma_f32_16x16x32_bf16 v[4:7], v[190:193], v[138:141], v[4:7]
	v_mfma_f32_16x16x32_bf16 v[138:141], v[198:201], v[146:149], v[28:31]
	v_mfma_f32_16x16x32_bf16 v[28:31], v[92:95], v[150:153], v[110:113]
	v_mfma_f32_16x16x32_bf16 v[142:145], v[190:193], v[174:177], v[28:31]
	v_mfma_f32_16x16x32_bf16 v[28:31], v[194:197], v[150:153], v[114:117]
	v_mfma_f32_16x16x32_bf16 v[146:149], v[198:201], v[174:177], v[28:31]
	s_setprio 2
	s_barrier
	v_mfma_f32_16x16x32_bf16 v[28:31], v[92:95], v[182:185], v[98:101]
	v_mfma_f32_16x16x32_bf16 v[150:153], v[190:193], v[186:189], v[28:31]
	v_mfma_f32_16x16x32_bf16 v[28:31], v[194:197], v[182:185], v[102:105]
	v_mfma_f32_16x16x32_bf16 v[174:177], v[198:201], v[186:189], v[28:31]
	s_setprio 0
	s_nop 4
	ds_read_b128 v[28:31], v129 offset:32768
	ds_read_b128 v[32:35], v129 offset:33792
	ds_read_b128 v[182:185], v129 offset:34816
	ds_read_b128 v[186:189], v129 offset:35840
	ds_read_b128 v[64:67], v178 offset:32768
	ds_read_b128 v[190:193], v178 offset:33792
	ds_read_b128 v[194:197], v178 offset:34816
	ds_read_b128 v[198:201], v178 offset:35840
	ds_read_b128 v[202:205], v178 offset:36864
	ds_read_b128 v[206:209], v178 offset:37888
	ds_read_b128 v[210:213], v178 offset:38912
	ds_read_b128 v[214:217], v178 offset:39936
	s_waitcnt vmcnt(2)
	s_barrier
; #define LDA(dst, b, h) for (int m = 0; m < 4; ++m) for (int k = 0; k < 2; ++k) \
;     dst[m][k] = *reinterpret_cast<const bf16x8*>(a_rd + ((b) * 2 + (h)) * (HT * 2) + m * 2048 + k * 1024)
; #define LDB(dst, b, h) for (int n = 0; n < 2; ++n) for (int k = 0; k < 2; ++k) \
;     dst[n][k] = *reinterpret_cast<const bf16x8*>(b_rd + ((b) * 2 + (h)) * (HT * 2) + n * 2048 + k * 1024)
; #define MMA(ai, bj, At_, Bt_) do { __builtin_amdgcn_s_setprio(1); \
;     for (int m = 0; m < 4; ++m) for (int n = 0; n < 2; ++n) for (int k = 0; k < 2; ++k) \
;       acc[ai][bj][m][n] = __builtin_amdgcn_mfma_f32_16x16x32_bf16(Bt_[n][k], At_[m][k], acc[ai][bj][m][n], 0, 0, 0); \
;     __builtin_amdgcn_s_setprio(0); } while (0)
; #define WAIT_V(n) asm volatile("s_waitcnt vmcnt(" #n ")" ::: "memory")
; #define WAIT_L(n) asm volatile("s_waitcnt lgkmcnt(" #n ")" ::: "memory")
; #define BAR __builtin_amdgcn_s_barrier()
;     ...
;     LDA(At, 0, 1); WAIT_V(4); BAR; WAIT_L(0); MMA(1, 0, At, B0); MMA(1, 1, At, B1); BAR; }
;   { LDB(B0, 1, 0); LDA(At, 1, 0); WAIT_V(2); BAR; WAIT_L(0); MMA(0, 0, At, B0); BAR;
;     LDB(B1, 1, 1); WAIT_V(0); BAR; WAIT_L(0); MMA(0, 1, At, B1); BAR;
;     LDA(At, 1, 1); BAR; WAIT_L(0); MMA(1, 0, At, B0); MMA(1, 1, At, B1); BAR; }
;   if (wr == 0) BAR;
	s_waitcnt lgkmcnt(0)
	s_setprio 1
	s_waitcnt lgkmcnt(0)
	v_mfma_f32_16x16x32_bf16 v[0:3], v[28:31], v[64:67], v[0:3]
	v_mfma_f32_16x16x32_bf16 v[124:127], v[32:35], v[190:193], v[0:3]
	v_mfma_f32_16x16x32_bf16 v[0:3], v[182:185], v[64:67], v[16:19]
	v_mfma_f32_16x16x32_bf16 v[120:123], v[186:189], v[190:193], v[0:3]
	v_mfma_f32_16x16x32_bf16 v[0:3], v[28:31], v[194:197], v[68:71]
	v_mfma_f32_16x16x32_bf16 v[116:119], v[32:35], v[198:201], v[0:3]
	v_mfma_f32_16x16x32_bf16 v[0:3], v[182:185], v[194:197], v[72:75]
	v_mfma_f32_16x16x32_bf16 v[112:115], v[186:189], v[198:201], v[0:3]
	v_mfma_f32_16x16x32_bf16 v[0:3], v[28:31], v[202:205], v[76:79]
	v_mfma_f32_16x16x32_bf16 v[108:111], v[32:35], v[206:209], v[0:3]
	v_mfma_f32_16x16x32_bf16 v[0:3], v[182:185], v[202:205], v[80:83]
	v_mfma_f32_16x16x32_bf16 v[104:107], v[186:189], v[206:209], v[0:3]
	s_setprio 2
	s_barrier
	v_mfma_f32_16x16x32_bf16 v[0:3], v[28:31], v[210:213], v[84:87]
	v_mfma_f32_16x16x32_bf16 v[100:103], v[32:35], v[214:217], v[0:3]
	v_mfma_f32_16x16x32_bf16 v[0:3], v[182:185], v[210:213], v[88:91]
	v_mfma_f32_16x16x32_bf16 v[96:99], v[186:189], v[214:217], v[0:3]
	s_setprio 0
	s_nop 4
	ds_read_b128 v[0:3], v129 offset:49152
	ds_read_b128 v[218:221], v129 offset:50176
	ds_read_b128 v[230:233], v129 offset:51200
	ds_read_b128 v[238:241], v129 offset:52224
	s_waitcnt vmcnt(0)
	s_barrier
	s_waitcnt lgkmcnt(0)
	s_setprio 1
	s_waitcnt lgkmcnt(0)
	v_mfma_f32_16x16x32_bf16 v[12:15], v[0:3], v[64:67], v[12:15]
	v_mfma_f32_16x16x32_bf16 v[92:95], v[218:221], v[190:193], v[12:15]
	v_mfma_f32_16x16x32_bf16 v[12:15], v[230:233], v[64:67], v[36:39]
	v_mfma_f32_16x16x32_bf16 v[88:91], v[238:241], v[190:193], v[12:15]
	v_mfma_f32_16x16x32_bf16 v[12:15], v[0:3], v[194:197], v[40:43]
	v_mfma_f32_16x16x32_bf16 v[84:87], v[218:221], v[198:201], v[12:15]
	v_mfma_f32_16x16x32_bf16 v[12:15], v[230:233], v[194:197], v[44:47]
	v_mfma_f32_16x16x32_bf16 v[80:83], v[238:241], v[198:201], v[12:15]
	v_mfma_f32_16x16x32_bf16 v[12:15], v[0:3], v[202:205], v[48:51]
	v_mfma_f32_16x16x32_bf16 v[76:79], v[218:221], v[206:209], v[12:15]
	v_mfma_f32_16x16x32_bf16 v[12:15], v[230:233], v[202:205], v[52:55]
	v_mfma_f32_16x16x32_bf16 v[72:75], v[238:241], v[206:209], v[12:15]
	s_setprio 2
	s_barrier
	v_mfma_f32_16x16x32_bf16 v[12:15], v[0:3], v[210:213], v[56:59]
	v_mfma_f32_16x16x32_bf16 v[68:71], v[218:221], v[214:217], v[12:15]
	v_mfma_f32_16x16x32_bf16 v[12:15], v[230:233], v[210:213], v[60:63]
	v_mfma_f32_16x16x32_bf16 v[64:67], v[238:241], v[214:217], v[12:15]
	s_setprio 0
	s_nop 4
	ds_read_b128 v[12:15], v178 offset:49152
	ds_read_b128 v[16:19], v178 offset:50176
	ds_read_b128 v[190:193], v178 offset:51200
	ds_read_b128 v[194:197], v178 offset:52224
	ds_read_b128 v[198:201], v178 offset:53248
	ds_read_b128 v[202:205], v178 offset:54272
	ds_read_b128 v[206:209], v178 offset:55296
	ds_read_b128 v[210:213], v178 offset:56320
	s_barrier
	s_waitcnt lgkmcnt(0)
	s_setprio 1
	s_waitcnt lgkmcnt(0)
	v_mfma_f32_16x16x32_bf16 v[8:11], v[28:31], v[12:15], v[8:11]
	v_mfma_f32_16x16x32_bf16 v[60:63], v[32:35], v[16:19], v[8:11]
	v_mfma_f32_16x16x32_bf16 v[8:11], v[182:185], v[12:15], v[154:157]
	v_mfma_f32_16x16x32_bf16 v[56:59], v[186:189], v[16:19], v[8:11]
	v_mfma_f32_16x16x32_bf16 v[8:11], v[28:31], v[190:193], v[158:161]
	v_mfma_f32_16x16x32_bf16 v[52:55], v[32:35], v[194:197], v[8:11]
	v_mfma_f32_16x16x32_bf16 v[8:11], v[182:185], v[190:193], v[162:165]
	v_mfma_f32_16x16x32_bf16 v[48:51], v[186:189], v[194:197], v[8:11]
	v_mfma_f32_16x16x32_bf16 v[8:11], v[28:31], v[198:201], v[166:169]
	v_mfma_f32_16x16x32_bf16 v[44:47], v[32:35], v[202:205], v[8:11]
	v_mfma_f32_16x16x32_bf16 v[8:11], v[182:185], v[198:201], v[170:173]
	v_mfma_f32_16x16x32_bf16 v[40:43], v[186:189], v[202:205], v[8:11]
	v_mfma_f32_16x16x32_bf16 v[8:11], v[28:31], v[206:209], v[20:23]
	v_mfma_f32_16x16x32_bf16 v[36:39], v[32:35], v[210:213], v[8:11]
	v_mfma_f32_16x16x32_bf16 v[8:11], v[182:185], v[206:209], v[24:27]
	v_mfma_f32_16x16x32_bf16 v[32:35], v[186:189], v[210:213], v[8:11]
	s_setprio 0
	s_setprio 1
	v_mfma_f32_16x16x32_bf16 v[4:7], v[0:3], v[12:15], v[4:7]
	v_mfma_f32_16x16x32_bf16 v[28:31], v[218:221], v[16:19], v[4:7]
	v_mfma_f32_16x16x32_bf16 v[4:7], v[230:233], v[12:15], v[130:133]
	v_mfma_f32_16x16x32_bf16 v[24:27], v[238:241], v[16:19], v[4:7]
	v_mfma_f32_16x16x32_bf16 v[4:7], v[0:3], v[190:193], v[134:137]
	v_mfma_f32_16x16x32_bf16 v[20:23], v[218:221], v[194:197], v[4:7]
	v_mfma_f32_16x16x32_bf16 v[4:7], v[230:233], v[190:193], v[138:141]
	v_mfma_f32_16x16x32_bf16 v[16:19], v[238:241], v[194:197], v[4:7]
	v_mfma_f32_16x16x32_bf16 v[4:7], v[0:3], v[198:201], v[142:145]
	v_mfma_f32_16x16x32_bf16 v[12:15], v[218:221], v[202:205], v[4:7]
	v_mfma_f32_16x16x32_bf16 v[4:7], v[230:233], v[198:201], v[146:149]
	v_mfma_f32_16x16x32_bf16 v[0:3], v[0:3], v[206:209], v[150:153]
	s_setprio 2
	s_barrier
	v_mfma_f32_16x16x32_bf16 v[8:11], v[238:241], v[202:205], v[4:7]
	v_mfma_f32_16x16x32_bf16 v[4:7], v[218:221], v[210:213], v[0:3]
	v_mfma_f32_16x16x32_bf16 v[0:3], v[230:233], v[206:209], v[174:177]
	v_mfma_f32_16x16x32_bf16 v[0:3], v[238:241], v[210:213], v[0:3]
	s_setprio 0
	v_cmp_gt_u32_e32 vcc, s60, v128
	s_and_saveexec_b64 s[6:7], vcc
	s_cbranch_execz .LBB0_2416
	s_barrier
	s_branch .LBB0_2416

; #define STAGE_A(P, br, kt) do { const char* _base = (const char*)(((kt) < G.ksplit ? G.A1 : A2m) + (long)(br) * G.lda + (long)(kt) * BK); \
;     __builtin_amdgcn_global_load_lds((const unsigned*)(_base + aoff0), (unsigned*)((char*)(P) + sb0), 16, 0, 0); \
;     __builtin_amdgcn_global_load_lds((const unsigned*)(_base + aoff1), (unsigned*)((char*)(P) + sb1), 16, 0, 0); } while (0)
; #define STAGE_B(P, br, kt) do { const char* _base = (const char*)(G.Bt + (long)(br) * G.ldb + (long)(kt) * BK); \
;     __builtin_amdgcn_global_load_lds((const unsigned*)(_base + boff0), (unsigned*)((char*)(P) + sb0), 16, 0, 0); \
;     __builtin_amdgcn_global_load_lds((const unsigned*)(_base + boff1), (unsigned*)((char*)(P) + sb1), 16, 0, 0); } while (0)
; #define LDA(dst, b, h) for (int m = 0; m < 4; ++m) for (int k = 0; k < 2; ++k) \
;     dst[m][k] = *reinterpret_cast<const bf16x8*>(a_rd + ((b) * 2 + (h)) * (HT * 2) + m * 2048 + k * 1024)
; #define LDB(dst, b, h) for (int n = 0; n < 2; ++n) for (int k = 0; k < 2; ++k) \
;     dst[n][k] = *reinterpret_cast<const bf16x8*>(b_rd + ((b) * 2 + (h)) * (HT * 2) + n * 2048 + k * 1024)
; #define MMA(ai, bj, At_, Bt_) do { __builtin_amdgcn_s_setprio(1); \
;     for (int m = 0; m < 4; ++m) for (int n = 0; n < 2; ++n) for (int k = 0; k < 2; ++k) \
;       acc[ai][bj][m][n] = __builtin_amdgcn_mfma_f32_16x16x32_bf16(Bt_[n][k], At_[m][k], acc[ai][bj][m][n], 0, 0, 0); \
;     __builtin_amdgcn_s_setprio(0); } while (0)
; #define WAIT_V(n) asm volatile("s_waitcnt vmcnt(" #n ")" ::: "memory")
; #define WAIT_L(n) asm volatile("s_waitcnt lgkmcnt(" #n ")" ::: "memory")
; #define BAR __builtin_amdgcn_s_barrier()
; #define SCHED __builtin_amdgcn_sched_barrier(0)
;     ...
;   if (EPI == EPI_RESID || first) {
;     STAGE_B(SB(0, 0), bcol, 0); STAGE_A(SA(0, 0), brow, 0);
;     STAGE_B(SB(0, 1), bcol + HALF, 0); STAGE_A(SA(0, 1), brow + HALF, 0);
;   }
;   if (wr == 1) BAR;
;   WAIT_V(0); BAR;
;   STAGE_B(SB(1, 0), bcol, 1); STAGE_A(SA(1, 0), brow, 1); STAGE_B(SB(1, 1), bcol + HALF, 1);
;   WAIT_V(6); BAR;
;   for (int t = 0; t < nt - 2; t += 2) {
;     LDB(B0, 0, 0); SCHED; LDA(At, 0, 0); STAGE_A(SA(1, 1), brow + HALF, t + 1);
;     WAIT_L(8); BAR; WAIT_L(0); MMA(0, 0, At, B0); BAR; SCHED;
;     LDB(B1, 0, 1); STAGE_B(SB(0, 0), bcol, t + 2);
;     BAR; WAIT_L(0); MMA(0, 1, At, B1); BAR;
.LBB0_2500:
	s_or_b64 exec, exec, s[8:9]
	v_and_b32_e32 v20, 15, v144
	v_lshlrev_b32_e32 v22, 2, v144
	v_and_b32_e32 v21, 48, v144
	v_lshlrev_b32_e32 v20, 6, v20
	v_and_b32_e32 v22, 32, v22
	v_bitop3_b32 v20, v20, v22, v21 bitop3:0x36
	v_lshlrev_b32_e32 v21, 6, v144
	v_and_b32_e32 v21, 0x3000, v21
	v_add_u32_e32 v21, s35, v21
	v_readlane_b32 s35, v253, 46
	s_mov_b64 s[38:39], 0x80
	v_lshl_add_u64 v[2:3], v[2:3], 0, s[38:39]
	v_add_u32_e32 v153, s35, v12
	v_add_u32_e32 v154, 0x2000, v153
	v_readfirstlane_b32 s35, v153
	s_mov_b32 m0, s35
	v_readfirstlane_b32 s35, v154
	v_add_u32_e32 v155, 0x8000, v147
	s_waitcnt vmcnt(0)
	s_barrier
	global_load_lds_dwordx4 v[2:3], off
	v_lshl_add_u64 v[2:3], v[4:5], 0, s[38:39]
	s_mov_b32 m0, s35
	v_readfirstlane_b32 s35, v155
	v_add_u32_e32 v156, 0xa000, v147
	global_load_lds_dwordx4 v[2:3], off
	v_lshl_add_u64 v[2:3], v[6:7], 0, s[38:39]
	s_mov_b32 m0, s35
	v_readfirstlane_b32 s35, v156
	s_lshl_b64 s[8:9], s[18:19], 10
	global_load_lds_dwordx4 v[2:3], off
	s_mov_b32 m0, s35
	v_readlane_b32 s35, v253, 47
	s_add_u32 s36, s36, 0x84080
	v_lshl_add_u64 v[2:3], v[8:9], 0, s[38:39]
	v_add_u32_e32 v157, s35, v12
	s_addc_u32 s37, s37, 0
	v_readfirstlane_b32 s35, v157
	v_add_u32_e32 v158, 0x2000, v157
	global_load_lds_dwordx4 v[2:3], off
	v_lshl_add_u64 v[2:3], s[36:37], 0, v[180:181]
	s_mov_b32 m0, s35
	v_readfirstlane_b32 s35, v158
	global_load_lds_dwordx4 v[2:3], off
	v_lshl_add_u64 v[0:1], s[36:37], 0, v[0:1]
	s_mov_b32 m0, s35
	v_lshrrev_b32_e32 v2, 1, v11
	global_load_lds_dwordx4 v[0:1], off
	v_lshrrev_b32_e32 v1, 1, v10
	v_mul_lo_u32 v0, v13, s62
	v_mad_u64_u32 v[0:1], s[36:37], v1, s84, v[0:1]
	v_or_b32_e32 v0, v0, v14
	v_add_lshl_u32 v180, v0, v16, 1
	v_mul_lo_u32 v0, v15, s62
	v_lshlrev_b32_e32 v3, 11, v15
	v_mad_u64_u32 v[0:1], s[36:37], v2, s84, v[0:1]
	v_lshl_add_u32 v2, v2, 15, v3
	v_and_b32_e32 v3, 1, v11
	s_add_u32 s24, s12, s24
	v_lshl_or_b32 v2, v3, 6, v2
	s_addc_u32 s25, s13, s25
	v_lshl_add_u32 v2, v17, 1, v2
	v_mov_b32_e32 v3, v181
	v_or_b32_e32 v0, v0, v18
	v_lshl_add_u64 v[136:137], s[10:11], 0, v[130:131]
	v_lshl_add_u64 v[138:139], s[10:11], 0, v[2:3]
	s_add_u32 s10, s12, s22
	s_waitcnt vmcnt(6)
	v_add_lshl_u32 v0, v0, v17, 1
	v_mov_b32_e32 v1, v181
	s_addc_u32 s11, s13, s23
	v_lshl_add_u32 v19, v19, 13, 32
	v_lshl_add_u64 v[134:135], s[24:25], 0, v[0:1]
	v_lshl_add_u64 v[142:143], s[10:11], 0, v[0:1]
	v_lshl_add_u64 v[132:133], s[24:25], 0, v[180:181]
	v_lshl_add_u64 v[140:141], s[10:11], 0, v[180:181]
	s_mov_b32 s22, -2
	s_mov_b64 s[10:11], 0
	v_add_u32_e32 v149, v21, v20
	v_add_u32_e32 v146, v19, v20
	s_waitcnt vmcnt(0)
	s_mov_b64 s[36:37], 0x40080
	s_mov_b64 s[38:39], 0x54e8100
	s_mov_b64 s[40:41], 0x556c100
	s_mov_b64 s[42:43], 0x40100
	s_mov_b64 s[44:45], 0x54e8180
	s_mov_b64 s[46:47], 0x556c180
	s_barrier
	ds_read_b128 v[162:165], v149
	ds_read_b128 v[166:169], v149 offset:1024
	ds_read_b128 v[170:173], v149 offset:2048
	ds_read_b128 v[174:177], v149 offset:3072
	s_add_i32 s22, s22, 2
	s_cmp_lt_u32 s22, 16
	s_cselect_b32 s25, s28, s34
	s_cselect_b32 s24, s27, s31
	v_lshl_add_u64 v[160:161], s[24:25], 0, v[136:137]
	v_add_u32_e32 v159, 0xc000, v147
	v_lshl_add_u64 v[160:161], v[160:161], 0, s[10:11]
	v_readfirstlane_b32 s23, v159
	v_lshl_add_u64 v[160:161], v[160:161], 0, s[36:37]
	s_mov_b32 m0, s23
	ds_read_b128 v[182:185], v146
	ds_read_b128 v[186:189], v146 offset:1024
	ds_read_b128 v[190:193], v146 offset:2048
	ds_read_b128 v[194:197], v146 offset:3072
	ds_read_b128 v[198:201], v146 offset:4096
	ds_read_b128 v[202:205], v146 offset:5120
	ds_read_b128 v[206:209], v146 offset:6144
	ds_read_b128 v[210:213], v146 offset:7168
	global_load_lds_dwordx4 v[160:161], off
	v_lshl_add_u64 v[160:161], s[24:25], 0, v[138:139]
	v_lshl_add_u64 v[160:161], v[160:161], 0, s[10:11]
	v_lshl_add_u64 v[178:179], v[160:161], 0, s[36:37]
	v_add_u32_e32 v160, 0xe000, v147
	s_nop 0
	v_readfirstlane_b32 s23, v160
	s_mov_b32 m0, s23
	s_nop 0
	global_load_lds_dwordx4 v[178:179], off
	ds_read_b128 v[214:217], v149 offset:16384
	ds_read_b128 v[218:221], v149 offset:17408
	ds_read_b128 v[246:249], v149 offset:18432
	ds_read_b128 v[230:233], v149 offset:19456
	s_waitcnt lgkmcnt(0)
	s_waitcnt vmcnt(8)
	s_barrier
	s_setprio 1
	v_mfma_f32_16x16x32_bf16 v[124:127], v[162:165], v[182:185], 0
	v_mfma_f32_16x16x32_bf16 v[120:123], v[170:173], v[182:185], 0
	v_mfma_f32_16x16x32_bf16 v[116:119], v[162:165], v[190:193], 0
	v_mfma_f32_16x16x32_bf16 v[112:115], v[170:173], v[190:193], 0
	v_mfma_f32_16x16x32_bf16 v[108:111], v[162:165], v[198:201], 0
	v_mfma_f32_16x16x32_bf16 v[104:107], v[170:173], v[198:201], 0
	v_mfma_f32_16x16x32_bf16 v[100:103], v[162:165], v[206:209], 0
	v_mfma_f32_16x16x32_bf16 v[96:99], v[170:173], v[206:209], 0
	v_mfma_f32_16x16x32_bf16 v[124:127], v[166:169], v[186:189], v[124:127]
	v_mfma_f32_16x16x32_bf16 v[120:123], v[174:177], v[186:189], v[120:123]
	v_mfma_f32_16x16x32_bf16 v[116:119], v[166:169], v[194:197], v[116:119]
	v_mfma_f32_16x16x32_bf16 v[112:115], v[174:177], v[194:197], v[112:115]
	v_mfma_f32_16x16x32_bf16 v[108:111], v[166:169], v[202:205], v[108:111]
	v_mfma_f32_16x16x32_bf16 v[104:107], v[174:177], v[202:205], v[104:107]
	v_mfma_f32_16x16x32_bf16 v[100:103], v[166:169], v[210:213], v[100:103]
	v_mfma_f32_16x16x32_bf16 v[96:99], v[174:177], v[210:213], v[96:99]
	v_mfma_f32_16x16x32_bf16 v[92:95], v[214:217], v[182:185], 0
	v_mfma_f32_16x16x32_bf16 v[88:91], v[246:249], v[182:185], 0
	v_mfma_f32_16x16x32_bf16 v[84:87], v[214:217], v[190:193], 0
	v_mfma_f32_16x16x32_bf16 v[80:83], v[246:249], v[190:193], 0
	v_mfma_f32_16x16x32_bf16 v[76:79], v[214:217], v[198:201], 0
	v_mfma_f32_16x16x32_bf16 v[72:75], v[246:249], v[198:201], 0
	v_mfma_f32_16x16x32_bf16 v[68:71], v[214:217], v[206:209], 0
	v_mfma_f32_16x16x32_bf16 v[64:67], v[246:249], v[206:209], 0
	v_mfma_f32_16x16x32_bf16 v[92:95], v[218:221], v[186:189], v[92:95]
	v_mfma_f32_16x16x32_bf16 v[88:91], v[230:233], v[186:189], v[88:91]
	v_mfma_f32_16x16x32_bf16 v[84:87], v[218:221], v[194:197], v[84:87]
	v_mfma_f32_16x16x32_bf16 v[80:83], v[230:233], v[194:197], v[80:83]
	s_setprio 2
	s_barrier
; #define STAGE_A(P, br, kt) do { const char* _base = (const char*)(((kt) < G.ksplit ? G.A1 : A2m) + (long)(br) * G.lda + (long)(kt) * BK); \
;     __builtin_amdgcn_global_load_lds((const unsigned*)(_base + aoff0), (unsigned*)((char*)(P) + sb0), 16, 0, 0); \
;     __builtin_amdgcn_global_load_lds((const unsigned*)(_base + aoff1), (unsigned*)((char*)(P) + sb1), 16, 0, 0); } while (0)
; #define STAGE_B(P, br, kt) do { const char* _base = (const char*)(G.Bt + (long)(br) * G.ldb + (long)(kt) * BK); \
;     __builtin_amdgcn_global_load_lds((const unsigned*)(_base + boff0), (unsigned*)((char*)(P) + sb0), 16, 0, 0); \
;     __builtin_amdgcn_global_load_lds((const unsigned*)(_base + boff1), (unsigned*)((char*)(P) + sb1), 16, 0, 0); } while (0)
; #define LDA(dst, b, h) for (int m = 0; m < 4; ++m) for (int k = 0; k < 2; ++k) \
;     dst[m][k] = *reinterpret_cast<const bf16x8*>(a_rd + ((b) * 2 + (h)) * (HT * 2) + m * 2048 + k * 1024)
; #define LDB(dst, b, h) for (int n = 0; n < 2; ++n) for (int k = 0; k < 2; ++k) \
;     dst[n][k] = *reinterpret_cast<const bf16x8*>(b_rd + ((b) * 2 + (h)) * (HT * 2) + n * 2048 + k * 1024)
; #define MMA(ai, bj, At_, Bt_) do { __builtin_amdgcn_s_setprio(1); \
;     for (int m = 0; m < 4; ++m) for (int n = 0; n < 2; ++n) for (int k = 0; k < 2; ++k) \
;       acc[ai][bj][m][n] = __builtin_amdgcn_mfma_f32_16x16x32_bf16(Bt_[n][k], At_[m][k], acc[ai][bj][m][n], 0, 0, 0); \
;     __builtin_amdgcn_s_setprio(0); } while (0)
;     ...
;   for (int t = 0; t < nt - 2; t += 2) {
;     LDB(B0, 0, 0); SCHED; LDA(At, 0, 0); STAGE_A(SA(1, 1), brow + HALF, t + 1);
;     WAIT_L(8); BAR; WAIT_L(0); MMA(0, 0, At, B0); BAR; SCHED;
;     LDB(B1, 0, 1); STAGE_B(SB(0, 0), bcol, t + 2);
;     BAR; WAIT_L(0); MMA(0, 1, At, B1); BAR;
;     LDA(At, 0, 1); STAGE_A(SA(0, 0), brow, t + 2);
;     BAR; WAIT_L(0); MMA(1, 0, At, B0); BAR; SCHED;
;     STAGE_B(SB(0, 1), bcol + HALF, t + 2);
;     WAIT_V(6); BAR; MMA(1, 1, At, B1); BAR;
;     LDB(B0, 1, 0); SCHED; LDA(At, 1, 0); STAGE_A(SA(0, 1), brow + HALF, t + 2);
;     WAIT_L(8); BAR; WAIT_L(0); MMA(0, 0, At, B0); BAR; SCHED;
;     LDB(B1, 1, 1); STAGE_B(SB(1, 0), bcol, t + 3);
;     BAR; WAIT_L(0); MMA(0, 1, At, B1); BAR;
;     LDA(At, 1, 1); STAGE_A(SA(1, 0), brow, t + 3);
;     BAR; WAIT_L(0); MMA(1, 0, At, B0); BAR; SCHED;
;     STAGE_B(SB(1, 1), bcol + HALF, t + 3);
;     WAIT_V(6); BAR; MMA(1, 1, At, B1); BAR;
;   }
	v_mfma_f32_16x16x32_bf16 v[76:79], v[218:221], v[202:205], v[76:79]
	v_mfma_f32_16x16x32_bf16 v[72:75], v[230:233], v[202:205], v[72:75]
	v_mfma_f32_16x16x32_bf16 v[68:71], v[218:221], v[210:213], v[68:71]
	v_mfma_f32_16x16x32_bf16 v[64:67], v[230:233], v[210:213], v[64:67]
	s_setprio 0
	v_lshl_add_u64 v[178:179], v[132:133], 0, s[10:11]
	v_readfirstlane_b32 s23, v145
	v_lshl_add_u64 v[222:223], v[178:179], 0, s[38:39]
	s_mov_b32 m0, s23
	v_add_u32_e32 v161, 0x2000, v145
	global_load_lds_dwordx4 v[222:223], off
	v_lshl_add_u64 v[222:223], v[134:135], 0, s[10:11]
	v_readfirstlane_b32 s23, v161
	v_lshl_add_u64 v[234:235], v[222:223], 0, s[38:39]
	s_mov_b32 m0, s23
	s_nop 0
	global_load_lds_dwordx4 v[234:235], off
	s_cmp_lt_u32 s22, 14
	s_cselect_b32 s25, s28, s34
	s_cselect_b32 s24, s27, s31
	v_lshl_add_u64 v[234:235], s[24:25], 0, v[136:137]
	v_lshl_add_u64 v[234:235], v[234:235], 0, s[10:11]
	v_readfirstlane_b32 s23, v147
	v_lshl_add_u64 v[236:237], v[234:235], 0, s[90:91]
	s_mov_b32 m0, s23
	ds_read_b128 v[182:185], v146 offset:16384
	ds_read_b128 v[186:189], v146 offset:17408
	ds_read_b128 v[190:193], v146 offset:18432
	ds_read_b128 v[194:197], v146 offset:19456
	ds_read_b128 v[198:201], v146 offset:20480
	ds_read_b128 v[202:205], v146 offset:21504
	ds_read_b128 v[206:209], v146 offset:22528
	ds_read_b128 v[210:213], v146 offset:23552
	global_load_lds_dwordx4 v[236:237], off
	v_lshl_add_u64 v[236:237], s[24:25], 0, v[138:139]
	v_lshl_add_u64 v[236:237], v[236:237], 0, s[10:11]
	v_readfirstlane_b32 s23, v148
	v_lshl_add_u64 v[238:239], v[236:237], 0, s[90:91]
	s_mov_b32 m0, s23
	s_nop 0
	global_load_lds_dwordx4 v[238:239], off
	v_lshl_add_u64 v[238:239], v[140:141], 0, s[10:11]
	v_readfirstlane_b32 s23, v150
	v_add_u32_e32 v161, 0x2000, v150
	v_lshl_add_u64 v[250:251], v[238:239], 0, s[40:41]
	s_mov_b32 m0, s23
	v_lshl_add_u64 v[240:241], v[142:143], 0, s[10:11]
	v_readfirstlane_b32 s23, v161
	global_load_lds_dwordx4 v[250:251], off
	v_lshl_add_u64 v[250:251], v[240:241], 0, s[40:41]
	s_mov_b32 m0, s23
	s_nop 0
	global_load_lds_dwordx4 v[250:251], off
	s_waitcnt lgkmcnt(0)
	s_waitcnt vmcnt(8)
	s_barrier
	s_setprio 1
	v_mfma_f32_16x16x32_bf16 v[60:63], v[162:165], v[182:185], 0
	v_mfma_f32_16x16x32_bf16 v[56:59], v[170:173], v[182:185], 0
	v_mfma_f32_16x16x32_bf16 v[52:55], v[162:165], v[190:193], 0
	v_mfma_f32_16x16x32_bf16 v[48:51], v[170:173], v[190:193], 0
	v_mfma_f32_16x16x32_bf16 v[44:47], v[162:165], v[198:201], 0
	v_mfma_f32_16x16x32_bf16 v[40:43], v[170:173], v[198:201], 0
	v_mfma_f32_16x16x32_bf16 v[36:39], v[162:165], v[206:209], 0
	v_mfma_f32_16x16x32_bf16 v[32:35], v[170:173], v[206:209], 0
	v_mfma_f32_16x16x32_bf16 v[60:63], v[166:169], v[186:189], v[60:63]
	v_mfma_f32_16x16x32_bf16 v[56:59], v[174:177], v[186:189], v[56:59]
	v_mfma_f32_16x16x32_bf16 v[52:55], v[166:169], v[194:197], v[52:55]
	v_mfma_f32_16x16x32_bf16 v[48:51], v[174:177], v[194:197], v[48:51]
	v_mfma_f32_16x16x32_bf16 v[44:47], v[166:169], v[202:205], v[44:47]
	v_mfma_f32_16x16x32_bf16 v[40:43], v[174:177], v[202:205], v[40:43]
	v_mfma_f32_16x16x32_bf16 v[36:39], v[166:169], v[210:213], v[36:39]
	v_mfma_f32_16x16x32_bf16 v[32:35], v[174:177], v[210:213], v[32:35]
	v_mfma_f32_16x16x32_bf16 v[28:31], v[214:217], v[182:185], 0
	v_mfma_f32_16x16x32_bf16 v[24:27], v[246:249], v[182:185], 0
	v_mfma_f32_16x16x32_bf16 v[20:23], v[214:217], v[190:193], 0
	v_mfma_f32_16x16x32_bf16 v[16:19], v[246:249], v[190:193], 0
	v_mfma_f32_16x16x32_bf16 v[12:15], v[214:217], v[198:201], 0
	v_mfma_f32_16x16x32_bf16 v[8:11], v[246:249], v[198:201], 0
	v_mfma_f32_16x16x32_bf16 v[4:7], v[214:217], v[206:209], 0
	v_mfma_f32_16x16x32_bf16 v[0:3], v[246:249], v[206:209], 0
	v_mfma_f32_16x16x32_bf16 v[28:31], v[218:221], v[186:189], v[28:31]
	v_mfma_f32_16x16x32_bf16 v[24:27], v[230:233], v[186:189], v[24:27]
	v_mfma_f32_16x16x32_bf16 v[20:23], v[218:221], v[194:197], v[20:23]
	v_mfma_f32_16x16x32_bf16 v[16:19], v[230:233], v[194:197], v[16:19]
	s_setprio 2
	s_barrier
	v_mfma_f32_16x16x32_bf16 v[12:15], v[218:221], v[202:205], v[12:15]
	v_mfma_f32_16x16x32_bf16 v[8:11], v[230:233], v[202:205], v[8:11]
	v_mfma_f32_16x16x32_bf16 v[4:7], v[218:221], v[210:213], v[4:7]
	v_mfma_f32_16x16x32_bf16 v[0:3], v[230:233], v[210:213], v[0:3]
	s_setprio 0
	ds_read_b128 v[162:165], v149 offset:32768
	ds_read_b128 v[166:169], v149 offset:33792
	ds_read_b128 v[170:173], v149 offset:34816
	ds_read_b128 v[174:177], v149 offset:35840
	v_readfirstlane_b32 s23, v151
	v_lshl_add_u64 v[214:215], v[234:235], 0, s[42:43]
	s_mov_b32 m0, s23
	v_readfirstlane_b32 s23, v152
	ds_read_b128 v[182:185], v146 offset:32768
	ds_read_b128 v[186:189], v146 offset:33792
	ds_read_b128 v[190:193], v146 offset:34816
	ds_read_b128 v[194:197], v146 offset:35840
	ds_read_b128 v[198:201], v146 offset:36864
	ds_read_b128 v[202:205], v146 offset:37888
	ds_read_b128 v[206:209], v146 offset:38912
	ds_read_b128 v[210:213], v146 offset:39936
	global_load_lds_dwordx4 v[214:215], off
	v_lshl_add_u64 v[214:215], v[236:237], 0, s[42:43]
	s_mov_b32 m0, s23
	s_nop 0
	global_load_lds_dwordx4 v[214:215], off
	ds_read_b128 v[214:217], v149 offset:49152
	ds_read_b128 v[218:221], v149 offset:50176
	ds_read_b128 v[230:233], v149 offset:51200
	ds_read_b128 v[246:249], v149 offset:52224
	s_waitcnt lgkmcnt(0)
	s_waitcnt vmcnt(8)
	s_barrier
; #define STAGE_A(P, br, kt) do { const char* _base = (const char*)(((kt) < G.ksplit ? G.A1 : A2m) + (long)(br) * G.lda + (long)(kt) * BK); \
;     __builtin_amdgcn_global_load_lds((const unsigned*)(_base + aoff0), (unsigned*)((char*)(P) + sb0), 16, 0, 0); \
;     __builtin_amdgcn_global_load_lds((const unsigned*)(_base + aoff1), (unsigned*)((char*)(P) + sb1), 16, 0, 0); } while (0)
; #define STAGE_B(P, br, kt) do { const char* _base = (const char*)(G.Bt + (long)(br) * G.ldb + (long)(kt) * BK); \
;     __builtin_amdgcn_global_load_lds((const unsigned*)(_base + boff0), (unsigned*)((char*)(P) + sb0), 16, 0, 0); \
;     __builtin_amdgcn_global_load_lds((const unsigned*)(_base + boff1), (unsigned*)((char*)(P) + sb1), 16, 0, 0); } while (0)
; #define LDA(dst, b, h) for (int m = 0; m < 4; ++m) for (int k = 0; k < 2; ++k) \
;     dst[m][k] = *reinterpret_cast<const bf16x8*>(a_rd + ((b) * 2 + (h)) * (HT * 2) + m * 2048 + k * 1024)
; #define LDB(dst, b, h) for (int n = 0; n < 2; ++n) for (int k = 0; k < 2; ++k) \
;     dst[n][k] = *reinterpret_cast<const bf16x8*>(b_rd + ((b) * 2 + (h)) * (HT * 2) + n * 2048 + k * 1024)
; #define MMA(ai, bj, At_, Bt_) do { __builtin_amdgcn_s_setprio(1); \
;     for (int m = 0; m < 4; ++m) for (int n = 0; n < 2; ++n) for (int k = 0; k < 2; ++k) \
;       acc[ai][bj][m][n] = __builtin_amdgcn_mfma_f32_16x16x32_bf16(Bt_[n][k], At_[m][k], acc[ai][bj][m][n], 0, 0, 0); \
;     __builtin_amdgcn_s_setprio(0); } while (0)
;     ...
;   for (int t = 0; t < nt - 2; t += 2) {
;     LDB(B0, 0, 0); SCHED; LDA(At, 0, 0); STAGE_A(SA(1, 1), brow + HALF, t + 1);
;     WAIT_L(8); BAR; WAIT_L(0); MMA(0, 0, At, B0); BAR; SCHED;
;     LDB(B1, 0, 1); STAGE_B(SB(0, 0), bcol, t + 2);
;     BAR; WAIT_L(0); MMA(0, 1, At, B1); BAR;
;     LDA(At, 0, 1); STAGE_A(SA(0, 0), brow, t + 2);
;     BAR; WAIT_L(0); MMA(1, 0, At, B0); BAR; SCHED;
;     STAGE_B(SB(0, 1), bcol + HALF, t + 2);
;     WAIT_V(6); BAR; MMA(1, 1, At, B1); BAR;
;     LDB(B0, 1, 0); SCHED; LDA(At, 1, 0); STAGE_A(SA(0, 1), brow + HALF, t + 2);
;     WAIT_L(8); BAR; WAIT_L(0); MMA(0, 0, At, B0); BAR; SCHED;
;     LDB(B1, 1, 1); STAGE_B(SB(1, 0), bcol, t + 3);
;     BAR; WAIT_L(0); MMA(0, 1, At, B1); BAR;
;     LDA(At, 1, 1); STAGE_A(SA(1, 0), brow, t + 3);
;     BAR; WAIT_L(0); MMA(1, 0, At, B0); BAR; SCHED;
;     STAGE_B(SB(1, 1), bcol + HALF, t + 3);
;     WAIT_V(6); BAR; MMA(1, 1, At, B1); BAR;
;   }
	s_setprio 1
	v_mfma_f32_16x16x32_bf16 v[124:127], v[162:165], v[182:185], v[124:127]
	v_mfma_f32_16x16x32_bf16 v[120:123], v[170:173], v[182:185], v[120:123]
	v_mfma_f32_16x16x32_bf16 v[116:119], v[162:165], v[190:193], v[116:119]
	v_mfma_f32_16x16x32_bf16 v[112:115], v[170:173], v[190:193], v[112:115]
	v_mfma_f32_16x16x32_bf16 v[108:111], v[162:165], v[198:201], v[108:111]
	v_mfma_f32_16x16x32_bf16 v[104:107], v[170:173], v[198:201], v[104:107]
	v_mfma_f32_16x16x32_bf16 v[100:103], v[162:165], v[206:209], v[100:103]
	v_mfma_f32_16x16x32_bf16 v[96:99], v[170:173], v[206:209], v[96:99]
	v_mfma_f32_16x16x32_bf16 v[124:127], v[166:169], v[186:189], v[124:127]
	v_mfma_f32_16x16x32_bf16 v[120:123], v[174:177], v[186:189], v[120:123]
	v_mfma_f32_16x16x32_bf16 v[116:119], v[166:169], v[194:197], v[116:119]
	v_mfma_f32_16x16x32_bf16 v[112:115], v[174:177], v[194:197], v[112:115]
	v_mfma_f32_16x16x32_bf16 v[108:111], v[166:169], v[202:205], v[108:111]
	v_mfma_f32_16x16x32_bf16 v[104:107], v[174:177], v[202:205], v[104:107]
	v_mfma_f32_16x16x32_bf16 v[100:103], v[166:169], v[210:213], v[100:103]
	v_mfma_f32_16x16x32_bf16 v[96:99], v[174:177], v[210:213], v[96:99]
	v_mfma_f32_16x16x32_bf16 v[92:95], v[214:217], v[182:185], v[92:95]
	v_mfma_f32_16x16x32_bf16 v[88:91], v[230:233], v[182:185], v[88:91]
	v_mfma_f32_16x16x32_bf16 v[84:87], v[214:217], v[190:193], v[84:87]
	v_mfma_f32_16x16x32_bf16 v[80:83], v[230:233], v[190:193], v[80:83]
	v_mfma_f32_16x16x32_bf16 v[76:79], v[214:217], v[198:201], v[76:79]
	v_mfma_f32_16x16x32_bf16 v[72:75], v[230:233], v[198:201], v[72:75]
	v_mfma_f32_16x16x32_bf16 v[68:71], v[214:217], v[206:209], v[68:71]
	v_mfma_f32_16x16x32_bf16 v[64:67], v[230:233], v[206:209], v[64:67]
	v_mfma_f32_16x16x32_bf16 v[92:95], v[218:221], v[186:189], v[92:95]
	v_mfma_f32_16x16x32_bf16 v[88:91], v[246:249], v[186:189], v[88:91]
	v_mfma_f32_16x16x32_bf16 v[84:87], v[218:221], v[194:197], v[84:87]
	v_mfma_f32_16x16x32_bf16 v[80:83], v[246:249], v[194:197], v[80:83]
	s_setprio 2
	s_barrier
	v_mfma_f32_16x16x32_bf16 v[76:79], v[218:221], v[202:205], v[76:79]
	v_mfma_f32_16x16x32_bf16 v[72:75], v[246:249], v[202:205], v[72:75]
	v_mfma_f32_16x16x32_bf16 v[68:71], v[218:221], v[210:213], v[68:71]
	v_mfma_f32_16x16x32_bf16 v[64:67], v[246:249], v[210:213], v[64:67]
	s_setprio 0
	v_readfirstlane_b32 s23, v153
	v_lshl_add_u64 v[178:179], v[178:179], 0, s[44:45]
	s_mov_b32 m0, s23
	v_readfirstlane_b32 s23, v154
	global_load_lds_dwordx4 v[178:179], off
	v_lshl_add_u64 v[178:179], v[222:223], 0, s[44:45]
	s_mov_b32 m0, s23
	s_nop 0
	global_load_lds_dwordx4 v[178:179], off
	s_cmp_lt_u32 s22, 13
	s_cselect_b32 s25, s28, s34
	s_cselect_b32 s24, s27, s31
	v_lshl_add_u64 v[178:179], s[24:25], 0, v[136:137]
	v_lshl_add_u64 v[178:179], v[178:179], 0, s[10:11]
	v_readfirstlane_b32 s23, v155
	v_lshl_add_u64 v[178:179], v[178:179], 0, s[88:89]
	s_mov_b32 m0, s23
	ds_read_b128 v[182:185], v146 offset:49152
	ds_read_b128 v[186:189], v146 offset:50176
	ds_read_b128 v[190:193], v146 offset:51200
	ds_read_b128 v[194:197], v146 offset:52224
	ds_read_b128 v[198:201], v146 offset:53248
	ds_read_b128 v[202:205], v146 offset:54272
	ds_read_b128 v[206:209], v146 offset:55296
	ds_read_b128 v[210:213], v146 offset:56320
	global_load_lds_dwordx4 v[178:179], off
	v_lshl_add_u64 v[178:179], s[24:25], 0, v[138:139]
	v_lshl_add_u64 v[178:179], v[178:179], 0, s[10:11]
	v_readfirstlane_b32 s23, v156
	v_lshl_add_u64 v[178:179], v[178:179], 0, s[88:89]
	s_mov_b32 m0, s23
	s_nop 0
	global_load_lds_dwordx4 v[178:179], off
	v_readfirstlane_b32 s23, v157
	v_lshl_add_u64 v[250:251], v[238:239], 0, s[46:47]
	s_mov_b32 m0, s23
	v_readfirstlane_b32 s23, v158
	global_load_lds_dwordx4 v[250:251], off
	v_lshl_add_u64 v[250:251], v[240:241], 0, s[46:47]
	s_mov_b32 m0, s23
	s_nop 0
	global_load_lds_dwordx4 v[250:251], off
	s_waitcnt lgkmcnt(0)
	s_waitcnt vmcnt(8)
	s_barrier
	s_setprio 1
	v_mfma_f32_16x16x32_bf16 v[60:63], v[162:165], v[182:185], v[60:63]
	v_mfma_f32_16x16x32_bf16 v[56:59], v[170:173], v[182:185], v[56:59]
	v_mfma_f32_16x16x32_bf16 v[52:55], v[162:165], v[190:193], v[52:55]
	v_mfma_f32_16x16x32_bf16 v[48:51], v[170:173], v[190:193], v[48:51]
	v_mfma_f32_16x16x32_bf16 v[44:47], v[162:165], v[198:201], v[44:47]
	v_mfma_f32_16x16x32_bf16 v[40:43], v[170:173], v[198:201], v[40:43]
	v_mfma_f32_16x16x32_bf16 v[36:39], v[162:165], v[206:209], v[36:39]
	v_mfma_f32_16x16x32_bf16 v[32:35], v[170:173], v[206:209], v[32:35]
	v_mfma_f32_16x16x32_bf16 v[60:63], v[166:169], v[186:189], v[60:63]
	v_mfma_f32_16x16x32_bf16 v[56:59], v[174:177], v[186:189], v[56:59]
	v_mfma_f32_16x16x32_bf16 v[52:55], v[166:169], v[194:197], v[52:55]
	v_mfma_f32_16x16x32_bf16 v[48:51], v[174:177], v[194:197], v[48:51]
	v_mfma_f32_16x16x32_bf16 v[44:47], v[166:169], v[202:205], v[44:47]
	v_mfma_f32_16x16x32_bf16 v[40:43], v[174:177], v[202:205], v[40:43]
	v_mfma_f32_16x16x32_bf16 v[36:39], v[166:169], v[210:213], v[36:39]
	v_mfma_f32_16x16x32_bf16 v[32:35], v[174:177], v[210:213], v[32:35]
	v_mfma_f32_16x16x32_bf16 v[28:31], v[214:217], v[182:185], v[28:31]
	v_mfma_f32_16x16x32_bf16 v[24:27], v[230:233], v[182:185], v[24:27]
	v_mfma_f32_16x16x32_bf16 v[20:23], v[214:217], v[190:193], v[20:23]
	v_mfma_f32_16x16x32_bf16 v[16:19], v[230:233], v[190:193], v[16:19]
	v_mfma_f32_16x16x32_bf16 v[12:15], v[214:217], v[198:201], v[12:15]
	v_mfma_f32_16x16x32_bf16 v[8:11], v[230:233], v[198:201], v[8:11]
	v_mfma_f32_16x16x32_bf16 v[4:7], v[214:217], v[206:209], v[4:7]
	v_mfma_f32_16x16x32_bf16 v[0:3], v[230:233], v[206:209], v[0:3]
	v_mfma_f32_16x16x32_bf16 v[28:31], v[218:221], v[186:189], v[28:31]
	v_mfma_f32_16x16x32_bf16 v[24:27], v[246:249], v[186:189], v[24:27]
	v_mfma_f32_16x16x32_bf16 v[20:23], v[218:221], v[194:197], v[20:23]
	v_mfma_f32_16x16x32_bf16 v[16:19], v[246:249], v[194:197], v[16:19]
	s_setprio 2
	s_barrier
	v_mfma_f32_16x16x32_bf16 v[12:15], v[218:221], v[202:205], v[12:15]
	v_mfma_f32_16x16x32_bf16 v[8:11], v[246:249], v[202:205], v[8:11]
	v_mfma_f32_16x16x32_bf16 v[4:7], v[218:221], v[210:213], v[4:7]
	v_mfma_f32_16x16x32_bf16 v[0:3], v[246:249], v[210:213], v[0:3]
	s_setprio 0
	s_add_u32 s10, s10, 0x100
	s_addc_u32 s11, s11, 0
	s_cmp_lt_u32 s22, 28
	s_cbranch_scc0 .Lmy_kexit_3
; #define STAGE_A(P, br, kt) do { const char* _base = (const char*)(((kt) < G.ksplit ? G.A1 : A2m) + (long)(br) * G.lda + (long)(kt) * BK); \
;     __builtin_amdgcn_global_load_lds((const unsigned*)(_base + aoff0), (unsigned*)((char*)(P) + sb0), 16, 0, 0); \
;     __builtin_amdgcn_global_load_lds((const unsigned*)(_base + aoff1), (unsigned*)((char*)(P) + sb1), 16, 0, 0); } while (0)
; #define STAGE_B(P, br, kt) do { const char* _base = (const char*)(G.Bt + (long)(br) * G.ldb + (long)(kt) * BK); \
;     __builtin_amdgcn_global_load_lds((const unsigned*)(_base + boff0), (unsigned*)((char*)(P) + sb0), 16, 0, 0); \
;     __builtin_amdgcn_global_load_lds((const unsigned*)(_base + boff1), (unsigned*)((char*)(P) + sb1), 16, 0, 0); } while (0)
; #define LDA(dst, b, h) for (int m = 0; m < 4; ++m) for (int k = 0; k < 2; ++k) \
;     dst[m][k] = *reinterpret_cast<const bf16x8*>(a_rd + ((b) * 2 + (h)) * (HT * 2) + m * 2048 + k * 1024)
; #define LDB(dst, b, h) for (int n = 0; n < 2; ++n) for (int k = 0; k < 2; ++k) \
;     dst[n][k] = *reinterpret_cast<const bf16x8*>(b_rd + ((b) * 2 + (h)) * (HT * 2) + n * 2048 + k * 1024)
; #define MMA(ai, bj, At_, Bt_) do { __builtin_amdgcn_s_setprio(1); \
;     for (int m = 0; m < 4; ++m) for (int n = 0; n < 2; ++n) for (int k = 0; k < 2; ++k) \
;       acc[ai][bj][m][n] = __builtin_amdgcn_mfma_f32_16x16x32_bf16(Bt_[n][k], At_[m][k], acc[ai][bj][m][n], 0, 0, 0); \
;     __builtin_amdgcn_s_setprio(0); } while (0)
;     ...
;   for (int t = 0; t < nt - 2; t += 2) {
;     LDB(B0, 0, 0); SCHED; LDA(At, 0, 0); STAGE_A(SA(1, 1), brow + HALF, t + 1);
;     WAIT_L(8); BAR; WAIT_L(0); MMA(0, 0, At, B0); BAR; SCHED;
;     LDB(B1, 0, 1); STAGE_B(SB(0, 0), bcol, t + 2);
;     BAR; WAIT_L(0); MMA(0, 1, At, B1); BAR;
;     LDA(At, 0, 1); STAGE_A(SA(0, 0), brow, t + 2);
;     BAR; WAIT_L(0); MMA(1, 0, At, B0); BAR; SCHED;
;     STAGE_B(SB(0, 1), bcol + HALF, t + 2);
;     WAIT_V(6); BAR; MMA(1, 1, At, B1); BAR;
;     LDB(B0, 1, 0); SCHED; LDA(At, 1, 0); STAGE_A(SA(0, 1), brow + HALF, t + 2);
;     WAIT_L(8); BAR; WAIT_L(0); MMA(0, 0, At, B0); BAR; SCHED;
;     LDB(B1, 1, 1); STAGE_B(SB(1, 0), bcol, t + 3);
;     BAR; WAIT_L(0); MMA(0, 1, At, B1); BAR;
;     LDA(At, 1, 1); STAGE_A(SA(1, 0), brow, t + 3);
;     BAR; WAIT_L(0); MMA(1, 0, At, B0); BAR; SCHED;
;     STAGE_B(SB(1, 1), bcol + HALF, t + 3);
;     WAIT_V(6); BAR; MMA(1, 1, At, B1); BAR;
;   }
.LBB0_2501:
	ds_read_b128 v[162:165], v149
	ds_read_b128 v[166:169], v149 offset:1024
	ds_read_b128 v[170:173], v149 offset:2048
	ds_read_b128 v[174:177], v149 offset:3072
	s_add_i32 s22, s22, 2
	s_cmp_lt_u32 s22, 16
	s_cselect_b32 s25, s28, s34
	s_cselect_b32 s24, s27, s31
	v_lshl_add_u64 v[160:161], s[24:25], 0, v[136:137]
	v_add_u32_e32 v159, 0xc000, v147
	v_lshl_add_u64 v[160:161], v[160:161], 0, s[10:11]
	v_readfirstlane_b32 s23, v159
	v_lshl_add_u64 v[160:161], v[160:161], 0, s[36:37]
	s_mov_b32 m0, s23
	ds_read_b128 v[182:185], v146
	ds_read_b128 v[186:189], v146 offset:1024
	ds_read_b128 v[190:193], v146 offset:2048
	ds_read_b128 v[194:197], v146 offset:3072
	ds_read_b128 v[198:201], v146 offset:4096
	ds_read_b128 v[202:205], v146 offset:5120
	ds_read_b128 v[206:209], v146 offset:6144
	ds_read_b128 v[210:213], v146 offset:7168
	global_load_lds_dwordx4 v[160:161], off
	v_lshl_add_u64 v[160:161], s[24:25], 0, v[138:139]
	v_lshl_add_u64 v[160:161], v[160:161], 0, s[10:11]
	v_lshl_add_u64 v[178:179], v[160:161], 0, s[36:37]
	v_add_u32_e32 v160, 0xe000, v147
	s_nop 0
	v_readfirstlane_b32 s23, v160
	s_mov_b32 m0, s23
	s_nop 0
	global_load_lds_dwordx4 v[178:179], off
	ds_read_b128 v[214:217], v149 offset:16384
	ds_read_b128 v[218:221], v149 offset:17408
	ds_read_b128 v[246:249], v149 offset:18432
	ds_read_b128 v[230:233], v149 offset:19456
	s_waitcnt lgkmcnt(0)
	s_waitcnt vmcnt(8)
	s_barrier
	s_setprio 1
	v_mfma_f32_16x16x32_bf16 v[124:127], v[162:165], v[182:185], v[124:127]
	v_mfma_f32_16x16x32_bf16 v[120:123], v[170:173], v[182:185], v[120:123]
	v_mfma_f32_16x16x32_bf16 v[116:119], v[162:165], v[190:193], v[116:119]
	v_mfma_f32_16x16x32_bf16 v[112:115], v[170:173], v[190:193], v[112:115]
	v_mfma_f32_16x16x32_bf16 v[108:111], v[162:165], v[198:201], v[108:111]
	v_mfma_f32_16x16x32_bf16 v[104:107], v[170:173], v[198:201], v[104:107]
	v_mfma_f32_16x16x32_bf16 v[100:103], v[162:165], v[206:209], v[100:103]
	v_mfma_f32_16x16x32_bf16 v[96:99], v[170:173], v[206:209], v[96:99]
	v_mfma_f32_16x16x32_bf16 v[124:127], v[166:169], v[186:189], v[124:127]
	v_mfma_f32_16x16x32_bf16 v[120:123], v[174:177], v[186:189], v[120:123]
	v_mfma_f32_16x16x32_bf16 v[116:119], v[166:169], v[194:197], v[116:119]
	v_mfma_f32_16x16x32_bf16 v[112:115], v[174:177], v[194:197], v[112:115]
	v_mfma_f32_16x16x32_bf16 v[108:111], v[166:169], v[202:205], v[108:111]
	v_mfma_f32_16x16x32_bf16 v[104:107], v[174:177], v[202:205], v[104:107]
	v_mfma_f32_16x16x32_bf16 v[100:103], v[166:169], v[210:213], v[100:103]
	v_mfma_f32_16x16x32_bf16 v[96:99], v[174:177], v[210:213], v[96:99]
	v_mfma_f32_16x16x32_bf16 v[92:95], v[214:217], v[182:185], v[92:95]
	v_mfma_f32_16x16x32_bf16 v[88:91], v[246:249], v[182:185], v[88:91]
	v_mfma_f32_16x16x32_bf16 v[84:87], v[214:217], v[190:193], v[84:87]
	v_mfma_f32_16x16x32_bf16 v[80:83], v[246:249], v[190:193], v[80:83]
	v_mfma_f32_16x16x32_bf16 v[76:79], v[214:217], v[198:201], v[76:79]
	v_mfma_f32_16x16x32_bf16 v[72:75], v[246:249], v[198:201], v[72:75]
	v_mfma_f32_16x16x32_bf16 v[68:71], v[214:217], v[206:209], v[68:71]
	v_mfma_f32_16x16x32_bf16 v[64:67], v[246:249], v[206:209], v[64:67]
	v_mfma_f32_16x16x32_bf16 v[92:95], v[218:221], v[186:189], v[92:95]
	v_mfma_f32_16x16x32_bf16 v[88:91], v[230:233], v[186:189], v[88:91]
	v_mfma_f32_16x16x32_bf16 v[84:87], v[218:221], v[194:197], v[84:87]
	v_mfma_f32_16x16x32_bf16 v[80:83], v[230:233], v[194:197], v[80:83]
	s_setprio 2
	s_barrier
	v_mfma_f32_16x16x32_bf16 v[76:79], v[218:221], v[202:205], v[76:79]
	v_mfma_f32_16x16x32_bf16 v[72:75], v[230:233], v[202:205], v[72:75]
	v_mfma_f32_16x16x32_bf16 v[68:71], v[218:221], v[210:213], v[68:71]
	v_mfma_f32_16x16x32_bf16 v[64:67], v[230:233], v[210:213], v[64:67]
	s_setprio 0
	v_lshl_add_u64 v[178:179], v[132:133], 0, s[10:11]
	v_readfirstlane_b32 s23, v145
	v_lshl_add_u64 v[222:223], v[178:179], 0, s[38:39]
	s_mov_b32 m0, s23
	v_add_u32_e32 v161, 0x2000, v145
	global_load_lds_dwordx4 v[222:223], off
	v_lshl_add_u64 v[222:223], v[134:135], 0, s[10:11]
	v_readfirstlane_b32 s23, v161
	v_lshl_add_u64 v[234:235], v[222:223], 0, s[38:39]
	s_mov_b32 m0, s23
	s_nop 0
	global_load_lds_dwordx4 v[234:235], off
	s_cmp_lt_u32 s22, 14
	s_cselect_b32 s25, s28, s34
	s_cselect_b32 s24, s27, s31
	v_lshl_add_u64 v[234:235], s[24:25], 0, v[136:137]
	v_lshl_add_u64 v[234:235], v[234:235], 0, s[10:11]
	v_readfirstlane_b32 s23, v147
	v_lshl_add_u64 v[236:237], v[234:235], 0, s[90:91]
	s_mov_b32 m0, s23
	ds_read_b128 v[182:185], v146 offset:16384
	ds_read_b128 v[186:189], v146 offset:17408
	ds_read_b128 v[190:193], v146 offset:18432
	ds_read_b128 v[194:197], v146 offset:19456
	ds_read_b128 v[198:201], v146 offset:20480
	ds_read_b128 v[202:205], v146 offset:21504
	ds_read_b128 v[206:209], v146 offset:22528
	ds_read_b128 v[210:213], v146 offset:23552
	global_load_lds_dwordx4 v[236:237], off
	v_lshl_add_u64 v[236:237], s[24:25], 0, v[138:139]
	v_lshl_add_u64 v[236:237], v[236:237], 0, s[10:11]
	v_readfirstlane_b32 s23, v148
	v_lshl_add_u64 v[238:239], v[236:237], 0, s[90:91]
	s_mov_b32 m0, s23
	s_nop 0
	global_load_lds_dwordx4 v[238:239], off
	v_lshl_add_u64 v[238:239], v[140:141], 0, s[10:11]
	v_readfirstlane_b32 s23, v150
	v_add_u32_e32 v161, 0x2000, v150
	v_lshl_add_u64 v[250:251], v[238:239], 0, s[40:41]
	s_mov_b32 m0, s23
	v_lshl_add_u64 v[240:241], v[142:143], 0, s[10:11]
	v_readfirstlane_b32 s23, v161
	global_load_lds_dwordx4 v[250:251], off
	v_lshl_add_u64 v[250:251], v[240:241], 0, s[40:41]
	s_mov_b32 m0, s23
	s_nop 0
	global_load_lds_dwordx4 v[250:251], off
	s_waitcnt lgkmcnt(0)
	s_waitcnt vmcnt(8)
	s_barrier
; #define STAGE_A(P, br, kt) do { const char* _base = (const char*)(((kt) < G.ksplit ? G.A1 : A2m) + (long)(br) * G.lda + (long)(kt) * BK); \
;     __builtin_amdgcn_global_load_lds((const unsigned*)(_base + aoff0), (unsigned*)((char*)(P) + sb0), 16, 0, 0); \
;     __builtin_amdgcn_global_load_lds((const unsigned*)(_base + aoff1), (unsigned*)((char*)(P) + sb1), 16, 0, 0); } while (0)
; #define STAGE_B(P, br, kt) do { const char* _base = (const char*)(G.Bt + (long)(br) * G.ldb + (long)(kt) * BK); \
;     __builtin_amdgcn_global_load_lds((const unsigned*)(_base + boff0), (unsigned*)((char*)(P) + sb0), 16, 0, 0); \
;     __builtin_amdgcn_global_load_lds((const unsigned*)(_base + boff1), (unsigned*)((char*)(P) + sb1), 16, 0, 0); } while (0)
; #define LDA(dst, b, h) for (int m = 0; m < 4; ++m) for (int k = 0; k < 2; ++k) \
;     dst[m][k] = *reinterpret_cast<const bf16x8*>(a_rd + ((b) * 2 + (h)) * (HT * 2) + m * 2048 + k * 1024)
; #define LDB(dst, b, h) for (int n = 0; n < 2; ++n) for (int k = 0; k < 2; ++k) \
;     dst[n][k] = *reinterpret_cast<const bf16x8*>(b_rd + ((b) * 2 + (h)) * (HT * 2) + n * 2048 + k * 1024)
; #define MMA(ai, bj, At_, Bt_) do { __builtin_amdgcn_s_setprio(1); \
;     for (int m = 0; m < 4; ++m) for (int n = 0; n < 2; ++n) for (int k = 0; k < 2; ++k) \
;       acc[ai][bj][m][n] = __builtin_amdgcn_mfma_f32_16x16x32_bf16(Bt_[n][k], At_[m][k], acc[ai][bj][m][n], 0, 0, 0); \
;     __builtin_amdgcn_s_setprio(0); } while (0)
;     ...
;   for (int t = 0; t < nt - 2; t += 2) {
;     LDB(B0, 0, 0); SCHED; LDA(At, 0, 0); STAGE_A(SA(1, 1), brow + HALF, t + 1);
;     WAIT_L(8); BAR; WAIT_L(0); MMA(0, 0, At, B0); BAR; SCHED;
;     LDB(B1, 0, 1); STAGE_B(SB(0, 0), bcol, t + 2);
;     BAR; WAIT_L(0); MMA(0, 1, At, B1); BAR;
;     LDA(At, 0, 1); STAGE_A(SA(0, 0), brow, t + 2);
;     BAR; WAIT_L(0); MMA(1, 0, At, B0); BAR; SCHED;
;     STAGE_B(SB(0, 1), bcol + HALF, t + 2);
;     WAIT_V(6); BAR; MMA(1, 1, At, B1); BAR;
;     LDB(B0, 1, 0); SCHED; LDA(At, 1, 0); STAGE_A(SA(0, 1), brow + HALF, t + 2);
;     WAIT_L(8); BAR; WAIT_L(0); MMA(0, 0, At, B0); BAR; SCHED;
;     LDB(B1, 1, 1); STAGE_B(SB(1, 0), bcol, t + 3);
;     BAR; WAIT_L(0); MMA(0, 1, At, B1); BAR;
;     LDA(At, 1, 1); STAGE_A(SA(1, 0), brow, t + 3);
;     BAR; WAIT_L(0); MMA(1, 0, At, B0); BAR; SCHED;
;     STAGE_B(SB(1, 1), bcol + HALF, t + 3);
;     WAIT_V(6); BAR; MMA(1, 1, At, B1); BAR;
;   }
	s_setprio 1
	v_mfma_f32_16x16x32_bf16 v[60:63], v[162:165], v[182:185], v[60:63]
	v_mfma_f32_16x16x32_bf16 v[56:59], v[170:173], v[182:185], v[56:59]
	v_mfma_f32_16x16x32_bf16 v[52:55], v[162:165], v[190:193], v[52:55]
	v_mfma_f32_16x16x32_bf16 v[48:51], v[170:173], v[190:193], v[48:51]
	v_mfma_f32_16x16x32_bf16 v[44:47], v[162:165], v[198:201], v[44:47]
	v_mfma_f32_16x16x32_bf16 v[40:43], v[170:173], v[198:201], v[40:43]
	v_mfma_f32_16x16x32_bf16 v[36:39], v[162:165], v[206:209], v[36:39]
	v_mfma_f32_16x16x32_bf16 v[32:35], v[170:173], v[206:209], v[32:35]
	v_mfma_f32_16x16x32_bf16 v[60:63], v[166:169], v[186:189], v[60:63]
	v_mfma_f32_16x16x32_bf16 v[56:59], v[174:177], v[186:189], v[56:59]
	v_mfma_f32_16x16x32_bf16 v[52:55], v[166:169], v[194:197], v[52:55]
	v_mfma_f32_16x16x32_bf16 v[48:51], v[174:177], v[194:197], v[48:51]
	v_mfma_f32_16x16x32_bf16 v[44:47], v[166:169], v[202:205], v[44:47]
	v_mfma_f32_16x16x32_bf16 v[40:43], v[174:177], v[202:205], v[40:43]
	v_mfma_f32_16x16x32_bf16 v[36:39], v[166:169], v[210:213], v[36:39]
	v_mfma_f32_16x16x32_bf16 v[32:35], v[174:177], v[210:213], v[32:35]
	v_mfma_f32_16x16x32_bf16 v[28:31], v[214:217], v[182:185], v[28:31]
	v_mfma_f32_16x16x32_bf16 v[24:27], v[246:249], v[182:185], v[24:27]
	v_mfma_f32_16x16x32_bf16 v[20:23], v[214:217], v[190:193], v[20:23]
	v_mfma_f32_16x16x32_bf16 v[16:19], v[246:249], v[190:193], v[16:19]
	v_mfma_f32_16x16x32_bf16 v[12:15], v[214:217], v[198:201], v[12:15]
	v_mfma_f32_16x16x32_bf16 v[8:11], v[246:249], v[198:201], v[8:11]
	v_mfma_f32_16x16x32_bf16 v[4:7], v[214:217], v[206:209], v[4:7]
	v_mfma_f32_16x16x32_bf16 v[0:3], v[246:249], v[206:209], v[0:3]
	v_mfma_f32_16x16x32_bf16 v[28:31], v[218:221], v[186:189], v[28:31]
	v_mfma_f32_16x16x32_bf16 v[24:27], v[230:233], v[186:189], v[24:27]
	v_mfma_f32_16x16x32_bf16 v[20:23], v[218:221], v[194:197], v[20:23]
	v_mfma_f32_16x16x32_bf16 v[16:19], v[230:233], v[194:197], v[16:19]
	s_setprio 2
	s_barrier
	v_mfma_f32_16x16x32_bf16 v[12:15], v[218:221], v[202:205], v[12:15]
	v_mfma_f32_16x16x32_bf16 v[8:11], v[230:233], v[202:205], v[8:11]
	v_mfma_f32_16x16x32_bf16 v[4:7], v[218:221], v[210:213], v[4:7]
	v_mfma_f32_16x16x32_bf16 v[0:3], v[230:233], v[210:213], v[0:3]
	s_setprio 0
	ds_read_b128 v[162:165], v149 offset:32768
	ds_read_b128 v[166:169], v149 offset:33792
	ds_read_b128 v[170:173], v149 offset:34816
	ds_read_b128 v[174:177], v149 offset:35840
	v_readfirstlane_b32 s23, v151
	v_lshl_add_u64 v[214:215], v[234:235], 0, s[42:43]
	s_mov_b32 m0, s23
	v_readfirstlane_b32 s23, v152
	ds_read_b128 v[182:185], v146 offset:32768
	ds_read_b128 v[186:189], v146 offset:33792
	ds_read_b128 v[190:193], v146 offset:34816
	ds_read_b128 v[194:197], v146 offset:35840
	ds_read_b128 v[198:201], v146 offset:36864
	ds_read_b128 v[202:205], v146 offset:37888
	ds_read_b128 v[206:209], v146 offset:38912
	ds_read_b128 v[210:213], v146 offset:39936
	global_load_lds_dwordx4 v[214:215], off
	v_lshl_add_u64 v[214:215], v[236:237], 0, s[42:43]
	s_mov_b32 m0, s23
	s_nop 0
	global_load_lds_dwordx4 v[214:215], off
	ds_read_b128 v[214:217], v149 offset:49152
	ds_read_b128 v[218:221], v149 offset:50176
	ds_read_b128 v[230:233], v149 offset:51200
	ds_read_b128 v[246:249], v149 offset:52224
	s_waitcnt lgkmcnt(0)
	s_waitcnt vmcnt(8)
	s_barrier
	s_setprio 1
	v_mfma_f32_16x16x32_bf16 v[124:127], v[162:165], v[182:185], v[124:127]
	v_mfma_f32_16x16x32_bf16 v[120:123], v[170:173], v[182:185], v[120:123]
	v_mfma_f32_16x16x32_bf16 v[116:119], v[162:165], v[190:193], v[116:119]
	v_mfma_f32_16x16x32_bf16 v[112:115], v[170:173], v[190:193], v[112:115]
	v_mfma_f32_16x16x32_bf16 v[108:111], v[162:165], v[198:201], v[108:111]
	v_mfma_f32_16x16x32_bf16 v[104:107], v[170:173], v[198:201], v[104:107]
	v_mfma_f32_16x16x32_bf16 v[100:103], v[162:165], v[206:209], v[100:103]
	v_mfma_f32_16x16x32_bf16 v[96:99], v[170:173], v[206:209], v[96:99]
	v_mfma_f32_16x16x32_bf16 v[124:127], v[166:169], v[186:189], v[124:127]
	v_mfma_f32_16x16x32_bf16 v[120:123], v[174:177], v[186:189], v[120:123]
	v_mfma_f32_16x16x32_bf16 v[116:119], v[166:169], v[194:197], v[116:119]
	v_mfma_f32_16x16x32_bf16 v[112:115], v[174:177], v[194:197], v[112:115]
	v_mfma_f32_16x16x32_bf16 v[108:111], v[166:169], v[202:205], v[108:111]
	v_mfma_f32_16x16x32_bf16 v[104:107], v[174:177], v[202:205], v[104:107]
	v_mfma_f32_16x16x32_bf16 v[100:103], v[166:169], v[210:213], v[100:103]
	v_mfma_f32_16x16x32_bf16 v[96:99], v[174:177], v[210:213], v[96:99]
	v_mfma_f32_16x16x32_bf16 v[92:95], v[214:217], v[182:185], v[92:95]
	v_mfma_f32_16x16x32_bf16 v[88:91], v[230:233], v[182:185], v[88:91]
	v_mfma_f32_16x16x32_bf16 v[84:87], v[214:217], v[190:193], v[84:87]
	v_mfma_f32_16x16x32_bf16 v[80:83], v[230:233], v[190:193], v[80:83]
	v_mfma_f32_16x16x32_bf16 v[76:79], v[214:217], v[198:201], v[76:79]
	v_mfma_f32_16x16x32_bf16 v[72:75], v[230:233], v[198:201], v[72:75]
	v_mfma_f32_16x16x32_bf16 v[68:71], v[214:217], v[206:209], v[68:71]
	v_mfma_f32_16x16x32_bf16 v[64:67], v[230:233], v[206:209], v[64:67]
	v_mfma_f32_16x16x32_bf16 v[92:95], v[218:221], v[186:189], v[92:95]
	v_mfma_f32_16x16x32_bf16 v[88:91], v[246:249], v[186:189], v[88:91]
	v_mfma_f32_16x16x32_bf16 v[84:87], v[218:221], v[194:197], v[84:87]
	v_mfma_f32_16x16x32_bf16 v[80:83], v[246:249], v[194:197], v[80:83]
	s_setprio 2
	s_barrier
; #define STAGE_A(P, br, kt) do { const char* _base = (const char*)(((kt) < G.ksplit ? G.A1 : A2m) + (long)(br) * G.lda + (long)(kt) * BK); \
;     __builtin_amdgcn_global_load_lds((const unsigned*)(_base + aoff0), (unsigned*)((char*)(P) + sb0), 16, 0, 0); \
;     __builtin_amdgcn_global_load_lds((const unsigned*)(_base + aoff1), (unsigned*)((char*)(P) + sb1), 16, 0, 0); } while (0)
; #define LDA(dst, b, h) for (int m = 0; m < 4; ++m) for (int k = 0; k < 2; ++k) \
;     dst[m][k] = *reinterpret_cast<const bf16x8*>(a_rd + ((b) * 2 + (h)) * (HT * 2) + m * 2048 + k * 1024)
; #define WAIT_V(n) asm volatile("s_waitcnt vmcnt(" #n ")" ::: "memory")
;     ...
;   for (int t = 0; t < nt - 2; t += 2) {
;     LDB(B0, 0, 0); SCHED; LDA(At, 0, 0); STAGE_A(SA(1, 1), brow + HALF, t + 1);
;     WAIT_L(8); BAR; WAIT_L(0); MMA(0, 0, At, B0); BAR; SCHED;
;     LDB(B1, 0, 1); STAGE_B(SB(0, 0), bcol, t + 2);
;     BAR; WAIT_L(0); MMA(0, 1, At, B1); BAR;
;     LDA(At, 0, 1); STAGE_A(SA(0, 0), brow, t + 2);
;     BAR; WAIT_L(0); MMA(1, 0, At, B0); BAR; SCHED;
;     STAGE_B(SB(0, 1), bcol + HALF, t + 2);
;     WAIT_V(6); BAR; MMA(1, 1, At, B1); BAR;
;     LDB(B0, 1, 0); SCHED; LDA(At, 1, 0); STAGE_A(SA(0, 1), brow + HALF, t + 2);
;     WAIT_L(8); BAR; WAIT_L(0); MMA(0, 0, At, B0); BAR; SCHED;
;     LDB(B1, 1, 1); STAGE_B(SB(1, 0), bcol, t + 3);
;     BAR; WAIT_L(0); MMA(0, 1, At, B1); BAR;
;     LDA(At, 1, 1); STAGE_A(SA(1, 0), brow, t + 3);
;     BAR; WAIT_L(0); MMA(1, 0, At, B0); BAR; SCHED;
;     STAGE_B(SB(1, 1), bcol + HALF, t + 3);
;     WAIT_V(6); BAR; MMA(1, 1, At, B1); BAR;
;   }
;   float ssv[2][4] = {};
;   if constexpr (EPI == EPI_GU || EPI == EPI_EVIN || EPI == EPI_ODIN) {
; #pragma unroll
;     for (int ai = 0; ai < 2; ++ai)
; #pragma unroll
;       for (int m = 0; m < 4; ++m) ssv[ai][m] = G.ssr[brow + ai * HALF + wr * 64 + m * 16 + fr];
;   }
;   { LDB(B0, 0, 0); LDA(At, 0, 0); STAGE_A(SA(1, 1), brow + HALF, nt - 1);
;     BAR; WAIT_L(0); MMA(0, 0, At, B0); BAR;
;     LDB(B1, 0, 1); BAR; WAIT_L(0); MMA(0, 1, At, B1); BAR;
;     LDA(At, 0, 1); WAIT_V(4); BAR; WAIT_L(0); MMA(1, 0, At, B0); MMA(1, 1, At, B1); BAR; }
;   { LDB(B0, 1, 0); LDA(At, 1, 0); WAIT_V(2); BAR; WAIT_L(0); MMA(0, 0, At, B0); BAR;
;     LDB(B1, 1, 1); WAIT_V(0); BAR; WAIT_L(0); MMA(0, 1, At, B1); BAR;
;     LDA(At, 1, 1); BAR; WAIT_L(0); MMA(1, 0, At, B0); MMA(1, 1, At, B1); BAR; }
	v_mfma_f32_16x16x32_bf16 v[76:79], v[218:221], v[202:205], v[76:79]
	v_mfma_f32_16x16x32_bf16 v[72:75], v[246:249], v[202:205], v[72:75]
	v_mfma_f32_16x16x32_bf16 v[68:71], v[218:221], v[210:213], v[68:71]
	v_mfma_f32_16x16x32_bf16 v[64:67], v[246:249], v[210:213], v[64:67]
	s_setprio 0
	v_readfirstlane_b32 s23, v153
	v_lshl_add_u64 v[178:179], v[178:179], 0, s[44:45]
	s_mov_b32 m0, s23
	v_readfirstlane_b32 s23, v154
	global_load_lds_dwordx4 v[178:179], off
	v_lshl_add_u64 v[178:179], v[222:223], 0, s[44:45]
	s_mov_b32 m0, s23
	s_nop 0
	global_load_lds_dwordx4 v[178:179], off
	s_cmp_lt_u32 s22, 13
	s_cselect_b32 s25, s28, s34
	s_cselect_b32 s24, s27, s31
	v_lshl_add_u64 v[178:179], s[24:25], 0, v[136:137]
	v_lshl_add_u64 v[178:179], v[178:179], 0, s[10:11]
	v_readfirstlane_b32 s23, v155
	v_lshl_add_u64 v[178:179], v[178:179], 0, s[88:89]
	s_mov_b32 m0, s23
	ds_read_b128 v[182:185], v146 offset:49152
	ds_read_b128 v[186:189], v146 offset:50176
	ds_read_b128 v[190:193], v146 offset:51200
	ds_read_b128 v[194:197], v146 offset:52224
	ds_read_b128 v[198:201], v146 offset:53248
	ds_read_b128 v[202:205], v146 offset:54272
	ds_read_b128 v[206:209], v146 offset:55296
	ds_read_b128 v[210:213], v146 offset:56320
	global_load_lds_dwordx4 v[178:179], off
	v_lshl_add_u64 v[178:179], s[24:25], 0, v[138:139]
	v_lshl_add_u64 v[178:179], v[178:179], 0, s[10:11]
	v_readfirstlane_b32 s23, v156
	v_lshl_add_u64 v[178:179], v[178:179], 0, s[88:89]
	s_mov_b32 m0, s23
	s_nop 0
	global_load_lds_dwordx4 v[178:179], off
	v_readfirstlane_b32 s23, v157
	v_lshl_add_u64 v[250:251], v[238:239], 0, s[46:47]
	s_mov_b32 m0, s23
	v_readfirstlane_b32 s23, v158
	global_load_lds_dwordx4 v[250:251], off
	v_lshl_add_u64 v[250:251], v[240:241], 0, s[46:47]
	s_mov_b32 m0, s23
	s_nop 0
	global_load_lds_dwordx4 v[250:251], off
	s_waitcnt lgkmcnt(0)
	s_waitcnt vmcnt(8)
	s_barrier
	s_setprio 1
	v_mfma_f32_16x16x32_bf16 v[60:63], v[162:165], v[182:185], v[60:63]
	v_mfma_f32_16x16x32_bf16 v[56:59], v[170:173], v[182:185], v[56:59]
	v_mfma_f32_16x16x32_bf16 v[52:55], v[162:165], v[190:193], v[52:55]
	v_mfma_f32_16x16x32_bf16 v[48:51], v[170:173], v[190:193], v[48:51]
	v_mfma_f32_16x16x32_bf16 v[44:47], v[162:165], v[198:201], v[44:47]
	v_mfma_f32_16x16x32_bf16 v[40:43], v[170:173], v[198:201], v[40:43]
	v_mfma_f32_16x16x32_bf16 v[36:39], v[162:165], v[206:209], v[36:39]
	v_mfma_f32_16x16x32_bf16 v[32:35], v[170:173], v[206:209], v[32:35]
	v_mfma_f32_16x16x32_bf16 v[60:63], v[166:169], v[186:189], v[60:63]
	v_mfma_f32_16x16x32_bf16 v[56:59], v[174:177], v[186:189], v[56:59]
	v_mfma_f32_16x16x32_bf16 v[52:55], v[166:169], v[194:197], v[52:55]
	v_mfma_f32_16x16x32_bf16 v[48:51], v[174:177], v[194:197], v[48:51]
	v_mfma_f32_16x16x32_bf16 v[44:47], v[166:169], v[202:205], v[44:47]
	v_mfma_f32_16x16x32_bf16 v[40:43], v[174:177], v[202:205], v[40:43]
	v_mfma_f32_16x16x32_bf16 v[36:39], v[166:169], v[210:213], v[36:39]
	v_mfma_f32_16x16x32_bf16 v[32:35], v[174:177], v[210:213], v[32:35]
	v_mfma_f32_16x16x32_bf16 v[28:31], v[214:217], v[182:185], v[28:31]
	v_mfma_f32_16x16x32_bf16 v[24:27], v[230:233], v[182:185], v[24:27]
	v_mfma_f32_16x16x32_bf16 v[20:23], v[214:217], v[190:193], v[20:23]
	v_mfma_f32_16x16x32_bf16 v[16:19], v[230:233], v[190:193], v[16:19]
	v_mfma_f32_16x16x32_bf16 v[12:15], v[214:217], v[198:201], v[12:15]
	v_mfma_f32_16x16x32_bf16 v[8:11], v[230:233], v[198:201], v[8:11]
	v_mfma_f32_16x16x32_bf16 v[4:7], v[214:217], v[206:209], v[4:7]
	v_mfma_f32_16x16x32_bf16 v[0:3], v[230:233], v[206:209], v[0:3]
	v_mfma_f32_16x16x32_bf16 v[28:31], v[218:221], v[186:189], v[28:31]
	v_mfma_f32_16x16x32_bf16 v[24:27], v[246:249], v[186:189], v[24:27]
	v_mfma_f32_16x16x32_bf16 v[20:23], v[218:221], v[194:197], v[20:23]
	v_mfma_f32_16x16x32_bf16 v[16:19], v[246:249], v[194:197], v[16:19]
	s_setprio 2
	s_barrier
	v_mfma_f32_16x16x32_bf16 v[12:15], v[218:221], v[202:205], v[12:15]
	v_mfma_f32_16x16x32_bf16 v[8:11], v[246:249], v[202:205], v[8:11]
	v_mfma_f32_16x16x32_bf16 v[4:7], v[218:221], v[210:213], v[4:7]
	v_mfma_f32_16x16x32_bf16 v[0:3], v[246:249], v[210:213], v[0:3]
	s_setprio 0
	s_add_u32 s10, s10, 0x100
	s_addc_u32 s11, s11, 0
	s_cmp_lt_u32 s22, 28
	s_cbranch_scc1 .LBB0_2501
.Lmy_kexit_3:
	s_waitcnt vmcnt(6)
	v_not_b32_e32 v250, 63
	v_mov_b32_e32 v251, 0x41b17218
	s_lshl_b64 s[8:9], s[8:9], 1
	s_add_u32 s8, s31, s8
	s_addc_u32 s9, s34, s9
	v_lshl_add_u64 v[130:131], s[8:9], 0, v[130:131]
	v_readfirstlane_b32 s10, v159
	v_lshl_add_u64 v[130:131], v[130:131], 0, s[52:53]
	s_mov_b32 m0, s10
	v_lshl_add_u64 v[128:129], s[8:9], 0, v[128:129]
	v_readfirstlane_b32 s8, v160
	ds_read_b128 v[132:135], v149
	ds_read_b128 v[136:139], v149 offset:1024
	ds_read_b128 v[140:143], v149 offset:2048
	ds_read_b128 v[150:153], v149 offset:3072
	ds_read_b128 v[154:157], v146
	ds_read_b128 v[162:165], v146 offset:1024
	ds_read_b128 v[166:169], v146 offset:2048
	ds_read_b128 v[170:173], v146 offset:3072
	ds_read_b128 v[174:177], v146 offset:4096
	ds_read_b128 v[182:185], v146 offset:5120
	ds_read_b128 v[186:189], v146 offset:6144
	ds_read_b128 v[190:193], v146 offset:7168
	global_load_lds_dwordx4 v[130:131], off
	v_lshl_add_u64 v[128:129], v[128:129], 0, s[52:53]
	s_mov_b32 m0, s8
	s_nop 0
	global_load_lds_dwordx4 v[128:129], off
	s_barrier
; #define STAGE_A(P, br, kt) do { const char* _base = (const char*)(((kt) < G.ksplit ? G.A1 : A2m) + (long)(br) * G.lda + (long)(kt) * BK); \
;     __builtin_amdgcn_global_load_lds((const unsigned*)(_base + aoff0), (unsigned*)((char*)(P) + sb0), 16, 0, 0); \
;     __builtin_amdgcn_global_load_lds((const unsigned*)(_base + aoff1), (unsigned*)((char*)(P) + sb1), 16, 0, 0); } while (0)
; #define LDA(dst, b, h) for (int m = 0; m < 4; ++m) for (int k = 0; k < 2; ++k) \
;     dst[m][k] = *reinterpret_cast<const bf16x8*>(a_rd + ((b) * 2 + (h)) * (HT * 2) + m * 2048 + k * 1024)
; #define LDB(dst, b, h) for (int n = 0; n < 2; ++n) for (int k = 0; k < 2; ++k) \
;     dst[n][k] = *reinterpret_cast<const bf16x8*>(b_rd + ((b) * 2 + (h)) * (HT * 2) + n * 2048 + k * 1024)
; #define MMA(ai, bj, At_, Bt_) do { __builtin_amdgcn_s_setprio(1); \
;     for (int m = 0; m < 4; ++m) for (int n = 0; n < 2; ++n) for (int k = 0; k < 2; ++k) \
;       acc[ai][bj][m][n] = __builtin_amdgcn_mfma_f32_16x16x32_bf16(Bt_[n][k], At_[m][k], acc[ai][bj][m][n], 0, 0, 0); \
;     __builtin_amdgcn_s_setprio(0); } while (0)
; #define WAIT_V(n) asm volatile("s_waitcnt vmcnt(" #n ")" ::: "memory")
; #define WAIT_L(n) asm volatile("s_waitcnt lgkmcnt(" #n ")" ::: "memory")
; #define BAR __builtin_amdgcn_s_barrier()
;     ...
;   { LDB(B0, 0, 0); LDA(At, 0, 0); STAGE_A(SA(1, 1), brow + HALF, nt - 1);
;     BAR; WAIT_L(0); MMA(0, 0, At, B0); BAR;
;     LDB(B1, 0, 1); BAR; WAIT_L(0); MMA(0, 1, At, B1); BAR;
;     LDA(At, 0, 1); WAIT_V(4); BAR; WAIT_L(0); MMA(1, 0, At, B0); MMA(1, 1, At, B1); BAR; }
;   { LDB(B0, 1, 0); LDA(At, 1, 0); WAIT_V(2); BAR; WAIT_L(0); MMA(0, 0, At, B0); BAR;
;     LDB(B1, 1, 1); WAIT_V(0); BAR; WAIT_L(0); MMA(0, 1, At, B1); BAR;
;     LDA(At, 1, 1); BAR; WAIT_L(0); MMA(1, 0, At, B0); MMA(1, 1, At, B1); BAR; }
	s_waitcnt lgkmcnt(0)
	s_setprio 1
	s_waitcnt lgkmcnt(0)
	v_mfma_f32_16x16x32_bf16 v[124:127], v[132:135], v[154:157], v[124:127]
	v_mfma_f32_16x16x32_bf16 v[120:123], v[140:143], v[154:157], v[120:123]
	v_mfma_f32_16x16x32_bf16 v[116:119], v[132:135], v[166:169], v[116:119]
	v_mfma_f32_16x16x32_bf16 v[112:115], v[140:143], v[166:169], v[112:115]
	v_mfma_f32_16x16x32_bf16 v[108:111], v[132:135], v[174:177], v[108:111]
	v_mfma_f32_16x16x32_bf16 v[104:107], v[140:143], v[174:177], v[104:107]
	v_mfma_f32_16x16x32_bf16 v[100:103], v[132:135], v[186:189], v[100:103]
	v_mfma_f32_16x16x32_bf16 v[96:99], v[140:143], v[186:189], v[96:99]
	v_mfma_f32_16x16x32_bf16 v[124:127], v[136:139], v[162:165], v[124:127]
	v_mfma_f32_16x16x32_bf16 v[120:123], v[150:153], v[162:165], v[120:123]
	v_mfma_f32_16x16x32_bf16 v[116:119], v[136:139], v[170:173], v[116:119]
	v_mfma_f32_16x16x32_bf16 v[112:115], v[150:153], v[170:173], v[112:115]
	s_setprio 2
	s_barrier
	v_mfma_f32_16x16x32_bf16 v[108:111], v[136:139], v[182:185], v[108:111]
	v_mfma_f32_16x16x32_bf16 v[104:107], v[150:153], v[182:185], v[104:107]
	v_mfma_f32_16x16x32_bf16 v[100:103], v[136:139], v[190:193], v[100:103]
	v_mfma_f32_16x16x32_bf16 v[96:99], v[150:153], v[190:193], v[96:99]
	s_setprio 0
	ds_read_b128 v[128:131], v149 offset:16384
	ds_read_b128 v[158:161], v149 offset:17408
	ds_read_b128 v[194:197], v149 offset:18432
	ds_read_b128 v[198:201], v149 offset:19456
	s_barrier
	s_waitcnt lgkmcnt(0)
	s_setprio 1
	s_waitcnt lgkmcnt(0)
	v_mfma_f32_16x16x32_bf16 v[92:95], v[128:131], v[154:157], v[92:95]
	v_mfma_f32_16x16x32_bf16 v[88:91], v[194:197], v[154:157], v[88:91]
	v_mfma_f32_16x16x32_bf16 v[84:87], v[128:131], v[166:169], v[84:87]
	v_mfma_f32_16x16x32_bf16 v[80:83], v[194:197], v[166:169], v[80:83]
	v_mfma_f32_16x16x32_bf16 v[76:79], v[128:131], v[174:177], v[76:79]
	v_mfma_f32_16x16x32_bf16 v[72:75], v[194:197], v[174:177], v[72:75]
	v_mfma_f32_16x16x32_bf16 v[68:71], v[128:131], v[186:189], v[68:71]
	v_mfma_f32_16x16x32_bf16 v[64:67], v[194:197], v[186:189], v[64:67]
	v_mfma_f32_16x16x32_bf16 v[202:205], v[158:161], v[162:165], v[92:95]
	v_mfma_f32_16x16x32_bf16 v[154:157], v[198:201], v[162:165], v[88:91]
	v_mfma_f32_16x16x32_bf16 v[162:165], v[158:161], v[170:173], v[84:87]
	v_mfma_f32_16x16x32_bf16 v[166:169], v[198:201], v[170:173], v[80:83]
	s_setprio 2
	s_barrier
	v_mfma_f32_16x16x32_bf16 v[170:173], v[158:161], v[182:185], v[76:79]
	v_mfma_f32_16x16x32_bf16 v[174:177], v[198:201], v[182:185], v[72:75]
	v_mfma_f32_16x16x32_bf16 v[182:185], v[158:161], v[190:193], v[68:71]
	v_mfma_f32_16x16x32_bf16 v[186:189], v[198:201], v[190:193], v[64:67]
	s_setprio 0
	s_nop 0
	ds_read_b128 v[64:67], v146 offset:16384
	ds_read_b128 v[68:71], v146 offset:17408
	ds_read_b128 v[72:75], v146 offset:18432
	ds_read_b128 v[76:79], v146 offset:19456
	ds_read_b128 v[80:83], v146 offset:20480
	ds_read_b128 v[84:87], v146 offset:21504
	ds_read_b128 v[88:91], v146 offset:22528
	ds_read_b128 v[92:95], v146 offset:23552
	s_waitcnt vmcnt(4)
	s_barrier
	s_waitcnt lgkmcnt(0)
	s_setprio 1
	s_waitcnt lgkmcnt(0)
	v_mfma_f32_16x16x32_bf16 v[60:63], v[132:135], v[64:67], v[60:63]
	v_mfma_f32_16x16x32_bf16 v[56:59], v[140:143], v[64:67], v[56:59]
	v_mfma_f32_16x16x32_bf16 v[52:55], v[132:135], v[72:75], v[52:55]
	v_mfma_f32_16x16x32_bf16 v[48:51], v[140:143], v[72:75], v[48:51]
	v_mfma_f32_16x16x32_bf16 v[44:47], v[132:135], v[80:83], v[44:47]
	v_mfma_f32_16x16x32_bf16 v[40:43], v[140:143], v[80:83], v[40:43]
	v_mfma_f32_16x16x32_bf16 v[36:39], v[132:135], v[88:91], v[36:39]
	v_mfma_f32_16x16x32_bf16 v[32:35], v[140:143], v[88:91], v[32:35]
	v_mfma_f32_16x16x32_bf16 v[60:63], v[136:139], v[68:71], v[60:63]
	v_mfma_f32_16x16x32_bf16 v[56:59], v[150:153], v[68:71], v[56:59]
	v_mfma_f32_16x16x32_bf16 v[52:55], v[136:139], v[76:79], v[52:55]
	v_mfma_f32_16x16x32_bf16 v[48:51], v[150:153], v[76:79], v[48:51]
	v_mfma_f32_16x16x32_bf16 v[44:47], v[136:139], v[84:87], v[44:47]
	v_mfma_f32_16x16x32_bf16 v[40:43], v[150:153], v[84:87], v[40:43]
	v_mfma_f32_16x16x32_bf16 v[36:39], v[136:139], v[92:95], v[36:39]
	v_mfma_f32_16x16x32_bf16 v[32:35], v[150:153], v[92:95], v[32:35]
	s_setprio 0
	s_setprio 1
	v_mfma_f32_16x16x32_bf16 v[28:31], v[128:131], v[64:67], v[28:31]
	v_mfma_f32_16x16x32_bf16 v[24:27], v[194:197], v[64:67], v[24:27]
	v_mfma_f32_16x16x32_bf16 v[20:23], v[128:131], v[72:75], v[20:23]
	v_mfma_f32_16x16x32_bf16 v[16:19], v[194:197], v[72:75], v[16:19]
	v_mfma_f32_16x16x32_bf16 v[12:15], v[128:131], v[80:83], v[12:15]
	v_mfma_f32_16x16x32_bf16 v[8:11], v[194:197], v[80:83], v[8:11]
	v_mfma_f32_16x16x32_bf16 v[4:7], v[128:131], v[88:91], v[4:7]
	v_mfma_f32_16x16x32_bf16 v[0:3], v[194:197], v[88:91], v[0:3]
	v_mfma_f32_16x16x32_bf16 v[132:135], v[158:161], v[68:71], v[28:31]
	v_mfma_f32_16x16x32_bf16 v[136:139], v[198:201], v[68:71], v[24:27]
	v_mfma_f32_16x16x32_bf16 v[140:143], v[158:161], v[76:79], v[20:23]
	v_mfma_f32_16x16x32_bf16 v[150:153], v[198:201], v[76:79], v[16:19]
	s_setprio 2
	s_barrier
	v_mfma_f32_16x16x32_bf16 v[190:193], v[158:161], v[84:87], v[12:15]
	v_mfma_f32_16x16x32_bf16 v[206:209], v[198:201], v[84:87], v[8:11]
	v_mfma_f32_16x16x32_bf16 v[128:131], v[158:161], v[92:95], v[4:7]
	v_mfma_f32_16x16x32_bf16 v[158:161], v[198:201], v[92:95], v[0:3]
	s_setprio 0
	ds_read_b128 v[24:27], v149 offset:32768
	ds_read_b128 v[28:31], v149 offset:33792
	ds_read_b128 v[194:197], v149 offset:34816
	ds_read_b128 v[198:201], v149 offset:35840
	ds_read_b128 v[0:3], v146 offset:32768
	ds_read_b128 v[4:7], v146 offset:33792
	ds_read_b128 v[8:11], v146 offset:34816
	ds_read_b128 v[12:15], v146 offset:35840
	ds_read_b128 v[16:19], v146 offset:36864
	ds_read_b128 v[20:23], v146 offset:37888
	ds_read_b128 v[210:213], v146 offset:38912
	ds_read_b128 v[214:217], v146 offset:39936
	s_waitcnt vmcnt(2)
	s_barrier
; #define LDA(dst, b, h) for (int m = 0; m < 4; ++m) for (int k = 0; k < 2; ++k) \
;     dst[m][k] = *reinterpret_cast<const bf16x8*>(a_rd + ((b) * 2 + (h)) * (HT * 2) + m * 2048 + k * 1024)
; #define LDB(dst, b, h) for (int n = 0; n < 2; ++n) for (int k = 0; k < 2; ++k) \
;     dst[n][k] = *reinterpret_cast<const bf16x8*>(b_rd + ((b) * 2 + (h)) * (HT * 2) + n * 2048 + k * 1024)
; #define MMA(ai, bj, At_, Bt_) do { __builtin_amdgcn_s_setprio(1); \
;     for (int m = 0; m < 4; ++m) for (int n = 0; n < 2; ++n) for (int k = 0; k < 2; ++k) \
;       acc[ai][bj][m][n] = __builtin_amdgcn_mfma_f32_16x16x32_bf16(Bt_[n][k], At_[m][k], acc[ai][bj][m][n], 0, 0, 0); \
;     __builtin_amdgcn_s_setprio(0); } while (0)
; #define WAIT_V(n) asm volatile("s_waitcnt vmcnt(" #n ")" ::: "memory")
; #define WAIT_L(n) asm volatile("s_waitcnt lgkmcnt(" #n ")" ::: "memory")
; #define BAR __builtin_amdgcn_s_barrier()
;     ...
;   { LDB(B0, 1, 0); LDA(At, 1, 0); WAIT_V(2); BAR; WAIT_L(0); MMA(0, 0, At, B0); BAR;
;     LDB(B1, 1, 1); WAIT_V(0); BAR; WAIT_L(0); MMA(0, 1, At, B1); BAR;
;     LDA(At, 1, 1); BAR; WAIT_L(0); MMA(1, 0, At, B0); MMA(1, 1, At, B1); BAR; }
;   if (wr == 0) BAR;
	s_waitcnt lgkmcnt(0)
	s_setprio 1
	s_waitcnt lgkmcnt(0)
	v_mfma_f32_16x16x32_bf16 v[64:67], v[24:27], v[0:3], v[124:127]
	v_mfma_f32_16x16x32_bf16 v[68:71], v[194:197], v[0:3], v[120:123]
	v_mfma_f32_16x16x32_bf16 v[72:75], v[24:27], v[8:11], v[116:119]
	v_mfma_f32_16x16x32_bf16 v[76:79], v[194:197], v[8:11], v[112:115]
	v_mfma_f32_16x16x32_bf16 v[80:83], v[24:27], v[16:19], v[108:111]
	v_mfma_f32_16x16x32_bf16 v[84:87], v[194:197], v[16:19], v[104:107]
	v_mfma_f32_16x16x32_bf16 v[88:91], v[24:27], v[210:213], v[100:103]
	v_mfma_f32_16x16x32_bf16 v[92:95], v[194:197], v[210:213], v[96:99]
	v_mfma_f32_16x16x32_bf16 v[64:67], v[28:31], v[4:7], v[64:67]
	v_mfma_f32_16x16x32_bf16 v[68:71], v[198:201], v[4:7], v[68:71]
	v_mfma_f32_16x16x32_bf16 v[72:75], v[28:31], v[12:15], v[72:75]
	v_mfma_f32_16x16x32_bf16 v[76:79], v[198:201], v[12:15], v[76:79]
	s_setprio 2
	s_barrier
	v_mfma_f32_16x16x32_bf16 v[80:83], v[28:31], v[20:23], v[80:83]
	v_mfma_f32_16x16x32_bf16 v[84:87], v[198:201], v[20:23], v[84:87]
	v_mfma_f32_16x16x32_bf16 v[88:91], v[28:31], v[214:217], v[88:91]
	v_mfma_f32_16x16x32_bf16 v[92:95], v[198:201], v[214:217], v[92:95]
	s_setprio 0
	ds_read_b128 v[218:221], v149 offset:49152
	ds_read_b128 v[230:233], v149 offset:50176
	ds_read_b128 v[246:249], v149 offset:51200
	ds_read_b128 v[238:241], v149 offset:52224
	s_waitcnt vmcnt(0)
	s_barrier
	s_waitcnt lgkmcnt(0)
	s_setprio 1
	s_waitcnt lgkmcnt(0)
	v_mfma_f32_16x16x32_bf16 v[96:99], v[218:221], v[0:3], v[202:205]
	v_mfma_f32_16x16x32_bf16 v[0:3], v[246:249], v[0:3], v[154:157]
	v_mfma_f32_16x16x32_bf16 v[100:103], v[238:241], v[4:7], v[0:3]
	v_mfma_f32_16x16x32_bf16 v[0:3], v[218:221], v[8:11], v[162:165]
	v_mfma_f32_16x16x32_bf16 v[104:107], v[230:233], v[12:15], v[0:3]
	v_mfma_f32_16x16x32_bf16 v[0:3], v[246:249], v[8:11], v[166:169]
	v_mfma_f32_16x16x32_bf16 v[108:111], v[238:241], v[12:15], v[0:3]
	v_mfma_f32_16x16x32_bf16 v[0:3], v[218:221], v[16:19], v[170:173]
	v_mfma_f32_16x16x32_bf16 v[112:115], v[230:233], v[20:23], v[0:3]
	v_mfma_f32_16x16x32_bf16 v[0:3], v[246:249], v[16:19], v[174:177]
	v_mfma_f32_16x16x32_bf16 v[116:119], v[238:241], v[20:23], v[0:3]
	v_mfma_f32_16x16x32_bf16 v[0:3], v[218:221], v[210:213], v[182:185]
	s_setprio 2
	s_barrier
	v_mfma_f32_16x16x32_bf16 v[120:123], v[230:233], v[214:217], v[0:3]
	v_mfma_f32_16x16x32_bf16 v[0:3], v[246:249], v[210:213], v[186:189]
	v_mfma_f32_16x16x32_bf16 v[96:99], v[230:233], v[4:7], v[96:99]
	v_mfma_f32_16x16x32_bf16 v[124:127], v[238:241], v[214:217], v[0:3]
	s_setprio 0
	ds_read_b128 v[154:157], v146 offset:49152
	ds_read_b128 v[162:165], v146 offset:50176
	ds_read_b128 v[166:169], v146 offset:51200
	ds_read_b128 v[170:173], v146 offset:52224
	ds_read_b128 v[174:177], v146 offset:53248
	ds_read_b128 v[182:185], v146 offset:54272
	ds_read_b128 v[186:189], v146 offset:55296
	ds_read_b128 v[146:149], v146 offset:56320
	s_barrier
	s_waitcnt lgkmcnt(0)
	s_setprio 1
	s_waitcnt lgkmcnt(0)
	v_mfma_f32_16x16x32_bf16 v[0:3], v[24:27], v[154:157], v[60:63]
	v_mfma_f32_16x16x32_bf16 v[8:11], v[24:27], v[166:169], v[52:55]
	v_mfma_f32_16x16x32_bf16 v[16:19], v[24:27], v[174:177], v[44:47]
	v_mfma_f32_16x16x32_bf16 v[24:27], v[24:27], v[186:189], v[36:39]
	v_mfma_f32_16x16x32_bf16 v[0:3], v[28:31], v[162:165], v[0:3]
	v_mfma_f32_16x16x32_bf16 v[4:7], v[194:197], v[154:157], v[56:59]
	v_mfma_f32_16x16x32_bf16 v[8:11], v[28:31], v[170:173], v[8:11]
	v_mfma_f32_16x16x32_bf16 v[12:15], v[194:197], v[166:169], v[48:51]
	v_mfma_f32_16x16x32_bf16 v[16:19], v[28:31], v[182:185], v[16:19]
	v_mfma_f32_16x16x32_bf16 v[20:23], v[194:197], v[174:177], v[40:43]
	v_mfma_f32_16x16x32_bf16 v[24:27], v[28:31], v[146:149], v[24:27]
	v_mfma_f32_16x16x32_bf16 v[28:31], v[194:197], v[186:189], v[32:35]
	v_mfma_f32_16x16x32_bf16 v[4:7], v[198:201], v[162:165], v[4:7]
	v_mfma_f32_16x16x32_bf16 v[12:15], v[198:201], v[170:173], v[12:15]
	v_mfma_f32_16x16x32_bf16 v[20:23], v[198:201], v[182:185], v[20:23]
	v_mfma_f32_16x16x32_bf16 v[28:31], v[198:201], v[146:149], v[28:31]
	s_setprio 0
	s_setprio 1
	v_mfma_f32_16x16x32_bf16 v[32:35], v[218:221], v[154:157], v[132:135]
	v_mfma_f32_16x16x32_bf16 v[36:39], v[246:249], v[154:157], v[136:139]
	v_mfma_f32_16x16x32_bf16 v[40:43], v[218:221], v[166:169], v[140:143]
	v_mfma_f32_16x16x32_bf16 v[44:47], v[246:249], v[166:169], v[150:153]
	v_mfma_f32_16x16x32_bf16 v[48:51], v[218:221], v[174:177], v[190:193]
	v_mfma_f32_16x16x32_bf16 v[52:55], v[246:249], v[174:177], v[206:209]
	v_mfma_f32_16x16x32_bf16 v[56:59], v[218:221], v[186:189], v[128:131]
	v_mfma_f32_16x16x32_bf16 v[60:63], v[246:249], v[186:189], v[158:161]
	v_mfma_f32_16x16x32_bf16 v[32:35], v[230:233], v[162:165], v[32:35]
	v_mfma_f32_16x16x32_bf16 v[36:39], v[238:241], v[162:165], v[36:39]
	v_mfma_f32_16x16x32_bf16 v[40:43], v[230:233], v[170:173], v[40:43]
	v_mfma_f32_16x16x32_bf16 v[44:47], v[238:241], v[170:173], v[44:47]
	s_setprio 2
	s_barrier
	v_mfma_f32_16x16x32_bf16 v[48:51], v[230:233], v[182:185], v[48:51]
	v_mfma_f32_16x16x32_bf16 v[52:55], v[238:241], v[182:185], v[52:55]
	v_mfma_f32_16x16x32_bf16 v[56:59], v[230:233], v[146:149], v[56:59]
	v_mfma_f32_16x16x32_bf16 v[60:63], v[238:241], v[146:149], v[60:63]
	s_setprio 0
	v_cmp_gt_u32_e32 vcc, s60, v144
	s_and_saveexec_b64 s[8:9], vcc
	s_cbranch_execz .LBB0_2504
	s_barrier

; #define STAGE_A(P, br, kt) do { const char* _base = (const char*)(((kt) < G.ksplit ? G.A1 : A2m) + (long)(br) * G.lda + (long)(kt) * BK); \
;     __builtin_amdgcn_global_load_lds((const unsigned*)(_base + aoff0), (unsigned*)((char*)(P) + sb0), 16, 0, 0); \
;     __builtin_amdgcn_global_load_lds((const unsigned*)(_base + aoff1), (unsigned*)((char*)(P) + sb1), 16, 0, 0); } while (0)
; #define STAGE_B(P, br, kt) do { const char* _base = (const char*)(G.Bt + (long)(br) * G.ldb + (long)(kt) * BK); \
;     __builtin_amdgcn_global_load_lds((const unsigned*)(_base + boff0), (unsigned*)((char*)(P) + sb0), 16, 0, 0); \
;     __builtin_amdgcn_global_load_lds((const unsigned*)(_base + boff1), (unsigned*)((char*)(P) + sb1), 16, 0, 0); } while (0)
; #define LDA(dst, b, h) for (int m = 0; m < 4; ++m) for (int k = 0; k < 2; ++k) \
;     dst[m][k] = *reinterpret_cast<const bf16x8*>(a_rd + ((b) * 2 + (h)) * (HT * 2) + m * 2048 + k * 1024)
; #define LDB(dst, b, h) for (int n = 0; n < 2; ++n) for (int k = 0; k < 2; ++k) \
;     dst[n][k] = *reinterpret_cast<const bf16x8*>(b_rd + ((b) * 2 + (h)) * (HT * 2) + n * 2048 + k * 1024)
; #define MMA(ai, bj, At_, Bt_) do { __builtin_amdgcn_s_setprio(1); \
;     for (int m = 0; m < 4; ++m) for (int n = 0; n < 2; ++n) for (int k = 0; k < 2; ++k) \
;       acc[ai][bj][m][n] = __builtin_amdgcn_mfma_f32_16x16x32_bf16(Bt_[n][k], At_[m][k], acc[ai][bj][m][n], 0, 0, 0); \
;     __builtin_amdgcn_s_setprio(0); } while (0)
; #define WAIT_V(n) asm volatile("s_waitcnt vmcnt(" #n ")" ::: "memory")
; #define WAIT_L(n) asm volatile("s_waitcnt lgkmcnt(" #n ")" ::: "memory")
; #define BAR __builtin_amdgcn_s_barrier()
; #define SCHED __builtin_amdgcn_sched_barrier(0)
;     ...
;   if (EPI == EPI_RESID || first) {
;     STAGE_B(SB(0, 0), bcol, 0); STAGE_A(SA(0, 0), brow, 0);
;     STAGE_B(SB(0, 1), bcol + HALF, 0); STAGE_A(SA(0, 1), brow + HALF, 0);
;   }
;   if (wr == 1) BAR;
;   WAIT_V(0); BAR;
;   STAGE_B(SB(1, 0), bcol, 1); STAGE_A(SA(1, 0), brow, 1); STAGE_B(SB(1, 1), bcol + HALF, 1);
;   WAIT_V(6); BAR;
;   for (int t = 0; t < nt - 2; t += 2) {
;     LDB(B0, 0, 0); SCHED; LDA(At, 0, 0); STAGE_A(SA(1, 1), brow + HALF, t + 1);
;     WAIT_L(8); BAR; WAIT_L(0); MMA(0, 0, At, B0); BAR; SCHED;
;     LDB(B1, 0, 1); STAGE_B(SB(0, 0), bcol, t + 2);
;     BAR; WAIT_L(0); MMA(0, 1, At, B1); BAR;
.LBB0_2565:
	s_or_b64 exec, exec, s[20:21]
	v_and_b32_e32 v152, 15, v144
	v_lshlrev_b32_e32 v10, 2, v144
	s_ashr_i32 s19, s18, 31
	v_and_b32_e32 v8, 48, v144
	v_lshlrev_b32_e32 v9, 6, v152
	v_and_b32_e32 v10, 32, v10
	s_add_i32 s21, 32, 0x10000
	s_lshl_b32 s29, s29, 8
	s_lshl_b64 s[36:37], s[18:19], 1
	v_bitop3_b32 v10, v9, v10, v8 bitop3:0x36
	v_lshlrev_b32_e32 v8, 6, v144
	s_add_u32 s38, s8, s36
	v_readlane_b32 s19, v253, 46
	v_and_b32_e32 v8, 0x3000, v8
	s_addc_u32 s39, s9, s37
	v_add_u32_e32 v153, s19, v148
	s_waitcnt vmcnt(16)
	v_add_u32_e32 v12, s21, v8
	v_lshl_add_u64 v[8:9], s[38:39], 0, v[180:181]
	s_mov_b64 s[44:45], 0x80
	v_readfirstlane_b32 s19, v153
	v_lshl_add_u64 v[8:9], v[8:9], 0, s[44:45]
	s_mov_b32 m0, s19
	v_mov_b32_e32 v129, v181
	v_add_u32_e32 v154, 0x2000, v153
	s_waitcnt vmcnt(16)
	s_barrier
	global_load_lds_dwordx4 v[8:9], off
	v_lshl_add_u64 v[8:9], s[38:39], 0, v[128:129]
	v_readfirstlane_b32 s19, v154
	s_add_u32 s34, s23, s34
	v_lshl_add_u64 v[8:9], v[8:9], 0, s[44:45]
	s_mov_b32 m0, s19
	s_addc_u32 s35, s24, s31
	v_add_u32_e32 v155, 0x8000, v147
	global_load_lds_dwordx4 v[8:9], off
	v_lshl_add_u64 v[8:9], s[34:35], 0, v[180:181]
	v_readfirstlane_b32 s19, v155
	v_lshl_add_u64 v[8:9], v[8:9], 0, s[44:45]
	s_mov_b32 m0, s19
	s_or_b32 s20, s29, 0x80
	global_load_lds_dwordx4 v[8:9], off
	v_lshl_add_u64 v[8:9], s[34:35], 0, v[128:129]
	s_mul_i32 s34, s20, 0x840
	v_add_u32_e32 v156, 0xa000, v147
	s_ashr_i32 s35, s34, 31
	v_readfirstlane_b32 s19, v156
	s_lshl_b64 s[34:35], s[34:35], 1
	s_mov_b32 m0, s19
	s_add_u32 s34, s8, s34
	v_readlane_b32 s19, v253, 47
	v_lshl_add_u64 v[8:9], v[8:9], 0, s[44:45]
	s_addc_u32 s35, s9, s35
	v_add_u32_e32 v157, s19, v148
	global_load_lds_dwordx4 v[8:9], off
	v_lshl_add_u64 v[8:9], s[34:35], 0, v[180:181]
	v_readfirstlane_b32 s19, v157
	v_lshl_add_u64 v[8:9], v[8:9], 0, s[44:45]
	s_mov_b32 m0, s19
	v_add_u32_e32 v158, 0x2000, v157
	global_load_lds_dwordx4 v[8:9], off
	v_lshl_add_u64 v[8:9], s[34:35], 0, v[128:129]
	v_readfirstlane_b32 s19, v158
	v_lshl_add_u64 v[8:9], v[8:9], 0, s[44:45]
	s_mov_b32 m0, s19
	s_add_i32 s18, s18, 0x40000
	global_load_lds_dwordx4 v[8:9], off
	v_lshrrev_b32_e32 v8, 1, v0
	v_mul_lo_u32 v0, v1, s41
	v_mad_u64_u32 v[0:1], s[34:35], v8, s84, v[0:1]
	v_or_b32_e32 v0, v0, v2
	v_add_lshl_u32 v0, v0, v3, 1
	v_lshrrev_b32_e32 v3, 1, v4
	v_mul_lo_u32 v2, v5, s41
	v_mad_u64_u32 v[2:3], s[34:35], v3, s84, v[2:3]
	s_ashr_i32 s19, s18, 31
	s_waitcnt vmcnt(6)
	v_mov_b32_e32 v1, v181
	v_or_b32_e32 v2, v2, v6
	s_lshl_b64 s[18:19], s[18:19], 1
	v_lshl_add_u32 v11, v151, 13, 32
	v_lshl_add_u64 v[130:131], s[36:37], 0, v[0:1]
	v_add_lshl_u32 v2, v2, v7, 1
	v_mov_b32_e32 v3, v181
	v_mad_i64_i32 v[134:135], s[34:35], s28, v243, v[0:1]
	v_lshl_add_u64 v[138:139], s[18:19], 0, v[0:1]
	v_mov_b32_e32 v245, 0x80003fff
	v_lshl_add_u64 v[132:133], s[36:37], 0, v[2:3]
	v_mad_i64_i32 v[136:137], s[34:35], s28, v243, v[2:3]
	v_lshl_add_u64 v[140:141], s[18:19], 0, v[2:3]
	s_mov_b32 s31, -2
	v_add_u32_e32 v150, v12, v10
	v_add_u32_e32 v149, v11, v10
	s_mov_b64 s[18:19], s[8:9]
	s_barrier
	ds_read_b128 v[164:167], v150
	ds_read_b128 v[168:171], v150 offset:1024
	ds_read_b128 v[172:175], v150 offset:2048
	ds_read_b128 v[176:179], v150 offset:3072
	v_add_u32_e32 v162, 0xc000, v147
	v_lshl_add_u64 v[222:223], s[18:19], 0, v[134:135]
	v_readfirstlane_b32 s34, v162
	v_add_u32_e32 v163, 0xe000, v147
	v_lshl_add_u64 v[160:161], v[222:223], 0, s[94:95]
	s_mov_b32 m0, s34
	v_lshl_add_u64 v[226:227], s[18:19], 0, v[136:137]
	v_readfirstlane_b32 s34, v163
	ds_read_b128 v[182:185], v149
	ds_read_b128 v[186:189], v149 offset:1024
	ds_read_b128 v[190:193], v149 offset:2048
	ds_read_b128 v[194:197], v149 offset:3072
	ds_read_b128 v[198:201], v149 offset:4096
	ds_read_b128 v[202:205], v149 offset:5120
	ds_read_b128 v[206:209], v149 offset:6144
	ds_read_b128 v[210:213], v149 offset:7168
	global_load_lds_dwordx4 v[160:161], off
	v_lshl_add_u64 v[160:161], v[226:227], 0, s[94:95]
	s_mov_b32 m0, s34
	s_nop 0
	global_load_lds_dwordx4 v[160:161], off
	ds_read_b128 v[214:217], v150 offset:16384
	ds_read_b128 v[218:221], v150 offset:17408
	ds_read_b128 v[230:233], v150 offset:18432
	ds_read_b128 v[238:241], v150 offset:19456
	s_waitcnt lgkmcnt(0)
	s_waitcnt vmcnt(8)
	s_barrier
	s_setprio 1
	v_mfma_f32_16x16x32_bf16 v[124:127], v[164:167], v[182:185], 0
	v_mfma_f32_16x16x32_bf16 v[120:123], v[172:175], v[182:185], 0
	v_mfma_f32_16x16x32_bf16 v[116:119], v[164:167], v[190:193], 0
	v_mfma_f32_16x16x32_bf16 v[112:115], v[172:175], v[190:193], 0
	v_mfma_f32_16x16x32_bf16 v[108:111], v[164:167], v[198:201], 0
	v_mfma_f32_16x16x32_bf16 v[104:107], v[172:175], v[198:201], 0
	v_mfma_f32_16x16x32_bf16 v[100:103], v[164:167], v[206:209], 0
	v_mfma_f32_16x16x32_bf16 v[96:99], v[172:175], v[206:209], 0
	v_mfma_f32_16x16x32_bf16 v[124:127], v[168:171], v[186:189], v[124:127]
	v_mfma_f32_16x16x32_bf16 v[120:123], v[176:179], v[186:189], v[120:123]
	v_mfma_f32_16x16x32_bf16 v[116:119], v[168:171], v[194:197], v[116:119]
	v_mfma_f32_16x16x32_bf16 v[112:115], v[176:179], v[194:197], v[112:115]
	v_mfma_f32_16x16x32_bf16 v[108:111], v[168:171], v[202:205], v[108:111]
	v_mfma_f32_16x16x32_bf16 v[104:107], v[176:179], v[202:205], v[104:107]
	v_mfma_f32_16x16x32_bf16 v[100:103], v[168:171], v[210:213], v[100:103]
	v_mfma_f32_16x16x32_bf16 v[96:99], v[176:179], v[210:213], v[96:99]
	v_mfma_f32_16x16x32_bf16 v[92:95], v[214:217], v[182:185], 0
	v_mfma_f32_16x16x32_bf16 v[88:91], v[230:233], v[182:185], 0
	v_mfma_f32_16x16x32_bf16 v[84:87], v[214:217], v[190:193], 0
	v_mfma_f32_16x16x32_bf16 v[80:83], v[230:233], v[190:193], 0
	v_mfma_f32_16x16x32_bf16 v[76:79], v[214:217], v[198:201], 0
	v_mfma_f32_16x16x32_bf16 v[72:75], v[230:233], v[198:201], 0
	v_mfma_f32_16x16x32_bf16 v[68:71], v[214:217], v[206:209], 0
	v_mfma_f32_16x16x32_bf16 v[64:67], v[230:233], v[206:209], 0
	v_mfma_f32_16x16x32_bf16 v[92:95], v[218:221], v[186:189], v[92:95]
	v_mfma_f32_16x16x32_bf16 v[88:91], v[238:241], v[186:189], v[88:91]
	v_mfma_f32_16x16x32_bf16 v[84:87], v[218:221], v[194:197], v[84:87]
	v_mfma_f32_16x16x32_bf16 v[80:83], v[238:241], v[194:197], v[80:83]
	s_setprio 2
	s_barrier
; #define STAGE_A(P, br, kt) do { const char* _base = (const char*)(((kt) < G.ksplit ? G.A1 : A2m) + (long)(br) * G.lda + (long)(kt) * BK); \
;     __builtin_amdgcn_global_load_lds((const unsigned*)(_base + aoff0), (unsigned*)((char*)(P) + sb0), 16, 0, 0); \
;     __builtin_amdgcn_global_load_lds((const unsigned*)(_base + aoff1), (unsigned*)((char*)(P) + sb1), 16, 0, 0); } while (0)
; #define STAGE_B(P, br, kt) do { const char* _base = (const char*)(G.Bt + (long)(br) * G.ldb + (long)(kt) * BK); \
;     __builtin_amdgcn_global_load_lds((const unsigned*)(_base + boff0), (unsigned*)((char*)(P) + sb0), 16, 0, 0); \
;     __builtin_amdgcn_global_load_lds((const unsigned*)(_base + boff1), (unsigned*)((char*)(P) + sb1), 16, 0, 0); } while (0)
; #define LDA(dst, b, h) for (int m = 0; m < 4; ++m) for (int k = 0; k < 2; ++k) \
;     dst[m][k] = *reinterpret_cast<const bf16x8*>(a_rd + ((b) * 2 + (h)) * (HT * 2) + m * 2048 + k * 1024)
; #define LDB(dst, b, h) for (int n = 0; n < 2; ++n) for (int k = 0; k < 2; ++k) \
;     dst[n][k] = *reinterpret_cast<const bf16x8*>(b_rd + ((b) * 2 + (h)) * (HT * 2) + n * 2048 + k * 1024)
; #define MMA(ai, bj, At_, Bt_) do { __builtin_amdgcn_s_setprio(1); \
;     for (int m = 0; m < 4; ++m) for (int n = 0; n < 2; ++n) for (int k = 0; k < 2; ++k) \
;       acc[ai][bj][m][n] = __builtin_amdgcn_mfma_f32_16x16x32_bf16(Bt_[n][k], At_[m][k], acc[ai][bj][m][n], 0, 0, 0); \
;     __builtin_amdgcn_s_setprio(0); } while (0)
;     ...
;   for (int t = 0; t < nt - 2; t += 2) {
;     LDB(B0, 0, 0); SCHED; LDA(At, 0, 0); STAGE_A(SA(1, 1), brow + HALF, t + 1);
;     WAIT_L(8); BAR; WAIT_L(0); MMA(0, 0, At, B0); BAR; SCHED;
;     LDB(B1, 0, 1); STAGE_B(SB(0, 0), bcol, t + 2);
;     BAR; WAIT_L(0); MMA(0, 1, At, B1); BAR;
;     LDA(At, 0, 1); STAGE_A(SA(0, 0), brow, t + 2);
;     BAR; WAIT_L(0); MMA(1, 0, At, B0); BAR; SCHED;
;     STAGE_B(SB(0, 1), bcol + HALF, t + 2);
;     WAIT_V(6); BAR; MMA(1, 1, At, B1); BAR;
;     LDB(B0, 1, 0); SCHED; LDA(At, 1, 0); STAGE_A(SA(0, 1), brow + HALF, t + 2);
;     WAIT_L(8); BAR; WAIT_L(0); MMA(0, 0, At, B0); BAR; SCHED;
;     LDB(B1, 1, 1); STAGE_B(SB(1, 0), bcol, t + 3);
;     BAR; WAIT_L(0); MMA(0, 1, At, B1); BAR;
;     LDA(At, 1, 1); STAGE_A(SA(1, 0), brow, t + 3);
;     BAR; WAIT_L(0); MMA(1, 0, At, B0); BAR; SCHED;
;     STAGE_B(SB(1, 1), bcol + HALF, t + 3);
;     WAIT_V(6); BAR; MMA(1, 1, At, B1); BAR;
;   }
	v_mfma_f32_16x16x32_bf16 v[76:79], v[218:221], v[202:205], v[76:79]
	v_mfma_f32_16x16x32_bf16 v[72:75], v[238:241], v[202:205], v[72:75]
	v_mfma_f32_16x16x32_bf16 v[68:71], v[218:221], v[210:213], v[68:71]
	v_mfma_f32_16x16x32_bf16 v[64:67], v[238:241], v[210:213], v[64:67]
	s_setprio 0
	v_add_u32_e32 v159, s21, v148
	v_lshl_add_u64 v[234:235], s[18:19], 0, v[130:131]
	v_readfirstlane_b32 s34, v159
	v_lshl_add_u64 v[160:161], v[234:235], 0, s[90:91]
	s_mov_b32 m0, s34
	global_load_lds_dwordx4 v[160:161], off
	v_add_u32_e32 v160, 0x2000, v159
	v_lshl_add_u64 v[236:237], s[18:19], 0, v[132:133]
	v_readfirstlane_b32 s34, v160
	v_lshl_add_u64 v[246:247], v[236:237], 0, s[90:91]
	s_mov_b32 m0, s34
	s_nop 0
	global_load_lds_dwordx4 v[246:247], off
	v_readfirstlane_b32 s34, v147
	v_lshl_add_u64 v[246:247], v[222:223], 0, s[4:5]
	s_mov_b32 m0, s34
	v_readfirstlane_b32 s34, v146
	ds_read_b128 v[182:185], v149 offset:16384
	ds_read_b128 v[186:189], v149 offset:17408
	ds_read_b128 v[190:193], v149 offset:18432
	ds_read_b128 v[194:197], v149 offset:19456
	ds_read_b128 v[198:201], v149 offset:20480
	ds_read_b128 v[202:205], v149 offset:21504
	ds_read_b128 v[206:209], v149 offset:22528
	ds_read_b128 v[210:213], v149 offset:23552
	global_load_lds_dwordx4 v[246:247], off
	v_lshl_add_u64 v[246:247], v[226:227], 0, s[4:5]
	s_mov_b32 m0, s34
	s_nop 0
	global_load_lds_dwordx4 v[246:247], off
	v_lshl_add_u64 v[246:247], s[18:19], 0, v[138:139]
	v_readfirstlane_b32 s34, v145
	v_add_u32_e32 v161, 0x2000, v145
	v_lshl_add_u64 v[250:251], v[246:247], 0, s[68:69]
	s_mov_b32 m0, s34
	v_lshl_add_u64 v[248:249], s[18:19], 0, v[140:141]
	v_readfirstlane_b32 s34, v161
	global_load_lds_dwordx4 v[250:251], off
	v_lshl_add_u64 v[250:251], v[248:249], 0, s[68:69]
	s_mov_b32 m0, s34
	s_nop 0
	global_load_lds_dwordx4 v[250:251], off
	s_waitcnt lgkmcnt(0)
	s_waitcnt vmcnt(8)
	s_barrier
	s_setprio 1
	v_mfma_f32_16x16x32_bf16 v[60:63], v[164:167], v[182:185], 0
	v_mfma_f32_16x16x32_bf16 v[56:59], v[172:175], v[182:185], 0
	v_mfma_f32_16x16x32_bf16 v[52:55], v[164:167], v[190:193], 0
	v_mfma_f32_16x16x32_bf16 v[48:51], v[172:175], v[190:193], 0
	v_mfma_f32_16x16x32_bf16 v[44:47], v[164:167], v[198:201], 0
	v_mfma_f32_16x16x32_bf16 v[40:43], v[172:175], v[198:201], 0
	v_mfma_f32_16x16x32_bf16 v[36:39], v[164:167], v[206:209], 0
	v_mfma_f32_16x16x32_bf16 v[32:35], v[172:175], v[206:209], 0
	v_mfma_f32_16x16x32_bf16 v[60:63], v[168:171], v[186:189], v[60:63]
	v_mfma_f32_16x16x32_bf16 v[56:59], v[176:179], v[186:189], v[56:59]
	v_mfma_f32_16x16x32_bf16 v[52:55], v[168:171], v[194:197], v[52:55]
	v_mfma_f32_16x16x32_bf16 v[48:51], v[176:179], v[194:197], v[48:51]
	v_mfma_f32_16x16x32_bf16 v[44:47], v[168:171], v[202:205], v[44:47]
	v_mfma_f32_16x16x32_bf16 v[40:43], v[176:179], v[202:205], v[40:43]
	v_mfma_f32_16x16x32_bf16 v[36:39], v[168:171], v[210:213], v[36:39]
	v_mfma_f32_16x16x32_bf16 v[32:35], v[176:179], v[210:213], v[32:35]
	v_mfma_f32_16x16x32_bf16 v[28:31], v[214:217], v[182:185], 0
	v_mfma_f32_16x16x32_bf16 v[24:27], v[230:233], v[182:185], 0
	v_mfma_f32_16x16x32_bf16 v[20:23], v[214:217], v[190:193], 0
	v_mfma_f32_16x16x32_bf16 v[16:19], v[230:233], v[190:193], 0
	v_mfma_f32_16x16x32_bf16 v[12:15], v[214:217], v[198:201], 0
	v_mfma_f32_16x16x32_bf16 v[8:11], v[230:233], v[198:201], 0
	v_mfma_f32_16x16x32_bf16 v[4:7], v[214:217], v[206:209], 0
	v_mfma_f32_16x16x32_bf16 v[0:3], v[230:233], v[206:209], 0
	v_mfma_f32_16x16x32_bf16 v[28:31], v[218:221], v[186:189], v[28:31]
	v_mfma_f32_16x16x32_bf16 v[24:27], v[238:241], v[186:189], v[24:27]
	v_mfma_f32_16x16x32_bf16 v[20:23], v[218:221], v[194:197], v[20:23]
	v_mfma_f32_16x16x32_bf16 v[16:19], v[238:241], v[194:197], v[16:19]
	s_setprio 2
	s_barrier
	v_mfma_f32_16x16x32_bf16 v[12:15], v[218:221], v[202:205], v[12:15]
	v_mfma_f32_16x16x32_bf16 v[8:11], v[238:241], v[202:205], v[8:11]
	v_mfma_f32_16x16x32_bf16 v[4:7], v[218:221], v[210:213], v[4:7]
	v_mfma_f32_16x16x32_bf16 v[0:3], v[238:241], v[210:213], v[0:3]
	s_setprio 0
	ds_read_b128 v[164:167], v150 offset:32768
	ds_read_b128 v[168:171], v150 offset:33792
	ds_read_b128 v[172:175], v150 offset:34816
	ds_read_b128 v[176:179], v150 offset:35840
	v_readfirstlane_b32 s34, v143
	v_lshl_add_u64 v[214:215], v[222:223], 0, s[96:97]
	s_mov_b32 m0, s34
	v_readfirstlane_b32 s34, v142
	ds_read_b128 v[182:185], v149 offset:32768
	ds_read_b128 v[186:189], v149 offset:33792
	ds_read_b128 v[190:193], v149 offset:34816
	ds_read_b128 v[194:197], v149 offset:35840
	ds_read_b128 v[198:201], v149 offset:36864
	ds_read_b128 v[202:205], v149 offset:37888
	ds_read_b128 v[206:209], v149 offset:38912
	ds_read_b128 v[210:213], v149 offset:39936
	global_load_lds_dwordx4 v[214:215], off
	v_lshl_add_u64 v[214:215], v[226:227], 0, s[96:97]
	s_mov_b32 m0, s34
	s_nop 0
	global_load_lds_dwordx4 v[214:215], off
	ds_read_b128 v[214:217], v150 offset:49152
	ds_read_b128 v[218:221], v150 offset:50176
	ds_read_b128 v[230:233], v150 offset:51200
	ds_read_b128 v[238:241], v150 offset:52224
	s_waitcnt lgkmcnt(0)
	s_waitcnt vmcnt(8)
	s_barrier
; #define STAGE_A(P, br, kt) do { const char* _base = (const char*)(((kt) < G.ksplit ? G.A1 : A2m) + (long)(br) * G.lda + (long)(kt) * BK); \
;     __builtin_amdgcn_global_load_lds((const unsigned*)(_base + aoff0), (unsigned*)((char*)(P) + sb0), 16, 0, 0); \
;     __builtin_amdgcn_global_load_lds((const unsigned*)(_base + aoff1), (unsigned*)((char*)(P) + sb1), 16, 0, 0); } while (0)
; #define STAGE_B(P, br, kt) do { const char* _base = (const char*)(G.Bt + (long)(br) * G.ldb + (long)(kt) * BK); \
;     __builtin_amdgcn_global_load_lds((const unsigned*)(_base + boff0), (unsigned*)((char*)(P) + sb0), 16, 0, 0); \
;     __builtin_amdgcn_global_load_lds((const unsigned*)(_base + boff1), (unsigned*)((char*)(P) + sb1), 16, 0, 0); } while (0)
; #define LDA(dst, b, h) for (int m = 0; m < 4; ++m) for (int k = 0; k < 2; ++k) \
;     dst[m][k] = *reinterpret_cast<const bf16x8*>(a_rd + ((b) * 2 + (h)) * (HT * 2) + m * 2048 + k * 1024)
; #define LDB(dst, b, h) for (int n = 0; n < 2; ++n) for (int k = 0; k < 2; ++k) \
;     dst[n][k] = *reinterpret_cast<const bf16x8*>(b_rd + ((b) * 2 + (h)) * (HT * 2) + n * 2048 + k * 1024)
; #define MMA(ai, bj, At_, Bt_) do { __builtin_amdgcn_s_setprio(1); \
;     for (int m = 0; m < 4; ++m) for (int n = 0; n < 2; ++n) for (int k = 0; k < 2; ++k) \
;       acc[ai][bj][m][n] = __builtin_amdgcn_mfma_f32_16x16x32_bf16(Bt_[n][k], At_[m][k], acc[ai][bj][m][n], 0, 0, 0); \
;     __builtin_amdgcn_s_setprio(0); } while (0)
;     ...
;   for (int t = 0; t < nt - 2; t += 2) {
;     LDB(B0, 0, 0); SCHED; LDA(At, 0, 0); STAGE_A(SA(1, 1), brow + HALF, t + 1);
;     WAIT_L(8); BAR; WAIT_L(0); MMA(0, 0, At, B0); BAR; SCHED;
;     LDB(B1, 0, 1); STAGE_B(SB(0, 0), bcol, t + 2);
;     BAR; WAIT_L(0); MMA(0, 1, At, B1); BAR;
;     LDA(At, 0, 1); STAGE_A(SA(0, 0), brow, t + 2);
;     BAR; WAIT_L(0); MMA(1, 0, At, B0); BAR; SCHED;
;     STAGE_B(SB(0, 1), bcol + HALF, t + 2);
;     WAIT_V(6); BAR; MMA(1, 1, At, B1); BAR;
;     LDB(B0, 1, 0); SCHED; LDA(At, 1, 0); STAGE_A(SA(0, 1), brow + HALF, t + 2);
;     WAIT_L(8); BAR; WAIT_L(0); MMA(0, 0, At, B0); BAR; SCHED;
;     LDB(B1, 1, 1); STAGE_B(SB(1, 0), bcol, t + 3);
;     BAR; WAIT_L(0); MMA(0, 1, At, B1); BAR;
;     LDA(At, 1, 1); STAGE_A(SA(1, 0), brow, t + 3);
;     BAR; WAIT_L(0); MMA(1, 0, At, B0); BAR; SCHED;
;     STAGE_B(SB(1, 1), bcol + HALF, t + 3);
;     WAIT_V(6); BAR; MMA(1, 1, At, B1); BAR;
;   }
	s_setprio 1
	v_mfma_f32_16x16x32_bf16 v[124:127], v[164:167], v[182:185], v[124:127]
	v_mfma_f32_16x16x32_bf16 v[120:123], v[172:175], v[182:185], v[120:123]
	v_mfma_f32_16x16x32_bf16 v[116:119], v[164:167], v[190:193], v[116:119]
	v_mfma_f32_16x16x32_bf16 v[112:115], v[172:175], v[190:193], v[112:115]
	v_mfma_f32_16x16x32_bf16 v[108:111], v[164:167], v[198:201], v[108:111]
	v_mfma_f32_16x16x32_bf16 v[104:107], v[172:175], v[198:201], v[104:107]
	v_mfma_f32_16x16x32_bf16 v[100:103], v[164:167], v[206:209], v[100:103]
	v_mfma_f32_16x16x32_bf16 v[96:99], v[172:175], v[206:209], v[96:99]
	v_mfma_f32_16x16x32_bf16 v[124:127], v[168:171], v[186:189], v[124:127]
	v_mfma_f32_16x16x32_bf16 v[120:123], v[176:179], v[186:189], v[120:123]
	v_mfma_f32_16x16x32_bf16 v[116:119], v[168:171], v[194:197], v[116:119]
	v_mfma_f32_16x16x32_bf16 v[112:115], v[176:179], v[194:197], v[112:115]
	v_mfma_f32_16x16x32_bf16 v[108:111], v[168:171], v[202:205], v[108:111]
	v_mfma_f32_16x16x32_bf16 v[104:107], v[176:179], v[202:205], v[104:107]
	v_mfma_f32_16x16x32_bf16 v[100:103], v[168:171], v[210:213], v[100:103]
	v_mfma_f32_16x16x32_bf16 v[96:99], v[176:179], v[210:213], v[96:99]
	v_mfma_f32_16x16x32_bf16 v[92:95], v[214:217], v[182:185], v[92:95]
	v_mfma_f32_16x16x32_bf16 v[88:91], v[230:233], v[182:185], v[88:91]
	v_mfma_f32_16x16x32_bf16 v[84:87], v[214:217], v[190:193], v[84:87]
	v_mfma_f32_16x16x32_bf16 v[80:83], v[230:233], v[190:193], v[80:83]
	v_mfma_f32_16x16x32_bf16 v[76:79], v[214:217], v[198:201], v[76:79]
	v_mfma_f32_16x16x32_bf16 v[72:75], v[230:233], v[198:201], v[72:75]
	v_mfma_f32_16x16x32_bf16 v[68:71], v[214:217], v[206:209], v[68:71]
	v_mfma_f32_16x16x32_bf16 v[64:67], v[230:233], v[206:209], v[64:67]
	v_mfma_f32_16x16x32_bf16 v[92:95], v[218:221], v[186:189], v[92:95]
	v_mfma_f32_16x16x32_bf16 v[88:91], v[238:241], v[186:189], v[88:91]
	v_mfma_f32_16x16x32_bf16 v[84:87], v[218:221], v[194:197], v[84:87]
	v_mfma_f32_16x16x32_bf16 v[80:83], v[238:241], v[194:197], v[80:83]
	s_setprio 2
	s_barrier
	v_mfma_f32_16x16x32_bf16 v[76:79], v[218:221], v[202:205], v[76:79]
	v_mfma_f32_16x16x32_bf16 v[72:75], v[238:241], v[202:205], v[72:75]
	v_mfma_f32_16x16x32_bf16 v[68:71], v[218:221], v[210:213], v[68:71]
	v_mfma_f32_16x16x32_bf16 v[64:67], v[238:241], v[210:213], v[64:67]
	s_setprio 0
	v_readfirstlane_b32 s34, v153
	v_lshl_add_u64 v[234:235], v[234:235], 0, s[88:89]
	s_mov_b32 m0, s34
	v_readfirstlane_b32 s34, v154
	global_load_lds_dwordx4 v[234:235], off
	v_lshl_add_u64 v[234:235], v[236:237], 0, s[88:89]
	s_mov_b32 m0, s34
	s_nop 0
	global_load_lds_dwordx4 v[234:235], off
	v_readfirstlane_b32 s34, v155
	v_lshl_add_u64 v[222:223], v[222:223], 0, s[2:3]
	s_mov_b32 m0, s34
	v_readfirstlane_b32 s34, v156
	ds_read_b128 v[182:185], v149 offset:49152
	ds_read_b128 v[186:189], v149 offset:50176
	ds_read_b128 v[190:193], v149 offset:51200
	ds_read_b128 v[194:197], v149 offset:52224
	ds_read_b128 v[198:201], v149 offset:53248
	ds_read_b128 v[202:205], v149 offset:54272
	ds_read_b128 v[206:209], v149 offset:55296
	ds_read_b128 v[210:213], v149 offset:56320
	global_load_lds_dwordx4 v[222:223], off
	v_lshl_add_u64 v[222:223], v[226:227], 0, s[2:3]
	s_mov_b32 m0, s34
	s_nop 0
	global_load_lds_dwordx4 v[222:223], off
	v_readfirstlane_b32 s34, v157
	v_lshl_add_u64 v[250:251], v[246:247], 0, s[70:71]
	s_mov_b32 m0, s34
	v_readfirstlane_b32 s34, v158
	global_load_lds_dwordx4 v[250:251], off
	v_lshl_add_u64 v[250:251], v[248:249], 0, s[70:71]
	s_mov_b32 m0, s34
	s_nop 0
	global_load_lds_dwordx4 v[250:251], off
	s_waitcnt lgkmcnt(0)
	s_waitcnt vmcnt(8)
	s_barrier
	s_setprio 1
	v_mfma_f32_16x16x32_bf16 v[60:63], v[164:167], v[182:185], v[60:63]
	v_mfma_f32_16x16x32_bf16 v[56:59], v[172:175], v[182:185], v[56:59]
	v_mfma_f32_16x16x32_bf16 v[52:55], v[164:167], v[190:193], v[52:55]
	v_mfma_f32_16x16x32_bf16 v[48:51], v[172:175], v[190:193], v[48:51]
	v_mfma_f32_16x16x32_bf16 v[44:47], v[164:167], v[198:201], v[44:47]
	v_mfma_f32_16x16x32_bf16 v[40:43], v[172:175], v[198:201], v[40:43]
	v_mfma_f32_16x16x32_bf16 v[36:39], v[164:167], v[206:209], v[36:39]
	v_mfma_f32_16x16x32_bf16 v[32:35], v[172:175], v[206:209], v[32:35]
	v_mfma_f32_16x16x32_bf16 v[60:63], v[168:171], v[186:189], v[60:63]
	v_mfma_f32_16x16x32_bf16 v[56:59], v[176:179], v[186:189], v[56:59]
	v_mfma_f32_16x16x32_bf16 v[52:55], v[168:171], v[194:197], v[52:55]
	v_mfma_f32_16x16x32_bf16 v[48:51], v[176:179], v[194:197], v[48:51]
	v_mfma_f32_16x16x32_bf16 v[44:47], v[168:171], v[202:205], v[44:47]
	v_mfma_f32_16x16x32_bf16 v[40:43], v[176:179], v[202:205], v[40:43]
	v_mfma_f32_16x16x32_bf16 v[36:39], v[168:171], v[210:213], v[36:39]
	v_mfma_f32_16x16x32_bf16 v[32:35], v[176:179], v[210:213], v[32:35]
	v_mfma_f32_16x16x32_bf16 v[28:31], v[214:217], v[182:185], v[28:31]
	v_mfma_f32_16x16x32_bf16 v[24:27], v[230:233], v[182:185], v[24:27]
	v_mfma_f32_16x16x32_bf16 v[20:23], v[214:217], v[190:193], v[20:23]
	v_mfma_f32_16x16x32_bf16 v[16:19], v[230:233], v[190:193], v[16:19]
	v_mfma_f32_16x16x32_bf16 v[12:15], v[214:217], v[198:201], v[12:15]
	v_mfma_f32_16x16x32_bf16 v[8:11], v[230:233], v[198:201], v[8:11]
	v_mfma_f32_16x16x32_bf16 v[4:7], v[214:217], v[206:209], v[4:7]
	v_mfma_f32_16x16x32_bf16 v[0:3], v[230:233], v[206:209], v[0:3]
	v_mfma_f32_16x16x32_bf16 v[28:31], v[218:221], v[186:189], v[28:31]
	v_mfma_f32_16x16x32_bf16 v[24:27], v[238:241], v[186:189], v[24:27]
	v_mfma_f32_16x16x32_bf16 v[20:23], v[218:221], v[194:197], v[20:23]
	v_mfma_f32_16x16x32_bf16 v[16:19], v[238:241], v[194:197], v[16:19]
	s_setprio 2
	s_barrier
	v_mfma_f32_16x16x32_bf16 v[12:15], v[218:221], v[202:205], v[12:15]
	v_mfma_f32_16x16x32_bf16 v[8:11], v[238:241], v[202:205], v[8:11]
	v_mfma_f32_16x16x32_bf16 v[4:7], v[218:221], v[210:213], v[4:7]
	v_mfma_f32_16x16x32_bf16 v[0:3], v[238:241], v[210:213], v[0:3]
	s_setprio 0
	s_add_i32 s31, s31, 2
	s_add_u32 s18, s18, 0x100
	s_addc_u32 s19, s19, 0
	s_cmp_lt_u32 s31, 28
	s_cbranch_scc0 .Lmy_kexit_4
; #define STAGE_A(P, br, kt) do { const char* _base = (const char*)(((kt) < G.ksplit ? G.A1 : A2m) + (long)(br) * G.lda + (long)(kt) * BK); \
;     __builtin_amdgcn_global_load_lds((const unsigned*)(_base + aoff0), (unsigned*)((char*)(P) + sb0), 16, 0, 0); \
;     __builtin_amdgcn_global_load_lds((const unsigned*)(_base + aoff1), (unsigned*)((char*)(P) + sb1), 16, 0, 0); } while (0)
; #define STAGE_B(P, br, kt) do { const char* _base = (const char*)(G.Bt + (long)(br) * G.ldb + (long)(kt) * BK); \
;     __builtin_amdgcn_global_load_lds((const unsigned*)(_base + boff0), (unsigned*)((char*)(P) + sb0), 16, 0, 0); \
;     __builtin_amdgcn_global_load_lds((const unsigned*)(_base + boff1), (unsigned*)((char*)(P) + sb1), 16, 0, 0); } while (0)
; #define LDA(dst, b, h) for (int m = 0; m < 4; ++m) for (int k = 0; k < 2; ++k) \
;     dst[m][k] = *reinterpret_cast<const bf16x8*>(a_rd + ((b) * 2 + (h)) * (HT * 2) + m * 2048 + k * 1024)
; #define LDB(dst, b, h) for (int n = 0; n < 2; ++n) for (int k = 0; k < 2; ++k) \
;     dst[n][k] = *reinterpret_cast<const bf16x8*>(b_rd + ((b) * 2 + (h)) * (HT * 2) + n * 2048 + k * 1024)
; #define MMA(ai, bj, At_, Bt_) do { __builtin_amdgcn_s_setprio(1); \
;     for (int m = 0; m < 4; ++m) for (int n = 0; n < 2; ++n) for (int k = 0; k < 2; ++k) \
;       acc[ai][bj][m][n] = __builtin_amdgcn_mfma_f32_16x16x32_bf16(Bt_[n][k], At_[m][k], acc[ai][bj][m][n], 0, 0, 0); \
;     __builtin_amdgcn_s_setprio(0); } while (0)
;     ...
;   for (int t = 0; t < nt - 2; t += 2) {
;     LDB(B0, 0, 0); SCHED; LDA(At, 0, 0); STAGE_A(SA(1, 1), brow + HALF, t + 1);
;     WAIT_L(8); BAR; WAIT_L(0); MMA(0, 0, At, B0); BAR; SCHED;
;     LDB(B1, 0, 1); STAGE_B(SB(0, 0), bcol, t + 2);
;     BAR; WAIT_L(0); MMA(0, 1, At, B1); BAR;
;     LDA(At, 0, 1); STAGE_A(SA(0, 0), brow, t + 2);
;     BAR; WAIT_L(0); MMA(1, 0, At, B0); BAR; SCHED;
;     STAGE_B(SB(0, 1), bcol + HALF, t + 2);
;     WAIT_V(6); BAR; MMA(1, 1, At, B1); BAR;
;     LDB(B0, 1, 0); SCHED; LDA(At, 1, 0); STAGE_A(SA(0, 1), brow + HALF, t + 2);
;     WAIT_L(8); BAR; WAIT_L(0); MMA(0, 0, At, B0); BAR; SCHED;
;     LDB(B1, 1, 1); STAGE_B(SB(1, 0), bcol, t + 3);
;     BAR; WAIT_L(0); MMA(0, 1, At, B1); BAR;
;     LDA(At, 1, 1); STAGE_A(SA(1, 0), brow, t + 3);
;     BAR; WAIT_L(0); MMA(1, 0, At, B0); BAR; SCHED;
;     STAGE_B(SB(1, 1), bcol + HALF, t + 3);
;     WAIT_V(6); BAR; MMA(1, 1, At, B1); BAR;
;   }
.LBB0_2566:
	ds_read_b128 v[164:167], v150
	ds_read_b128 v[168:171], v150 offset:1024
	ds_read_b128 v[172:175], v150 offset:2048
	ds_read_b128 v[176:179], v150 offset:3072
	v_add_u32_e32 v162, 0xc000, v147
	v_lshl_add_u64 v[222:223], s[18:19], 0, v[134:135]
	v_readfirstlane_b32 s34, v162
	v_add_u32_e32 v163, 0xe000, v147
	v_lshl_add_u64 v[160:161], v[222:223], 0, s[94:95]
	s_mov_b32 m0, s34
	v_lshl_add_u64 v[226:227], s[18:19], 0, v[136:137]
	v_readfirstlane_b32 s34, v163
	ds_read_b128 v[182:185], v149
	ds_read_b128 v[186:189], v149 offset:1024
	ds_read_b128 v[190:193], v149 offset:2048
	ds_read_b128 v[194:197], v149 offset:3072
	ds_read_b128 v[198:201], v149 offset:4096
	ds_read_b128 v[202:205], v149 offset:5120
	ds_read_b128 v[206:209], v149 offset:6144
	ds_read_b128 v[210:213], v149 offset:7168
	global_load_lds_dwordx4 v[160:161], off
	v_lshl_add_u64 v[160:161], v[226:227], 0, s[94:95]
	s_mov_b32 m0, s34
	s_nop 0
	global_load_lds_dwordx4 v[160:161], off
	ds_read_b128 v[214:217], v150 offset:16384
	ds_read_b128 v[218:221], v150 offset:17408
	ds_read_b128 v[230:233], v150 offset:18432
	ds_read_b128 v[238:241], v150 offset:19456
	s_waitcnt lgkmcnt(0)
	s_waitcnt vmcnt(8)
	s_barrier
	s_setprio 1
	v_mfma_f32_16x16x32_bf16 v[124:127], v[164:167], v[182:185], v[124:127]
	v_mfma_f32_16x16x32_bf16 v[120:123], v[172:175], v[182:185], v[120:123]
	v_mfma_f32_16x16x32_bf16 v[116:119], v[164:167], v[190:193], v[116:119]
	v_mfma_f32_16x16x32_bf16 v[112:115], v[172:175], v[190:193], v[112:115]
	v_mfma_f32_16x16x32_bf16 v[108:111], v[164:167], v[198:201], v[108:111]
	v_mfma_f32_16x16x32_bf16 v[104:107], v[172:175], v[198:201], v[104:107]
	v_mfma_f32_16x16x32_bf16 v[100:103], v[164:167], v[206:209], v[100:103]
	v_mfma_f32_16x16x32_bf16 v[96:99], v[172:175], v[206:209], v[96:99]
	v_mfma_f32_16x16x32_bf16 v[124:127], v[168:171], v[186:189], v[124:127]
	v_mfma_f32_16x16x32_bf16 v[120:123], v[176:179], v[186:189], v[120:123]
	v_mfma_f32_16x16x32_bf16 v[116:119], v[168:171], v[194:197], v[116:119]
	v_mfma_f32_16x16x32_bf16 v[112:115], v[176:179], v[194:197], v[112:115]
	v_mfma_f32_16x16x32_bf16 v[108:111], v[168:171], v[202:205], v[108:111]
	v_mfma_f32_16x16x32_bf16 v[104:107], v[176:179], v[202:205], v[104:107]
	v_mfma_f32_16x16x32_bf16 v[100:103], v[168:171], v[210:213], v[100:103]
	v_mfma_f32_16x16x32_bf16 v[96:99], v[176:179], v[210:213], v[96:99]
	v_mfma_f32_16x16x32_bf16 v[92:95], v[214:217], v[182:185], v[92:95]
	v_mfma_f32_16x16x32_bf16 v[88:91], v[230:233], v[182:185], v[88:91]
	v_mfma_f32_16x16x32_bf16 v[84:87], v[214:217], v[190:193], v[84:87]
	v_mfma_f32_16x16x32_bf16 v[80:83], v[230:233], v[190:193], v[80:83]
	v_mfma_f32_16x16x32_bf16 v[76:79], v[214:217], v[198:201], v[76:79]
	v_mfma_f32_16x16x32_bf16 v[72:75], v[230:233], v[198:201], v[72:75]
	v_mfma_f32_16x16x32_bf16 v[68:71], v[214:217], v[206:209], v[68:71]
	v_mfma_f32_16x16x32_bf16 v[64:67], v[230:233], v[206:209], v[64:67]
	v_mfma_f32_16x16x32_bf16 v[92:95], v[218:221], v[186:189], v[92:95]
	v_mfma_f32_16x16x32_bf16 v[88:91], v[238:241], v[186:189], v[88:91]
	v_mfma_f32_16x16x32_bf16 v[84:87], v[218:221], v[194:197], v[84:87]
	v_mfma_f32_16x16x32_bf16 v[80:83], v[238:241], v[194:197], v[80:83]
	s_setprio 2
	s_barrier
	v_mfma_f32_16x16x32_bf16 v[76:79], v[218:221], v[202:205], v[76:79]
	v_mfma_f32_16x16x32_bf16 v[72:75], v[238:241], v[202:205], v[72:75]
	v_mfma_f32_16x16x32_bf16 v[68:71], v[218:221], v[210:213], v[68:71]
	v_mfma_f32_16x16x32_bf16 v[64:67], v[238:241], v[210:213], v[64:67]
	s_setprio 0
	v_add_u32_e32 v159, s21, v148
	v_lshl_add_u64 v[234:235], s[18:19], 0, v[130:131]
	v_readfirstlane_b32 s34, v159
	v_lshl_add_u64 v[160:161], v[234:235], 0, s[90:91]
	s_mov_b32 m0, s34
	global_load_lds_dwordx4 v[160:161], off
	v_add_u32_e32 v160, 0x2000, v159
	v_lshl_add_u64 v[236:237], s[18:19], 0, v[132:133]
	v_readfirstlane_b32 s34, v160
	v_lshl_add_u64 v[246:247], v[236:237], 0, s[90:91]
	s_mov_b32 m0, s34
	s_nop 0
	global_load_lds_dwordx4 v[246:247], off
	v_readfirstlane_b32 s34, v147
	v_lshl_add_u64 v[246:247], v[222:223], 0, s[4:5]
	s_mov_b32 m0, s34
	v_readfirstlane_b32 s34, v146
	ds_read_b128 v[182:185], v149 offset:16384
	ds_read_b128 v[186:189], v149 offset:17408
	ds_read_b128 v[190:193], v149 offset:18432
	ds_read_b128 v[194:197], v149 offset:19456
	ds_read_b128 v[198:201], v149 offset:20480
	ds_read_b128 v[202:205], v149 offset:21504
	ds_read_b128 v[206:209], v149 offset:22528
	ds_read_b128 v[210:213], v149 offset:23552
	global_load_lds_dwordx4 v[246:247], off
	v_lshl_add_u64 v[246:247], v[226:227], 0, s[4:5]
	s_mov_b32 m0, s34
	s_nop 0
	global_load_lds_dwordx4 v[246:247], off
	v_lshl_add_u64 v[246:247], s[18:19], 0, v[138:139]
	v_readfirstlane_b32 s34, v145
	v_add_u32_e32 v161, 0x2000, v145
	v_lshl_add_u64 v[250:251], v[246:247], 0, s[68:69]
	s_mov_b32 m0, s34
	v_lshl_add_u64 v[248:249], s[18:19], 0, v[140:141]
	v_readfirstlane_b32 s34, v161
	global_load_lds_dwordx4 v[250:251], off
	v_lshl_add_u64 v[250:251], v[248:249], 0, s[68:69]
	s_mov_b32 m0, s34
	s_nop 0
	global_load_lds_dwordx4 v[250:251], off
	s_waitcnt lgkmcnt(0)
	s_waitcnt vmcnt(8)
	s_barrier
; #define STAGE_A(P, br, kt) do { const char* _base = (const char*)(((kt) < G.ksplit ? G.A1 : A2m) + (long)(br) * G.lda + (long)(kt) * BK); \
;     __builtin_amdgcn_global_load_lds((const unsigned*)(_base + aoff0), (unsigned*)((char*)(P) + sb0), 16, 0, 0); \
;     __builtin_amdgcn_global_load_lds((const unsigned*)(_base + aoff1), (unsigned*)((char*)(P) + sb1), 16, 0, 0); } while (0)
; #define STAGE_B(P, br, kt) do { const char* _base = (const char*)(G.Bt + (long)(br) * G.ldb + (long)(kt) * BK); \
;     __builtin_amdgcn_global_load_lds((const unsigned*)(_base + boff0), (unsigned*)((char*)(P) + sb0), 16, 0, 0); \
;     __builtin_amdgcn_global_load_lds((const unsigned*)(_base + boff1), (unsigned*)((char*)(P) + sb1), 16, 0, 0); } while (0)
; #define LDA(dst, b, h) for (int m = 0; m < 4; ++m) for (int k = 0; k < 2; ++k) \
;     dst[m][k] = *reinterpret_cast<const bf16x8*>(a_rd + ((b) * 2 + (h)) * (HT * 2) + m * 2048 + k * 1024)
; #define LDB(dst, b, h) for (int n = 0; n < 2; ++n) for (int k = 0; k < 2; ++k) \
;     dst[n][k] = *reinterpret_cast<const bf16x8*>(b_rd + ((b) * 2 + (h)) * (HT * 2) + n * 2048 + k * 1024)
; #define MMA(ai, bj, At_, Bt_) do { __builtin_amdgcn_s_setprio(1); \
;     for (int m = 0; m < 4; ++m) for (int n = 0; n < 2; ++n) for (int k = 0; k < 2; ++k) \
;       acc[ai][bj][m][n] = __builtin_amdgcn_mfma_f32_16x16x32_bf16(Bt_[n][k], At_[m][k], acc[ai][bj][m][n], 0, 0, 0); \
;     __builtin_amdgcn_s_setprio(0); } while (0)
;     ...
;   for (int t = 0; t < nt - 2; t += 2) {
;     LDB(B0, 0, 0); SCHED; LDA(At, 0, 0); STAGE_A(SA(1, 1), brow + HALF, t + 1);
;     WAIT_L(8); BAR; WAIT_L(0); MMA(0, 0, At, B0); BAR; SCHED;
;     LDB(B1, 0, 1); STAGE_B(SB(0, 0), bcol, t + 2);
;     BAR; WAIT_L(0); MMA(0, 1, At, B1); BAR;
;     LDA(At, 0, 1); STAGE_A(SA(0, 0), brow, t + 2);
;     BAR; WAIT_L(0); MMA(1, 0, At, B0); BAR; SCHED;
;     STAGE_B(SB(0, 1), bcol + HALF, t + 2);
;     WAIT_V(6); BAR; MMA(1, 1, At, B1); BAR;
;     LDB(B0, 1, 0); SCHED; LDA(At, 1, 0); STAGE_A(SA(0, 1), brow + HALF, t + 2);
;     WAIT_L(8); BAR; WAIT_L(0); MMA(0, 0, At, B0); BAR; SCHED;
;     LDB(B1, 1, 1); STAGE_B(SB(1, 0), bcol, t + 3);
;     BAR; WAIT_L(0); MMA(0, 1, At, B1); BAR;
;     LDA(At, 1, 1); STAGE_A(SA(1, 0), brow, t + 3);
;     BAR; WAIT_L(0); MMA(1, 0, At, B0); BAR; SCHED;
;     STAGE_B(SB(1, 1), bcol + HALF, t + 3);
;     WAIT_V(6); BAR; MMA(1, 1, At, B1); BAR;
;   }
	s_setprio 1
	v_mfma_f32_16x16x32_bf16 v[60:63], v[164:167], v[182:185], v[60:63]
	v_mfma_f32_16x16x32_bf16 v[56:59], v[172:175], v[182:185], v[56:59]
	v_mfma_f32_16x16x32_bf16 v[52:55], v[164:167], v[190:193], v[52:55]
	v_mfma_f32_16x16x32_bf16 v[48:51], v[172:175], v[190:193], v[48:51]
	v_mfma_f32_16x16x32_bf16 v[44:47], v[164:167], v[198:201], v[44:47]
	v_mfma_f32_16x16x32_bf16 v[40:43], v[172:175], v[198:201], v[40:43]
	v_mfma_f32_16x16x32_bf16 v[36:39], v[164:167], v[206:209], v[36:39]
	v_mfma_f32_16x16x32_bf16 v[32:35], v[172:175], v[206:209], v[32:35]
	v_mfma_f32_16x16x32_bf16 v[60:63], v[168:171], v[186:189], v[60:63]
	v_mfma_f32_16x16x32_bf16 v[56:59], v[176:179], v[186:189], v[56:59]
	v_mfma_f32_16x16x32_bf16 v[52:55], v[168:171], v[194:197], v[52:55]
	v_mfma_f32_16x16x32_bf16 v[48:51], v[176:179], v[194:197], v[48:51]
	v_mfma_f32_16x16x32_bf16 v[44:47], v[168:171], v[202:205], v[44:47]
	v_mfma_f32_16x16x32_bf16 v[40:43], v[176:179], v[202:205], v[40:43]
	v_mfma_f32_16x16x32_bf16 v[36:39], v[168:171], v[210:213], v[36:39]
	v_mfma_f32_16x16x32_bf16 v[32:35], v[176:179], v[210:213], v[32:35]
	v_mfma_f32_16x16x32_bf16 v[28:31], v[214:217], v[182:185], v[28:31]
	v_mfma_f32_16x16x32_bf16 v[24:27], v[230:233], v[182:185], v[24:27]
	v_mfma_f32_16x16x32_bf16 v[20:23], v[214:217], v[190:193], v[20:23]
	v_mfma_f32_16x16x32_bf16 v[16:19], v[230:233], v[190:193], v[16:19]
	v_mfma_f32_16x16x32_bf16 v[12:15], v[214:217], v[198:201], v[12:15]
	v_mfma_f32_16x16x32_bf16 v[8:11], v[230:233], v[198:201], v[8:11]
	v_mfma_f32_16x16x32_bf16 v[4:7], v[214:217], v[206:209], v[4:7]
	v_mfma_f32_16x16x32_bf16 v[0:3], v[230:233], v[206:209], v[0:3]
	v_mfma_f32_16x16x32_bf16 v[28:31], v[218:221], v[186:189], v[28:31]
	v_mfma_f32_16x16x32_bf16 v[24:27], v[238:241], v[186:189], v[24:27]
	v_mfma_f32_16x16x32_bf16 v[20:23], v[218:221], v[194:197], v[20:23]
	v_mfma_f32_16x16x32_bf16 v[16:19], v[238:241], v[194:197], v[16:19]
	s_setprio 2
	s_barrier
	v_mfma_f32_16x16x32_bf16 v[12:15], v[218:221], v[202:205], v[12:15]
	v_mfma_f32_16x16x32_bf16 v[8:11], v[238:241], v[202:205], v[8:11]
	v_mfma_f32_16x16x32_bf16 v[4:7], v[218:221], v[210:213], v[4:7]
	v_mfma_f32_16x16x32_bf16 v[0:3], v[238:241], v[210:213], v[0:3]
	s_setprio 0
	ds_read_b128 v[164:167], v150 offset:32768
	ds_read_b128 v[168:171], v150 offset:33792
	ds_read_b128 v[172:175], v150 offset:34816
	ds_read_b128 v[176:179], v150 offset:35840
	v_readfirstlane_b32 s34, v143
	v_lshl_add_u64 v[214:215], v[222:223], 0, s[96:97]
	s_mov_b32 m0, s34
	v_readfirstlane_b32 s34, v142
	ds_read_b128 v[182:185], v149 offset:32768
	ds_read_b128 v[186:189], v149 offset:33792
	ds_read_b128 v[190:193], v149 offset:34816
	ds_read_b128 v[194:197], v149 offset:35840
	ds_read_b128 v[198:201], v149 offset:36864
	ds_read_b128 v[202:205], v149 offset:37888
	ds_read_b128 v[206:209], v149 offset:38912
	ds_read_b128 v[210:213], v149 offset:39936
	global_load_lds_dwordx4 v[214:215], off
	v_lshl_add_u64 v[214:215], v[226:227], 0, s[96:97]
	s_mov_b32 m0, s34
	s_nop 0
	global_load_lds_dwordx4 v[214:215], off
	ds_read_b128 v[214:217], v150 offset:49152
	ds_read_b128 v[218:221], v150 offset:50176
	ds_read_b128 v[230:233], v150 offset:51200
	ds_read_b128 v[238:241], v150 offset:52224
	s_waitcnt lgkmcnt(0)
	s_waitcnt vmcnt(8)
	s_barrier
	s_setprio 1
	v_mfma_f32_16x16x32_bf16 v[124:127], v[164:167], v[182:185], v[124:127]
	v_mfma_f32_16x16x32_bf16 v[120:123], v[172:175], v[182:185], v[120:123]
	v_mfma_f32_16x16x32_bf16 v[116:119], v[164:167], v[190:193], v[116:119]
	v_mfma_f32_16x16x32_bf16 v[112:115], v[172:175], v[190:193], v[112:115]
	v_mfma_f32_16x16x32_bf16 v[108:111], v[164:167], v[198:201], v[108:111]
	v_mfma_f32_16x16x32_bf16 v[104:107], v[172:175], v[198:201], v[104:107]
	v_mfma_f32_16x16x32_bf16 v[100:103], v[164:167], v[206:209], v[100:103]
	v_mfma_f32_16x16x32_bf16 v[96:99], v[172:175], v[206:209], v[96:99]
	v_mfma_f32_16x16x32_bf16 v[124:127], v[168:171], v[186:189], v[124:127]
	v_mfma_f32_16x16x32_bf16 v[120:123], v[176:179], v[186:189], v[120:123]
	v_mfma_f32_16x16x32_bf16 v[116:119], v[168:171], v[194:197], v[116:119]
	v_mfma_f32_16x16x32_bf16 v[112:115], v[176:179], v[194:197], v[112:115]
	v_mfma_f32_16x16x32_bf16 v[108:111], v[168:171], v[202:205], v[108:111]
	v_mfma_f32_16x16x32_bf16 v[104:107], v[176:179], v[202:205], v[104:107]
	v_mfma_f32_16x16x32_bf16 v[100:103], v[168:171], v[210:213], v[100:103]
	v_mfma_f32_16x16x32_bf16 v[96:99], v[176:179], v[210:213], v[96:99]
	v_mfma_f32_16x16x32_bf16 v[92:95], v[214:217], v[182:185], v[92:95]
	v_mfma_f32_16x16x32_bf16 v[88:91], v[230:233], v[182:185], v[88:91]
	v_mfma_f32_16x16x32_bf16 v[84:87], v[214:217], v[190:193], v[84:87]
	v_mfma_f32_16x16x32_bf16 v[80:83], v[230:233], v[190:193], v[80:83]
	v_mfma_f32_16x16x32_bf16 v[76:79], v[214:217], v[198:201], v[76:79]
	v_mfma_f32_16x16x32_bf16 v[72:75], v[230:233], v[198:201], v[72:75]
	v_mfma_f32_16x16x32_bf16 v[68:71], v[214:217], v[206:209], v[68:71]
	v_mfma_f32_16x16x32_bf16 v[64:67], v[230:233], v[206:209], v[64:67]
	v_mfma_f32_16x16x32_bf16 v[92:95], v[218:221], v[186:189], v[92:95]
	v_mfma_f32_16x16x32_bf16 v[88:91], v[238:241], v[186:189], v[88:91]
	v_mfma_f32_16x16x32_bf16 v[84:87], v[218:221], v[194:197], v[84:87]
	v_mfma_f32_16x16x32_bf16 v[80:83], v[238:241], v[194:197], v[80:83]
	s_setprio 2
	s_barrier
; #define STAGE_A(P, br, kt) do { const char* _base = (const char*)(((kt) < G.ksplit ? G.A1 : A2m) + (long)(br) * G.lda + (long)(kt) * BK); \
;     __builtin_amdgcn_global_load_lds((const unsigned*)(_base + aoff0), (unsigned*)((char*)(P) + sb0), 16, 0, 0); \
;     __builtin_amdgcn_global_load_lds((const unsigned*)(_base + aoff1), (unsigned*)((char*)(P) + sb1), 16, 0, 0); } while (0)
; #define STAGE_B(P, br, kt) do { const char* _base = (const char*)(G.Bt + (long)(br) * G.ldb + (long)(kt) * BK); \
;     __builtin_amdgcn_global_load_lds((const unsigned*)(_base + boff0), (unsigned*)((char*)(P) + sb0), 16, 0, 0); \
;     __builtin_amdgcn_global_load_lds((const unsigned*)(_base + boff1), (unsigned*)((char*)(P) + sb1), 16, 0, 0); } while (0)
; #define LDA(dst, b, h) for (int m = 0; m < 4; ++m) for (int k = 0; k < 2; ++k) \
;     dst[m][k] = *reinterpret_cast<const bf16x8*>(a_rd + ((b) * 2 + (h)) * (HT * 2) + m * 2048 + k * 1024)
; #define LDB(dst, b, h) for (int n = 0; n < 2; ++n) for (int k = 0; k < 2; ++k) \
;     dst[n][k] = *reinterpret_cast<const bf16x8*>(b_rd + ((b) * 2 + (h)) * (HT * 2) + n * 2048 + k * 1024)
; #define MMA(ai, bj, At_, Bt_) do { __builtin_amdgcn_s_setprio(1); \
;     for (int m = 0; m < 4; ++m) for (int n = 0; n < 2; ++n) for (int k = 0; k < 2; ++k) \
;       acc[ai][bj][m][n] = __builtin_amdgcn_mfma_f32_16x16x32_bf16(Bt_[n][k], At_[m][k], acc[ai][bj][m][n], 0, 0, 0); \
;     __builtin_amdgcn_s_setprio(0); } while (0)
; #define WAIT_V(n) asm volatile("s_waitcnt vmcnt(" #n ")" ::: "memory")
; #define BAR __builtin_amdgcn_s_barrier()
;     ...
;     STAGE_B(SB(1, 1), bcol + HALF, t + 3);
;     WAIT_V(6); BAR; MMA(1, 1, At, B1); BAR;
;   }
;   float ssv[2][4] = {};
;   if constexpr (EPI == EPI_GU || EPI == EPI_EVIN || EPI == EPI_ODIN) {
; #pragma unroll
;     for (int ai = 0; ai < 2; ++ai)
; #pragma unroll
;       for (int m = 0; m < 4; ++m) ssv[ai][m] = G.ssr[brow + ai * HALF + wr * 64 + m * 16 + fr];
;   }
;   { LDB(B0, 0, 0); LDA(At, 0, 0); STAGE_A(SA(1, 1), brow + HALF, nt - 1);
	v_mfma_f32_16x16x32_bf16 v[76:79], v[218:221], v[202:205], v[76:79]
	v_mfma_f32_16x16x32_bf16 v[72:75], v[238:241], v[202:205], v[72:75]
	v_mfma_f32_16x16x32_bf16 v[68:71], v[218:221], v[210:213], v[68:71]
	v_mfma_f32_16x16x32_bf16 v[64:67], v[238:241], v[210:213], v[64:67]
	s_setprio 0
	v_readfirstlane_b32 s34, v153
	v_lshl_add_u64 v[234:235], v[234:235], 0, s[88:89]
	s_mov_b32 m0, s34
	v_readfirstlane_b32 s34, v154
	global_load_lds_dwordx4 v[234:235], off
	v_lshl_add_u64 v[234:235], v[236:237], 0, s[88:89]
	s_mov_b32 m0, s34
	s_nop 0
	global_load_lds_dwordx4 v[234:235], off
	v_readfirstlane_b32 s34, v155
	v_lshl_add_u64 v[222:223], v[222:223], 0, s[2:3]
	s_mov_b32 m0, s34
	v_readfirstlane_b32 s34, v156
	ds_read_b128 v[182:185], v149 offset:49152
	ds_read_b128 v[186:189], v149 offset:50176
	ds_read_b128 v[190:193], v149 offset:51200
	ds_read_b128 v[194:197], v149 offset:52224
	ds_read_b128 v[198:201], v149 offset:53248
	ds_read_b128 v[202:205], v149 offset:54272
	ds_read_b128 v[206:209], v149 offset:55296
	ds_read_b128 v[210:213], v149 offset:56320
	global_load_lds_dwordx4 v[222:223], off
	v_lshl_add_u64 v[222:223], v[226:227], 0, s[2:3]
	s_mov_b32 m0, s34
	s_nop 0
	global_load_lds_dwordx4 v[222:223], off
	v_readfirstlane_b32 s34, v157
	v_lshl_add_u64 v[250:251], v[246:247], 0, s[70:71]
	s_mov_b32 m0, s34
	v_readfirstlane_b32 s34, v158
	global_load_lds_dwordx4 v[250:251], off
	v_lshl_add_u64 v[250:251], v[248:249], 0, s[70:71]
	s_mov_b32 m0, s34
	s_nop 0
	global_load_lds_dwordx4 v[250:251], off
	s_waitcnt lgkmcnt(0)
	s_waitcnt vmcnt(8)
	s_barrier
	s_setprio 1
	v_mfma_f32_16x16x32_bf16 v[60:63], v[164:167], v[182:185], v[60:63]
	v_mfma_f32_16x16x32_bf16 v[56:59], v[172:175], v[182:185], v[56:59]
	v_mfma_f32_16x16x32_bf16 v[52:55], v[164:167], v[190:193], v[52:55]
	v_mfma_f32_16x16x32_bf16 v[48:51], v[172:175], v[190:193], v[48:51]
	v_mfma_f32_16x16x32_bf16 v[44:47], v[164:167], v[198:201], v[44:47]
	v_mfma_f32_16x16x32_bf16 v[40:43], v[172:175], v[198:201], v[40:43]
	v_mfma_f32_16x16x32_bf16 v[36:39], v[164:167], v[206:209], v[36:39]
	v_mfma_f32_16x16x32_bf16 v[32:35], v[172:175], v[206:209], v[32:35]
	v_mfma_f32_16x16x32_bf16 v[60:63], v[168:171], v[186:189], v[60:63]
	v_mfma_f32_16x16x32_bf16 v[56:59], v[176:179], v[186:189], v[56:59]
	v_mfma_f32_16x16x32_bf16 v[52:55], v[168:171], v[194:197], v[52:55]
	v_mfma_f32_16x16x32_bf16 v[48:51], v[176:179], v[194:197], v[48:51]
	v_mfma_f32_16x16x32_bf16 v[44:47], v[168:171], v[202:205], v[44:47]
	v_mfma_f32_16x16x32_bf16 v[40:43], v[176:179], v[202:205], v[40:43]
	v_mfma_f32_16x16x32_bf16 v[36:39], v[168:171], v[210:213], v[36:39]
	v_mfma_f32_16x16x32_bf16 v[32:35], v[176:179], v[210:213], v[32:35]
	v_mfma_f32_16x16x32_bf16 v[28:31], v[214:217], v[182:185], v[28:31]
	v_mfma_f32_16x16x32_bf16 v[24:27], v[230:233], v[182:185], v[24:27]
	v_mfma_f32_16x16x32_bf16 v[20:23], v[214:217], v[190:193], v[20:23]
	v_mfma_f32_16x16x32_bf16 v[16:19], v[230:233], v[190:193], v[16:19]
	v_mfma_f32_16x16x32_bf16 v[12:15], v[214:217], v[198:201], v[12:15]
	v_mfma_f32_16x16x32_bf16 v[8:11], v[230:233], v[198:201], v[8:11]
	v_mfma_f32_16x16x32_bf16 v[4:7], v[214:217], v[206:209], v[4:7]
	v_mfma_f32_16x16x32_bf16 v[0:3], v[230:233], v[206:209], v[0:3]
	v_mfma_f32_16x16x32_bf16 v[28:31], v[218:221], v[186:189], v[28:31]
	v_mfma_f32_16x16x32_bf16 v[24:27], v[238:241], v[186:189], v[24:27]
	v_mfma_f32_16x16x32_bf16 v[20:23], v[218:221], v[194:197], v[20:23]
	v_mfma_f32_16x16x32_bf16 v[16:19], v[238:241], v[194:197], v[16:19]
	s_setprio 2
	s_barrier
	v_mfma_f32_16x16x32_bf16 v[12:15], v[218:221], v[202:205], v[12:15]
	v_mfma_f32_16x16x32_bf16 v[8:11], v[238:241], v[202:205], v[8:11]
	v_mfma_f32_16x16x32_bf16 v[4:7], v[218:221], v[210:213], v[4:7]
	v_mfma_f32_16x16x32_bf16 v[0:3], v[238:241], v[210:213], v[0:3]
	s_setprio 0
	s_add_i32 s31, s31, 2
	s_add_u32 s18, s18, 0x100
	s_addc_u32 s19, s19, 0
	s_cmp_lt_u32 s31, 28
	s_cbranch_scc1 .LBB0_2566
.Lmy_kexit_4:
	s_waitcnt vmcnt(6)
	v_not_b32_e32 v250, 63
	v_mov_b32_e32 v251, 0x41b17218
	v_or_b32_e32 v130, s28, v152
	v_lshl_add_u32 v130, v151, 6, v130
	v_add_u32_e32 v134, 0x80, v130
	v_ashrrev_i32_e32 v135, 31, v134
	v_lshl_add_u64 v[140:141], v[134:135], 2, s[12:13]
	v_add_u32_e32 v134, 0x90, v130
	v_ashrrev_i32_e32 v131, 31, v130
	v_ashrrev_i32_e32 v135, 31, v134
	v_lshl_add_u64 v[132:133], v[130:131], 2, s[12:13]
	v_lshl_add_u64 v[152:153], v[134:135], 2, s[12:13]
	v_add_u32_e32 v134, 0xa0, v130
	v_add_u32_e32 v130, 0xb0, v130
	s_or_b32 s21, s28, 0x80
	v_ashrrev_i32_e32 v135, 31, v134
	v_ashrrev_i32_e32 v131, 31, v130
	s_mul_i32 s18, s21, 0x1080
	v_lshl_add_u64 v[154:155], v[134:135], 2, s[12:13]
	v_lshl_add_u64 v[156:157], v[130:131], 2, s[12:13]
	global_load_dword v139, v[132:133], off
	global_load_dword v138, v[132:133], off offset:64
	global_load_dword v137, v[132:133], off offset:128
	global_load_dword v134, v[132:133], off offset:192
	s_nop 0
	global_load_dword v133, v[140:141], off
	global_load_dword v132, v[152:153], off
	global_load_dword v131, v[154:155], off
	global_load_dword v130, v[156:157], off
	s_mul_hi_i32 s19, s21, 0x1080
	s_add_u32 s18, s23, s18
	s_addc_u32 s19, s24, s19
	v_lshl_add_u64 v[140:141], s[18:19], 0, v[180:181]
	v_readfirstlane_b32 s31, v162
	v_lshl_add_u64 v[140:141], v[140:141], 0, s[46:47]
	s_mov_b32 m0, s31
	ds_read_b128 v[152:155], v150
	ds_read_b128 v[164:167], v150 offset:1024
	ds_read_b128 v[168:171], v150 offset:2048
	ds_read_b128 v[172:175], v150 offset:3072
	ds_read_b128 v[176:179], v149
	ds_read_b128 v[182:185], v149 offset:1024
	ds_read_b128 v[186:189], v149 offset:2048
	ds_read_b128 v[190:193], v149 offset:3072
	ds_read_b128 v[194:197], v149 offset:4096
	ds_read_b128 v[198:201], v149 offset:5120
	ds_read_b128 v[202:205], v149 offset:6144
	ds_read_b128 v[206:209], v149 offset:7168
	global_load_lds_dwordx4 v[140:141], off
	v_lshl_add_u64 v[140:141], s[18:19], 0, v[128:129]
	v_readfirstlane_b32 s18, v163
	v_lshl_add_u64 v[140:141], v[140:141], 0, s[46:47]
	s_mov_b32 m0, s18
	s_nop 0
	global_load_lds_dwordx4 v[140:141], off
	s_barrier
; #define STAGE_A(P, br, kt) do { const char* _base = (const char*)(((kt) < G.ksplit ? G.A1 : A2m) + (long)(br) * G.lda + (long)(kt) * BK); \
;     __builtin_amdgcn_global_load_lds((const unsigned*)(_base + aoff0), (unsigned*)((char*)(P) + sb0), 16, 0, 0); \
;     __builtin_amdgcn_global_load_lds((const unsigned*)(_base + aoff1), (unsigned*)((char*)(P) + sb1), 16, 0, 0); } while (0)
; #define LDA(dst, b, h) for (int m = 0; m < 4; ++m) for (int k = 0; k < 2; ++k) \
;     dst[m][k] = *reinterpret_cast<const bf16x8*>(a_rd + ((b) * 2 + (h)) * (HT * 2) + m * 2048 + k * 1024)
; #define LDB(dst, b, h) for (int n = 0; n < 2; ++n) for (int k = 0; k < 2; ++k) \
;     dst[n][k] = *reinterpret_cast<const bf16x8*>(b_rd + ((b) * 2 + (h)) * (HT * 2) + n * 2048 + k * 1024)
; #define MMA(ai, bj, At_, Bt_) do { __builtin_amdgcn_s_setprio(1); \
;     for (int m = 0; m < 4; ++m) for (int n = 0; n < 2; ++n) for (int k = 0; k < 2; ++k) \
;       acc[ai][bj][m][n] = __builtin_amdgcn_mfma_f32_16x16x32_bf16(Bt_[n][k], At_[m][k], acc[ai][bj][m][n], 0, 0, 0); \
;     __builtin_amdgcn_s_setprio(0); } while (0)
; #define WAIT_V(n) asm volatile("s_waitcnt vmcnt(" #n ")" ::: "memory")
; #define WAIT_L(n) asm volatile("s_waitcnt lgkmcnt(" #n ")" ::: "memory")
; #define BAR __builtin_amdgcn_s_barrier()
;     ...
;   { LDB(B0, 0, 0); LDA(At, 0, 0); STAGE_A(SA(1, 1), brow + HALF, nt - 1);
;     BAR; WAIT_L(0); MMA(0, 0, At, B0); BAR;
;     LDB(B1, 0, 1); BAR; WAIT_L(0); MMA(0, 1, At, B1); BAR;
;     LDA(At, 0, 1); WAIT_V(4); BAR; WAIT_L(0); MMA(1, 0, At, B0); MMA(1, 1, At, B1); BAR; }
;   { LDB(B0, 1, 0); LDA(At, 1, 0); WAIT_V(2); BAR; WAIT_L(0); MMA(0, 0, At, B0); BAR;
;     LDB(B1, 1, 1); WAIT_V(0); BAR; WAIT_L(0); MMA(0, 1, At, B1); BAR;
;     LDA(At, 1, 1); BAR; WAIT_L(0); MMA(1, 0, At, B0); MMA(1, 1, At, B1); BAR; }
	s_waitcnt lgkmcnt(0)
	s_setprio 1
	s_waitcnt lgkmcnt(0)
	v_mfma_f32_16x16x32_bf16 v[124:127], v[152:155], v[176:179], v[124:127]
	v_mfma_f32_16x16x32_bf16 v[116:119], v[152:155], v[186:189], v[116:119]
	v_mfma_f32_16x16x32_bf16 v[108:111], v[152:155], v[194:197], v[108:111]
	v_mfma_f32_16x16x32_bf16 v[100:103], v[152:155], v[202:205], v[100:103]
	v_mfma_f32_16x16x32_bf16 v[124:127], v[164:167], v[182:185], v[124:127]
	v_mfma_f32_16x16x32_bf16 v[120:123], v[168:171], v[176:179], v[120:123]
	v_mfma_f32_16x16x32_bf16 v[116:119], v[164:167], v[190:193], v[116:119]
	v_mfma_f32_16x16x32_bf16 v[112:115], v[168:171], v[186:189], v[112:115]
	v_mfma_f32_16x16x32_bf16 v[108:111], v[164:167], v[198:201], v[108:111]
	v_mfma_f32_16x16x32_bf16 v[104:107], v[168:171], v[194:197], v[104:107]
	v_mfma_f32_16x16x32_bf16 v[100:103], v[164:167], v[206:209], v[100:103]
	v_mfma_f32_16x16x32_bf16 v[96:99], v[168:171], v[202:205], v[96:99]
	s_setprio 2
	s_barrier
	v_mfma_f32_16x16x32_bf16 v[210:213], v[172:175], v[182:185], v[120:123]
	v_mfma_f32_16x16x32_bf16 v[214:217], v[172:175], v[190:193], v[112:115]
	v_mfma_f32_16x16x32_bf16 v[218:221], v[172:175], v[198:201], v[104:107]
	v_mfma_f32_16x16x32_bf16 v[230:233], v[172:175], v[206:209], v[96:99]
	s_setprio 0
	s_nop 1
	ds_read_b128 v[96:99], v150 offset:16384
	ds_read_b128 v[104:107], v150 offset:17408
	ds_read_b128 v[112:115], v150 offset:18432
	ds_read_b128 v[120:123], v150 offset:19456
	s_barrier
	s_waitcnt lgkmcnt(0)
	s_setprio 1
	s_waitcnt lgkmcnt(0)
	v_mfma_f32_16x16x32_bf16 v[92:95], v[96:99], v[176:179], v[92:95]
	v_mfma_f32_16x16x32_bf16 v[84:87], v[96:99], v[186:189], v[84:87]
	v_mfma_f32_16x16x32_bf16 v[76:79], v[96:99], v[194:197], v[76:79]
	v_mfma_f32_16x16x32_bf16 v[68:71], v[96:99], v[202:205], v[68:71]
	v_mfma_f32_16x16x32_bf16 v[92:95], v[104:107], v[182:185], v[92:95]
	v_mfma_f32_16x16x32_bf16 v[88:91], v[112:115], v[176:179], v[88:91]
	v_mfma_f32_16x16x32_bf16 v[84:87], v[104:107], v[190:193], v[84:87]
	v_mfma_f32_16x16x32_bf16 v[80:83], v[112:115], v[186:189], v[80:83]
	v_mfma_f32_16x16x32_bf16 v[76:79], v[104:107], v[198:201], v[76:79]
	v_mfma_f32_16x16x32_bf16 v[72:75], v[112:115], v[194:197], v[72:75]
	v_mfma_f32_16x16x32_bf16 v[68:71], v[104:107], v[206:209], v[68:71]
	v_mfma_f32_16x16x32_bf16 v[64:67], v[112:115], v[202:205], v[64:67]
	s_setprio 2
	s_barrier
	v_mfma_f32_16x16x32_bf16 v[176:179], v[120:123], v[182:185], v[88:91]
	v_mfma_f32_16x16x32_bf16 v[182:185], v[120:123], v[190:193], v[80:83]
	v_mfma_f32_16x16x32_bf16 v[186:189], v[120:123], v[198:201], v[72:75]
	v_mfma_f32_16x16x32_bf16 v[190:193], v[120:123], v[206:209], v[64:67]
	s_setprio 0
	s_nop 1
	ds_read_b128 v[64:67], v149 offset:16384
	ds_read_b128 v[72:75], v149 offset:17408
	ds_read_b128 v[80:83], v149 offset:18432
	ds_read_b128 v[88:91], v149 offset:19456
	ds_read_b128 v[194:197], v149 offset:20480
	ds_read_b128 v[198:201], v149 offset:21504
	ds_read_b128 v[202:205], v149 offset:22528
	ds_read_b128 v[206:209], v149 offset:23552
	s_waitcnt vmcnt(4)
	s_barrier
	s_waitcnt lgkmcnt(0)
	s_setprio 1
	s_waitcnt lgkmcnt(0)
	v_mfma_f32_16x16x32_bf16 v[60:63], v[152:155], v[64:67], v[60:63]
	v_mfma_f32_16x16x32_bf16 v[52:55], v[152:155], v[80:83], v[52:55]
	v_mfma_f32_16x16x32_bf16 v[44:47], v[152:155], v[194:197], v[44:47]
	v_mfma_f32_16x16x32_bf16 v[36:39], v[152:155], v[202:205], v[36:39]
	v_mfma_f32_16x16x32_bf16 v[60:63], v[164:167], v[72:75], v[60:63]
	v_mfma_f32_16x16x32_bf16 v[56:59], v[168:171], v[64:67], v[56:59]
	v_mfma_f32_16x16x32_bf16 v[52:55], v[164:167], v[88:91], v[52:55]
	v_mfma_f32_16x16x32_bf16 v[48:51], v[168:171], v[80:83], v[48:51]
	v_mfma_f32_16x16x32_bf16 v[44:47], v[164:167], v[198:201], v[44:47]
	v_mfma_f32_16x16x32_bf16 v[40:43], v[168:171], v[194:197], v[40:43]
	v_mfma_f32_16x16x32_bf16 v[36:39], v[164:167], v[206:209], v[36:39]
	v_mfma_f32_16x16x32_bf16 v[32:35], v[168:171], v[202:205], v[32:35]
	v_mfma_f32_16x16x32_bf16 v[238:241], v[172:175], v[72:75], v[56:59]
	v_mfma_f32_16x16x32_bf16 v[246:249], v[172:175], v[88:91], v[48:51]
	v_mfma_f32_16x16x32_bf16 v[234:237], v[172:175], v[198:201], v[40:43]
	v_mfma_f32_16x16x32_bf16 v[152:155], v[172:175], v[206:209], v[32:35]
	s_setprio 0
	s_setprio 1
	v_mfma_f32_16x16x32_bf16 v[28:31], v[96:99], v[64:67], v[28:31]
	v_mfma_f32_16x16x32_bf16 v[20:23], v[96:99], v[80:83], v[20:23]
	v_mfma_f32_16x16x32_bf16 v[12:15], v[96:99], v[194:197], v[12:15]
	v_mfma_f32_16x16x32_bf16 v[4:7], v[96:99], v[202:205], v[4:7]
	v_mfma_f32_16x16x32_bf16 v[28:31], v[104:107], v[72:75], v[28:31]
	v_mfma_f32_16x16x32_bf16 v[24:27], v[112:115], v[64:67], v[24:27]
	v_mfma_f32_16x16x32_bf16 v[20:23], v[104:107], v[88:91], v[20:23]
	v_mfma_f32_16x16x32_bf16 v[16:19], v[112:115], v[80:83], v[16:19]
	v_mfma_f32_16x16x32_bf16 v[12:15], v[104:107], v[198:201], v[12:15]
	v_mfma_f32_16x16x32_bf16 v[8:11], v[112:115], v[194:197], v[8:11]
	v_mfma_f32_16x16x32_bf16 v[4:7], v[104:107], v[206:209], v[4:7]
	v_mfma_f32_16x16x32_bf16 v[0:3], v[112:115], v[202:205], v[0:3]
	s_setprio 2
	s_barrier
	v_mfma_f32_16x16x32_bf16 v[162:165], v[120:123], v[72:75], v[24:27]
	v_mfma_f32_16x16x32_bf16 v[166:169], v[120:123], v[88:91], v[16:19]
	v_mfma_f32_16x16x32_bf16 v[170:173], v[120:123], v[198:201], v[8:11]
	v_mfma_f32_16x16x32_bf16 v[194:197], v[120:123], v[206:209], v[0:3]
	s_setprio 0
	s_nop 1
	ds_read_b128 v[0:3], v150 offset:32768
	ds_read_b128 v[8:11], v150 offset:33792
	ds_read_b128 v[16:19], v150 offset:34816
	ds_read_b128 v[24:27], v150 offset:35840
	ds_read_b128 v[32:35], v149 offset:32768
	ds_read_b128 v[40:43], v149 offset:33792
	ds_read_b128 v[48:51], v149 offset:34816
	ds_read_b128 v[56:59], v149 offset:35840
	ds_read_b128 v[64:67], v149 offset:36864
	ds_read_b128 v[198:201], v149 offset:37888
	ds_read_b128 v[202:205], v149 offset:38912
	ds_read_b128 v[206:209], v149 offset:39936
	s_waitcnt vmcnt(2)
	s_barrier
; #define STAGE_A(P, br, kt) do { const char* _base = (const char*)(((kt) < G.ksplit ? G.A1 : A2m) + (long)(br) * G.lda + (long)(kt) * BK); \
;     __builtin_amdgcn_global_load_lds((const unsigned*)(_base + aoff0), (unsigned*)((char*)(P) + sb0), 16, 0, 0); \
;     __builtin_amdgcn_global_load_lds((const unsigned*)(_base + aoff1), (unsigned*)((char*)(P) + sb1), 16, 0, 0); } while (0)
; #define STAGE_B(P, br, kt) do { const char* _base = (const char*)(G.Bt + (long)(br) * G.ldb + (long)(kt) * BK); \
;     __builtin_amdgcn_global_load_lds((const unsigned*)(_base + boff0), (unsigned*)((char*)(P) + sb0), 16, 0, 0); \
;     __builtin_amdgcn_global_load_lds((const unsigned*)(_base + boff1), (unsigned*)((char*)(P) + sb1), 16, 0, 0); } while (0)
; #define LDA(dst, b, h) for (int m = 0; m < 4; ++m) for (int k = 0; k < 2; ++k) \
;     dst[m][k] = *reinterpret_cast<const bf16x8*>(a_rd + ((b) * 2 + (h)) * (HT * 2) + m * 2048 + k * 1024)
; #define LDB(dst, b, h) for (int n = 0; n < 2; ++n) for (int k = 0; k < 2; ++k) \
;     dst[n][k] = *reinterpret_cast<const bf16x8*>(b_rd + ((b) * 2 + (h)) * (HT * 2) + n * 2048 + k * 1024)
; #define MMA(ai, bj, At_, Bt_) do { __builtin_amdgcn_s_setprio(1); \
;     for (int m = 0; m < 4; ++m) for (int n = 0; n < 2; ++n) for (int k = 0; k < 2; ++k) \
;       acc[ai][bj][m][n] = __builtin_amdgcn_mfma_f32_16x16x32_bf16(Bt_[n][k], At_[m][k], acc[ai][bj][m][n], 0, 0, 0); \
;     __builtin_amdgcn_s_setprio(0); } while (0)
; #define WAIT_V(n) asm volatile("s_waitcnt vmcnt(" #n ")" ::: "memory")
; #define WAIT_L(n) asm volatile("s_waitcnt lgkmcnt(" #n ")" ::: "memory")
; #define BAR __builtin_amdgcn_s_barrier()
;     ...
;   { LDB(B0, 1, 0); LDA(At, 1, 0); WAIT_V(2); BAR; WAIT_L(0); MMA(0, 0, At, B0); BAR;
;     LDB(B1, 1, 1); WAIT_V(0); BAR; WAIT_L(0); MMA(0, 1, At, B1); BAR;
;     LDA(At, 1, 1); BAR; WAIT_L(0); MMA(1, 0, At, B0); MMA(1, 1, At, B1); BAR; }
;   if (wr == 0) BAR;
;   if (EPI != EPI_RESID && has_next) {
;     STAGE_B(SB(0, 0), nbcol, 0); STAGE_A(SA(0, 0), nbrow, 0);
;     STAGE_B(SB(0, 1), nbcol + HALF, 0); STAGE_A(SA(0, 1), nbrow + HALF, 0);
;   }
	s_waitcnt lgkmcnt(0)
	s_setprio 1
	s_waitcnt lgkmcnt(0)
	v_mfma_f32_16x16x32_bf16 v[72:75], v[0:3], v[32:35], v[124:127]
	v_mfma_f32_16x16x32_bf16 v[120:123], v[8:11], v[40:43], v[72:75]
	v_mfma_f32_16x16x32_bf16 v[72:75], v[16:19], v[32:35], v[210:213]
	v_mfma_f32_16x16x32_bf16 v[124:127], v[24:27], v[40:43], v[72:75]
	v_mfma_f32_16x16x32_bf16 v[72:75], v[0:3], v[48:51], v[116:119]
	v_mfma_f32_16x16x32_bf16 v[112:115], v[8:11], v[56:59], v[72:75]
	v_mfma_f32_16x16x32_bf16 v[72:75], v[16:19], v[48:51], v[214:217]
	v_mfma_f32_16x16x32_bf16 v[116:119], v[24:27], v[56:59], v[72:75]
	v_mfma_f32_16x16x32_bf16 v[72:75], v[0:3], v[64:67], v[108:111]
	v_mfma_f32_16x16x32_bf16 v[104:107], v[8:11], v[198:201], v[72:75]
	v_mfma_f32_16x16x32_bf16 v[72:75], v[16:19], v[64:67], v[218:221]
	v_mfma_f32_16x16x32_bf16 v[108:111], v[24:27], v[198:201], v[72:75]
	s_setprio 2
	s_barrier
	v_mfma_f32_16x16x32_bf16 v[72:75], v[0:3], v[202:205], v[100:103]
	v_mfma_f32_16x16x32_bf16 v[96:99], v[8:11], v[206:209], v[72:75]
	v_mfma_f32_16x16x32_bf16 v[72:75], v[16:19], v[202:205], v[230:233]
	v_mfma_f32_16x16x32_bf16 v[100:103], v[24:27], v[206:209], v[72:75]
	s_setprio 0
	ds_read_b128 v[210:213], v150 offset:49152
	ds_read_b128 v[214:217], v150 offset:50176
	ds_read_b128 v[218:221], v150 offset:51200
	ds_read_b128 v[230:233], v150 offset:52224
	s_waitcnt vmcnt(0)
	s_barrier
	s_waitcnt lgkmcnt(0)
	s_setprio 1
	s_waitcnt lgkmcnt(0)
	v_mfma_f32_16x16x32_bf16 v[72:75], v[210:213], v[32:35], v[92:95]
	v_mfma_f32_16x16x32_bf16 v[32:35], v[218:221], v[32:35], v[176:179]
	v_mfma_f32_16x16x32_bf16 v[92:95], v[230:233], v[40:43], v[32:35]
	v_mfma_f32_16x16x32_bf16 v[32:35], v[210:213], v[48:51], v[84:87]
	v_mfma_f32_16x16x32_bf16 v[80:83], v[214:217], v[56:59], v[32:35]
	v_mfma_f32_16x16x32_bf16 v[32:35], v[218:221], v[48:51], v[182:185]
	v_mfma_f32_16x16x32_bf16 v[84:87], v[230:233], v[56:59], v[32:35]
	v_mfma_f32_16x16x32_bf16 v[32:35], v[210:213], v[64:67], v[76:79]
	v_mfma_f32_16x16x32_bf16 v[88:91], v[214:217], v[40:43], v[72:75]
	v_mfma_f32_16x16x32_bf16 v[72:75], v[214:217], v[198:201], v[32:35]
	v_mfma_f32_16x16x32_bf16 v[32:35], v[218:221], v[64:67], v[186:189]
	v_mfma_f32_16x16x32_bf16 v[76:79], v[230:233], v[198:201], v[32:35]
	s_setprio 2
	s_barrier
	v_mfma_f32_16x16x32_bf16 v[32:35], v[210:213], v[202:205], v[68:71]
	v_mfma_f32_16x16x32_bf16 v[64:67], v[214:217], v[206:209], v[32:35]
	v_mfma_f32_16x16x32_bf16 v[32:35], v[218:221], v[202:205], v[190:193]
	v_mfma_f32_16x16x32_bf16 v[68:71], v[230:233], v[206:209], v[32:35]
	s_setprio 0
	ds_read_b128 v[174:177], v149 offset:49152
	ds_read_b128 v[182:185], v149 offset:50176
	ds_read_b128 v[186:189], v149 offset:51200
	ds_read_b128 v[190:193], v149 offset:52224
	ds_read_b128 v[198:201], v149 offset:53248
	ds_read_b128 v[202:205], v149 offset:54272
	ds_read_b128 v[206:209], v149 offset:55296
	ds_read_b128 v[148:151], v149 offset:56320
	s_barrier
	s_waitcnt lgkmcnt(0)
	s_setprio 1
	s_waitcnt lgkmcnt(0)
	v_mfma_f32_16x16x32_bf16 v[32:35], v[0:3], v[174:177], v[60:63]
	v_mfma_f32_16x16x32_bf16 v[56:59], v[8:11], v[182:185], v[32:35]
	v_mfma_f32_16x16x32_bf16 v[32:35], v[16:19], v[174:177], v[238:241]
	v_mfma_f32_16x16x32_bf16 v[60:63], v[24:27], v[182:185], v[32:35]
	v_mfma_f32_16x16x32_bf16 v[32:35], v[0:3], v[186:189], v[52:55]
	v_mfma_f32_16x16x32_bf16 v[48:51], v[8:11], v[190:193], v[32:35]
	v_mfma_f32_16x16x32_bf16 v[32:35], v[16:19], v[186:189], v[246:249]
	v_mfma_f32_16x16x32_bf16 v[52:55], v[24:27], v[190:193], v[32:35]
	v_mfma_f32_16x16x32_bf16 v[32:35], v[0:3], v[198:201], v[44:47]
	v_mfma_f32_16x16x32_bf16 v[40:43], v[8:11], v[202:205], v[32:35]
	v_mfma_f32_16x16x32_bf16 v[32:35], v[16:19], v[198:201], v[234:237]
	v_mfma_f32_16x16x32_bf16 v[0:3], v[0:3], v[206:209], v[36:39]
	v_mfma_f32_16x16x32_bf16 v[44:47], v[24:27], v[202:205], v[32:35]
	v_mfma_f32_16x16x32_bf16 v[32:35], v[8:11], v[148:151], v[0:3]
	v_mfma_f32_16x16x32_bf16 v[0:3], v[16:19], v[206:209], v[152:155]
	v_mfma_f32_16x16x32_bf16 v[36:39], v[24:27], v[148:151], v[0:3]
	s_setprio 0
	s_setprio 1
	v_mfma_f32_16x16x32_bf16 v[0:3], v[210:213], v[174:177], v[28:31]
	v_mfma_f32_16x16x32_bf16 v[24:27], v[214:217], v[182:185], v[0:3]
	v_mfma_f32_16x16x32_bf16 v[0:3], v[218:221], v[174:177], v[162:165]
	v_mfma_f32_16x16x32_bf16 v[28:31], v[230:233], v[182:185], v[0:3]
	v_mfma_f32_16x16x32_bf16 v[0:3], v[210:213], v[186:189], v[20:23]
	v_mfma_f32_16x16x32_bf16 v[16:19], v[214:217], v[190:193], v[0:3]
	v_mfma_f32_16x16x32_bf16 v[0:3], v[218:221], v[186:189], v[166:169]
	v_mfma_f32_16x16x32_bf16 v[20:23], v[230:233], v[190:193], v[0:3]
	v_mfma_f32_16x16x32_bf16 v[0:3], v[210:213], v[198:201], v[12:15]
	v_mfma_f32_16x16x32_bf16 v[8:11], v[214:217], v[202:205], v[0:3]
	v_mfma_f32_16x16x32_bf16 v[0:3], v[218:221], v[198:201], v[170:173]
	v_mfma_f32_16x16x32_bf16 v[12:15], v[230:233], v[202:205], v[0:3]
	s_setprio 2
	s_barrier
	v_mfma_f32_16x16x32_bf16 v[0:3], v[210:213], v[206:209], v[4:7]
	v_mfma_f32_16x16x32_bf16 v[4:7], v[218:221], v[206:209], v[194:197]
	v_mfma_f32_16x16x32_bf16 v[0:3], v[214:217], v[148:151], v[0:3]
	v_mfma_f32_16x16x32_bf16 v[4:7], v[230:233], v[148:151], v[4:7]
	s_setprio 0
	s_andn2_b64 vcc, exec, s[16:17]
	v_mov_b32_e32 v249, v245
	s_cbranch_vccnz .LBB0_2558
	s_mul_i32 s16, s27, 0x840
	s_ashr_i32 s17, s16, 31
	s_lshl_b64 s[16:17], s[16:17], 1
	s_add_u32 s16, s8, s16
	s_addc_u32 s17, s9, s17
	v_readfirstlane_b32 s18, v159
	v_lshl_add_u64 v[140:141], s[16:17], 0, v[180:181]
	s_mov_b32 m0, s18
	s_mul_i32 s18, s26, 0x1080
	global_load_lds_dwordx4 v[140:141], off
	v_lshl_add_u64 v[140:141], s[16:17], 0, v[128:129]
	v_readfirstlane_b32 s16, v160
	s_mov_b32 m0, s16
	s_mul_hi_i32 s17, s26, 0x1080
	s_add_u32 s16, s23, s18
	s_addc_u32 s17, s24, s17
	v_readfirstlane_b32 s19, v147
	global_load_lds_dwordx4 v[140:141], off
	v_lshl_add_u64 v[140:141], s[16:17], 0, v[180:181]
	s_mov_b32 m0, s19
	v_readfirstlane_b32 s19, v145
	global_load_lds_dwordx4 v[140:141], off
	v_lshl_add_u64 v[140:141], s[16:17], 0, v[128:129]
	v_readfirstlane_b32 s16, v146
	s_mov_b32 m0, s16
	s_or_b32 s16, s27, 0x80
	s_mul_hi_i32 s17, s16, 0x1080
	s_mulk_i32 s16, 0x1080
	s_add_u32 s16, s8, s16
	s_addc_u32 s17, s9, s17
	global_load_lds_dwordx4 v[140:141], off
	v_lshl_add_u64 v[140:141], s[16:17], 0, v[180:181]
	s_mov_b32 m0, s19
	s_add_i32 s18, s18, 0x84000
	global_load_lds_dwordx4 v[140:141], off
	v_lshl_add_u64 v[140:141], s[16:17], 0, v[128:129]
	v_readfirstlane_b32 s16, v161
	s_mov_b32 m0, s16
	s_add_i32 s16, s26, 0x80
	s_mul_hi_i32 s17, s16, 0x1080
	s_add_u32 s16, s23, s18
	s_addc_u32 s17, s24, s17
	v_readfirstlane_b32 s18, v143
	global_load_lds_dwordx4 v[140:141], off
	v_lshl_add_u64 v[140:141], s[16:17], 0, v[180:181]
	s_mov_b32 m0, s18
	v_lshl_add_u64 v[128:129], s[16:17], 0, v[128:129]
	v_readfirstlane_b32 s16, v142
	global_load_lds_dwordx4 v[140:141], off
	s_mov_b32 m0, s16
	s_nop 0
	global_load_lds_dwordx4 v[128:129], off
	s_branch .LBB0_2558

; #define STAGE_A(P, br, kt) do { const char* _base = (const char*)(((kt) < G.ksplit ? G.A1 : A2m) + (long)(br) * G.lda + (long)(kt) * BK); \
;     __builtin_amdgcn_global_load_lds((const unsigned*)(_base + aoff0), (unsigned*)((char*)(P) + sb0), 16, 0, 0); \
;     __builtin_amdgcn_global_load_lds((const unsigned*)(_base + aoff1), (unsigned*)((char*)(P) + sb1), 16, 0, 0); } while (0)
; #define STAGE_B(P, br, kt) do { const char* _base = (const char*)(G.Bt + (long)(br) * G.ldb + (long)(kt) * BK); \
;     __builtin_amdgcn_global_load_lds((const unsigned*)(_base + boff0), (unsigned*)((char*)(P) + sb0), 16, 0, 0); \
;     __builtin_amdgcn_global_load_lds((const unsigned*)(_base + boff1), (unsigned*)((char*)(P) + sb1), 16, 0, 0); } while (0)
; #define LDA(dst, b, h) for (int m = 0; m < 4; ++m) for (int k = 0; k < 2; ++k) \
;     dst[m][k] = *reinterpret_cast<const bf16x8*>(a_rd + ((b) * 2 + (h)) * (HT * 2) + m * 2048 + k * 1024)
; #define LDB(dst, b, h) for (int n = 0; n < 2; ++n) for (int k = 0; k < 2; ++k) \
;     dst[n][k] = *reinterpret_cast<const bf16x8*>(b_rd + ((b) * 2 + (h)) * (HT * 2) + n * 2048 + k * 1024)
; #define MMA(ai, bj, At_, Bt_) do { __builtin_amdgcn_s_setprio(1); \
;     for (int m = 0; m < 4; ++m) for (int n = 0; n < 2; ++n) for (int k = 0; k < 2; ++k) \
;       acc[ai][bj][m][n] = __builtin_amdgcn_mfma_f32_16x16x32_bf16(Bt_[n][k], At_[m][k], acc[ai][bj][m][n], 0, 0, 0); \
;     __builtin_amdgcn_s_setprio(0); } while (0)
; #define WAIT_V(n) asm volatile("s_waitcnt vmcnt(" #n ")" ::: "memory")
; #define WAIT_L(n) asm volatile("s_waitcnt lgkmcnt(" #n ")" ::: "memory")
; #define BAR __builtin_amdgcn_s_barrier()
; #define SCHED __builtin_amdgcn_sched_barrier(0)
;     ...
;   if (EPI == EPI_RESID || first) {
;     STAGE_B(SB(0, 0), bcol, 0); STAGE_A(SA(0, 0), brow, 0);
;     STAGE_B(SB(0, 1), bcol + HALF, 0); STAGE_A(SA(0, 1), brow + HALF, 0);
;   }
;   if (wr == 1) BAR;
;   WAIT_V(0); BAR;
;   STAGE_B(SB(1, 0), bcol, 1); STAGE_A(SA(1, 0), brow, 1); STAGE_B(SB(1, 1), bcol + HALF, 1);
;   WAIT_V(6); BAR;
;   for (int t = 0; t < nt - 2; t += 2) {
;     LDB(B0, 0, 0); SCHED; LDA(At, 0, 0); STAGE_A(SA(1, 1), brow + HALF, t + 1);
;     WAIT_L(8); BAR; WAIT_L(0); MMA(0, 0, At, B0); BAR; SCHED;
;     LDB(B1, 0, 1); STAGE_B(SB(0, 0), bcol, t + 2);
;     BAR; WAIT_L(0); MMA(0, 1, At, B1); BAR;
.LBB0_2621:
	s_or_b64 exec, exec, s[12:13]
	v_readlane_b32 s12, v253, 46
	v_and_b32_e32 v18, 15, v142
	s_waitcnt vmcnt(0)
	v_lshlrev_b32_e32 v20, 2, v142
	v_add_u32_e32 v151, s12, v9
	v_and_b32_e32 v19, 48, v142
	v_lshlrev_b32_e32 v18, 6, v18
	v_and_b32_e32 v20, 32, v20
	s_mov_b64 s[22:23], 0x80
	v_readfirstlane_b32 s12, v151
	v_add_u32_e32 v152, 0x2000, v151
	v_bitop3_b32 v18, v18, v20, v19 bitop3:0x36
	v_lshlrev_b32_e32 v19, 6, v142
	v_lshl_add_u64 v[0:1], v[0:1], 0, s[22:23]
	s_mov_b32 m0, s12
	v_readfirstlane_b32 s12, v152
	v_add_u32_e32 v153, 0x8000, v145
	v_and_b32_e32 v19, 0x3000, v19
	s_waitcnt vmcnt(0)
	s_barrier
	global_load_lds_dwordx4 v[0:1], off
	v_lshl_add_u64 v[0:1], v[2:3], 0, s[22:23]
	s_mov_b32 m0, s12
	v_readfirstlane_b32 s12, v153
	v_add_u32_e32 v154, 0xa000, v145
	v_add_u32_e32 v19, s16, v19
	global_load_lds_dwordx4 v[0:1], off
	v_lshl_add_u64 v[0:1], v[4:5], 0, s[22:23]
	s_mov_b32 m0, s12
	v_readfirstlane_b32 s12, v154
	v_readlane_b32 s16, v253, 47
	global_load_lds_dwordx4 v[0:1], off
	s_mov_b32 m0, s12
	s_add_u32 s12, s17, 0x160080
	v_add_u32_e32 v155, s16, v9
	v_lshl_add_u64 v[0:1], v[6:7], 0, s[22:23]
	s_addc_u32 s13, s38, 0
	v_readfirstlane_b32 s16, v155
	global_load_lds_dwordx4 v[0:1], off
	v_lshl_add_u64 v[0:1], s[12:13], 0, v[180:181]
	s_mov_b32 m0, s16
	v_add_u32_e32 v156, 0x2000, v155
	global_load_lds_dwordx4 v[0:1], off
	v_lshl_add_u64 v[0:1], s[12:13], 0, v[128:129]
	v_readfirstlane_b32 s12, v156
	s_mov_b32 m0, s12
	s_mov_b32 s16, 0x16000
	global_load_lds_dwordx4 v[0:1], off
	v_lshrrev_b32_e32 v1, 1, v8
	v_mul_lo_u32 v0, v11, s18
	v_lshrrev_b32_e32 v3, 1, v13
	v_mul_lo_u32 v2, v15, s18
	v_mad_u64_u32 v[0:1], s[12:13], v1, s16, v[0:1]
	v_mad_u64_u32 v[2:3], s[12:13], v3, s16, v[2:3]
	v_or_b32_e32 v0, v0, v10
	v_or_b32_e32 v2, v2, v14
	v_add_lshl_u32 v0, v0, v12, 1
	v_mov_b32_e32 v1, v181
	v_add_lshl_u32 v2, v2, v16, 1
	v_mov_b32_e32 v3, v181
	v_lshl_add_u64 v[130:131], s[8:9], 0, v[0:1]
	v_lshl_add_u64 v[132:133], s[8:9], 0, v[2:3]
	s_add_u32 s8, s48, s15
	s_waitcnt vmcnt(6)
	s_addc_u32 s9, s49, s14
	v_lshl_add_u32 v17, v17, 13, 32
	v_lshl_add_u64 v[134:135], s[8:9], 0, v[0:1]
	v_lshl_add_u64 v[138:139], s[10:11], 0, v[0:1]
	v_lshl_add_u64 v[136:137], s[8:9], 0, v[2:3]
	v_lshl_add_u64 v[140:141], s[10:11], 0, v[2:3]
	s_mov_b32 s8, -2
	v_add_u32_e32 v147, v19, v18
	v_add_u32_e32 v144, v17, v18
	s_barrier
	ds_read_b128 v[160:163], v147
	ds_read_b128 v[164:167], v147 offset:1024
	ds_read_b128 v[168:171], v147 offset:2048
	ds_read_b128 v[172:175], v147 offset:3072
	v_add_u32_e32 v157, 0xc000, v145
	v_lshl_add_u64 v[222:223], s[86:87], 0, v[134:135]
	v_readfirstlane_b32 s9, v157
	v_lshl_add_u64 v[158:159], v[222:223], 0, s[72:73]
	s_mov_b32 m0, s9
	ds_read_b128 v[176:179], v144
	ds_read_b128 v[182:185], v144 offset:1024
	ds_read_b128 v[186:189], v144 offset:2048
	ds_read_b128 v[190:193], v144 offset:3072
	ds_read_b128 v[194:197], v144 offset:4096
	ds_read_b128 v[198:201], v144 offset:5120
	ds_read_b128 v[202:205], v144 offset:6144
	ds_read_b128 v[206:209], v144 offset:7168
	global_load_lds_dwordx4 v[158:159], off
	v_add_u32_e32 v158, 0xe000, v145
	v_lshl_add_u64 v[226:227], s[86:87], 0, v[136:137]
	v_readfirstlane_b32 s9, v158
	v_lshl_add_u64 v[210:211], v[226:227], 0, s[72:73]
	s_mov_b32 m0, s9
	s_nop 0
	global_load_lds_dwordx4 v[210:211], off
	ds_read_b128 v[210:213], v147 offset:16384
	ds_read_b128 v[214:217], v147 offset:17408
	ds_read_b128 v[218:221], v147 offset:18432
	ds_read_b128 v[230:233], v147 offset:19456
	s_waitcnt lgkmcnt(0)
	s_waitcnt vmcnt(8)
	s_barrier
	s_setprio 1
	v_mfma_f32_16x16x32_bf16 v[124:127], v[160:163], v[176:179], 0
	v_mfma_f32_16x16x32_bf16 v[120:123], v[168:171], v[176:179], 0
	v_mfma_f32_16x16x32_bf16 v[116:119], v[160:163], v[186:189], 0
	v_mfma_f32_16x16x32_bf16 v[112:115], v[168:171], v[186:189], 0
	v_mfma_f32_16x16x32_bf16 v[108:111], v[160:163], v[194:197], 0
	v_mfma_f32_16x16x32_bf16 v[104:107], v[168:171], v[194:197], 0
	v_mfma_f32_16x16x32_bf16 v[100:103], v[160:163], v[202:205], 0
	v_mfma_f32_16x16x32_bf16 v[96:99], v[168:171], v[202:205], 0
	v_mfma_f32_16x16x32_bf16 v[124:127], v[164:167], v[182:185], v[124:127]
	v_mfma_f32_16x16x32_bf16 v[120:123], v[172:175], v[182:185], v[120:123]
	v_mfma_f32_16x16x32_bf16 v[116:119], v[164:167], v[190:193], v[116:119]
	v_mfma_f32_16x16x32_bf16 v[112:115], v[172:175], v[190:193], v[112:115]
	v_mfma_f32_16x16x32_bf16 v[108:111], v[164:167], v[198:201], v[108:111]
	v_mfma_f32_16x16x32_bf16 v[104:107], v[172:175], v[198:201], v[104:107]
	v_mfma_f32_16x16x32_bf16 v[100:103], v[164:167], v[206:209], v[100:103]
	v_mfma_f32_16x16x32_bf16 v[96:99], v[172:175], v[206:209], v[96:99]
	v_mfma_f32_16x16x32_bf16 v[92:95], v[210:213], v[176:179], 0
	v_mfma_f32_16x16x32_bf16 v[88:91], v[218:221], v[176:179], 0
	v_mfma_f32_16x16x32_bf16 v[84:87], v[210:213], v[186:189], 0
	v_mfma_f32_16x16x32_bf16 v[80:83], v[218:221], v[186:189], 0
	v_mfma_f32_16x16x32_bf16 v[76:79], v[210:213], v[194:197], 0
	v_mfma_f32_16x16x32_bf16 v[72:75], v[218:221], v[194:197], 0
	v_mfma_f32_16x16x32_bf16 v[68:71], v[210:213], v[202:205], 0
	v_mfma_f32_16x16x32_bf16 v[64:67], v[218:221], v[202:205], 0
	v_mfma_f32_16x16x32_bf16 v[92:95], v[214:217], v[182:185], v[92:95]
	v_mfma_f32_16x16x32_bf16 v[88:91], v[230:233], v[182:185], v[88:91]
	v_mfma_f32_16x16x32_bf16 v[84:87], v[214:217], v[190:193], v[84:87]
	v_mfma_f32_16x16x32_bf16 v[80:83], v[230:233], v[190:193], v[80:83]
	s_setprio 2
	s_barrier
; #define STAGE_A(P, br, kt) do { const char* _base = (const char*)(((kt) < G.ksplit ? G.A1 : A2m) + (long)(br) * G.lda + (long)(kt) * BK); \
;     __builtin_amdgcn_global_load_lds((const unsigned*)(_base + aoff0), (unsigned*)((char*)(P) + sb0), 16, 0, 0); \
;     __builtin_amdgcn_global_load_lds((const unsigned*)(_base + aoff1), (unsigned*)((char*)(P) + sb1), 16, 0, 0); } while (0)
; #define STAGE_B(P, br, kt) do { const char* _base = (const char*)(G.Bt + (long)(br) * G.ldb + (long)(kt) * BK); \
;     __builtin_amdgcn_global_load_lds((const unsigned*)(_base + boff0), (unsigned*)((char*)(P) + sb0), 16, 0, 0); \
;     __builtin_amdgcn_global_load_lds((const unsigned*)(_base + boff1), (unsigned*)((char*)(P) + sb1), 16, 0, 0); } while (0)
; #define LDA(dst, b, h) for (int m = 0; m < 4; ++m) for (int k = 0; k < 2; ++k) \
;     dst[m][k] = *reinterpret_cast<const bf16x8*>(a_rd + ((b) * 2 + (h)) * (HT * 2) + m * 2048 + k * 1024)
; #define LDB(dst, b, h) for (int n = 0; n < 2; ++n) for (int k = 0; k < 2; ++k) \
;     dst[n][k] = *reinterpret_cast<const bf16x8*>(b_rd + ((b) * 2 + (h)) * (HT * 2) + n * 2048 + k * 1024)
; #define MMA(ai, bj, At_, Bt_) do { __builtin_amdgcn_s_setprio(1); \
;     for (int m = 0; m < 4; ++m) for (int n = 0; n < 2; ++n) for (int k = 0; k < 2; ++k) \
;       acc[ai][bj][m][n] = __builtin_amdgcn_mfma_f32_16x16x32_bf16(Bt_[n][k], At_[m][k], acc[ai][bj][m][n], 0, 0, 0); \
;     __builtin_amdgcn_s_setprio(0); } while (0)
; #define BAR __builtin_amdgcn_s_barrier()
;     ...
;     LDB(B0, 0, 0); SCHED; LDA(At, 0, 0); STAGE_A(SA(1, 1), brow + HALF, t + 1);
;     WAIT_L(8); BAR; WAIT_L(0); MMA(0, 0, At, B0); BAR; SCHED;
;     LDB(B1, 0, 1); STAGE_B(SB(0, 0), bcol, t + 2);
;     BAR; WAIT_L(0); MMA(0, 1, At, B1); BAR;
;     LDA(At, 0, 1); STAGE_A(SA(0, 0), brow, t + 2);
;     BAR; WAIT_L(0); MMA(1, 0, At, B0); BAR; SCHED;
;     STAGE_B(SB(0, 1), bcol + HALF, t + 2);
;     WAIT_V(6); BAR; MMA(1, 1, At, B1); BAR;
;     LDB(B0, 1, 0); SCHED; LDA(At, 1, 0); STAGE_A(SA(0, 1), brow + HALF, t + 2);
;     WAIT_L(8); BAR; WAIT_L(0); MMA(0, 0, At, B0); BAR; SCHED;
;     LDB(B1, 1, 1); STAGE_B(SB(1, 0), bcol, t + 3);
;     BAR; WAIT_L(0); MMA(0, 1, At, B1); BAR;
;     LDA(At, 1, 1); STAGE_A(SA(1, 0), brow, t + 3);
;     BAR; WAIT_L(0); MMA(1, 0, At, B0); BAR; SCHED;
;     STAGE_B(SB(1, 1), bcol + HALF, t + 3);
;     WAIT_V(6); BAR; MMA(1, 1, At, B1); BAR;
	v_mfma_f32_16x16x32_bf16 v[76:79], v[214:217], v[198:201], v[76:79]
	v_mfma_f32_16x16x32_bf16 v[72:75], v[230:233], v[198:201], v[72:75]
	v_mfma_f32_16x16x32_bf16 v[68:71], v[214:217], v[206:209], v[68:71]
	v_mfma_f32_16x16x32_bf16 v[64:67], v[230:233], v[206:209], v[64:67]
	s_setprio 0
	v_lshl_add_u64 v[234:235], s[86:87], 0, v[130:131]
	v_readfirstlane_b32 s9, v143
	v_lshl_add_u64 v[236:237], v[234:235], 0, s[74:75]
	s_mov_b32 m0, s9
	v_add_u32_e32 v159, 0x2000, v143
	global_load_lds_dwordx4 v[236:237], off
	v_lshl_add_u64 v[236:237], s[86:87], 0, v[132:133]
	v_readfirstlane_b32 s9, v159
	v_lshl_add_u64 v[238:239], v[236:237], 0, s[74:75]
	s_mov_b32 m0, s9
	s_nop 0
	global_load_lds_dwordx4 v[238:239], off
	v_readfirstlane_b32 s9, v145
	v_lshl_add_u64 v[238:239], v[222:223], 0, s[76:77]
	s_mov_b32 m0, s9
	v_readfirstlane_b32 s9, v146
	ds_read_b128 v[176:179], v144 offset:16384
	ds_read_b128 v[182:185], v144 offset:17408
	ds_read_b128 v[186:189], v144 offset:18432
	ds_read_b128 v[190:193], v144 offset:19456
	ds_read_b128 v[194:197], v144 offset:20480
	ds_read_b128 v[198:201], v144 offset:21504
	ds_read_b128 v[202:205], v144 offset:22528
	ds_read_b128 v[206:209], v144 offset:23552
	global_load_lds_dwordx4 v[238:239], off
	v_lshl_add_u64 v[238:239], v[226:227], 0, s[76:77]
	s_mov_b32 m0, s9
	s_nop 0
	global_load_lds_dwordx4 v[238:239], off
	v_lshl_add_u64 v[238:239], s[86:87], 0, v[138:139]
	v_readfirstlane_b32 s9, v148
	v_add_u32_e32 v159, 0x2000, v148
	v_lshl_add_u64 v[250:251], v[238:239], 0, s[78:79]
	s_mov_b32 m0, s9
	v_lshl_add_u64 v[240:241], s[86:87], 0, v[140:141]
	v_readfirstlane_b32 s9, v159
	global_load_lds_dwordx4 v[250:251], off
	v_lshl_add_u64 v[250:251], v[240:241], 0, s[78:79]
	s_mov_b32 m0, s9
	s_nop 0
	global_load_lds_dwordx4 v[250:251], off
	s_waitcnt lgkmcnt(0)
	s_waitcnt vmcnt(8)
	s_barrier
	s_setprio 1
	v_mfma_f32_16x16x32_bf16 v[60:63], v[160:163], v[176:179], 0
	v_mfma_f32_16x16x32_bf16 v[56:59], v[168:171], v[176:179], 0
	v_mfma_f32_16x16x32_bf16 v[52:55], v[160:163], v[186:189], 0
	v_mfma_f32_16x16x32_bf16 v[48:51], v[168:171], v[186:189], 0
	v_mfma_f32_16x16x32_bf16 v[44:47], v[160:163], v[194:197], 0
	v_mfma_f32_16x16x32_bf16 v[40:43], v[168:171], v[194:197], 0
	v_mfma_f32_16x16x32_bf16 v[36:39], v[160:163], v[202:205], 0
	v_mfma_f32_16x16x32_bf16 v[32:35], v[168:171], v[202:205], 0
	v_mfma_f32_16x16x32_bf16 v[60:63], v[164:167], v[182:185], v[60:63]
	v_mfma_f32_16x16x32_bf16 v[56:59], v[172:175], v[182:185], v[56:59]
	v_mfma_f32_16x16x32_bf16 v[52:55], v[164:167], v[190:193], v[52:55]
	v_mfma_f32_16x16x32_bf16 v[48:51], v[172:175], v[190:193], v[48:51]
	v_mfma_f32_16x16x32_bf16 v[44:47], v[164:167], v[198:201], v[44:47]
	v_mfma_f32_16x16x32_bf16 v[40:43], v[172:175], v[198:201], v[40:43]
	v_mfma_f32_16x16x32_bf16 v[36:39], v[164:167], v[206:209], v[36:39]
	v_mfma_f32_16x16x32_bf16 v[32:35], v[172:175], v[206:209], v[32:35]
	v_mfma_f32_16x16x32_bf16 v[28:31], v[210:213], v[176:179], 0
	v_mfma_f32_16x16x32_bf16 v[24:27], v[218:221], v[176:179], 0
	v_mfma_f32_16x16x32_bf16 v[20:23], v[210:213], v[186:189], 0
	v_mfma_f32_16x16x32_bf16 v[16:19], v[218:221], v[186:189], 0
	v_mfma_f32_16x16x32_bf16 v[12:15], v[210:213], v[194:197], 0
	v_mfma_f32_16x16x32_bf16 v[8:11], v[218:221], v[194:197], 0
	v_mfma_f32_16x16x32_bf16 v[4:7], v[210:213], v[202:205], 0
	v_mfma_f32_16x16x32_bf16 v[0:3], v[218:221], v[202:205], 0
	v_mfma_f32_16x16x32_bf16 v[28:31], v[214:217], v[182:185], v[28:31]
	v_mfma_f32_16x16x32_bf16 v[24:27], v[230:233], v[182:185], v[24:27]
	v_mfma_f32_16x16x32_bf16 v[20:23], v[214:217], v[190:193], v[20:23]
	v_mfma_f32_16x16x32_bf16 v[16:19], v[230:233], v[190:193], v[16:19]
	s_setprio 2
	s_barrier
	v_mfma_f32_16x16x32_bf16 v[12:15], v[214:217], v[198:201], v[12:15]
	v_mfma_f32_16x16x32_bf16 v[8:11], v[230:233], v[198:201], v[8:11]
	v_mfma_f32_16x16x32_bf16 v[4:7], v[214:217], v[206:209], v[4:7]
	v_mfma_f32_16x16x32_bf16 v[0:3], v[230:233], v[206:209], v[0:3]
	s_setprio 0
	ds_read_b128 v[160:163], v147 offset:32768
	ds_read_b128 v[164:167], v147 offset:33792
	ds_read_b128 v[168:171], v147 offset:34816
	ds_read_b128 v[172:175], v147 offset:35840
	v_readfirstlane_b32 s9, v149
	v_lshl_add_u64 v[210:211], v[222:223], 0, s[80:81]
	s_mov_b32 m0, s9
	v_readfirstlane_b32 s9, v150
	ds_read_b128 v[176:179], v144 offset:32768
	ds_read_b128 v[182:185], v144 offset:33792
	ds_read_b128 v[186:189], v144 offset:34816
	ds_read_b128 v[190:193], v144 offset:35840
	ds_read_b128 v[194:197], v144 offset:36864
	ds_read_b128 v[198:201], v144 offset:37888
	ds_read_b128 v[202:205], v144 offset:38912
	ds_read_b128 v[206:209], v144 offset:39936
	global_load_lds_dwordx4 v[210:211], off
	v_lshl_add_u64 v[210:211], v[226:227], 0, s[80:81]
	s_mov_b32 m0, s9
	s_nop 0
	global_load_lds_dwordx4 v[210:211], off
	ds_read_b128 v[210:213], v147 offset:49152
	ds_read_b128 v[214:217], v147 offset:50176
	ds_read_b128 v[218:221], v147 offset:51200
	ds_read_b128 v[230:233], v147 offset:52224
	s_waitcnt lgkmcnt(0)
	s_waitcnt vmcnt(8)
	s_barrier
; #define STAGE_A(P, br, kt) do { const char* _base = (const char*)(((kt) < G.ksplit ? G.A1 : A2m) + (long)(br) * G.lda + (long)(kt) * BK); \
;     __builtin_amdgcn_global_load_lds((const unsigned*)(_base + aoff0), (unsigned*)((char*)(P) + sb0), 16, 0, 0); \
;     __builtin_amdgcn_global_load_lds((const unsigned*)(_base + aoff1), (unsigned*)((char*)(P) + sb1), 16, 0, 0); } while (0)
; #define STAGE_B(P, br, kt) do { const char* _base = (const char*)(G.Bt + (long)(br) * G.ldb + (long)(kt) * BK); \
;     __builtin_amdgcn_global_load_lds((const unsigned*)(_base + boff0), (unsigned*)((char*)(P) + sb0), 16, 0, 0); \
;     __builtin_amdgcn_global_load_lds((const unsigned*)(_base + boff1), (unsigned*)((char*)(P) + sb1), 16, 0, 0); } while (0)
; #define LDA(dst, b, h) for (int m = 0; m < 4; ++m) for (int k = 0; k < 2; ++k) \
;     dst[m][k] = *reinterpret_cast<const bf16x8*>(a_rd + ((b) * 2 + (h)) * (HT * 2) + m * 2048 + k * 1024)
; #define LDB(dst, b, h) for (int n = 0; n < 2; ++n) for (int k = 0; k < 2; ++k) \
;     dst[n][k] = *reinterpret_cast<const bf16x8*>(b_rd + ((b) * 2 + (h)) * (HT * 2) + n * 2048 + k * 1024)
; #define MMA(ai, bj, At_, Bt_) do { __builtin_amdgcn_s_setprio(1); \
;     for (int m = 0; m < 4; ++m) for (int n = 0; n < 2; ++n) for (int k = 0; k < 2; ++k) \
;       acc[ai][bj][m][n] = __builtin_amdgcn_mfma_f32_16x16x32_bf16(Bt_[n][k], At_[m][k], acc[ai][bj][m][n], 0, 0, 0); \
;     __builtin_amdgcn_s_setprio(0); } while (0)
; #define BAR __builtin_amdgcn_s_barrier()
;     ...
;     LDB(B0, 0, 0); SCHED; LDA(At, 0, 0); STAGE_A(SA(1, 1), brow + HALF, t + 1);
;     WAIT_L(8); BAR; WAIT_L(0); MMA(0, 0, At, B0); BAR; SCHED;
;     LDB(B1, 0, 1); STAGE_B(SB(0, 0), bcol, t + 2);
;     BAR; WAIT_L(0); MMA(0, 1, At, B1); BAR;
;     LDA(At, 0, 1); STAGE_A(SA(0, 0), brow, t + 2);
;     BAR; WAIT_L(0); MMA(1, 0, At, B0); BAR; SCHED;
;     STAGE_B(SB(0, 1), bcol + HALF, t + 2);
;     WAIT_V(6); BAR; MMA(1, 1, At, B1); BAR;
;     LDB(B0, 1, 0); SCHED; LDA(At, 1, 0); STAGE_A(SA(0, 1), brow + HALF, t + 2);
;     WAIT_L(8); BAR; WAIT_L(0); MMA(0, 0, At, B0); BAR; SCHED;
;     LDB(B1, 1, 1); STAGE_B(SB(1, 0), bcol, t + 3);
;     BAR; WAIT_L(0); MMA(0, 1, At, B1); BAR;
;     LDA(At, 1, 1); STAGE_A(SA(1, 0), brow, t + 3);
;     BAR; WAIT_L(0); MMA(1, 0, At, B0); BAR; SCHED;
;     STAGE_B(SB(1, 1), bcol + HALF, t + 3);
;     WAIT_V(6); BAR; MMA(1, 1, At, B1); BAR;
;   }
	s_setprio 1
	v_mfma_f32_16x16x32_bf16 v[124:127], v[160:163], v[176:179], v[124:127]
	v_mfma_f32_16x16x32_bf16 v[120:123], v[168:171], v[176:179], v[120:123]
	v_mfma_f32_16x16x32_bf16 v[116:119], v[160:163], v[186:189], v[116:119]
	v_mfma_f32_16x16x32_bf16 v[112:115], v[168:171], v[186:189], v[112:115]
	v_mfma_f32_16x16x32_bf16 v[108:111], v[160:163], v[194:197], v[108:111]
	v_mfma_f32_16x16x32_bf16 v[104:107], v[168:171], v[194:197], v[104:107]
	v_mfma_f32_16x16x32_bf16 v[100:103], v[160:163], v[202:205], v[100:103]
	v_mfma_f32_16x16x32_bf16 v[96:99], v[168:171], v[202:205], v[96:99]
	v_mfma_f32_16x16x32_bf16 v[124:127], v[164:167], v[182:185], v[124:127]
	v_mfma_f32_16x16x32_bf16 v[120:123], v[172:175], v[182:185], v[120:123]
	v_mfma_f32_16x16x32_bf16 v[116:119], v[164:167], v[190:193], v[116:119]
	v_mfma_f32_16x16x32_bf16 v[112:115], v[172:175], v[190:193], v[112:115]
	v_mfma_f32_16x16x32_bf16 v[108:111], v[164:167], v[198:201], v[108:111]
	v_mfma_f32_16x16x32_bf16 v[104:107], v[172:175], v[198:201], v[104:107]
	v_mfma_f32_16x16x32_bf16 v[100:103], v[164:167], v[206:209], v[100:103]
	v_mfma_f32_16x16x32_bf16 v[96:99], v[172:175], v[206:209], v[96:99]
	v_mfma_f32_16x16x32_bf16 v[92:95], v[210:213], v[176:179], v[92:95]
	v_mfma_f32_16x16x32_bf16 v[88:91], v[218:221], v[176:179], v[88:91]
	v_mfma_f32_16x16x32_bf16 v[84:87], v[210:213], v[186:189], v[84:87]
	v_mfma_f32_16x16x32_bf16 v[80:83], v[218:221], v[186:189], v[80:83]
	v_mfma_f32_16x16x32_bf16 v[76:79], v[210:213], v[194:197], v[76:79]
	v_mfma_f32_16x16x32_bf16 v[72:75], v[218:221], v[194:197], v[72:75]
	v_mfma_f32_16x16x32_bf16 v[68:71], v[210:213], v[202:205], v[68:71]
	v_mfma_f32_16x16x32_bf16 v[64:67], v[218:221], v[202:205], v[64:67]
	v_mfma_f32_16x16x32_bf16 v[92:95], v[214:217], v[182:185], v[92:95]
	v_mfma_f32_16x16x32_bf16 v[88:91], v[230:233], v[182:185], v[88:91]
	v_mfma_f32_16x16x32_bf16 v[84:87], v[214:217], v[190:193], v[84:87]
	v_mfma_f32_16x16x32_bf16 v[80:83], v[230:233], v[190:193], v[80:83]
	s_setprio 2
	s_barrier
	v_mfma_f32_16x16x32_bf16 v[76:79], v[214:217], v[198:201], v[76:79]
	v_mfma_f32_16x16x32_bf16 v[72:75], v[230:233], v[198:201], v[72:75]
	v_mfma_f32_16x16x32_bf16 v[68:71], v[214:217], v[206:209], v[68:71]
	v_mfma_f32_16x16x32_bf16 v[64:67], v[230:233], v[206:209], v[64:67]
	s_setprio 0
	v_readfirstlane_b32 s9, v151
	v_lshl_add_u64 v[234:235], v[234:235], 0, s[82:83]
	s_mov_b32 m0, s9
	v_readfirstlane_b32 s9, v152
	global_load_lds_dwordx4 v[234:235], off
	v_lshl_add_u64 v[234:235], v[236:237], 0, s[82:83]
	s_mov_b32 m0, s9
	s_nop 0
	global_load_lds_dwordx4 v[234:235], off
	v_readfirstlane_b32 s9, v153
	v_lshl_add_u64 v[222:223], v[222:223], 0, s[54:55]
	s_mov_b32 m0, s9
	v_readfirstlane_b32 s9, v154
	ds_read_b128 v[176:179], v144 offset:49152
	ds_read_b128 v[182:185], v144 offset:50176
	ds_read_b128 v[186:189], v144 offset:51200
	ds_read_b128 v[190:193], v144 offset:52224
	ds_read_b128 v[194:197], v144 offset:53248
	ds_read_b128 v[198:201], v144 offset:54272
	ds_read_b128 v[202:205], v144 offset:55296
	ds_read_b128 v[206:209], v144 offset:56320
	global_load_lds_dwordx4 v[222:223], off
	v_lshl_add_u64 v[222:223], v[226:227], 0, s[54:55]
	s_mov_b32 m0, s9
	s_nop 0
	global_load_lds_dwordx4 v[222:223], off
	v_readfirstlane_b32 s9, v155
	v_lshl_add_u64 v[250:251], v[238:239], 0, s[92:93]
	s_mov_b32 m0, s9
	v_readfirstlane_b32 s9, v156
	global_load_lds_dwordx4 v[250:251], off
	v_lshl_add_u64 v[250:251], v[240:241], 0, s[92:93]
	s_mov_b32 m0, s9
	s_nop 0
	global_load_lds_dwordx4 v[250:251], off
	s_waitcnt lgkmcnt(0)
	s_waitcnt vmcnt(8)
	s_barrier
	s_setprio 1
	v_mfma_f32_16x16x32_bf16 v[60:63], v[160:163], v[176:179], v[60:63]
	v_mfma_f32_16x16x32_bf16 v[56:59], v[168:171], v[176:179], v[56:59]
	v_mfma_f32_16x16x32_bf16 v[52:55], v[160:163], v[186:189], v[52:55]
	v_mfma_f32_16x16x32_bf16 v[48:51], v[168:171], v[186:189], v[48:51]
	v_mfma_f32_16x16x32_bf16 v[44:47], v[160:163], v[194:197], v[44:47]
	v_mfma_f32_16x16x32_bf16 v[40:43], v[168:171], v[194:197], v[40:43]
	v_mfma_f32_16x16x32_bf16 v[36:39], v[160:163], v[202:205], v[36:39]
	v_mfma_f32_16x16x32_bf16 v[32:35], v[168:171], v[202:205], v[32:35]
	v_mfma_f32_16x16x32_bf16 v[60:63], v[164:167], v[182:185], v[60:63]
	v_mfma_f32_16x16x32_bf16 v[56:59], v[172:175], v[182:185], v[56:59]
	v_mfma_f32_16x16x32_bf16 v[52:55], v[164:167], v[190:193], v[52:55]
	v_mfma_f32_16x16x32_bf16 v[48:51], v[172:175], v[190:193], v[48:51]
	v_mfma_f32_16x16x32_bf16 v[44:47], v[164:167], v[198:201], v[44:47]
	v_mfma_f32_16x16x32_bf16 v[40:43], v[172:175], v[198:201], v[40:43]
	v_mfma_f32_16x16x32_bf16 v[36:39], v[164:167], v[206:209], v[36:39]
	v_mfma_f32_16x16x32_bf16 v[32:35], v[172:175], v[206:209], v[32:35]
	v_mfma_f32_16x16x32_bf16 v[28:31], v[210:213], v[176:179], v[28:31]
	v_mfma_f32_16x16x32_bf16 v[24:27], v[218:221], v[176:179], v[24:27]
	v_mfma_f32_16x16x32_bf16 v[20:23], v[210:213], v[186:189], v[20:23]
	v_mfma_f32_16x16x32_bf16 v[16:19], v[218:221], v[186:189], v[16:19]
	v_mfma_f32_16x16x32_bf16 v[12:15], v[210:213], v[194:197], v[12:15]
	v_mfma_f32_16x16x32_bf16 v[8:11], v[218:221], v[194:197], v[8:11]
	v_mfma_f32_16x16x32_bf16 v[4:7], v[210:213], v[202:205], v[4:7]
	v_mfma_f32_16x16x32_bf16 v[0:3], v[218:221], v[202:205], v[0:3]
	v_mfma_f32_16x16x32_bf16 v[28:31], v[214:217], v[182:185], v[28:31]
	v_mfma_f32_16x16x32_bf16 v[24:27], v[230:233], v[182:185], v[24:27]
	v_mfma_f32_16x16x32_bf16 v[20:23], v[214:217], v[190:193], v[20:23]
	v_mfma_f32_16x16x32_bf16 v[16:19], v[230:233], v[190:193], v[16:19]
	s_setprio 2
	s_barrier
	v_mfma_f32_16x16x32_bf16 v[12:15], v[214:217], v[198:201], v[12:15]
	v_mfma_f32_16x16x32_bf16 v[8:11], v[230:233], v[198:201], v[8:11]
	v_mfma_f32_16x16x32_bf16 v[4:7], v[214:217], v[206:209], v[4:7]
	v_mfma_f32_16x16x32_bf16 v[0:3], v[230:233], v[206:209], v[0:3]
	s_setprio 0
	s_add_i32 s8, s8, 2
	v_lshl_add_u64 v[130:131], v[130:131], 0, s[90:91]
	v_lshl_add_u64 v[132:133], v[132:133], 0, s[90:91]
	v_lshl_add_u64 v[134:135], v[134:135], 0, s[90:91]
	v_lshl_add_u64 v[136:137], v[136:137], 0, s[90:91]
	v_lshl_add_u64 v[138:139], v[138:139], 0, s[90:91]
	s_cmpk_lt_u32 s8, 0x54
	v_lshl_add_u64 v[140:141], v[140:141], 0, s[90:91]
	s_cbranch_scc0 .Lmy_kexit_5
; #define STAGE_A(P, br, kt) do { const char* _base = (const char*)(((kt) < G.ksplit ? G.A1 : A2m) + (long)(br) * G.lda + (long)(kt) * BK); \
;     __builtin_amdgcn_global_load_lds((const unsigned*)(_base + aoff0), (unsigned*)((char*)(P) + sb0), 16, 0, 0); \
;     __builtin_amdgcn_global_load_lds((const unsigned*)(_base + aoff1), (unsigned*)((char*)(P) + sb1), 16, 0, 0); } while (0)
; #define STAGE_B(P, br, kt) do { const char* _base = (const char*)(G.Bt + (long)(br) * G.ldb + (long)(kt) * BK); \
;     __builtin_amdgcn_global_load_lds((const unsigned*)(_base + boff0), (unsigned*)((char*)(P) + sb0), 16, 0, 0); \
;     __builtin_amdgcn_global_load_lds((const unsigned*)(_base + boff1), (unsigned*)((char*)(P) + sb1), 16, 0, 0); } while (0)
; #define LDA(dst, b, h) for (int m = 0; m < 4; ++m) for (int k = 0; k < 2; ++k) \
;     dst[m][k] = *reinterpret_cast<const bf16x8*>(a_rd + ((b) * 2 + (h)) * (HT * 2) + m * 2048 + k * 1024)
; #define LDB(dst, b, h) for (int n = 0; n < 2; ++n) for (int k = 0; k < 2; ++k) \
;     dst[n][k] = *reinterpret_cast<const bf16x8*>(b_rd + ((b) * 2 + (h)) * (HT * 2) + n * 2048 + k * 1024)
; #define MMA(ai, bj, At_, Bt_) do { __builtin_amdgcn_s_setprio(1); \
;     for (int m = 0; m < 4; ++m) for (int n = 0; n < 2; ++n) for (int k = 0; k < 2; ++k) \
;       acc[ai][bj][m][n] = __builtin_amdgcn_mfma_f32_16x16x32_bf16(Bt_[n][k], At_[m][k], acc[ai][bj][m][n], 0, 0, 0); \
;     __builtin_amdgcn_s_setprio(0); } while (0)
; #define WAIT_V(n) asm volatile("s_waitcnt vmcnt(" #n ")" ::: "memory")
; #define WAIT_L(n) asm volatile("s_waitcnt lgkmcnt(" #n ")" ::: "memory")
; #define BAR __builtin_amdgcn_s_barrier()
; #define SCHED __builtin_amdgcn_sched_barrier(0)
;     ...
;   for (int t = 0; t < nt - 2; t += 2) {
;     LDB(B0, 0, 0); SCHED; LDA(At, 0, 0); STAGE_A(SA(1, 1), brow + HALF, t + 1);
;     WAIT_L(8); BAR; WAIT_L(0); MMA(0, 0, At, B0); BAR; SCHED;
;     LDB(B1, 0, 1); STAGE_B(SB(0, 0), bcol, t + 2);
;     BAR; WAIT_L(0); MMA(0, 1, At, B1); BAR;
;     LDA(At, 0, 1); STAGE_A(SA(0, 0), brow, t + 2);
;     BAR; WAIT_L(0); MMA(1, 0, At, B0); BAR; SCHED;
;     STAGE_B(SB(0, 1), bcol + HALF, t + 2);
;     WAIT_V(6); BAR; MMA(1, 1, At, B1); BAR;
.LBB0_2622:
	ds_read_b128 v[160:163], v147
	ds_read_b128 v[164:167], v147 offset:1024
	ds_read_b128 v[168:171], v147 offset:2048
	ds_read_b128 v[172:175], v147 offset:3072
	v_add_u32_e32 v157, 0xc000, v145
	v_lshl_add_u64 v[222:223], s[86:87], 0, v[134:135]
	v_readfirstlane_b32 s9, v157
	v_lshl_add_u64 v[158:159], v[222:223], 0, s[72:73]
	s_mov_b32 m0, s9
	ds_read_b128 v[176:179], v144
	ds_read_b128 v[182:185], v144 offset:1024
	ds_read_b128 v[186:189], v144 offset:2048
	ds_read_b128 v[190:193], v144 offset:3072
	ds_read_b128 v[194:197], v144 offset:4096
	ds_read_b128 v[198:201], v144 offset:5120
	ds_read_b128 v[202:205], v144 offset:6144
	ds_read_b128 v[206:209], v144 offset:7168
	global_load_lds_dwordx4 v[158:159], off
	v_add_u32_e32 v158, 0xe000, v145
	v_lshl_add_u64 v[226:227], s[86:87], 0, v[136:137]
	v_readfirstlane_b32 s9, v158
	v_lshl_add_u64 v[210:211], v[226:227], 0, s[72:73]
	s_mov_b32 m0, s9
	s_nop 0
	global_load_lds_dwordx4 v[210:211], off
	ds_read_b128 v[210:213], v147 offset:16384
	ds_read_b128 v[214:217], v147 offset:17408
	ds_read_b128 v[218:221], v147 offset:18432
	ds_read_b128 v[230:233], v147 offset:19456
	s_waitcnt lgkmcnt(0)
	s_waitcnt vmcnt(8)
	s_barrier
	s_setprio 1
	v_mfma_f32_16x16x32_bf16 v[124:127], v[160:163], v[176:179], v[124:127]
	v_mfma_f32_16x16x32_bf16 v[120:123], v[168:171], v[176:179], v[120:123]
	v_mfma_f32_16x16x32_bf16 v[116:119], v[160:163], v[186:189], v[116:119]
	v_mfma_f32_16x16x32_bf16 v[112:115], v[168:171], v[186:189], v[112:115]
	v_mfma_f32_16x16x32_bf16 v[108:111], v[160:163], v[194:197], v[108:111]
	v_mfma_f32_16x16x32_bf16 v[104:107], v[168:171], v[194:197], v[104:107]
	v_mfma_f32_16x16x32_bf16 v[100:103], v[160:163], v[202:205], v[100:103]
	v_mfma_f32_16x16x32_bf16 v[96:99], v[168:171], v[202:205], v[96:99]
	v_mfma_f32_16x16x32_bf16 v[124:127], v[164:167], v[182:185], v[124:127]
	v_mfma_f32_16x16x32_bf16 v[120:123], v[172:175], v[182:185], v[120:123]
	v_mfma_f32_16x16x32_bf16 v[116:119], v[164:167], v[190:193], v[116:119]
	v_mfma_f32_16x16x32_bf16 v[112:115], v[172:175], v[190:193], v[112:115]
	v_mfma_f32_16x16x32_bf16 v[108:111], v[164:167], v[198:201], v[108:111]
	v_mfma_f32_16x16x32_bf16 v[104:107], v[172:175], v[198:201], v[104:107]
	v_mfma_f32_16x16x32_bf16 v[100:103], v[164:167], v[206:209], v[100:103]
	v_mfma_f32_16x16x32_bf16 v[96:99], v[172:175], v[206:209], v[96:99]
	v_mfma_f32_16x16x32_bf16 v[92:95], v[210:213], v[176:179], v[92:95]
	v_mfma_f32_16x16x32_bf16 v[88:91], v[218:221], v[176:179], v[88:91]
	v_mfma_f32_16x16x32_bf16 v[84:87], v[210:213], v[186:189], v[84:87]
	v_mfma_f32_16x16x32_bf16 v[80:83], v[218:221], v[186:189], v[80:83]
	v_mfma_f32_16x16x32_bf16 v[76:79], v[210:213], v[194:197], v[76:79]
	v_mfma_f32_16x16x32_bf16 v[72:75], v[218:221], v[194:197], v[72:75]
	v_mfma_f32_16x16x32_bf16 v[68:71], v[210:213], v[202:205], v[68:71]
	v_mfma_f32_16x16x32_bf16 v[64:67], v[218:221], v[202:205], v[64:67]
	v_mfma_f32_16x16x32_bf16 v[92:95], v[214:217], v[182:185], v[92:95]
	v_mfma_f32_16x16x32_bf16 v[88:91], v[230:233], v[182:185], v[88:91]
	v_mfma_f32_16x16x32_bf16 v[84:87], v[214:217], v[190:193], v[84:87]
	v_mfma_f32_16x16x32_bf16 v[80:83], v[230:233], v[190:193], v[80:83]
	s_setprio 2
	s_barrier
	v_mfma_f32_16x16x32_bf16 v[76:79], v[214:217], v[198:201], v[76:79]
	v_mfma_f32_16x16x32_bf16 v[72:75], v[230:233], v[198:201], v[72:75]
	v_mfma_f32_16x16x32_bf16 v[68:71], v[214:217], v[206:209], v[68:71]
	v_mfma_f32_16x16x32_bf16 v[64:67], v[230:233], v[206:209], v[64:67]
	s_setprio 0
	v_lshl_add_u64 v[234:235], s[86:87], 0, v[130:131]
	v_readfirstlane_b32 s9, v143
	v_lshl_add_u64 v[236:237], v[234:235], 0, s[74:75]
	s_mov_b32 m0, s9
	v_add_u32_e32 v159, 0x2000, v143
	global_load_lds_dwordx4 v[236:237], off
	v_lshl_add_u64 v[236:237], s[86:87], 0, v[132:133]
	v_readfirstlane_b32 s9, v159
	v_lshl_add_u64 v[238:239], v[236:237], 0, s[74:75]
	s_mov_b32 m0, s9
	s_nop 0
	global_load_lds_dwordx4 v[238:239], off
	v_readfirstlane_b32 s9, v145
	v_lshl_add_u64 v[238:239], v[222:223], 0, s[76:77]
	s_mov_b32 m0, s9
	v_readfirstlane_b32 s9, v146
	ds_read_b128 v[176:179], v144 offset:16384
	ds_read_b128 v[182:185], v144 offset:17408
	ds_read_b128 v[186:189], v144 offset:18432
	ds_read_b128 v[190:193], v144 offset:19456
	ds_read_b128 v[194:197], v144 offset:20480
	ds_read_b128 v[198:201], v144 offset:21504
	ds_read_b128 v[202:205], v144 offset:22528
	ds_read_b128 v[206:209], v144 offset:23552
	global_load_lds_dwordx4 v[238:239], off
	v_lshl_add_u64 v[238:239], v[226:227], 0, s[76:77]
	s_mov_b32 m0, s9
	s_nop 0
	global_load_lds_dwordx4 v[238:239], off
	v_lshl_add_u64 v[238:239], s[86:87], 0, v[138:139]
	v_readfirstlane_b32 s9, v148
	v_add_u32_e32 v159, 0x2000, v148
	v_lshl_add_u64 v[250:251], v[238:239], 0, s[78:79]
	s_mov_b32 m0, s9
	v_lshl_add_u64 v[240:241], s[86:87], 0, v[140:141]
	v_readfirstlane_b32 s9, v159
	global_load_lds_dwordx4 v[250:251], off
	v_lshl_add_u64 v[250:251], v[240:241], 0, s[78:79]
	s_mov_b32 m0, s9
	s_nop 0
	global_load_lds_dwordx4 v[250:251], off
	s_waitcnt lgkmcnt(0)
	s_waitcnt vmcnt(8)
	s_barrier
; #define STAGE_A(P, br, kt) do { const char* _base = (const char*)(((kt) < G.ksplit ? G.A1 : A2m) + (long)(br) * G.lda + (long)(kt) * BK); \
;     __builtin_amdgcn_global_load_lds((const unsigned*)(_base + aoff0), (unsigned*)((char*)(P) + sb0), 16, 0, 0); \
;     __builtin_amdgcn_global_load_lds((const unsigned*)(_base + aoff1), (unsigned*)((char*)(P) + sb1), 16, 0, 0); } while (0)
; #define STAGE_B(P, br, kt) do { const char* _base = (const char*)(G.Bt + (long)(br) * G.ldb + (long)(kt) * BK); \
;     __builtin_amdgcn_global_load_lds((const unsigned*)(_base + boff0), (unsigned*)((char*)(P) + sb0), 16, 0, 0); \
;     __builtin_amdgcn_global_load_lds((const unsigned*)(_base + boff1), (unsigned*)((char*)(P) + sb1), 16, 0, 0); } while (0)
; #define LDA(dst, b, h) for (int m = 0; m < 4; ++m) for (int k = 0; k < 2; ++k) \
;     dst[m][k] = *reinterpret_cast<const bf16x8*>(a_rd + ((b) * 2 + (h)) * (HT * 2) + m * 2048 + k * 1024)
; #define LDB(dst, b, h) for (int n = 0; n < 2; ++n) for (int k = 0; k < 2; ++k) \
;     dst[n][k] = *reinterpret_cast<const bf16x8*>(b_rd + ((b) * 2 + (h)) * (HT * 2) + n * 2048 + k * 1024)
; #define MMA(ai, bj, At_, Bt_) do { __builtin_amdgcn_s_setprio(1); \
;     for (int m = 0; m < 4; ++m) for (int n = 0; n < 2; ++n) for (int k = 0; k < 2; ++k) \
;       acc[ai][bj][m][n] = __builtin_amdgcn_mfma_f32_16x16x32_bf16(Bt_[n][k], At_[m][k], acc[ai][bj][m][n], 0, 0, 0); \
;     __builtin_amdgcn_s_setprio(0); } while (0)
; #define WAIT_L(n) asm volatile("s_waitcnt lgkmcnt(" #n ")" ::: "memory")
; #define BAR __builtin_amdgcn_s_barrier()
; #define SCHED __builtin_amdgcn_sched_barrier(0)
;     ...
;     LDB(B0, 1, 0); SCHED; LDA(At, 1, 0); STAGE_A(SA(0, 1), brow + HALF, t + 2);
;     WAIT_L(8); BAR; WAIT_L(0); MMA(0, 0, At, B0); BAR; SCHED;
;     LDB(B1, 1, 1); STAGE_B(SB(1, 0), bcol, t + 3);
;     BAR; WAIT_L(0); MMA(0, 1, At, B1); BAR;
;     LDA(At, 1, 1); STAGE_A(SA(1, 0), brow, t + 3);
;     BAR; WAIT_L(0); MMA(1, 0, At, B0); BAR; SCHED;
	s_setprio 1
	v_mfma_f32_16x16x32_bf16 v[60:63], v[160:163], v[176:179], v[60:63]
	v_mfma_f32_16x16x32_bf16 v[56:59], v[168:171], v[176:179], v[56:59]
	v_mfma_f32_16x16x32_bf16 v[52:55], v[160:163], v[186:189], v[52:55]
	v_mfma_f32_16x16x32_bf16 v[48:51], v[168:171], v[186:189], v[48:51]
	v_mfma_f32_16x16x32_bf16 v[44:47], v[160:163], v[194:197], v[44:47]
	v_mfma_f32_16x16x32_bf16 v[40:43], v[168:171], v[194:197], v[40:43]
	v_mfma_f32_16x16x32_bf16 v[36:39], v[160:163], v[202:205], v[36:39]
	v_mfma_f32_16x16x32_bf16 v[32:35], v[168:171], v[202:205], v[32:35]
	v_mfma_f32_16x16x32_bf16 v[60:63], v[164:167], v[182:185], v[60:63]
	v_mfma_f32_16x16x32_bf16 v[56:59], v[172:175], v[182:185], v[56:59]
	v_mfma_f32_16x16x32_bf16 v[52:55], v[164:167], v[190:193], v[52:55]
	v_mfma_f32_16x16x32_bf16 v[48:51], v[172:175], v[190:193], v[48:51]
	v_mfma_f32_16x16x32_bf16 v[44:47], v[164:167], v[198:201], v[44:47]
	v_mfma_f32_16x16x32_bf16 v[40:43], v[172:175], v[198:201], v[40:43]
	v_mfma_f32_16x16x32_bf16 v[36:39], v[164:167], v[206:209], v[36:39]
	v_mfma_f32_16x16x32_bf16 v[32:35], v[172:175], v[206:209], v[32:35]
	v_mfma_f32_16x16x32_bf16 v[28:31], v[210:213], v[176:179], v[28:31]
	v_mfma_f32_16x16x32_bf16 v[24:27], v[218:221], v[176:179], v[24:27]
	v_mfma_f32_16x16x32_bf16 v[20:23], v[210:213], v[186:189], v[20:23]
	v_mfma_f32_16x16x32_bf16 v[16:19], v[218:221], v[186:189], v[16:19]
	v_mfma_f32_16x16x32_bf16 v[12:15], v[210:213], v[194:197], v[12:15]
	v_mfma_f32_16x16x32_bf16 v[8:11], v[218:221], v[194:197], v[8:11]
	v_mfma_f32_16x16x32_bf16 v[4:7], v[210:213], v[202:205], v[4:7]
	v_mfma_f32_16x16x32_bf16 v[0:3], v[218:221], v[202:205], v[0:3]
	v_mfma_f32_16x16x32_bf16 v[28:31], v[214:217], v[182:185], v[28:31]
	v_mfma_f32_16x16x32_bf16 v[24:27], v[230:233], v[182:185], v[24:27]
	v_mfma_f32_16x16x32_bf16 v[20:23], v[214:217], v[190:193], v[20:23]
	v_mfma_f32_16x16x32_bf16 v[16:19], v[230:233], v[190:193], v[16:19]
	s_setprio 2
	s_barrier
	v_mfma_f32_16x16x32_bf16 v[12:15], v[214:217], v[198:201], v[12:15]
	v_mfma_f32_16x16x32_bf16 v[8:11], v[230:233], v[198:201], v[8:11]
	v_mfma_f32_16x16x32_bf16 v[4:7], v[214:217], v[206:209], v[4:7]
	v_mfma_f32_16x16x32_bf16 v[0:3], v[230:233], v[206:209], v[0:3]
	s_setprio 0
	ds_read_b128 v[160:163], v147 offset:32768
	ds_read_b128 v[164:167], v147 offset:33792
	ds_read_b128 v[168:171], v147 offset:34816
	ds_read_b128 v[172:175], v147 offset:35840
	v_readfirstlane_b32 s9, v149
	v_lshl_add_u64 v[210:211], v[222:223], 0, s[80:81]
	s_mov_b32 m0, s9
	v_readfirstlane_b32 s9, v150
	ds_read_b128 v[176:179], v144 offset:32768
	ds_read_b128 v[182:185], v144 offset:33792
	ds_read_b128 v[186:189], v144 offset:34816
	ds_read_b128 v[190:193], v144 offset:35840
	ds_read_b128 v[194:197], v144 offset:36864
	ds_read_b128 v[198:201], v144 offset:37888
	ds_read_b128 v[202:205], v144 offset:38912
	ds_read_b128 v[206:209], v144 offset:39936
	global_load_lds_dwordx4 v[210:211], off
	v_lshl_add_u64 v[210:211], v[226:227], 0, s[80:81]
	s_mov_b32 m0, s9
	s_nop 0
	global_load_lds_dwordx4 v[210:211], off
	ds_read_b128 v[210:213], v147 offset:49152
	ds_read_b128 v[214:217], v147 offset:50176
	ds_read_b128 v[218:221], v147 offset:51200
	ds_read_b128 v[230:233], v147 offset:52224
	s_waitcnt lgkmcnt(0)
	s_waitcnt vmcnt(8)
	s_barrier
	s_setprio 1
	v_mfma_f32_16x16x32_bf16 v[124:127], v[160:163], v[176:179], v[124:127]
	v_mfma_f32_16x16x32_bf16 v[120:123], v[168:171], v[176:179], v[120:123]
	v_mfma_f32_16x16x32_bf16 v[116:119], v[160:163], v[186:189], v[116:119]
	v_mfma_f32_16x16x32_bf16 v[112:115], v[168:171], v[186:189], v[112:115]
	v_mfma_f32_16x16x32_bf16 v[108:111], v[160:163], v[194:197], v[108:111]
	v_mfma_f32_16x16x32_bf16 v[104:107], v[168:171], v[194:197], v[104:107]
	v_mfma_f32_16x16x32_bf16 v[100:103], v[160:163], v[202:205], v[100:103]
	v_mfma_f32_16x16x32_bf16 v[96:99], v[168:171], v[202:205], v[96:99]
	v_mfma_f32_16x16x32_bf16 v[124:127], v[164:167], v[182:185], v[124:127]
	v_mfma_f32_16x16x32_bf16 v[120:123], v[172:175], v[182:185], v[120:123]
	v_mfma_f32_16x16x32_bf16 v[116:119], v[164:167], v[190:193], v[116:119]
	v_mfma_f32_16x16x32_bf16 v[112:115], v[172:175], v[190:193], v[112:115]
	v_mfma_f32_16x16x32_bf16 v[108:111], v[164:167], v[198:201], v[108:111]
	v_mfma_f32_16x16x32_bf16 v[104:107], v[172:175], v[198:201], v[104:107]
	v_mfma_f32_16x16x32_bf16 v[100:103], v[164:167], v[206:209], v[100:103]
	v_mfma_f32_16x16x32_bf16 v[96:99], v[172:175], v[206:209], v[96:99]
	v_mfma_f32_16x16x32_bf16 v[92:95], v[210:213], v[176:179], v[92:95]
	v_mfma_f32_16x16x32_bf16 v[88:91], v[218:221], v[176:179], v[88:91]
	v_mfma_f32_16x16x32_bf16 v[84:87], v[210:213], v[186:189], v[84:87]
	v_mfma_f32_16x16x32_bf16 v[80:83], v[218:221], v[186:189], v[80:83]
	v_mfma_f32_16x16x32_bf16 v[76:79], v[210:213], v[194:197], v[76:79]
	v_mfma_f32_16x16x32_bf16 v[72:75], v[218:221], v[194:197], v[72:75]
	v_mfma_f32_16x16x32_bf16 v[68:71], v[210:213], v[202:205], v[68:71]
	v_mfma_f32_16x16x32_bf16 v[64:67], v[218:221], v[202:205], v[64:67]
	v_mfma_f32_16x16x32_bf16 v[92:95], v[214:217], v[182:185], v[92:95]
	v_mfma_f32_16x16x32_bf16 v[88:91], v[230:233], v[182:185], v[88:91]
	v_mfma_f32_16x16x32_bf16 v[84:87], v[214:217], v[190:193], v[84:87]
	v_mfma_f32_16x16x32_bf16 v[80:83], v[230:233], v[190:193], v[80:83]
	s_setprio 2
	s_barrier
; #define STAGE_A(P, br, kt) do { const char* _base = (const char*)(((kt) < G.ksplit ? G.A1 : A2m) + (long)(br) * G.lda + (long)(kt) * BK); \
;     __builtin_amdgcn_global_load_lds((const unsigned*)(_base + aoff0), (unsigned*)((char*)(P) + sb0), 16, 0, 0); \
;     __builtin_amdgcn_global_load_lds((const unsigned*)(_base + aoff1), (unsigned*)((char*)(P) + sb1), 16, 0, 0); } while (0)
; #define STAGE_B(P, br, kt) do { const char* _base = (const char*)(G.Bt + (long)(br) * G.ldb + (long)(kt) * BK); \
;     __builtin_amdgcn_global_load_lds((const unsigned*)(_base + boff0), (unsigned*)((char*)(P) + sb0), 16, 0, 0); \
;     __builtin_amdgcn_global_load_lds((const unsigned*)(_base + boff1), (unsigned*)((char*)(P) + sb1), 16, 0, 0); } while (0)
; #define LDA(dst, b, h) for (int m = 0; m < 4; ++m) for (int k = 0; k < 2; ++k) \
;     dst[m][k] = *reinterpret_cast<const bf16x8*>(a_rd + ((b) * 2 + (h)) * (HT * 2) + m * 2048 + k * 1024)
; #define LDB(dst, b, h) for (int n = 0; n < 2; ++n) for (int k = 0; k < 2; ++k) \
;     dst[n][k] = *reinterpret_cast<const bf16x8*>(b_rd + ((b) * 2 + (h)) * (HT * 2) + n * 2048 + k * 1024)
; #define MMA(ai, bj, At_, Bt_) do { __builtin_amdgcn_s_setprio(1); \
;     for (int m = 0; m < 4; ++m) for (int n = 0; n < 2; ++n) for (int k = 0; k < 2; ++k) \
;       acc[ai][bj][m][n] = __builtin_amdgcn_mfma_f32_16x16x32_bf16(Bt_[n][k], At_[m][k], acc[ai][bj][m][n], 0, 0, 0); \
;     __builtin_amdgcn_s_setprio(0); } while (0)
; #define WAIT_V(n) asm volatile("s_waitcnt vmcnt(" #n ")" ::: "memory")
; #define WAIT_L(n) asm volatile("s_waitcnt lgkmcnt(" #n ")" ::: "memory")
; #define BAR __builtin_amdgcn_s_barrier()
;     ...
;     STAGE_B(SB(1, 1), bcol + HALF, t + 3);
;     WAIT_V(6); BAR; MMA(1, 1, At, B1); BAR;
;   }
;     ...
;   { LDB(B0, 0, 0); LDA(At, 0, 0); STAGE_A(SA(1, 1), brow + HALF, nt - 1);
;     BAR; WAIT_L(0); MMA(0, 0, At, B0); BAR;
	v_mfma_f32_16x16x32_bf16 v[76:79], v[214:217], v[198:201], v[76:79]
	v_mfma_f32_16x16x32_bf16 v[72:75], v[230:233], v[198:201], v[72:75]
	v_mfma_f32_16x16x32_bf16 v[68:71], v[214:217], v[206:209], v[68:71]
	v_mfma_f32_16x16x32_bf16 v[64:67], v[230:233], v[206:209], v[64:67]
	s_setprio 0
	v_readfirstlane_b32 s9, v151
	v_lshl_add_u64 v[234:235], v[234:235], 0, s[82:83]
	s_mov_b32 m0, s9
	v_readfirstlane_b32 s9, v152
	global_load_lds_dwordx4 v[234:235], off
	v_lshl_add_u64 v[234:235], v[236:237], 0, s[82:83]
	s_mov_b32 m0, s9
	s_nop 0
	global_load_lds_dwordx4 v[234:235], off
	v_readfirstlane_b32 s9, v153
	v_lshl_add_u64 v[222:223], v[222:223], 0, s[54:55]
	s_mov_b32 m0, s9
	v_readfirstlane_b32 s9, v154
	ds_read_b128 v[176:179], v144 offset:49152
	ds_read_b128 v[182:185], v144 offset:50176
	ds_read_b128 v[186:189], v144 offset:51200
	ds_read_b128 v[190:193], v144 offset:52224
	ds_read_b128 v[194:197], v144 offset:53248
	ds_read_b128 v[198:201], v144 offset:54272
	ds_read_b128 v[202:205], v144 offset:55296
	ds_read_b128 v[206:209], v144 offset:56320
	global_load_lds_dwordx4 v[222:223], off
	v_lshl_add_u64 v[222:223], v[226:227], 0, s[54:55]
	s_mov_b32 m0, s9
	s_nop 0
	global_load_lds_dwordx4 v[222:223], off
	v_readfirstlane_b32 s9, v155
	v_lshl_add_u64 v[250:251], v[238:239], 0, s[92:93]
	s_mov_b32 m0, s9
	v_readfirstlane_b32 s9, v156
	global_load_lds_dwordx4 v[250:251], off
	v_lshl_add_u64 v[250:251], v[240:241], 0, s[92:93]
	s_mov_b32 m0, s9
	s_nop 0
	global_load_lds_dwordx4 v[250:251], off
	s_waitcnt lgkmcnt(0)
	s_waitcnt vmcnt(8)
	s_barrier
	s_setprio 1
	v_mfma_f32_16x16x32_bf16 v[60:63], v[160:163], v[176:179], v[60:63]
	v_mfma_f32_16x16x32_bf16 v[56:59], v[168:171], v[176:179], v[56:59]
	v_mfma_f32_16x16x32_bf16 v[52:55], v[160:163], v[186:189], v[52:55]
	v_mfma_f32_16x16x32_bf16 v[48:51], v[168:171], v[186:189], v[48:51]
	v_mfma_f32_16x16x32_bf16 v[44:47], v[160:163], v[194:197], v[44:47]
	v_mfma_f32_16x16x32_bf16 v[40:43], v[168:171], v[194:197], v[40:43]
	v_mfma_f32_16x16x32_bf16 v[36:39], v[160:163], v[202:205], v[36:39]
	v_mfma_f32_16x16x32_bf16 v[32:35], v[168:171], v[202:205], v[32:35]
	v_mfma_f32_16x16x32_bf16 v[60:63], v[164:167], v[182:185], v[60:63]
	v_mfma_f32_16x16x32_bf16 v[56:59], v[172:175], v[182:185], v[56:59]
	v_mfma_f32_16x16x32_bf16 v[52:55], v[164:167], v[190:193], v[52:55]
	v_mfma_f32_16x16x32_bf16 v[48:51], v[172:175], v[190:193], v[48:51]
	v_mfma_f32_16x16x32_bf16 v[44:47], v[164:167], v[198:201], v[44:47]
	v_mfma_f32_16x16x32_bf16 v[40:43], v[172:175], v[198:201], v[40:43]
	v_mfma_f32_16x16x32_bf16 v[36:39], v[164:167], v[206:209], v[36:39]
	v_mfma_f32_16x16x32_bf16 v[32:35], v[172:175], v[206:209], v[32:35]
	v_mfma_f32_16x16x32_bf16 v[28:31], v[210:213], v[176:179], v[28:31]
	v_mfma_f32_16x16x32_bf16 v[24:27], v[218:221], v[176:179], v[24:27]
	v_mfma_f32_16x16x32_bf16 v[20:23], v[210:213], v[186:189], v[20:23]
	v_mfma_f32_16x16x32_bf16 v[16:19], v[218:221], v[186:189], v[16:19]
	v_mfma_f32_16x16x32_bf16 v[12:15], v[210:213], v[194:197], v[12:15]
	v_mfma_f32_16x16x32_bf16 v[8:11], v[218:221], v[194:197], v[8:11]
	v_mfma_f32_16x16x32_bf16 v[4:7], v[210:213], v[202:205], v[4:7]
	v_mfma_f32_16x16x32_bf16 v[0:3], v[218:221], v[202:205], v[0:3]
	v_mfma_f32_16x16x32_bf16 v[28:31], v[214:217], v[182:185], v[28:31]
	v_mfma_f32_16x16x32_bf16 v[24:27], v[230:233], v[182:185], v[24:27]
	v_mfma_f32_16x16x32_bf16 v[20:23], v[214:217], v[190:193], v[20:23]
	v_mfma_f32_16x16x32_bf16 v[16:19], v[230:233], v[190:193], v[16:19]
	s_setprio 2
	s_barrier
	v_mfma_f32_16x16x32_bf16 v[12:15], v[214:217], v[198:201], v[12:15]
	v_mfma_f32_16x16x32_bf16 v[8:11], v[230:233], v[198:201], v[8:11]
	v_mfma_f32_16x16x32_bf16 v[4:7], v[214:217], v[206:209], v[4:7]
	v_mfma_f32_16x16x32_bf16 v[0:3], v[230:233], v[206:209], v[0:3]
	s_setprio 0
	s_add_i32 s8, s8, 2
	v_lshl_add_u64 v[130:131], v[130:131], 0, s[90:91]
	v_lshl_add_u64 v[132:133], v[132:133], 0, s[90:91]
	v_lshl_add_u64 v[134:135], v[134:135], 0, s[90:91]
	v_lshl_add_u64 v[136:137], v[136:137], 0, s[90:91]
	v_lshl_add_u64 v[138:139], v[138:139], 0, s[90:91]
	s_cmpk_lt_u32 s8, 0x54
	v_lshl_add_u64 v[140:141], v[140:141], 0, s[90:91]
	s_cbranch_scc1 .LBB0_2622
.Lmy_kexit_5:
	s_waitcnt vmcnt(6)
	v_not_b32_e32 v250, 63
	v_mov_b32_e32 v251, 0x41b17218
	s_add_u32 s6, s6, 0x2b80
	s_addc_u32 s7, s7, 0
	v_readfirstlane_b32 s8, v157
	v_lshl_add_u64 v[190:191], s[6:7], 0, v[180:181]
	s_mov_b32 m0, s8
	v_lshl_add_u64 v[128:129], s[6:7], 0, v[128:129]
	v_readfirstlane_b32 s6, v158
	ds_read_b128 v[130:133], v147
	ds_read_b128 v[134:137], v147 offset:1024
	ds_read_b128 v[138:141], v147 offset:2048
	ds_read_b128 v[148:151], v147 offset:3072
	ds_read_b128 v[152:155], v144
	ds_read_b128 v[160:163], v144 offset:1024
	ds_read_b128 v[164:167], v144 offset:2048
	ds_read_b128 v[168:171], v144 offset:3072
	ds_read_b128 v[172:175], v144 offset:4096
	ds_read_b128 v[176:179], v144 offset:5120
	ds_read_b128 v[182:185], v144 offset:6144
	ds_read_b128 v[186:189], v144 offset:7168
	global_load_lds_dwordx4 v[190:191], off
	s_mov_b32 m0, s6
	s_nop 0
	global_load_lds_dwordx4 v[128:129], off
	s_barrier
	s_waitcnt lgkmcnt(0)
	s_setprio 1
	s_waitcnt lgkmcnt(0)
	v_mfma_f32_16x16x32_bf16 v[124:127], v[130:133], v[152:155], v[124:127]
	v_mfma_f32_16x16x32_bf16 v[120:123], v[138:141], v[152:155], v[120:123]
	v_mfma_f32_16x16x32_bf16 v[116:119], v[130:133], v[164:167], v[116:119]
	v_mfma_f32_16x16x32_bf16 v[112:115], v[138:141], v[164:167], v[112:115]
	v_mfma_f32_16x16x32_bf16 v[108:111], v[130:133], v[172:175], v[108:111]
	v_mfma_f32_16x16x32_bf16 v[104:107], v[138:141], v[172:175], v[104:107]
	v_mfma_f32_16x16x32_bf16 v[100:103], v[130:133], v[182:185], v[100:103]
	v_mfma_f32_16x16x32_bf16 v[96:99], v[138:141], v[182:185], v[96:99]
	v_mfma_f32_16x16x32_bf16 v[124:127], v[134:137], v[160:163], v[124:127]
	v_mfma_f32_16x16x32_bf16 v[120:123], v[148:151], v[160:163], v[120:123]
	v_mfma_f32_16x16x32_bf16 v[116:119], v[134:137], v[168:171], v[116:119]
	v_mfma_f32_16x16x32_bf16 v[112:115], v[148:151], v[168:171], v[112:115]
	s_setprio 2
	s_barrier
; #define LDA(dst, b, h) for (int m = 0; m < 4; ++m) for (int k = 0; k < 2; ++k) \
;     dst[m][k] = *reinterpret_cast<const bf16x8*>(a_rd + ((b) * 2 + (h)) * (HT * 2) + m * 2048 + k * 1024)
; #define LDB(dst, b, h) for (int n = 0; n < 2; ++n) for (int k = 0; k < 2; ++k) \
;     dst[n][k] = *reinterpret_cast<const bf16x8*>(b_rd + ((b) * 2 + (h)) * (HT * 2) + n * 2048 + k * 1024)
; #define MMA(ai, bj, At_, Bt_) do { __builtin_amdgcn_s_setprio(1); \
;     for (int m = 0; m < 4; ++m) for (int n = 0; n < 2; ++n) for (int k = 0; k < 2; ++k) \
;       acc[ai][bj][m][n] = __builtin_amdgcn_mfma_f32_16x16x32_bf16(Bt_[n][k], At_[m][k], acc[ai][bj][m][n], 0, 0, 0); \
;     __builtin_amdgcn_s_setprio(0); } while (0)
; #define WAIT_V(n) asm volatile("s_waitcnt vmcnt(" #n ")" ::: "memory")
; #define WAIT_L(n) asm volatile("s_waitcnt lgkmcnt(" #n ")" ::: "memory")
; #define BAR __builtin_amdgcn_s_barrier()
;     ...
;     BAR; WAIT_L(0); MMA(0, 0, At, B0); BAR;
;     LDB(B1, 0, 1); BAR; WAIT_L(0); MMA(0, 1, At, B1); BAR;
;     LDA(At, 0, 1); WAIT_V(4); BAR; WAIT_L(0); MMA(1, 0, At, B0); MMA(1, 1, At, B1); BAR; }
;   { LDB(B0, 1, 0); LDA(At, 1, 0); WAIT_V(2); BAR; WAIT_L(0); MMA(0, 0, At, B0); BAR;
	v_mfma_f32_16x16x32_bf16 v[108:111], v[134:137], v[176:179], v[108:111]
	v_mfma_f32_16x16x32_bf16 v[104:107], v[148:151], v[176:179], v[104:107]
	v_mfma_f32_16x16x32_bf16 v[100:103], v[134:137], v[186:189], v[100:103]
	v_mfma_f32_16x16x32_bf16 v[96:99], v[148:151], v[186:189], v[96:99]
	s_setprio 0
	ds_read_b128 v[156:159], v147 offset:16384
	ds_read_b128 v[190:193], v147 offset:17408
	ds_read_b128 v[194:197], v147 offset:18432
	ds_read_b128 v[198:201], v147 offset:19456
	s_barrier
	s_waitcnt lgkmcnt(0)
	s_setprio 1
	s_waitcnt lgkmcnt(0)
	v_mfma_f32_16x16x32_bf16 v[92:95], v[156:159], v[152:155], v[92:95]
	v_mfma_f32_16x16x32_bf16 v[88:91], v[194:197], v[152:155], v[88:91]
	v_mfma_f32_16x16x32_bf16 v[84:87], v[156:159], v[164:167], v[84:87]
	v_mfma_f32_16x16x32_bf16 v[80:83], v[194:197], v[164:167], v[80:83]
	v_mfma_f32_16x16x32_bf16 v[76:79], v[156:159], v[172:175], v[76:79]
	v_mfma_f32_16x16x32_bf16 v[72:75], v[194:197], v[172:175], v[72:75]
	v_mfma_f32_16x16x32_bf16 v[68:71], v[156:159], v[182:185], v[68:71]
	v_mfma_f32_16x16x32_bf16 v[64:67], v[194:197], v[182:185], v[64:67]
	v_mfma_f32_16x16x32_bf16 v[202:205], v[190:193], v[160:163], v[92:95]
	v_mfma_f32_16x16x32_bf16 v[152:155], v[198:201], v[160:163], v[88:91]
	v_mfma_f32_16x16x32_bf16 v[160:163], v[190:193], v[168:171], v[84:87]
	v_mfma_f32_16x16x32_bf16 v[164:167], v[198:201], v[168:171], v[80:83]
	s_setprio 2
	s_barrier
	v_mfma_f32_16x16x32_bf16 v[168:171], v[190:193], v[176:179], v[76:79]
	v_mfma_f32_16x16x32_bf16 v[172:175], v[198:201], v[176:179], v[72:75]
	v_mfma_f32_16x16x32_bf16 v[176:179], v[190:193], v[186:189], v[68:71]
	v_mfma_f32_16x16x32_bf16 v[182:185], v[198:201], v[186:189], v[64:67]
	s_setprio 0
	s_nop 0
	ds_read_b128 v[64:67], v144 offset:16384
	ds_read_b128 v[68:71], v144 offset:17408
	ds_read_b128 v[72:75], v144 offset:18432
	ds_read_b128 v[76:79], v144 offset:19456
	ds_read_b128 v[80:83], v144 offset:20480
	ds_read_b128 v[84:87], v144 offset:21504
	ds_read_b128 v[88:91], v144 offset:22528
	ds_read_b128 v[92:95], v144 offset:23552
	s_waitcnt vmcnt(4)
	s_barrier
	s_waitcnt lgkmcnt(0)
	s_setprio 1
	s_waitcnt lgkmcnt(0)
	v_mfma_f32_16x16x32_bf16 v[60:63], v[130:133], v[64:67], v[60:63]
	v_mfma_f32_16x16x32_bf16 v[56:59], v[138:141], v[64:67], v[56:59]
	v_mfma_f32_16x16x32_bf16 v[52:55], v[130:133], v[72:75], v[52:55]
	v_mfma_f32_16x16x32_bf16 v[48:51], v[138:141], v[72:75], v[48:51]
	v_mfma_f32_16x16x32_bf16 v[44:47], v[130:133], v[80:83], v[44:47]
	v_mfma_f32_16x16x32_bf16 v[40:43], v[138:141], v[80:83], v[40:43]
	v_mfma_f32_16x16x32_bf16 v[36:39], v[130:133], v[88:91], v[36:39]
	v_mfma_f32_16x16x32_bf16 v[32:35], v[138:141], v[88:91], v[32:35]
	v_mfma_f32_16x16x32_bf16 v[60:63], v[134:137], v[68:71], v[60:63]
	v_mfma_f32_16x16x32_bf16 v[56:59], v[148:151], v[68:71], v[56:59]
	v_mfma_f32_16x16x32_bf16 v[52:55], v[134:137], v[76:79], v[52:55]
	v_mfma_f32_16x16x32_bf16 v[48:51], v[148:151], v[76:79], v[48:51]
	v_mfma_f32_16x16x32_bf16 v[44:47], v[134:137], v[84:87], v[44:47]
	v_mfma_f32_16x16x32_bf16 v[40:43], v[148:151], v[84:87], v[40:43]
	v_mfma_f32_16x16x32_bf16 v[36:39], v[134:137], v[92:95], v[36:39]
	v_mfma_f32_16x16x32_bf16 v[32:35], v[148:151], v[92:95], v[32:35]
	s_setprio 0
	s_setprio 1
	v_mfma_f32_16x16x32_bf16 v[28:31], v[156:159], v[64:67], v[28:31]
	v_mfma_f32_16x16x32_bf16 v[24:27], v[194:197], v[64:67], v[24:27]
	v_mfma_f32_16x16x32_bf16 v[20:23], v[156:159], v[72:75], v[20:23]
	v_mfma_f32_16x16x32_bf16 v[16:19], v[194:197], v[72:75], v[16:19]
	v_mfma_f32_16x16x32_bf16 v[12:15], v[156:159], v[80:83], v[12:15]
	v_mfma_f32_16x16x32_bf16 v[8:11], v[194:197], v[80:83], v[8:11]
	v_mfma_f32_16x16x32_bf16 v[4:7], v[156:159], v[88:91], v[4:7]
	v_mfma_f32_16x16x32_bf16 v[0:3], v[194:197], v[88:91], v[0:3]
	v_mfma_f32_16x16x32_bf16 v[128:131], v[190:193], v[68:71], v[28:31]
	v_mfma_f32_16x16x32_bf16 v[132:135], v[198:201], v[68:71], v[24:27]
	v_mfma_f32_16x16x32_bf16 v[136:139], v[190:193], v[76:79], v[20:23]
	v_mfma_f32_16x16x32_bf16 v[148:151], v[198:201], v[76:79], v[16:19]
	s_setprio 2
	s_barrier
	v_mfma_f32_16x16x32_bf16 v[186:189], v[190:193], v[84:87], v[12:15]
	v_mfma_f32_16x16x32_bf16 v[206:209], v[198:201], v[84:87], v[8:11]
	v_mfma_f32_16x16x32_bf16 v[156:159], v[190:193], v[92:95], v[4:7]
	v_mfma_f32_16x16x32_bf16 v[190:193], v[198:201], v[92:95], v[0:3]
	s_setprio 0
	ds_read_b128 v[24:27], v147 offset:32768
	ds_read_b128 v[28:31], v147 offset:33792
	ds_read_b128 v[194:197], v147 offset:34816
	ds_read_b128 v[198:201], v147 offset:35840
	ds_read_b128 v[0:3], v144 offset:32768
	ds_read_b128 v[4:7], v144 offset:33792
	ds_read_b128 v[8:11], v144 offset:34816
	ds_read_b128 v[12:15], v144 offset:35840
	ds_read_b128 v[16:19], v144 offset:36864
	ds_read_b128 v[20:23], v144 offset:37888
	ds_read_b128 v[210:213], v144 offset:38912
	ds_read_b128 v[214:217], v144 offset:39936
	s_waitcnt vmcnt(2)
	s_barrier
; #define LDA(dst, b, h) for (int m = 0; m < 4; ++m) for (int k = 0; k < 2; ++k) \
;     dst[m][k] = *reinterpret_cast<const bf16x8*>(a_rd + ((b) * 2 + (h)) * (HT * 2) + m * 2048 + k * 1024)
; #define LDB(dst, b, h) for (int n = 0; n < 2; ++n) for (int k = 0; k < 2; ++k) \
;     dst[n][k] = *reinterpret_cast<const bf16x8*>(b_rd + ((b) * 2 + (h)) * (HT * 2) + n * 2048 + k * 1024)
; #define MMA(ai, bj, At_, Bt_) do { __builtin_amdgcn_s_setprio(1); \
;     for (int m = 0; m < 4; ++m) for (int n = 0; n < 2; ++n) for (int k = 0; k < 2; ++k) \
;       acc[ai][bj][m][n] = __builtin_amdgcn_mfma_f32_16x16x32_bf16(Bt_[n][k], At_[m][k], acc[ai][bj][m][n], 0, 0, 0); \
;     __builtin_amdgcn_s_setprio(0); } while (0)
; #define WAIT_V(n) asm volatile("s_waitcnt vmcnt(" #n ")" ::: "memory")
; #define WAIT_L(n) asm volatile("s_waitcnt lgkmcnt(" #n ")" ::: "memory")
; #define BAR __builtin_amdgcn_s_barrier()
;     ...
;   { LDB(B0, 1, 0); LDA(At, 1, 0); WAIT_V(2); BAR; WAIT_L(0); MMA(0, 0, At, B0); BAR;
;     LDB(B1, 1, 1); WAIT_V(0); BAR; WAIT_L(0); MMA(0, 1, At, B1); BAR;
;     LDA(At, 1, 1); BAR; WAIT_L(0); MMA(1, 0, At, B0); MMA(1, 1, At, B1); BAR; }
;   if (wr == 0) BAR;
	s_waitcnt lgkmcnt(0)
	s_setprio 1
	s_waitcnt lgkmcnt(0)
	v_mfma_f32_16x16x32_bf16 v[64:67], v[24:27], v[0:3], v[124:127]
	v_mfma_f32_16x16x32_bf16 v[68:71], v[194:197], v[0:3], v[120:123]
	v_mfma_f32_16x16x32_bf16 v[72:75], v[24:27], v[8:11], v[116:119]
	v_mfma_f32_16x16x32_bf16 v[76:79], v[194:197], v[8:11], v[112:115]
	v_mfma_f32_16x16x32_bf16 v[80:83], v[24:27], v[16:19], v[108:111]
	v_mfma_f32_16x16x32_bf16 v[84:87], v[194:197], v[16:19], v[104:107]
	v_mfma_f32_16x16x32_bf16 v[88:91], v[24:27], v[210:213], v[100:103]
	v_mfma_f32_16x16x32_bf16 v[92:95], v[194:197], v[210:213], v[96:99]
	v_mfma_f32_16x16x32_bf16 v[64:67], v[28:31], v[4:7], v[64:67]
	v_mfma_f32_16x16x32_bf16 v[68:71], v[198:201], v[4:7], v[68:71]
	v_mfma_f32_16x16x32_bf16 v[72:75], v[28:31], v[12:15], v[72:75]
	v_mfma_f32_16x16x32_bf16 v[76:79], v[198:201], v[12:15], v[76:79]
	s_setprio 2
	s_barrier
	v_mfma_f32_16x16x32_bf16 v[80:83], v[28:31], v[20:23], v[80:83]
	v_mfma_f32_16x16x32_bf16 v[84:87], v[198:201], v[20:23], v[84:87]
	v_mfma_f32_16x16x32_bf16 v[88:91], v[28:31], v[214:217], v[88:91]
	v_mfma_f32_16x16x32_bf16 v[92:95], v[198:201], v[214:217], v[92:95]
	s_setprio 0
	ds_read_b128 v[218:221], v147 offset:49152
	ds_read_b128 v[230:233], v147 offset:50176
	ds_read_b128 v[234:237], v147 offset:51200
	ds_read_b128 v[238:241], v147 offset:52224
	s_waitcnt vmcnt(0)
	s_barrier
	s_waitcnt lgkmcnt(0)
	s_setprio 1
	s_waitcnt lgkmcnt(0)
	v_mfma_f32_16x16x32_bf16 v[96:99], v[218:221], v[0:3], v[202:205]
	v_mfma_f32_16x16x32_bf16 v[0:3], v[234:237], v[0:3], v[152:155]
	v_mfma_f32_16x16x32_bf16 v[100:103], v[238:241], v[4:7], v[0:3]
	v_mfma_f32_16x16x32_bf16 v[0:3], v[218:221], v[8:11], v[160:163]
	v_mfma_f32_16x16x32_bf16 v[104:107], v[230:233], v[12:15], v[0:3]
	v_mfma_f32_16x16x32_bf16 v[0:3], v[234:237], v[8:11], v[164:167]
	v_mfma_f32_16x16x32_bf16 v[108:111], v[238:241], v[12:15], v[0:3]
	v_mfma_f32_16x16x32_bf16 v[0:3], v[218:221], v[16:19], v[168:171]
	v_mfma_f32_16x16x32_bf16 v[112:115], v[230:233], v[20:23], v[0:3]
	v_mfma_f32_16x16x32_bf16 v[0:3], v[234:237], v[16:19], v[172:175]
	v_mfma_f32_16x16x32_bf16 v[116:119], v[238:241], v[20:23], v[0:3]
	v_mfma_f32_16x16x32_bf16 v[0:3], v[218:221], v[210:213], v[176:179]
	s_setprio 2
	s_barrier
	v_mfma_f32_16x16x32_bf16 v[120:123], v[230:233], v[214:217], v[0:3]
	v_mfma_f32_16x16x32_bf16 v[0:3], v[234:237], v[210:213], v[182:185]
	v_mfma_f32_16x16x32_bf16 v[96:99], v[230:233], v[4:7], v[96:99]
	v_mfma_f32_16x16x32_bf16 v[124:127], v[238:241], v[214:217], v[0:3]
	s_setprio 0
	ds_read_b128 v[152:155], v144 offset:49152
	ds_read_b128 v[160:163], v144 offset:50176
	ds_read_b128 v[164:167], v144 offset:51200
	ds_read_b128 v[168:171], v144 offset:52224
	ds_read_b128 v[172:175], v144 offset:53248
	ds_read_b128 v[176:179], v144 offset:54272
	ds_read_b128 v[182:185], v144 offset:55296
	ds_read_b128 v[144:147], v144 offset:56320
	s_barrier
	s_waitcnt lgkmcnt(0)
	s_setprio 1
	s_waitcnt lgkmcnt(0)
	v_mfma_f32_16x16x32_bf16 v[0:3], v[24:27], v[152:155], v[60:63]
	v_mfma_f32_16x16x32_bf16 v[8:11], v[24:27], v[164:167], v[52:55]
	v_mfma_f32_16x16x32_bf16 v[16:19], v[24:27], v[172:175], v[44:47]
	v_mfma_f32_16x16x32_bf16 v[24:27], v[24:27], v[182:185], v[36:39]
	v_mfma_f32_16x16x32_bf16 v[0:3], v[28:31], v[160:163], v[0:3]
	v_mfma_f32_16x16x32_bf16 v[4:7], v[194:197], v[152:155], v[56:59]
	v_mfma_f32_16x16x32_bf16 v[8:11], v[28:31], v[168:171], v[8:11]
	v_mfma_f32_16x16x32_bf16 v[12:15], v[194:197], v[164:167], v[48:51]
	v_mfma_f32_16x16x32_bf16 v[16:19], v[28:31], v[176:179], v[16:19]
	v_mfma_f32_16x16x32_bf16 v[20:23], v[194:197], v[172:175], v[40:43]
	v_mfma_f32_16x16x32_bf16 v[24:27], v[28:31], v[144:147], v[24:27]
	v_mfma_f32_16x16x32_bf16 v[28:31], v[194:197], v[182:185], v[32:35]
	v_mfma_f32_16x16x32_bf16 v[4:7], v[198:201], v[160:163], v[4:7]
	v_mfma_f32_16x16x32_bf16 v[12:15], v[198:201], v[168:171], v[12:15]
	v_mfma_f32_16x16x32_bf16 v[20:23], v[198:201], v[176:179], v[20:23]
	v_mfma_f32_16x16x32_bf16 v[28:31], v[198:201], v[144:147], v[28:31]
	s_setprio 0
	s_setprio 1
	v_mfma_f32_16x16x32_bf16 v[32:35], v[218:221], v[152:155], v[128:131]
	v_mfma_f32_16x16x32_bf16 v[36:39], v[234:237], v[152:155], v[132:135]
	v_mfma_f32_16x16x32_bf16 v[40:43], v[218:221], v[164:167], v[136:139]
	v_mfma_f32_16x16x32_bf16 v[44:47], v[234:237], v[164:167], v[148:151]
	v_mfma_f32_16x16x32_bf16 v[48:51], v[218:221], v[172:175], v[186:189]
	v_mfma_f32_16x16x32_bf16 v[52:55], v[234:237], v[172:175], v[206:209]
	v_mfma_f32_16x16x32_bf16 v[56:59], v[218:221], v[182:185], v[156:159]
	v_mfma_f32_16x16x32_bf16 v[60:63], v[234:237], v[182:185], v[190:193]
	v_mfma_f32_16x16x32_bf16 v[32:35], v[230:233], v[160:163], v[32:35]
	v_mfma_f32_16x16x32_bf16 v[36:39], v[238:241], v[160:163], v[36:39]
	v_mfma_f32_16x16x32_bf16 v[40:43], v[230:233], v[168:171], v[40:43]
	v_mfma_f32_16x16x32_bf16 v[44:47], v[238:241], v[168:171], v[44:47]
	s_setprio 2
	s_barrier
	v_mfma_f32_16x16x32_bf16 v[48:51], v[230:233], v[176:179], v[48:51]
	v_mfma_f32_16x16x32_bf16 v[52:55], v[238:241], v[176:179], v[52:55]
	v_mfma_f32_16x16x32_bf16 v[56:59], v[230:233], v[144:147], v[56:59]
	v_mfma_f32_16x16x32_bf16 v[60:63], v[238:241], v[144:147], v[60:63]
	s_setprio 0
	v_cmp_gt_u32_e32 vcc, s60, v142
	s_and_saveexec_b64 s[6:7], vcc
	s_cbranch_execz .LBB0_2625
	s_barrier
